# U pass rewritten by hand too: in-LDS counting sort of each token expert list, one sweep of the fp8 u table per wave with 8 x-rows in registers, permlane/DPP transposed reduction, lane-parallel erf-gel
# speedup vs baseline: 1.0682x; 1.0682x over previous
; DI float bflo(unsigned u) { return __uint_as_float(u << 16); }
; DI float bfhi(unsigned u) { return __uint_as_float(u & 0xffff0000u); }
; template <bool STORE>
; DI void peer_item(const Params& p, int item, char* smem) {
;     ...
;   const unsigned char* U8 = (const unsigned char*)(ws + WS_UBF);
;   const float* SU = (const float*)(ws + WS_SU);
;   const float* SV = (const float*)(ws + WS_SV);
;   int* EG = (int*)(ws + WS_XN);
;   float* AG = (float*)(ws + WS_XN + (size_t)T_TOK * 128 * 4);
;   const bool b5 = (lane & 32) != 0, b4 = (lane & 16) != 0, b3 = (lane & 8) != 0;
; #pragma unroll 1
;   for (int ti = 0; ti < 8; ++ti) {
;     const int tl = wave * 8 + ti;
;     const size_t tok = (size_t)tok0 + tl;
;     float xf[16];
;     {
; #pragma unroll
;       for (int i = 0; i < 4; ++i) {
;         const uint2 xv = *(const uint2*)(XN2 + tok * 1024 + 256 * i + lane * 4);
;         xf[4 * i] = bflo(xv.x); xf[4 * i + 1] = bfhi(xv.x); xf[4 * i + 2] = bflo(xv.y); xf[4 * i + 3] = bfhi(xv.y);
;       }
;     }
.LBB0_1058:
	s_or_b64 exec, exec, s[0:1]
	s_waitcnt vmcnt(0) lgkmcnt(0)
	v_writelane_b32 v254, s6, 0
	v_writelane_b32 v254, s7, 1
	v_writelane_b32 v254, s12, 2
	v_writelane_b32 v254, s13, 3
	v_writelane_b32 v254, s14, 4
	v_writelane_b32 v254, s15, 5
	v_writelane_b32 v254, s16, 6
	v_writelane_b32 v254, s17, 7
	v_writelane_b32 v254, s18, 8
	v_writelane_b32 v254, s19, 9
	v_writelane_b32 v254, s20, 10
	v_writelane_b32 v254, s21, 11
	v_writelane_b32 v254, s22, 12
	v_writelane_b32 v254, s23, 13
	v_writelane_b32 v254, s24, 14
	v_writelane_b32 v254, s25, 15
	v_writelane_b32 v254, s26, 16
	v_writelane_b32 v254, s27, 17
	v_writelane_b32 v254, s28, 18
	v_writelane_b32 v254, s29, 19
	v_writelane_b32 v254, s30, 20
	v_writelane_b32 v254, s31, 21
	v_writelane_b32 v254, s33, 22
	v_writelane_b32 v254, s34, 23
	v_writelane_b32 v254, s35, 24
	v_writelane_b32 v254, s36, 25
	v_writelane_b32 v254, s37, 26
	v_writelane_b32 v254, s38, 27
	v_writelane_b32 v254, s39, 28
	v_writelane_b32 v254, s40, 29
	v_writelane_b32 v254, s41, 30
	v_writelane_b32 v254, s42, 31
	v_writelane_b32 v254, s44, 32
	v_writelane_b32 v254, s45, 33
	v_writelane_b32 v254, s48, 34
	v_writelane_b32 v254, s49, 35
	v_writelane_b32 v254, s50, 36
	v_writelane_b32 v254, s51, 37
	v_writelane_b32 v254, s52, 38
	v_writelane_b32 v254, s53, 39
	v_writelane_b32 v254, s55, 40
	v_writelane_b32 v254, s60, 41
	v_writelane_b32 v254, s61, 42
	v_writelane_b32 v254, s62, 43
	v_writelane_b32 v254, s63, 44
	v_writelane_b32 v254, s66, 45
	v_writelane_b32 v254, s67, 46
	v_writelane_b32 v254, s68, 47
	v_writelane_b32 v254, s69, 48
	v_writelane_b32 v254, s74, 49
	v_writelane_b32 v254, s75, 50
	v_writelane_b32 v254, s76, 51
	v_writelane_b32 v254, s77, 52
	v_writelane_b32 v254, s78, 53
	v_writelane_b32 v254, s79, 54
	v_writelane_b32 v254, s88, 55
	s_mov_b32 s16, s33
	s_mov_b32 s14, s42
	v_readlane_b32 s56, v253, 48
	v_readlane_b32 s57, v253, 49
	v_readfirstlane_b32 s13, v211
	v_mbcnt_lo_u32_b32 v213, -1, 0
	v_mbcnt_hi_u32_b32 v213, -1, v213
	s_nop 3
	s_bfe_u32 s17, s13, 0x20006
	s_add_u32 s0, s56, 0x1200200
	s_addc_u32 s1, s57, 0
	s_add_u32 s2, s56, 0x7200200
	s_addc_u32 s3, s57, 0
	s_add_u32 s4, s56, 0x5200200
	s_addc_u32 s5, s57, 0
	s_add_u32 s6, s56, 0x5a00200
	s_addc_u32 s7, s57, 0
	s_add_u32 s8, s56, 0x2200200
	s_addc_u32 s9, s57, 0
	s_add_u32 s10, s56, 0x4200200
	s_addc_u32 s11, s57, 0
	s_lshl_b32 s13, s17, 3
	s_add_u32 s14, s14, s13
	s_mul_i32 s18, s17, 6400
	s_add_u32 s18, s18, s16
	s_add_u32 s18, s18, 49152
	s_lshl_b32 s19, s17, 12
	s_add_u32 s19, s19, s16
	v_lshlrev_b32_e32 v238, 2, v213
	v_lshlrev_b32_e32 v234, 4, v213
	v_add_u32_e32 v236, s18, v238
	v_add_u32_e32 v237, s19, v238
	ds_write_b32 v236, v3 offset:512
	ds_write_b32 v236, v53 offset:768
	ds_write_b32 v236, v64 offset:1024
	ds_write_b32 v236, v65 offset:1280
	ds_write_b32 v236, v66 offset:1536
	ds_write_b32 v236, v67 offset:1792
	ds_write_b32 v236, v68 offset:2048
	ds_write_b32 v236, v69 offset:2304
	ds_write_b32 v236, v70 offset:2560
	ds_write_b32 v236, v71 offset:2816
	ds_write_b32 v236, v72 offset:3072
	ds_write_b32 v236, v73 offset:3328
	ds_write_b32 v236, v74 offset:3584
	ds_write_b32 v236, v75 offset:3840
	ds_write_b32 v236, v76 offset:4096
	ds_write_b32 v236, v77 offset:4352
	ds_write_b32 v236, v78 offset:4608
	ds_write_b32 v236, v79 offset:4864
	ds_write_b32 v236, v80 offset:5120
	ds_write_b32 v236, v81 offset:5376
	ds_write_b32 v236, v82 offset:5632
	ds_write_b32 v236, v83 offset:5888
	ds_write_b32 v236, v96 offset:6144
	s_mov_b32 s24, 0xff00ff00
	s_mov_b32 s25, 0xff00ff00
	s_mov_b32 s80, 0x378e98ab
	s_mov_b32 s81, 0x3b7cd369
	s_mov_b32 s82, 0xbcc618b2
	s_mov_b32 s83, 0x3dda74e4
	s_mov_b32 s84, 0x3f228afd
	s_mov_b32 s85, 0x3e03c728
	s_mov_b32 s86, 0xbfb8aa3b
	s_mov_b32 s87, 0x42ce8ed0
	s_mov_b32 s88, 0xc2b17218
	s_mov_b32 s89, 0x7fffffff
	s_waitcnt lgkmcnt(0)
	s_lshl_b32 s13, s14, 11
	s_add_u32 s32, s2, s13
	s_addc_u32 s33, s3, 0
	v_lshlrev_b32_e32 v239, 3, v213
	global_load_dwordx2 v[2:3], v239, s[32:33] offset:0
	global_load_dwordx2 v[6:7], v239, s[32:33] offset:512
	global_load_dwordx2 v[10:11], v239, s[32:33] offset:1024
	global_load_dwordx2 v[14:15], v239, s[32:33] offset:1536
	global_load_dwordx2 v[18:19], v239, s[32:33] offset:2048
	global_load_dwordx2 v[22:23], v239, s[32:33] offset:2560
	global_load_dwordx2 v[26:27], v239, s[32:33] offset:3072
	global_load_dwordx2 v[30:31], v239, s[32:33] offset:3584
	s_add_u32 s32, s32, 4096
	s_addc_u32 s33, s33, 0
	global_load_dwordx2 v[34:35], v239, s[32:33] offset:0
	global_load_dwordx2 v[38:39], v239, s[32:33] offset:512
	global_load_dwordx2 v[42:43], v239, s[32:33] offset:1024
	global_load_dwordx2 v[46:47], v239, s[32:33] offset:1536
	global_load_dwordx2 v[50:51], v239, s[32:33] offset:2048
	global_load_dwordx2 v[54:55], v239, s[32:33] offset:2560
	global_load_dwordx2 v[58:59], v239, s[32:33] offset:3072
	global_load_dwordx2 v[62:63], v239, s[32:33] offset:3584
	s_add_u32 s32, s32, 4096
	s_addc_u32 s33, s33, 0
	global_load_dwordx2 v[66:67], v239, s[32:33] offset:0
	global_load_dwordx2 v[70:71], v239, s[32:33] offset:512
	global_load_dwordx2 v[74:75], v239, s[32:33] offset:1024
	global_load_dwordx2 v[78:79], v239, s[32:33] offset:1536
	global_load_dwordx2 v[82:83], v239, s[32:33] offset:2048
	global_load_dwordx2 v[86:87], v239, s[32:33] offset:2560
	global_load_dwordx2 v[90:91], v239, s[32:33] offset:3072
	global_load_dwordx2 v[94:95], v239, s[32:33] offset:3584
	s_add_u32 s32, s32, 4096
	s_addc_u32 s33, s33, 0
	global_load_dwordx2 v[98:99], v239, s[32:33] offset:0
	global_load_dwordx2 v[102:103], v239, s[32:33] offset:512
	global_load_dwordx2 v[106:107], v239, s[32:33] offset:1024
	global_load_dwordx2 v[110:111], v239, s[32:33] offset:1536
	global_load_dwordx2 v[114:115], v239, s[32:33] offset:2048
	global_load_dwordx2 v[118:119], v239, s[32:33] offset:2560
	global_load_dwordx2 v[122:123], v239, s[32:33] offset:3072
	global_load_dwordx2 v[126:127], v239, s[32:33] offset:3584
	v_mov_b32_e32 v144, v236
	v_mov_b32_e32 v145, 0
	v_mov_b32_e32 v146, 1
	v_lshrrev_b32_e32 v147, 3, v213
	v_and_b32_e32 v148, 7, v213
	v_lshlrev_b32_e32 v147, 6, v147
	v_lshl_add_u32 v147, v148, 2, v147
	v_add_u32_e32 v147, s19, v147
	v_subrev_u32_e32 v149, 1, v213
	v_subrev_u32_e32 v150, 2, v213
	v_subrev_u32_e32 v151, 4, v213
	v_subrev_u32_e32 v152, 8, v213
	v_subrev_u32_e32 v153, 16, v213
	v_subrev_u32_e32 v154, 32, v213
	v_lshlrev_b32_e32 v149, 2, v149
	v_lshlrev_b32_e32 v150, 2, v150
	v_lshlrev_b32_e32 v151, 2, v151
	v_lshlrev_b32_e32 v152, 2, v152
	v_lshlrev_b32_e32 v153, 2, v153
	v_lshlrev_b32_e32 v154, 2, v154
	ds_read_b32 v166, v237 offset:0
	ds_read_b32 v167, v237 offset:256
	ds_read_b32 v168, v237 offset:16384
	ds_read_b32 v169, v237 offset:16640
	ds_write_b32 v144, v145
	ds_write_b32 v144, v145 offset:256
	s_waitcnt lgkmcnt(0)
; template <bool STORE>
; DI void peer_item(const Params& p, int item, char* smem) {
;     ...
;       const int emine = e_s[tl * 128 + k + (lane >> 3)];
;       const float gmine = g_s[tl * 128 + k + (lane >> 3)];
;       const float su = SU[emine], sv = SV[emine];
; #pragma unroll
;       for (int u = 0; u < 8; ++u) {
;         int e = e_s[tl * 128 + k + u];
;         uq[u] = *(const u32x4*)(U8 + (size_t)e * 1024 + lane * 16);
	v_lshrrev_b32_e32 v156, 5, v166
	v_lshrrev_b32_e32 v157, 5, v167
	v_and_b32_e32 v156, 0x1fc, v156
	v_and_b32_e32 v157, 0x1fc, v157
	v_add_u32_e32 v156, s18, v156
	v_add_u32_e32 v157, s18, v157
	ds_add_rtn_u32 v158, v156, v146
	ds_add_rtn_u32 v159, v157, v146
	ds_read_b32 v160, v144
	ds_read_b32 v161, v144 offset:256
	s_waitcnt lgkmcnt(0)
	v_mov_b32_e32 v164, v160
	v_mov_b32_e32 v165, v161
	v_cmp_le_u32_e32 vcc, 1, v213
	ds_bpermute_b32 v162, v149, v164
	ds_bpermute_b32 v163, v149, v165
	s_waitcnt lgkmcnt(0)
	v_cndmask_b32_e32 v162, 0, v162, vcc
	v_cndmask_b32_e32 v163, 0, v163, vcc
	v_add_u32_e32 v164, v164, v162
	v_add_u32_e32 v165, v165, v163
	v_cmp_le_u32_e32 vcc, 2, v213
	ds_bpermute_b32 v162, v150, v164
	ds_bpermute_b32 v163, v150, v165
	s_waitcnt lgkmcnt(0)
	v_cndmask_b32_e32 v162, 0, v162, vcc
	v_cndmask_b32_e32 v163, 0, v163, vcc
	v_add_u32_e32 v164, v164, v162
	v_add_u32_e32 v165, v165, v163
	v_cmp_le_u32_e32 vcc, 4, v213
	ds_bpermute_b32 v162, v151, v164
	ds_bpermute_b32 v163, v151, v165
	s_waitcnt lgkmcnt(0)
	v_cndmask_b32_e32 v162, 0, v162, vcc
	v_cndmask_b32_e32 v163, 0, v163, vcc
	v_add_u32_e32 v164, v164, v162
	v_add_u32_e32 v165, v165, v163
	v_cmp_le_u32_e32 vcc, 8, v213
	ds_bpermute_b32 v162, v152, v164
	ds_bpermute_b32 v163, v152, v165
	s_waitcnt lgkmcnt(0)
	v_cndmask_b32_e32 v162, 0, v162, vcc
	v_cndmask_b32_e32 v163, 0, v163, vcc
	v_add_u32_e32 v164, v164, v162
	v_add_u32_e32 v165, v165, v163
	v_cmp_le_u32_e32 vcc, 16, v213
	ds_bpermute_b32 v162, v153, v164
	ds_bpermute_b32 v163, v153, v165
	s_waitcnt lgkmcnt(0)
	v_cndmask_b32_e32 v162, 0, v162, vcc
	v_cndmask_b32_e32 v163, 0, v163, vcc
	v_add_u32_e32 v164, v164, v162
	v_add_u32_e32 v165, v165, v163
	v_cmp_le_u32_e32 vcc, 32, v213
	ds_bpermute_b32 v162, v154, v164
	ds_bpermute_b32 v163, v154, v165
	s_waitcnt lgkmcnt(0)
	v_cndmask_b32_e32 v162, 0, v162, vcc
	v_cndmask_b32_e32 v163, 0, v163, vcc
	v_add_u32_e32 v164, v164, v162
	v_add_u32_e32 v165, v165, v163
	v_readlane_b32 s13, v164, 63
	v_sub_u32_e32 v164, v164, v160
	v_sub_u32_e32 v165, v165, v161
	s_nop 0
	v_add_u32_e32 v165, s13, v165
	ds_write_b32 v144, v164
	ds_write_b32 v144, v165 offset:256
	ds_read_b32 v160, v156
	ds_read_b32 v161, v157
	s_waitcnt lgkmcnt(0)
	v_add_u32_e32 v160, v160, v158
	v_add_u32_e32 v161, v161, v159
	v_lshl_add_u32 v160, v160, 2, s19
	v_lshl_add_u32 v161, v161, 2, s19
	ds_write_b32 v160, v166 offset:0
	ds_write_b32 v160, v168 offset:16384
	ds_write_b32 v161, v167 offset:0
	ds_write_b32 v161, v169 offset:16384
	ds_read_b32 v128, v147 offset:0
	ds_read_b32 v129, v147 offset:32
	s_waitcnt lgkmcnt(0)
	v_lshlrev_b32_e32 v128, 10, v128
	v_lshlrev_b32_e32 v129, 10, v129
	ds_read_b32 v166, v237 offset:512
	ds_read_b32 v167, v237 offset:768
	ds_read_b32 v168, v237 offset:16896
	ds_read_b32 v169, v237 offset:17152
	ds_write_b32 v144, v145
	ds_write_b32 v144, v145 offset:256
	s_waitcnt lgkmcnt(0)
	v_lshrrev_b32_e32 v156, 5, v166
	v_lshrrev_b32_e32 v157, 5, v167
	v_and_b32_e32 v156, 0x1fc, v156
	v_and_b32_e32 v157, 0x1fc, v157
	v_add_u32_e32 v156, s18, v156
	v_add_u32_e32 v157, s18, v157
	ds_add_rtn_u32 v158, v156, v146
	ds_add_rtn_u32 v159, v157, v146
	ds_read_b32 v160, v144
	ds_read_b32 v161, v144 offset:256
	s_waitcnt lgkmcnt(0)
	v_mov_b32_e32 v164, v160
	v_mov_b32_e32 v165, v161
	v_cmp_le_u32_e32 vcc, 1, v213
	ds_bpermute_b32 v162, v149, v164
	ds_bpermute_b32 v163, v149, v165
	s_waitcnt lgkmcnt(0)
	v_cndmask_b32_e32 v162, 0, v162, vcc
	v_cndmask_b32_e32 v163, 0, v163, vcc
	v_add_u32_e32 v164, v164, v162
	v_add_u32_e32 v165, v165, v163
	v_cmp_le_u32_e32 vcc, 2, v213
	ds_bpermute_b32 v162, v150, v164
	ds_bpermute_b32 v163, v150, v165
	s_waitcnt lgkmcnt(0)
	v_cndmask_b32_e32 v162, 0, v162, vcc
	v_cndmask_b32_e32 v163, 0, v163, vcc
	v_add_u32_e32 v164, v164, v162
	v_add_u32_e32 v165, v165, v163
	v_cmp_le_u32_e32 vcc, 4, v213
	ds_bpermute_b32 v162, v151, v164
	ds_bpermute_b32 v163, v151, v165
	s_waitcnt lgkmcnt(0)
	v_cndmask_b32_e32 v162, 0, v162, vcc
	v_cndmask_b32_e32 v163, 0, v163, vcc
	v_add_u32_e32 v164, v164, v162
	v_add_u32_e32 v165, v165, v163
	v_cmp_le_u32_e32 vcc, 8, v213
	ds_bpermute_b32 v162, v152, v164
	ds_bpermute_b32 v163, v152, v165
	s_waitcnt lgkmcnt(0)
	v_cndmask_b32_e32 v162, 0, v162, vcc
	v_cndmask_b32_e32 v163, 0, v163, vcc
	v_add_u32_e32 v164, v164, v162
	v_add_u32_e32 v165, v165, v163
	v_cmp_le_u32_e32 vcc, 16, v213
	ds_bpermute_b32 v162, v153, v164
	ds_bpermute_b32 v163, v153, v165
	s_waitcnt lgkmcnt(0)
	v_cndmask_b32_e32 v162, 0, v162, vcc
	v_cndmask_b32_e32 v163, 0, v163, vcc
	v_add_u32_e32 v164, v164, v162
	v_add_u32_e32 v165, v165, v163
	v_cmp_le_u32_e32 vcc, 32, v213
	ds_bpermute_b32 v162, v154, v164
	ds_bpermute_b32 v163, v154, v165
	s_waitcnt lgkmcnt(0)
	v_cndmask_b32_e32 v162, 0, v162, vcc
	v_cndmask_b32_e32 v163, 0, v163, vcc
	v_add_u32_e32 v164, v164, v162
	v_add_u32_e32 v165, v165, v163
	v_readlane_b32 s13, v164, 63
	v_sub_u32_e32 v164, v164, v160
	v_sub_u32_e32 v165, v165, v161
	s_nop 0
	v_add_u32_e32 v165, s13, v165
	ds_write_b32 v144, v164
	ds_write_b32 v144, v165 offset:256
	ds_read_b32 v160, v156
	ds_read_b32 v161, v157
	s_waitcnt lgkmcnt(0)
	v_add_u32_e32 v160, v160, v158
	v_add_u32_e32 v161, v161, v159
	v_lshl_add_u32 v160, v160, 2, s19
	v_lshl_add_u32 v161, v161, 2, s19
	ds_write_b32 v160, v166 offset:512
	ds_write_b32 v160, v168 offset:16896
	ds_write_b32 v161, v167 offset:512
	ds_write_b32 v161, v169 offset:16896
	ds_read_b32 v130, v147 offset:512
	ds_read_b32 v131, v147 offset:544
	s_waitcnt lgkmcnt(0)
	v_lshlrev_b32_e32 v130, 10, v130
	v_lshlrev_b32_e32 v131, 10, v131
	ds_read_b32 v166, v237 offset:1024
	ds_read_b32 v167, v237 offset:1280
	ds_read_b32 v168, v237 offset:17408
	ds_read_b32 v169, v237 offset:17664
	ds_write_b32 v144, v145
	ds_write_b32 v144, v145 offset:256
	s_waitcnt lgkmcnt(0)
; template <bool STORE>
; DI void peer_item(const Params& p, int item, char* smem) {
;     ...
;       const int emine = e_s[tl * 128 + k + (lane >> 3)];
;       const float gmine = g_s[tl * 128 + k + (lane >> 3)];
;       const float su = SU[emine], sv = SV[emine];
; #pragma unroll
;       for (int u = 0; u < 8; ++u) {
;         int e = e_s[tl * 128 + k + u];
;         uq[u] = *(const u32x4*)(U8 + (size_t)e * 1024 + lane * 16);
	v_lshrrev_b32_e32 v156, 5, v166
	v_lshrrev_b32_e32 v157, 5, v167
	v_and_b32_e32 v156, 0x1fc, v156
	v_and_b32_e32 v157, 0x1fc, v157
	v_add_u32_e32 v156, s18, v156
	v_add_u32_e32 v157, s18, v157
	ds_add_rtn_u32 v158, v156, v146
	ds_add_rtn_u32 v159, v157, v146
	ds_read_b32 v160, v144
	ds_read_b32 v161, v144 offset:256
	s_waitcnt lgkmcnt(0)
	v_mov_b32_e32 v164, v160
	v_mov_b32_e32 v165, v161
	v_cmp_le_u32_e32 vcc, 1, v213
	ds_bpermute_b32 v162, v149, v164
	ds_bpermute_b32 v163, v149, v165
	s_waitcnt lgkmcnt(0)
	v_cndmask_b32_e32 v162, 0, v162, vcc
	v_cndmask_b32_e32 v163, 0, v163, vcc
	v_add_u32_e32 v164, v164, v162
	v_add_u32_e32 v165, v165, v163
	v_cmp_le_u32_e32 vcc, 2, v213
	ds_bpermute_b32 v162, v150, v164
	ds_bpermute_b32 v163, v150, v165
	s_waitcnt lgkmcnt(0)
	v_cndmask_b32_e32 v162, 0, v162, vcc
	v_cndmask_b32_e32 v163, 0, v163, vcc
	v_add_u32_e32 v164, v164, v162
	v_add_u32_e32 v165, v165, v163
	v_cmp_le_u32_e32 vcc, 4, v213
	ds_bpermute_b32 v162, v151, v164
	ds_bpermute_b32 v163, v151, v165
	s_waitcnt lgkmcnt(0)
	v_cndmask_b32_e32 v162, 0, v162, vcc
	v_cndmask_b32_e32 v163, 0, v163, vcc
	v_add_u32_e32 v164, v164, v162
	v_add_u32_e32 v165, v165, v163
	v_cmp_le_u32_e32 vcc, 8, v213
	ds_bpermute_b32 v162, v152, v164
	ds_bpermute_b32 v163, v152, v165
	s_waitcnt lgkmcnt(0)
	v_cndmask_b32_e32 v162, 0, v162, vcc
	v_cndmask_b32_e32 v163, 0, v163, vcc
	v_add_u32_e32 v164, v164, v162
	v_add_u32_e32 v165, v165, v163
	v_cmp_le_u32_e32 vcc, 16, v213
	ds_bpermute_b32 v162, v153, v164
	ds_bpermute_b32 v163, v153, v165
	s_waitcnt lgkmcnt(0)
	v_cndmask_b32_e32 v162, 0, v162, vcc
	v_cndmask_b32_e32 v163, 0, v163, vcc
	v_add_u32_e32 v164, v164, v162
	v_add_u32_e32 v165, v165, v163
	v_cmp_le_u32_e32 vcc, 32, v213
	ds_bpermute_b32 v162, v154, v164
	ds_bpermute_b32 v163, v154, v165
	s_waitcnt lgkmcnt(0)
	v_cndmask_b32_e32 v162, 0, v162, vcc
	v_cndmask_b32_e32 v163, 0, v163, vcc
	v_add_u32_e32 v164, v164, v162
	v_add_u32_e32 v165, v165, v163
	v_readlane_b32 s13, v164, 63
	v_sub_u32_e32 v164, v164, v160
	v_sub_u32_e32 v165, v165, v161
	s_nop 0
	v_add_u32_e32 v165, s13, v165
	ds_write_b32 v144, v164
	ds_write_b32 v144, v165 offset:256
	ds_read_b32 v160, v156
	ds_read_b32 v161, v157
	s_waitcnt lgkmcnt(0)
	v_add_u32_e32 v160, v160, v158
	v_add_u32_e32 v161, v161, v159
	v_lshl_add_u32 v160, v160, 2, s19
	v_lshl_add_u32 v161, v161, 2, s19
	ds_write_b32 v160, v166 offset:1024
	ds_write_b32 v160, v168 offset:17408
	ds_write_b32 v161, v167 offset:1024
	ds_write_b32 v161, v169 offset:17408
	ds_read_b32 v132, v147 offset:1024
	ds_read_b32 v133, v147 offset:1056
	s_waitcnt lgkmcnt(0)
	v_lshlrev_b32_e32 v132, 10, v132
	v_lshlrev_b32_e32 v133, 10, v133
	ds_read_b32 v166, v237 offset:1536
	ds_read_b32 v167, v237 offset:1792
	ds_read_b32 v168, v237 offset:17920
	ds_read_b32 v169, v237 offset:18176
	ds_write_b32 v144, v145
	ds_write_b32 v144, v145 offset:256
	s_waitcnt lgkmcnt(0)
	v_lshrrev_b32_e32 v156, 5, v166
	v_lshrrev_b32_e32 v157, 5, v167
	v_and_b32_e32 v156, 0x1fc, v156
	v_and_b32_e32 v157, 0x1fc, v157
	v_add_u32_e32 v156, s18, v156
	v_add_u32_e32 v157, s18, v157
	ds_add_rtn_u32 v158, v156, v146
	ds_add_rtn_u32 v159, v157, v146
	ds_read_b32 v160, v144
	ds_read_b32 v161, v144 offset:256
	s_waitcnt lgkmcnt(0)
	v_mov_b32_e32 v164, v160
	v_mov_b32_e32 v165, v161
	v_cmp_le_u32_e32 vcc, 1, v213
	ds_bpermute_b32 v162, v149, v164
	ds_bpermute_b32 v163, v149, v165
	s_waitcnt lgkmcnt(0)
	v_cndmask_b32_e32 v162, 0, v162, vcc
	v_cndmask_b32_e32 v163, 0, v163, vcc
	v_add_u32_e32 v164, v164, v162
	v_add_u32_e32 v165, v165, v163
	v_cmp_le_u32_e32 vcc, 2, v213
	ds_bpermute_b32 v162, v150, v164
	ds_bpermute_b32 v163, v150, v165
	s_waitcnt lgkmcnt(0)
	v_cndmask_b32_e32 v162, 0, v162, vcc
	v_cndmask_b32_e32 v163, 0, v163, vcc
	v_add_u32_e32 v164, v164, v162
	v_add_u32_e32 v165, v165, v163
	v_cmp_le_u32_e32 vcc, 4, v213
	ds_bpermute_b32 v162, v151, v164
	ds_bpermute_b32 v163, v151, v165
	s_waitcnt lgkmcnt(0)
	v_cndmask_b32_e32 v162, 0, v162, vcc
	v_cndmask_b32_e32 v163, 0, v163, vcc
	v_add_u32_e32 v164, v164, v162
	v_add_u32_e32 v165, v165, v163
	v_cmp_le_u32_e32 vcc, 8, v213
	ds_bpermute_b32 v162, v152, v164
	ds_bpermute_b32 v163, v152, v165
	s_waitcnt lgkmcnt(0)
	v_cndmask_b32_e32 v162, 0, v162, vcc
	v_cndmask_b32_e32 v163, 0, v163, vcc
	v_add_u32_e32 v164, v164, v162
	v_add_u32_e32 v165, v165, v163
	v_cmp_le_u32_e32 vcc, 16, v213
	ds_bpermute_b32 v162, v153, v164
	ds_bpermute_b32 v163, v153, v165
	s_waitcnt lgkmcnt(0)
	v_cndmask_b32_e32 v162, 0, v162, vcc
	v_cndmask_b32_e32 v163, 0, v163, vcc
	v_add_u32_e32 v164, v164, v162
	v_add_u32_e32 v165, v165, v163
	v_cmp_le_u32_e32 vcc, 32, v213
	ds_bpermute_b32 v162, v154, v164
	ds_bpermute_b32 v163, v154, v165
	s_waitcnt lgkmcnt(0)
	v_cndmask_b32_e32 v162, 0, v162, vcc
	v_cndmask_b32_e32 v163, 0, v163, vcc
	v_add_u32_e32 v164, v164, v162
	v_add_u32_e32 v165, v165, v163
	v_readlane_b32 s13, v164, 63
	v_sub_u32_e32 v164, v164, v160
	v_sub_u32_e32 v165, v165, v161
	s_nop 0
	v_add_u32_e32 v165, s13, v165
	ds_write_b32 v144, v164
	ds_write_b32 v144, v165 offset:256
	ds_read_b32 v160, v156
	ds_read_b32 v161, v157
	s_waitcnt lgkmcnt(0)
	v_add_u32_e32 v160, v160, v158
	v_add_u32_e32 v161, v161, v159
	v_lshl_add_u32 v160, v160, 2, s19
	v_lshl_add_u32 v161, v161, 2, s19
	ds_write_b32 v160, v166 offset:1536
	ds_write_b32 v160, v168 offset:17920
	ds_write_b32 v161, v167 offset:1536
	ds_write_b32 v161, v169 offset:17920
	ds_read_b32 v134, v147 offset:1536
	ds_read_b32 v135, v147 offset:1568
	s_waitcnt lgkmcnt(0)
; template <bool STORE>
; DI void peer_item(const Params& p, int item, char* smem) {
;     ...
;       const int emine = e_s[tl * 128 + k + (lane >> 3)];
;       const float gmine = g_s[tl * 128 + k + (lane >> 3)];
;       const float su = SU[emine], sv = SV[emine];
; #pragma unroll
;       for (int u = 0; u < 8; ++u) {
;         int e = e_s[tl * 128 + k + u];
;         uq[u] = *(const u32x4*)(U8 + (size_t)e * 1024 + lane * 16);
	v_lshlrev_b32_e32 v134, 10, v134
	v_lshlrev_b32_e32 v135, 10, v135
	ds_read_b32 v166, v237 offset:2048
	ds_read_b32 v167, v237 offset:2304
	ds_read_b32 v168, v237 offset:18432
	ds_read_b32 v169, v237 offset:18688
	ds_write_b32 v144, v145
	ds_write_b32 v144, v145 offset:256
	s_waitcnt lgkmcnt(0)
	v_lshrrev_b32_e32 v156, 5, v166
	v_lshrrev_b32_e32 v157, 5, v167
	v_and_b32_e32 v156, 0x1fc, v156
	v_and_b32_e32 v157, 0x1fc, v157
	v_add_u32_e32 v156, s18, v156
	v_add_u32_e32 v157, s18, v157
	ds_add_rtn_u32 v158, v156, v146
	ds_add_rtn_u32 v159, v157, v146
	ds_read_b32 v160, v144
	ds_read_b32 v161, v144 offset:256
	s_waitcnt lgkmcnt(0)
	v_mov_b32_e32 v164, v160
	v_mov_b32_e32 v165, v161
	v_cmp_le_u32_e32 vcc, 1, v213
	ds_bpermute_b32 v162, v149, v164
	ds_bpermute_b32 v163, v149, v165
	s_waitcnt lgkmcnt(0)
	v_cndmask_b32_e32 v162, 0, v162, vcc
	v_cndmask_b32_e32 v163, 0, v163, vcc
	v_add_u32_e32 v164, v164, v162
	v_add_u32_e32 v165, v165, v163
	v_cmp_le_u32_e32 vcc, 2, v213
	ds_bpermute_b32 v162, v150, v164
	ds_bpermute_b32 v163, v150, v165
	s_waitcnt lgkmcnt(0)
	v_cndmask_b32_e32 v162, 0, v162, vcc
	v_cndmask_b32_e32 v163, 0, v163, vcc
	v_add_u32_e32 v164, v164, v162
	v_add_u32_e32 v165, v165, v163
	v_cmp_le_u32_e32 vcc, 4, v213
	ds_bpermute_b32 v162, v151, v164
	ds_bpermute_b32 v163, v151, v165
	s_waitcnt lgkmcnt(0)
	v_cndmask_b32_e32 v162, 0, v162, vcc
	v_cndmask_b32_e32 v163, 0, v163, vcc
	v_add_u32_e32 v164, v164, v162
	v_add_u32_e32 v165, v165, v163
	v_cmp_le_u32_e32 vcc, 8, v213
	ds_bpermute_b32 v162, v152, v164
	ds_bpermute_b32 v163, v152, v165
	s_waitcnt lgkmcnt(0)
	v_cndmask_b32_e32 v162, 0, v162, vcc
	v_cndmask_b32_e32 v163, 0, v163, vcc
	v_add_u32_e32 v164, v164, v162
	v_add_u32_e32 v165, v165, v163
	v_cmp_le_u32_e32 vcc, 16, v213
	ds_bpermute_b32 v162, v153, v164
	ds_bpermute_b32 v163, v153, v165
	s_waitcnt lgkmcnt(0)
	v_cndmask_b32_e32 v162, 0, v162, vcc
	v_cndmask_b32_e32 v163, 0, v163, vcc
	v_add_u32_e32 v164, v164, v162
	v_add_u32_e32 v165, v165, v163
	v_cmp_le_u32_e32 vcc, 32, v213
	ds_bpermute_b32 v162, v154, v164
	ds_bpermute_b32 v163, v154, v165
	s_waitcnt lgkmcnt(0)
	v_cndmask_b32_e32 v162, 0, v162, vcc
	v_cndmask_b32_e32 v163, 0, v163, vcc
	v_add_u32_e32 v164, v164, v162
	v_add_u32_e32 v165, v165, v163
	v_readlane_b32 s13, v164, 63
	v_sub_u32_e32 v164, v164, v160
	v_sub_u32_e32 v165, v165, v161
	s_nop 0
	v_add_u32_e32 v165, s13, v165
	ds_write_b32 v144, v164
	ds_write_b32 v144, v165 offset:256
	ds_read_b32 v160, v156
	ds_read_b32 v161, v157
	s_waitcnt lgkmcnt(0)
	v_add_u32_e32 v160, v160, v158
	v_add_u32_e32 v161, v161, v159
	v_lshl_add_u32 v160, v160, 2, s19
	v_lshl_add_u32 v161, v161, 2, s19
	ds_write_b32 v160, v166 offset:2048
	ds_write_b32 v160, v168 offset:18432
	ds_write_b32 v161, v167 offset:2048
	ds_write_b32 v161, v169 offset:18432
	ds_read_b32 v136, v147 offset:2048
	ds_read_b32 v137, v147 offset:2080
	s_waitcnt lgkmcnt(0)
	v_lshlrev_b32_e32 v136, 10, v136
	v_lshlrev_b32_e32 v137, 10, v137
	ds_read_b32 v166, v237 offset:2560
	ds_read_b32 v167, v237 offset:2816
	ds_read_b32 v168, v237 offset:18944
	ds_read_b32 v169, v237 offset:19200
	ds_write_b32 v144, v145
	ds_write_b32 v144, v145 offset:256
	s_waitcnt lgkmcnt(0)
	v_lshrrev_b32_e32 v156, 5, v166
	v_lshrrev_b32_e32 v157, 5, v167
	v_and_b32_e32 v156, 0x1fc, v156
	v_and_b32_e32 v157, 0x1fc, v157
	v_add_u32_e32 v156, s18, v156
	v_add_u32_e32 v157, s18, v157
	ds_add_rtn_u32 v158, v156, v146
	ds_add_rtn_u32 v159, v157, v146
	ds_read_b32 v160, v144
	ds_read_b32 v161, v144 offset:256
	s_waitcnt lgkmcnt(0)
	v_mov_b32_e32 v164, v160
	v_mov_b32_e32 v165, v161
	v_cmp_le_u32_e32 vcc, 1, v213
	ds_bpermute_b32 v162, v149, v164
	ds_bpermute_b32 v163, v149, v165
	s_waitcnt lgkmcnt(0)
	v_cndmask_b32_e32 v162, 0, v162, vcc
	v_cndmask_b32_e32 v163, 0, v163, vcc
	v_add_u32_e32 v164, v164, v162
	v_add_u32_e32 v165, v165, v163
	v_cmp_le_u32_e32 vcc, 2, v213
	ds_bpermute_b32 v162, v150, v164
	ds_bpermute_b32 v163, v150, v165
	s_waitcnt lgkmcnt(0)
	v_cndmask_b32_e32 v162, 0, v162, vcc
	v_cndmask_b32_e32 v163, 0, v163, vcc
	v_add_u32_e32 v164, v164, v162
	v_add_u32_e32 v165, v165, v163
	v_cmp_le_u32_e32 vcc, 4, v213
	ds_bpermute_b32 v162, v151, v164
	ds_bpermute_b32 v163, v151, v165
	s_waitcnt lgkmcnt(0)
	v_cndmask_b32_e32 v162, 0, v162, vcc
	v_cndmask_b32_e32 v163, 0, v163, vcc
	v_add_u32_e32 v164, v164, v162
	v_add_u32_e32 v165, v165, v163
	v_cmp_le_u32_e32 vcc, 8, v213
	ds_bpermute_b32 v162, v152, v164
	ds_bpermute_b32 v163, v152, v165
	s_waitcnt lgkmcnt(0)
	v_cndmask_b32_e32 v162, 0, v162, vcc
	v_cndmask_b32_e32 v163, 0, v163, vcc
	v_add_u32_e32 v164, v164, v162
	v_add_u32_e32 v165, v165, v163
	v_cmp_le_u32_e32 vcc, 16, v213
	ds_bpermute_b32 v162, v153, v164
	ds_bpermute_b32 v163, v153, v165
	s_waitcnt lgkmcnt(0)
	v_cndmask_b32_e32 v162, 0, v162, vcc
	v_cndmask_b32_e32 v163, 0, v163, vcc
	v_add_u32_e32 v164, v164, v162
	v_add_u32_e32 v165, v165, v163
	v_cmp_le_u32_e32 vcc, 32, v213
	ds_bpermute_b32 v162, v154, v164
	ds_bpermute_b32 v163, v154, v165
	s_waitcnt lgkmcnt(0)
	v_cndmask_b32_e32 v162, 0, v162, vcc
	v_cndmask_b32_e32 v163, 0, v163, vcc
	v_add_u32_e32 v164, v164, v162
	v_add_u32_e32 v165, v165, v163
	v_readlane_b32 s13, v164, 63
	v_sub_u32_e32 v164, v164, v160
	v_sub_u32_e32 v165, v165, v161
	s_nop 0
	v_add_u32_e32 v165, s13, v165
	ds_write_b32 v144, v164
	ds_write_b32 v144, v165 offset:256
	ds_read_b32 v160, v156
	ds_read_b32 v161, v157
	s_waitcnt lgkmcnt(0)
	v_add_u32_e32 v160, v160, v158
	v_add_u32_e32 v161, v161, v159
	v_lshl_add_u32 v160, v160, 2, s19
	v_lshl_add_u32 v161, v161, 2, s19
	ds_write_b32 v160, v166 offset:2560
	ds_write_b32 v160, v168 offset:18944
	ds_write_b32 v161, v167 offset:2560
	ds_write_b32 v161, v169 offset:18944
	ds_read_b32 v138, v147 offset:2560
	ds_read_b32 v139, v147 offset:2592
	s_waitcnt lgkmcnt(0)
; template <bool STORE>
; DI void peer_item(const Params& p, int item, char* smem) {
;     ...
;       const int emine = e_s[tl * 128 + k + (lane >> 3)];
;       const float gmine = g_s[tl * 128 + k + (lane >> 3)];
;       const float su = SU[emine], sv = SV[emine];
; #pragma unroll
;       for (int u = 0; u < 8; ++u) {
;         int e = e_s[tl * 128 + k + u];
;         uq[u] = *(const u32x4*)(U8 + (size_t)e * 1024 + lane * 16);
	v_lshlrev_b32_e32 v138, 10, v138
	v_lshlrev_b32_e32 v139, 10, v139
	ds_read_b32 v166, v237 offset:3072
	ds_read_b32 v167, v237 offset:3328
	ds_read_b32 v168, v237 offset:19456
	ds_read_b32 v169, v237 offset:19712
	ds_write_b32 v144, v145
	ds_write_b32 v144, v145 offset:256
	s_waitcnt lgkmcnt(0)
	v_lshrrev_b32_e32 v156, 5, v166
	v_lshrrev_b32_e32 v157, 5, v167
	v_and_b32_e32 v156, 0x1fc, v156
	v_and_b32_e32 v157, 0x1fc, v157
	v_add_u32_e32 v156, s18, v156
	v_add_u32_e32 v157, s18, v157
	ds_add_rtn_u32 v158, v156, v146
	ds_add_rtn_u32 v159, v157, v146
	ds_read_b32 v160, v144
	ds_read_b32 v161, v144 offset:256
	s_waitcnt lgkmcnt(0)
	v_mov_b32_e32 v164, v160
	v_mov_b32_e32 v165, v161
	v_cmp_le_u32_e32 vcc, 1, v213
	ds_bpermute_b32 v162, v149, v164
	ds_bpermute_b32 v163, v149, v165
	s_waitcnt lgkmcnt(0)
	v_cndmask_b32_e32 v162, 0, v162, vcc
	v_cndmask_b32_e32 v163, 0, v163, vcc
	v_add_u32_e32 v164, v164, v162
	v_add_u32_e32 v165, v165, v163
	v_cmp_le_u32_e32 vcc, 2, v213
	ds_bpermute_b32 v162, v150, v164
	ds_bpermute_b32 v163, v150, v165
	s_waitcnt lgkmcnt(0)
	v_cndmask_b32_e32 v162, 0, v162, vcc
	v_cndmask_b32_e32 v163, 0, v163, vcc
	v_add_u32_e32 v164, v164, v162
	v_add_u32_e32 v165, v165, v163
	v_cmp_le_u32_e32 vcc, 4, v213
	ds_bpermute_b32 v162, v151, v164
	ds_bpermute_b32 v163, v151, v165
	s_waitcnt lgkmcnt(0)
	v_cndmask_b32_e32 v162, 0, v162, vcc
	v_cndmask_b32_e32 v163, 0, v163, vcc
	v_add_u32_e32 v164, v164, v162
	v_add_u32_e32 v165, v165, v163
	v_cmp_le_u32_e32 vcc, 8, v213
	ds_bpermute_b32 v162, v152, v164
	ds_bpermute_b32 v163, v152, v165
	s_waitcnt lgkmcnt(0)
	v_cndmask_b32_e32 v162, 0, v162, vcc
	v_cndmask_b32_e32 v163, 0, v163, vcc
	v_add_u32_e32 v164, v164, v162
	v_add_u32_e32 v165, v165, v163
	v_cmp_le_u32_e32 vcc, 16, v213
	ds_bpermute_b32 v162, v153, v164
	ds_bpermute_b32 v163, v153, v165
	s_waitcnt lgkmcnt(0)
	v_cndmask_b32_e32 v162, 0, v162, vcc
	v_cndmask_b32_e32 v163, 0, v163, vcc
	v_add_u32_e32 v164, v164, v162
	v_add_u32_e32 v165, v165, v163
	v_cmp_le_u32_e32 vcc, 32, v213
	ds_bpermute_b32 v162, v154, v164
	ds_bpermute_b32 v163, v154, v165
	s_waitcnt lgkmcnt(0)
	v_cndmask_b32_e32 v162, 0, v162, vcc
	v_cndmask_b32_e32 v163, 0, v163, vcc
	v_add_u32_e32 v164, v164, v162
	v_add_u32_e32 v165, v165, v163
	v_readlane_b32 s13, v164, 63
	v_sub_u32_e32 v164, v164, v160
	v_sub_u32_e32 v165, v165, v161
	s_nop 0
	v_add_u32_e32 v165, s13, v165
	ds_write_b32 v144, v164
	ds_write_b32 v144, v165 offset:256
	ds_read_b32 v160, v156
	ds_read_b32 v161, v157
	s_waitcnt lgkmcnt(0)
	v_add_u32_e32 v160, v160, v158
	v_add_u32_e32 v161, v161, v159
	v_lshl_add_u32 v160, v160, 2, s19
	v_lshl_add_u32 v161, v161, 2, s19
	ds_write_b32 v160, v166 offset:3072
	ds_write_b32 v160, v168 offset:19456
	ds_write_b32 v161, v167 offset:3072
	ds_write_b32 v161, v169 offset:19456
	ds_read_b32 v140, v147 offset:3072
	ds_read_b32 v141, v147 offset:3104
	s_waitcnt lgkmcnt(0)
	v_lshlrev_b32_e32 v140, 10, v140
	v_lshlrev_b32_e32 v141, 10, v141
	ds_read_b32 v166, v237 offset:3584
	ds_read_b32 v167, v237 offset:3840
	ds_read_b32 v168, v237 offset:19968
	ds_read_b32 v169, v237 offset:20224
	ds_write_b32 v144, v145
	ds_write_b32 v144, v145 offset:256
	s_waitcnt lgkmcnt(0)
	v_lshrrev_b32_e32 v156, 5, v166
	v_lshrrev_b32_e32 v157, 5, v167
	v_and_b32_e32 v156, 0x1fc, v156
	v_and_b32_e32 v157, 0x1fc, v157
	v_add_u32_e32 v156, s18, v156
	v_add_u32_e32 v157, s18, v157
	ds_add_rtn_u32 v158, v156, v146
	ds_add_rtn_u32 v159, v157, v146
	ds_read_b32 v160, v144
	ds_read_b32 v161, v144 offset:256
	s_waitcnt lgkmcnt(0)
	v_mov_b32_e32 v164, v160
	v_mov_b32_e32 v165, v161
	v_cmp_le_u32_e32 vcc, 1, v213
	ds_bpermute_b32 v162, v149, v164
	ds_bpermute_b32 v163, v149, v165
	s_waitcnt lgkmcnt(0)
	v_cndmask_b32_e32 v162, 0, v162, vcc
	v_cndmask_b32_e32 v163, 0, v163, vcc
	v_add_u32_e32 v164, v164, v162
	v_add_u32_e32 v165, v165, v163
	v_cmp_le_u32_e32 vcc, 2, v213
	ds_bpermute_b32 v162, v150, v164
	ds_bpermute_b32 v163, v150, v165
	s_waitcnt lgkmcnt(0)
	v_cndmask_b32_e32 v162, 0, v162, vcc
	v_cndmask_b32_e32 v163, 0, v163, vcc
	v_add_u32_e32 v164, v164, v162
	v_add_u32_e32 v165, v165, v163
	v_cmp_le_u32_e32 vcc, 4, v213
	ds_bpermute_b32 v162, v151, v164
	ds_bpermute_b32 v163, v151, v165
	s_waitcnt lgkmcnt(0)
	v_cndmask_b32_e32 v162, 0, v162, vcc
	v_cndmask_b32_e32 v163, 0, v163, vcc
	v_add_u32_e32 v164, v164, v162
	v_add_u32_e32 v165, v165, v163
	v_cmp_le_u32_e32 vcc, 8, v213
	ds_bpermute_b32 v162, v152, v164
	ds_bpermute_b32 v163, v152, v165
	s_waitcnt lgkmcnt(0)
	v_cndmask_b32_e32 v162, 0, v162, vcc
	v_cndmask_b32_e32 v163, 0, v163, vcc
	v_add_u32_e32 v164, v164, v162
	v_add_u32_e32 v165, v165, v163
	v_cmp_le_u32_e32 vcc, 16, v213
	ds_bpermute_b32 v162, v153, v164
	ds_bpermute_b32 v163, v153, v165
	s_waitcnt lgkmcnt(0)
	v_cndmask_b32_e32 v162, 0, v162, vcc
	v_cndmask_b32_e32 v163, 0, v163, vcc
	v_add_u32_e32 v164, v164, v162
	v_add_u32_e32 v165, v165, v163
	v_cmp_le_u32_e32 vcc, 32, v213
	ds_bpermute_b32 v162, v154, v164
	ds_bpermute_b32 v163, v154, v165
	s_waitcnt lgkmcnt(0)
	v_cndmask_b32_e32 v162, 0, v162, vcc
	v_cndmask_b32_e32 v163, 0, v163, vcc
	v_add_u32_e32 v164, v164, v162
	v_add_u32_e32 v165, v165, v163
	v_readlane_b32 s13, v164, 63
	v_sub_u32_e32 v164, v164, v160
	v_sub_u32_e32 v165, v165, v161
	s_nop 0
	v_add_u32_e32 v165, s13, v165
	ds_write_b32 v144, v164
	ds_write_b32 v144, v165 offset:256
	ds_read_b32 v160, v156
	ds_read_b32 v161, v157
	s_waitcnt lgkmcnt(0)
	v_add_u32_e32 v160, v160, v158
	v_add_u32_e32 v161, v161, v159
	v_lshl_add_u32 v160, v160, 2, s19
	v_lshl_add_u32 v161, v161, 2, s19
	ds_write_b32 v160, v166 offset:3584
	ds_write_b32 v160, v168 offset:19968
	ds_write_b32 v161, v167 offset:3584
	ds_write_b32 v161, v169 offset:19968
	ds_read_b32 v142, v147 offset:3584
	ds_read_b32 v143, v147 offset:3616
	s_waitcnt lgkmcnt(0)
; DI float bflo(unsigned u) { return __uint_as_float(u << 16); }
; DI float bfhi(unsigned u) { return __uint_as_float(u & 0xffff0000u); }
; template <bool STORE>
; DI void peer_item(const Params& p, int item, char* smem) {
;     ...
;     {
; #pragma unroll
;       for (int i = 0; i < 4; ++i) {
;         const uint2 xv = *(const uint2*)(XN2 + tok * 1024 + 256 * i + lane * 4);
;         xf[4 * i] = bflo(xv.x); xf[4 * i + 1] = bfhi(xv.x); xf[4 * i + 2] = bflo(xv.y); xf[4 * i + 3] = bfhi(xv.y);
;       }
;     }
; #pragma unroll 2
;     for (int k = 0; k < 128; k += 8) {
;       u32x4 uq[8];
;       const int emine = e_s[tl * 128 + k + (lane >> 3)];
;       const float gmine = g_s[tl * 128 + k + (lane >> 3)];
;       const float su = SU[emine], sv = SV[emine];
; #pragma unroll
;       for (int u = 0; u < 8; ++u) {
;         int e = e_s[tl * 128 + k + u];
;         uq[u] = *(const u32x4*)(U8 + (size_t)e * 1024 + lane * 16);
;       }
	v_lshlrev_b32_e32 v142, 10, v142
	v_lshlrev_b32_e32 v143, 10, v143
	s_waitcnt vmcnt(0)
	v_lshlrev_b32_e32 v0, 16, v2
	v_and_b32_e32 v1, 0xffff0000, v2
	v_lshlrev_b32_e32 v2, 16, v3
	v_and_b32_e32 v3, 0xffff0000, v3
	v_lshlrev_b32_e32 v4, 16, v6
	v_and_b32_e32 v5, 0xffff0000, v6
	v_lshlrev_b32_e32 v6, 16, v7
	v_and_b32_e32 v7, 0xffff0000, v7
	v_lshlrev_b32_e32 v8, 16, v10
	v_and_b32_e32 v9, 0xffff0000, v10
	v_lshlrev_b32_e32 v10, 16, v11
	v_and_b32_e32 v11, 0xffff0000, v11
	v_lshlrev_b32_e32 v12, 16, v14
	v_and_b32_e32 v13, 0xffff0000, v14
	v_lshlrev_b32_e32 v14, 16, v15
	v_and_b32_e32 v15, 0xffff0000, v15
	v_lshlrev_b32_e32 v16, 16, v18
	v_and_b32_e32 v17, 0xffff0000, v18
	v_lshlrev_b32_e32 v18, 16, v19
	v_and_b32_e32 v19, 0xffff0000, v19
	v_lshlrev_b32_e32 v20, 16, v22
	v_and_b32_e32 v21, 0xffff0000, v22
	v_lshlrev_b32_e32 v22, 16, v23
	v_and_b32_e32 v23, 0xffff0000, v23
	v_lshlrev_b32_e32 v24, 16, v26
	v_and_b32_e32 v25, 0xffff0000, v26
	v_lshlrev_b32_e32 v26, 16, v27
	v_and_b32_e32 v27, 0xffff0000, v27
	v_lshlrev_b32_e32 v28, 16, v30
	v_and_b32_e32 v29, 0xffff0000, v30
	v_lshlrev_b32_e32 v30, 16, v31
	v_and_b32_e32 v31, 0xffff0000, v31
	v_lshlrev_b32_e32 v32, 16, v34
	v_and_b32_e32 v33, 0xffff0000, v34
	v_lshlrev_b32_e32 v34, 16, v35
	v_and_b32_e32 v35, 0xffff0000, v35
	v_lshlrev_b32_e32 v36, 16, v38
	v_and_b32_e32 v37, 0xffff0000, v38
	v_lshlrev_b32_e32 v38, 16, v39
	v_and_b32_e32 v39, 0xffff0000, v39
	v_lshlrev_b32_e32 v40, 16, v42
	v_and_b32_e32 v41, 0xffff0000, v42
	v_lshlrev_b32_e32 v42, 16, v43
	v_and_b32_e32 v43, 0xffff0000, v43
	v_lshlrev_b32_e32 v44, 16, v46
	v_and_b32_e32 v45, 0xffff0000, v46
	v_lshlrev_b32_e32 v46, 16, v47
	v_and_b32_e32 v47, 0xffff0000, v47
	v_lshlrev_b32_e32 v48, 16, v50
	v_and_b32_e32 v49, 0xffff0000, v50
	v_lshlrev_b32_e32 v50, 16, v51
	v_and_b32_e32 v51, 0xffff0000, v51
	v_lshlrev_b32_e32 v52, 16, v54
	v_and_b32_e32 v53, 0xffff0000, v54
	v_lshlrev_b32_e32 v54, 16, v55
	v_and_b32_e32 v55, 0xffff0000, v55
	v_lshlrev_b32_e32 v56, 16, v58
	v_and_b32_e32 v57, 0xffff0000, v58
	v_lshlrev_b32_e32 v58, 16, v59
	v_and_b32_e32 v59, 0xffff0000, v59
	v_lshlrev_b32_e32 v60, 16, v62
	v_and_b32_e32 v61, 0xffff0000, v62
	v_lshlrev_b32_e32 v62, 16, v63
	v_and_b32_e32 v63, 0xffff0000, v63
	v_lshlrev_b32_e32 v64, 16, v66
	v_and_b32_e32 v65, 0xffff0000, v66
	v_lshlrev_b32_e32 v66, 16, v67
	v_and_b32_e32 v67, 0xffff0000, v67
	v_lshlrev_b32_e32 v68, 16, v70
	v_and_b32_e32 v69, 0xffff0000, v70
	v_lshlrev_b32_e32 v70, 16, v71
	v_and_b32_e32 v71, 0xffff0000, v71
	v_lshlrev_b32_e32 v72, 16, v74
	v_and_b32_e32 v73, 0xffff0000, v74
	v_lshlrev_b32_e32 v74, 16, v75
	v_and_b32_e32 v75, 0xffff0000, v75
	v_lshlrev_b32_e32 v76, 16, v78
	v_and_b32_e32 v77, 0xffff0000, v78
	v_lshlrev_b32_e32 v78, 16, v79
	v_and_b32_e32 v79, 0xffff0000, v79
	v_lshlrev_b32_e32 v80, 16, v82
	v_and_b32_e32 v81, 0xffff0000, v82
	v_lshlrev_b32_e32 v82, 16, v83
	v_and_b32_e32 v83, 0xffff0000, v83
	v_lshlrev_b32_e32 v84, 16, v86
	v_and_b32_e32 v85, 0xffff0000, v86
	v_lshlrev_b32_e32 v86, 16, v87
	v_and_b32_e32 v87, 0xffff0000, v87
	v_lshlrev_b32_e32 v88, 16, v90
	v_and_b32_e32 v89, 0xffff0000, v90
	v_lshlrev_b32_e32 v90, 16, v91
	v_and_b32_e32 v91, 0xffff0000, v91
	v_lshlrev_b32_e32 v92, 16, v94
	v_and_b32_e32 v93, 0xffff0000, v94
	v_lshlrev_b32_e32 v94, 16, v95
	v_and_b32_e32 v95, 0xffff0000, v95
	v_lshlrev_b32_e32 v96, 16, v98
	v_and_b32_e32 v97, 0xffff0000, v98
	v_lshlrev_b32_e32 v98, 16, v99
	v_and_b32_e32 v99, 0xffff0000, v99
	v_lshlrev_b32_e32 v100, 16, v102
	v_and_b32_e32 v101, 0xffff0000, v102
	v_lshlrev_b32_e32 v102, 16, v103
	v_and_b32_e32 v103, 0xffff0000, v103
	v_lshlrev_b32_e32 v104, 16, v106
	v_and_b32_e32 v105, 0xffff0000, v106
	v_lshlrev_b32_e32 v106, 16, v107
	v_and_b32_e32 v107, 0xffff0000, v107
	v_lshlrev_b32_e32 v108, 16, v110
	v_and_b32_e32 v109, 0xffff0000, v110
	v_lshlrev_b32_e32 v110, 16, v111
	v_and_b32_e32 v111, 0xffff0000, v111
	v_lshlrev_b32_e32 v112, 16, v114
	v_and_b32_e32 v113, 0xffff0000, v114
	v_lshlrev_b32_e32 v114, 16, v115
	v_and_b32_e32 v115, 0xffff0000, v115
	v_lshlrev_b32_e32 v116, 16, v118
	v_and_b32_e32 v117, 0xffff0000, v118
	v_lshlrev_b32_e32 v118, 16, v119
	v_and_b32_e32 v119, 0xffff0000, v119
	v_lshlrev_b32_e32 v120, 16, v122
	v_and_b32_e32 v121, 0xffff0000, v122
	v_lshlrev_b32_e32 v122, 16, v123
	v_and_b32_e32 v123, 0xffff0000, v123
	v_lshlrev_b32_e32 v124, 16, v126
	v_and_b32_e32 v125, 0xffff0000, v126
	v_lshlrev_b32_e32 v126, 16, v127
	v_and_b32_e32 v127, 0xffff0000, v127
	v_lshrrev_b32_e32 v235, 3, v213
	v_lshl_add_u32 v235, v235, 2, s19
	s_mov_b32 s72, 0
	s_mov_b32 s73, 1
	s_mov_b32 s74, 2
	s_mov_b32 s75, 3
	s_mov_b32 s76, 4
	s_mov_b32 s77, 5
	s_mov_b32 s78, 6
	s_mov_b32 s79, 7
	s_nop 0
	v_readlane_b32 s48, v128, s72
	v_readlane_b32 s49, v128, s73
	v_readlane_b32 s50, v128, s74
	v_readlane_b32 s51, v128, s75
	v_readlane_b32 s52, v128, s76
	v_readlane_b32 s53, v128, s77
	v_readlane_b32 s54, v128, s78
	v_readlane_b32 s55, v128, s79
	s_add_u32 s32, s0, s48
	s_addc_u32 s33, s1, 0
	s_add_u32 s34, s0, s49
	s_addc_u32 s35, s1, 0
	s_add_u32 s36, s0, s50
	s_addc_u32 s37, s1, 0
	s_add_u32 s38, s0, s51
	s_addc_u32 s39, s1, 0
	s_add_u32 s40, s0, s52
	s_addc_u32 s41, s1, 0
	s_add_u32 s42, s0, s53
	s_addc_u32 s43, s1, 0
	s_add_u32 s44, s0, s54
	s_addc_u32 s45, s1, 0
	s_add_u32 s46, s0, s55
	s_addc_u32 s47, s1, 0
	global_load_dwordx4 v[144:147], v234, s[32:33]
	global_load_dwordx4 v[148:151], v234, s[34:35]
	global_load_dwordx4 v[152:155], v234, s[36:37]
	global_load_dwordx4 v[156:159], v234, s[38:39]
	global_load_dwordx4 v[160:163], v234, s[40:41]
	global_load_dwordx4 v[164:167], v234, s[42:43]
	global_load_dwordx4 v[168:171], v234, s[44:45]
	global_load_dwordx4 v[172:175], v234, s[46:47]
	s_mov_b32 s12, 0
; template <bool STORE>
; DI void peer_item(const Params& p, int item, char* smem) {
;     ...
;       float part[8];
; #pragma unroll
;       for (int u = 0; u < 8; ++u) {
;         float d = 0.f;
; #pragma unroll
;         for (int i = 0; i < 4; ++i) {
;           f32x2_t lo = __builtin_amdgcn_cvt_pk_f32_fp8((int)uq[u][i], false);
;           f32x2_t hi = __builtin_amdgcn_cvt_pk_f32_fp8((int)uq[u][i], true);
;           d += xf[4 * i] * lo.x + xf[4 * i + 1] * lo.y + xf[4 * i + 2] * hi.x + xf[4 * i + 3] * hi.y;
;         }
;         part[u] = d;
;       }
.Lup_k:
	v_readlane_b32 s48, v130, s72
	v_readlane_b32 s49, v130, s73
	v_readlane_b32 s50, v130, s74
	v_readlane_b32 s51, v130, s75
	v_readlane_b32 s52, v130, s76
	v_readlane_b32 s53, v130, s77
	v_readlane_b32 s54, v130, s78
	v_readlane_b32 s55, v130, s79
	s_add_u32 s32, s0, s48
	s_addc_u32 s33, s1, 0
	s_add_u32 s34, s0, s49
	s_addc_u32 s35, s1, 0
	s_add_u32 s36, s0, s50
	s_addc_u32 s37, s1, 0
	s_add_u32 s38, s0, s51
	s_addc_u32 s39, s1, 0
	s_add_u32 s40, s0, s52
	s_addc_u32 s41, s1, 0
	s_add_u32 s42, s0, s53
	s_addc_u32 s43, s1, 0
	s_add_u32 s44, s0, s54
	s_addc_u32 s45, s1, 0
	s_add_u32 s46, s0, s55
	s_addc_u32 s47, s1, 0
	global_load_dwordx4 v[176:179], v234, s[32:33]
	global_load_dwordx4 v[180:183], v234, s[34:35]
	global_load_dwordx4 v[184:187], v234, s[36:37]
	global_load_dwordx4 v[188:191], v234, s[38:39]
	global_load_dwordx4 v[192:195], v234, s[40:41]
	global_load_dwordx4 v[196:199], v234, s[42:43]
	global_load_dwordx4 v[200:203], v234, s[44:45]
	global_load_dwordx4 v[204:207], v234, s[46:47]
	s_waitcnt vmcnt(8)
	v_cvt_pk_f32_fp8_e32 v[214:215], v144
	v_cvt_pk_f32_fp8_sdwa v[216:217], v144 src0_sel:WORD_1
	v_cvt_pk_f32_fp8_e32 v[218:219], v145
	v_cvt_pk_f32_fp8_sdwa v[220:221], v145 src0_sel:WORD_1
	v_pk_mul_f32 v[222:223], v[0:1], v[214:215]
	v_pk_mul_f32 v[224:225], v[2:3], v[216:217]
	v_cvt_pk_f32_fp8_e32 v[214:215], v146
	v_cvt_pk_f32_fp8_sdwa v[216:217], v146 src0_sel:WORD_1
	v_pk_fma_f32 v[222:223], v[4:5], v[218:219], v[222:223]
	v_pk_fma_f32 v[224:225], v[6:7], v[220:221], v[224:225]
	v_cvt_pk_f32_fp8_e32 v[218:219], v147
	v_cvt_pk_f32_fp8_sdwa v[220:221], v147 src0_sel:WORD_1
	v_pk_fma_f32 v[222:223], v[8:9], v[214:215], v[222:223]
	v_pk_fma_f32 v[224:225], v[10:11], v[216:217], v[224:225]
	v_pk_fma_f32 v[222:223], v[12:13], v[218:219], v[222:223]
	v_pk_fma_f32 v[224:225], v[14:15], v[220:221], v[224:225]
	v_pk_add_f32 v[222:223], v[222:223], v[224:225]
	s_nop 0
	v_add_f32_e32 v226, v222, v223
	v_cvt_pk_f32_fp8_e32 v[214:215], v148
	v_cvt_pk_f32_fp8_sdwa v[216:217], v148 src0_sel:WORD_1
	v_cvt_pk_f32_fp8_e32 v[218:219], v149
	v_cvt_pk_f32_fp8_sdwa v[220:221], v149 src0_sel:WORD_1
	v_pk_mul_f32 v[222:223], v[0:1], v[214:215]
	v_pk_mul_f32 v[224:225], v[2:3], v[216:217]
	v_cvt_pk_f32_fp8_e32 v[214:215], v150
	v_cvt_pk_f32_fp8_sdwa v[216:217], v150 src0_sel:WORD_1
	v_pk_fma_f32 v[222:223], v[4:5], v[218:219], v[222:223]
	v_pk_fma_f32 v[224:225], v[6:7], v[220:221], v[224:225]
	v_cvt_pk_f32_fp8_e32 v[218:219], v151
	v_cvt_pk_f32_fp8_sdwa v[220:221], v151 src0_sel:WORD_1
	v_pk_fma_f32 v[222:223], v[8:9], v[214:215], v[222:223]
	v_pk_fma_f32 v[224:225], v[10:11], v[216:217], v[224:225]
	v_pk_fma_f32 v[222:223], v[12:13], v[218:219], v[222:223]
	v_pk_fma_f32 v[224:225], v[14:15], v[220:221], v[224:225]
	v_pk_add_f32 v[222:223], v[222:223], v[224:225]
	s_nop 0
	v_add_f32_e32 v227, v222, v223
	v_cvt_pk_f32_fp8_e32 v[214:215], v152
	v_cvt_pk_f32_fp8_sdwa v[216:217], v152 src0_sel:WORD_1
	v_cvt_pk_f32_fp8_e32 v[218:219], v153
	v_cvt_pk_f32_fp8_sdwa v[220:221], v153 src0_sel:WORD_1
	v_pk_mul_f32 v[222:223], v[0:1], v[214:215]
	v_pk_mul_f32 v[224:225], v[2:3], v[216:217]
	v_cvt_pk_f32_fp8_e32 v[214:215], v154
	v_cvt_pk_f32_fp8_sdwa v[216:217], v154 src0_sel:WORD_1
	v_pk_fma_f32 v[222:223], v[4:5], v[218:219], v[222:223]
	v_pk_fma_f32 v[224:225], v[6:7], v[220:221], v[224:225]
	v_cvt_pk_f32_fp8_e32 v[218:219], v155
	v_cvt_pk_f32_fp8_sdwa v[220:221], v155 src0_sel:WORD_1
	v_pk_fma_f32 v[222:223], v[8:9], v[214:215], v[222:223]
	v_pk_fma_f32 v[224:225], v[10:11], v[216:217], v[224:225]
	v_pk_fma_f32 v[222:223], v[12:13], v[218:219], v[222:223]
	v_pk_fma_f32 v[224:225], v[14:15], v[220:221], v[224:225]
	v_pk_add_f32 v[222:223], v[222:223], v[224:225]
	s_nop 0
	v_add_f32_e32 v228, v222, v223
	v_cvt_pk_f32_fp8_e32 v[214:215], v156
	v_cvt_pk_f32_fp8_sdwa v[216:217], v156 src0_sel:WORD_1
	v_cvt_pk_f32_fp8_e32 v[218:219], v157
	v_cvt_pk_f32_fp8_sdwa v[220:221], v157 src0_sel:WORD_1
	v_pk_mul_f32 v[222:223], v[0:1], v[214:215]
	v_pk_mul_f32 v[224:225], v[2:3], v[216:217]
	v_cvt_pk_f32_fp8_e32 v[214:215], v158
	v_cvt_pk_f32_fp8_sdwa v[216:217], v158 src0_sel:WORD_1
	v_pk_fma_f32 v[222:223], v[4:5], v[218:219], v[222:223]
	v_pk_fma_f32 v[224:225], v[6:7], v[220:221], v[224:225]
	v_cvt_pk_f32_fp8_e32 v[218:219], v159
	v_cvt_pk_f32_fp8_sdwa v[220:221], v159 src0_sel:WORD_1
	v_pk_fma_f32 v[222:223], v[8:9], v[214:215], v[222:223]
	v_pk_fma_f32 v[224:225], v[10:11], v[216:217], v[224:225]
	v_pk_fma_f32 v[222:223], v[12:13], v[218:219], v[222:223]
	v_pk_fma_f32 v[224:225], v[14:15], v[220:221], v[224:225]
	v_pk_add_f32 v[222:223], v[222:223], v[224:225]
	s_nop 0
	v_add_f32_e32 v229, v222, v223
	v_cvt_pk_f32_fp8_e32 v[214:215], v160
	v_cvt_pk_f32_fp8_sdwa v[216:217], v160 src0_sel:WORD_1
	v_cvt_pk_f32_fp8_e32 v[218:219], v161
	v_cvt_pk_f32_fp8_sdwa v[220:221], v161 src0_sel:WORD_1
	v_pk_mul_f32 v[222:223], v[0:1], v[214:215]
	v_pk_mul_f32 v[224:225], v[2:3], v[216:217]
	v_cvt_pk_f32_fp8_e32 v[214:215], v162
	v_cvt_pk_f32_fp8_sdwa v[216:217], v162 src0_sel:WORD_1
	v_pk_fma_f32 v[222:223], v[4:5], v[218:219], v[222:223]
	v_pk_fma_f32 v[224:225], v[6:7], v[220:221], v[224:225]
	v_cvt_pk_f32_fp8_e32 v[218:219], v163
	v_cvt_pk_f32_fp8_sdwa v[220:221], v163 src0_sel:WORD_1
	v_pk_fma_f32 v[222:223], v[8:9], v[214:215], v[222:223]
	v_pk_fma_f32 v[224:225], v[10:11], v[216:217], v[224:225]
	v_pk_fma_f32 v[222:223], v[12:13], v[218:219], v[222:223]
	v_pk_fma_f32 v[224:225], v[14:15], v[220:221], v[224:225]
	v_pk_add_f32 v[222:223], v[222:223], v[224:225]
	s_nop 0
	v_add_f32_e32 v230, v222, v223
	v_cvt_pk_f32_fp8_e32 v[214:215], v164
; template <bool STORE>
; DI void peer_item(const Params& p, int item, char* smem) {
;     ...
;       float part[8];
; #pragma unroll
;       for (int u = 0; u < 8; ++u) {
;         float d = 0.f;
; #pragma unroll
;         for (int i = 0; i < 4; ++i) {
;           f32x2_t lo = __builtin_amdgcn_cvt_pk_f32_fp8((int)uq[u][i], false);
;           f32x2_t hi = __builtin_amdgcn_cvt_pk_f32_fp8((int)uq[u][i], true);
;           d += xf[4 * i] * lo.x + xf[4 * i + 1] * lo.y + xf[4 * i + 2] * hi.x + xf[4 * i + 3] * hi.y;
;         }
;         part[u] = d;
;       }
;       float q4[4], r2[2], h;
; #pragma unroll
;       for (int j = 0; j < 4; ++j) {
;         float mine = b5 ? part[j + 4] : part[j];
;         float other = b5 ? part[j] : part[j + 4];
;         q4[j] = mine + __shfl_xor(other, 32);
;       }
; #pragma unroll
;       for (int j = 0; j < 2; ++j) {
;         float mine = b4 ? q4[j + 2] : q4[j];
;         float other = b4 ? q4[j] : q4[j + 2];
;         r2[j] = mine + __shfl_xor(other, 16);
;       }
;       {
;         float mine = b3 ? r2[1] : r2[0];
;         float other = b3 ? r2[0] : r2[1];
;         h = mine + __shfl_xor(other, 8);
;       }
;       h += __shfl_xor(h, 4);
;       h += __shfl_xor(h, 2);
;       h += __shfl_xor(h, 1);
	v_cvt_pk_f32_fp8_sdwa v[216:217], v164 src0_sel:WORD_1
	v_cvt_pk_f32_fp8_e32 v[218:219], v165
	v_cvt_pk_f32_fp8_sdwa v[220:221], v165 src0_sel:WORD_1
	v_pk_mul_f32 v[222:223], v[0:1], v[214:215]
	v_pk_mul_f32 v[224:225], v[2:3], v[216:217]
	v_cvt_pk_f32_fp8_e32 v[214:215], v166
	v_cvt_pk_f32_fp8_sdwa v[216:217], v166 src0_sel:WORD_1
	v_pk_fma_f32 v[222:223], v[4:5], v[218:219], v[222:223]
	v_pk_fma_f32 v[224:225], v[6:7], v[220:221], v[224:225]
	v_cvt_pk_f32_fp8_e32 v[218:219], v167
	v_cvt_pk_f32_fp8_sdwa v[220:221], v167 src0_sel:WORD_1
	v_pk_fma_f32 v[222:223], v[8:9], v[214:215], v[222:223]
	v_pk_fma_f32 v[224:225], v[10:11], v[216:217], v[224:225]
	v_pk_fma_f32 v[222:223], v[12:13], v[218:219], v[222:223]
	v_pk_fma_f32 v[224:225], v[14:15], v[220:221], v[224:225]
	v_pk_add_f32 v[222:223], v[222:223], v[224:225]
	s_nop 0
	v_add_f32_e32 v231, v222, v223
	v_cvt_pk_f32_fp8_e32 v[214:215], v168
	v_cvt_pk_f32_fp8_sdwa v[216:217], v168 src0_sel:WORD_1
	v_cvt_pk_f32_fp8_e32 v[218:219], v169
	v_cvt_pk_f32_fp8_sdwa v[220:221], v169 src0_sel:WORD_1
	v_pk_mul_f32 v[222:223], v[0:1], v[214:215]
	v_pk_mul_f32 v[224:225], v[2:3], v[216:217]
	v_cvt_pk_f32_fp8_e32 v[214:215], v170
	v_cvt_pk_f32_fp8_sdwa v[216:217], v170 src0_sel:WORD_1
	v_pk_fma_f32 v[222:223], v[4:5], v[218:219], v[222:223]
	v_pk_fma_f32 v[224:225], v[6:7], v[220:221], v[224:225]
	v_cvt_pk_f32_fp8_e32 v[218:219], v171
	v_cvt_pk_f32_fp8_sdwa v[220:221], v171 src0_sel:WORD_1
	v_pk_fma_f32 v[222:223], v[8:9], v[214:215], v[222:223]
	v_pk_fma_f32 v[224:225], v[10:11], v[216:217], v[224:225]
	v_pk_fma_f32 v[222:223], v[12:13], v[218:219], v[222:223]
	v_pk_fma_f32 v[224:225], v[14:15], v[220:221], v[224:225]
	v_pk_add_f32 v[222:223], v[222:223], v[224:225]
	s_nop 0
	v_add_f32_e32 v232, v222, v223
	v_cvt_pk_f32_fp8_e32 v[214:215], v172
	v_cvt_pk_f32_fp8_sdwa v[216:217], v172 src0_sel:WORD_1
	v_cvt_pk_f32_fp8_e32 v[218:219], v173
	v_cvt_pk_f32_fp8_sdwa v[220:221], v173 src0_sel:WORD_1
	v_pk_mul_f32 v[222:223], v[0:1], v[214:215]
	v_pk_mul_f32 v[224:225], v[2:3], v[216:217]
	v_cvt_pk_f32_fp8_e32 v[214:215], v174
	v_cvt_pk_f32_fp8_sdwa v[216:217], v174 src0_sel:WORD_1
	v_pk_fma_f32 v[222:223], v[4:5], v[218:219], v[222:223]
	v_pk_fma_f32 v[224:225], v[6:7], v[220:221], v[224:225]
	v_cvt_pk_f32_fp8_e32 v[218:219], v175
	v_cvt_pk_f32_fp8_sdwa v[220:221], v175 src0_sel:WORD_1
	v_pk_fma_f32 v[222:223], v[8:9], v[214:215], v[222:223]
	v_pk_fma_f32 v[224:225], v[10:11], v[216:217], v[224:225]
	v_pk_fma_f32 v[222:223], v[12:13], v[218:219], v[222:223]
	v_pk_fma_f32 v[224:225], v[14:15], v[220:221], v[224:225]
	v_pk_add_f32 v[222:223], v[222:223], v[224:225]
	s_nop 0
	v_add_f32_e32 v233, v222, v223
	v_permlane32_swap_b32_e32 v226, v230
	v_permlane32_swap_b32_e32 v227, v231
	v_permlane32_swap_b32_e32 v228, v232
	v_permlane32_swap_b32_e32 v229, v233
	v_add_f32_e32 v226, v226, v230
	v_add_f32_e32 v228, v228, v232
	v_add_f32_e32 v227, v227, v231
	v_add_f32_e32 v229, v229, v233
	s_nop 1
	v_permlane16_swap_b32_e32 v226, v228
	v_permlane16_swap_b32_e32 v227, v229
	v_add_f32_e32 v226, v226, v228
	v_add_f32_e32 v227, v227, v229
	s_nop 0
	v_cndmask_b32_e64 v230, v226, v227, s[24:25]
	v_cndmask_b32_e64 v231, v227, v226, s[24:25]
	s_nop 1
	v_add_f32_dpp v232, v231, v230 row_ror:8 row_mask:0xf bank_mask:0xf
	s_nop 1
	v_add_f32_dpp v233, v232, v232 quad_perm:[1,0,3,2] row_mask:0xf bank_mask:0xf
	s_nop 1
	v_add_f32_dpp v232, v233, v233 quad_perm:[2,3,0,1] row_mask:0xf bank_mask:0xf
	s_nop 1
	v_add_f32_dpp v233, v232, v232 row_half_mirror row_mask:0xf bank_mask:0xf
	ds_write_b32 v235, v233 offset:32768
	v_readlane_b32 s48, v132, s72
	v_readlane_b32 s49, v132, s73
	v_readlane_b32 s50, v132, s74
	v_readlane_b32 s51, v132, s75
	v_readlane_b32 s52, v132, s76
	v_readlane_b32 s53, v132, s77
	v_readlane_b32 s54, v132, s78
	v_readlane_b32 s55, v132, s79
	s_add_u32 s32, s0, s48
	s_addc_u32 s33, s1, 0
	s_add_u32 s34, s0, s49
	s_addc_u32 s35, s1, 0
	s_add_u32 s36, s0, s50
	s_addc_u32 s37, s1, 0
	s_add_u32 s38, s0, s51
	s_addc_u32 s39, s1, 0
	s_add_u32 s40, s0, s52
	s_addc_u32 s41, s1, 0
	s_add_u32 s42, s0, s53
	s_addc_u32 s43, s1, 0
	s_add_u32 s44, s0, s54
	s_addc_u32 s45, s1, 0
	s_add_u32 s46, s0, s55
	s_addc_u32 s47, s1, 0
	global_load_dwordx4 v[144:147], v234, s[32:33]
	global_load_dwordx4 v[148:151], v234, s[34:35]
	global_load_dwordx4 v[152:155], v234, s[36:37]
	global_load_dwordx4 v[156:159], v234, s[38:39]
	global_load_dwordx4 v[160:163], v234, s[40:41]
	global_load_dwordx4 v[164:167], v234, s[42:43]
	global_load_dwordx4 v[168:171], v234, s[44:45]
	global_load_dwordx4 v[172:175], v234, s[46:47]
	s_waitcnt vmcnt(8)
; template <bool STORE>
; DI void peer_item(const Params& p, int item, char* smem) {
;     ...
; #pragma unroll
;       for (int u = 0; u < 8; ++u) {
;         float d = 0.f;
; #pragma unroll
;         for (int i = 0; i < 4; ++i) {
;           f32x2_t lo = __builtin_amdgcn_cvt_pk_f32_fp8((int)uq[u][i], false);
;           f32x2_t hi = __builtin_amdgcn_cvt_pk_f32_fp8((int)uq[u][i], true);
;           d += xf[4 * i] * lo.x + xf[4 * i + 1] * lo.y + xf[4 * i + 2] * hi.x + xf[4 * i + 3] * hi.y;
;         }
;         part[u] = d;
;       }
	v_cvt_pk_f32_fp8_e32 v[214:215], v176
	v_cvt_pk_f32_fp8_sdwa v[216:217], v176 src0_sel:WORD_1
	v_cvt_pk_f32_fp8_e32 v[218:219], v177
	v_cvt_pk_f32_fp8_sdwa v[220:221], v177 src0_sel:WORD_1
	v_pk_mul_f32 v[222:223], v[16:17], v[214:215]
	v_pk_mul_f32 v[224:225], v[18:19], v[216:217]
	v_cvt_pk_f32_fp8_e32 v[214:215], v178
	v_cvt_pk_f32_fp8_sdwa v[216:217], v178 src0_sel:WORD_1
	v_pk_fma_f32 v[222:223], v[20:21], v[218:219], v[222:223]
	v_pk_fma_f32 v[224:225], v[22:23], v[220:221], v[224:225]
	v_cvt_pk_f32_fp8_e32 v[218:219], v179
	v_cvt_pk_f32_fp8_sdwa v[220:221], v179 src0_sel:WORD_1
	v_pk_fma_f32 v[222:223], v[24:25], v[214:215], v[222:223]
	v_pk_fma_f32 v[224:225], v[26:27], v[216:217], v[224:225]
	v_pk_fma_f32 v[222:223], v[28:29], v[218:219], v[222:223]
	v_pk_fma_f32 v[224:225], v[30:31], v[220:221], v[224:225]
	v_pk_add_f32 v[222:223], v[222:223], v[224:225]
	s_nop 0
	v_add_f32_e32 v226, v222, v223
	v_cvt_pk_f32_fp8_e32 v[214:215], v180
	v_cvt_pk_f32_fp8_sdwa v[216:217], v180 src0_sel:WORD_1
	v_cvt_pk_f32_fp8_e32 v[218:219], v181
	v_cvt_pk_f32_fp8_sdwa v[220:221], v181 src0_sel:WORD_1
	v_pk_mul_f32 v[222:223], v[16:17], v[214:215]
	v_pk_mul_f32 v[224:225], v[18:19], v[216:217]
	v_cvt_pk_f32_fp8_e32 v[214:215], v182
	v_cvt_pk_f32_fp8_sdwa v[216:217], v182 src0_sel:WORD_1
	v_pk_fma_f32 v[222:223], v[20:21], v[218:219], v[222:223]
	v_pk_fma_f32 v[224:225], v[22:23], v[220:221], v[224:225]
	v_cvt_pk_f32_fp8_e32 v[218:219], v183
	v_cvt_pk_f32_fp8_sdwa v[220:221], v183 src0_sel:WORD_1
	v_pk_fma_f32 v[222:223], v[24:25], v[214:215], v[222:223]
	v_pk_fma_f32 v[224:225], v[26:27], v[216:217], v[224:225]
	v_pk_fma_f32 v[222:223], v[28:29], v[218:219], v[222:223]
	v_pk_fma_f32 v[224:225], v[30:31], v[220:221], v[224:225]
	v_pk_add_f32 v[222:223], v[222:223], v[224:225]
	s_nop 0
	v_add_f32_e32 v227, v222, v223
	v_cvt_pk_f32_fp8_e32 v[214:215], v184
	v_cvt_pk_f32_fp8_sdwa v[216:217], v184 src0_sel:WORD_1
	v_cvt_pk_f32_fp8_e32 v[218:219], v185
	v_cvt_pk_f32_fp8_sdwa v[220:221], v185 src0_sel:WORD_1
	v_pk_mul_f32 v[222:223], v[16:17], v[214:215]
	v_pk_mul_f32 v[224:225], v[18:19], v[216:217]
	v_cvt_pk_f32_fp8_e32 v[214:215], v186
	v_cvt_pk_f32_fp8_sdwa v[216:217], v186 src0_sel:WORD_1
	v_pk_fma_f32 v[222:223], v[20:21], v[218:219], v[222:223]
	v_pk_fma_f32 v[224:225], v[22:23], v[220:221], v[224:225]
	v_cvt_pk_f32_fp8_e32 v[218:219], v187
	v_cvt_pk_f32_fp8_sdwa v[220:221], v187 src0_sel:WORD_1
	v_pk_fma_f32 v[222:223], v[24:25], v[214:215], v[222:223]
	v_pk_fma_f32 v[224:225], v[26:27], v[216:217], v[224:225]
	v_pk_fma_f32 v[222:223], v[28:29], v[218:219], v[222:223]
	v_pk_fma_f32 v[224:225], v[30:31], v[220:221], v[224:225]
	v_pk_add_f32 v[222:223], v[222:223], v[224:225]
	s_nop 0
	v_add_f32_e32 v228, v222, v223
	v_cvt_pk_f32_fp8_e32 v[214:215], v188
	v_cvt_pk_f32_fp8_sdwa v[216:217], v188 src0_sel:WORD_1
	v_cvt_pk_f32_fp8_e32 v[218:219], v189
	v_cvt_pk_f32_fp8_sdwa v[220:221], v189 src0_sel:WORD_1
	v_pk_mul_f32 v[222:223], v[16:17], v[214:215]
	v_pk_mul_f32 v[224:225], v[18:19], v[216:217]
	v_cvt_pk_f32_fp8_e32 v[214:215], v190
	v_cvt_pk_f32_fp8_sdwa v[216:217], v190 src0_sel:WORD_1
	v_pk_fma_f32 v[222:223], v[20:21], v[218:219], v[222:223]
	v_pk_fma_f32 v[224:225], v[22:23], v[220:221], v[224:225]
	v_cvt_pk_f32_fp8_e32 v[218:219], v191
	v_cvt_pk_f32_fp8_sdwa v[220:221], v191 src0_sel:WORD_1
	v_pk_fma_f32 v[222:223], v[24:25], v[214:215], v[222:223]
	v_pk_fma_f32 v[224:225], v[26:27], v[216:217], v[224:225]
	v_pk_fma_f32 v[222:223], v[28:29], v[218:219], v[222:223]
	v_pk_fma_f32 v[224:225], v[30:31], v[220:221], v[224:225]
	v_pk_add_f32 v[222:223], v[222:223], v[224:225]
	s_nop 0
	v_add_f32_e32 v229, v222, v223
	v_cvt_pk_f32_fp8_e32 v[214:215], v192
	v_cvt_pk_f32_fp8_sdwa v[216:217], v192 src0_sel:WORD_1
	v_cvt_pk_f32_fp8_e32 v[218:219], v193
	v_cvt_pk_f32_fp8_sdwa v[220:221], v193 src0_sel:WORD_1
	v_pk_mul_f32 v[222:223], v[16:17], v[214:215]
	v_pk_mul_f32 v[224:225], v[18:19], v[216:217]
	v_cvt_pk_f32_fp8_e32 v[214:215], v194
	v_cvt_pk_f32_fp8_sdwa v[216:217], v194 src0_sel:WORD_1
	v_pk_fma_f32 v[222:223], v[20:21], v[218:219], v[222:223]
	v_pk_fma_f32 v[224:225], v[22:23], v[220:221], v[224:225]
	v_cvt_pk_f32_fp8_e32 v[218:219], v195
	v_cvt_pk_f32_fp8_sdwa v[220:221], v195 src0_sel:WORD_1
	v_pk_fma_f32 v[222:223], v[24:25], v[214:215], v[222:223]
	v_pk_fma_f32 v[224:225], v[26:27], v[216:217], v[224:225]
	v_pk_fma_f32 v[222:223], v[28:29], v[218:219], v[222:223]
	v_pk_fma_f32 v[224:225], v[30:31], v[220:221], v[224:225]
	v_pk_add_f32 v[222:223], v[222:223], v[224:225]
	s_nop 0
	v_add_f32_e32 v230, v222, v223
	v_cvt_pk_f32_fp8_e32 v[214:215], v196
	v_cvt_pk_f32_fp8_sdwa v[216:217], v196 src0_sel:WORD_1
	v_cvt_pk_f32_fp8_e32 v[218:219], v197
	v_cvt_pk_f32_fp8_sdwa v[220:221], v197 src0_sel:WORD_1
	v_pk_mul_f32 v[222:223], v[16:17], v[214:215]
	v_pk_mul_f32 v[224:225], v[18:19], v[216:217]
	v_cvt_pk_f32_fp8_e32 v[214:215], v198
	v_cvt_pk_f32_fp8_sdwa v[216:217], v198 src0_sel:WORD_1
	v_pk_fma_f32 v[222:223], v[20:21], v[218:219], v[222:223]
	v_pk_fma_f32 v[224:225], v[22:23], v[220:221], v[224:225]
	v_cvt_pk_f32_fp8_e32 v[218:219], v199
	v_cvt_pk_f32_fp8_sdwa v[220:221], v199 src0_sel:WORD_1
	v_pk_fma_f32 v[222:223], v[24:25], v[214:215], v[222:223]
	v_pk_fma_f32 v[224:225], v[26:27], v[216:217], v[224:225]
	v_pk_fma_f32 v[222:223], v[28:29], v[218:219], v[222:223]
	v_pk_fma_f32 v[224:225], v[30:31], v[220:221], v[224:225]
	v_pk_add_f32 v[222:223], v[222:223], v[224:225]
	s_nop 0
	v_add_f32_e32 v231, v222, v223
	v_cvt_pk_f32_fp8_e32 v[214:215], v200
	v_cvt_pk_f32_fp8_sdwa v[216:217], v200 src0_sel:WORD_1
	v_cvt_pk_f32_fp8_e32 v[218:219], v201
; template <bool STORE>
; DI void peer_item(const Params& p, int item, char* smem) {
;     ...
; #pragma unroll
;       for (int u = 0; u < 8; ++u) {
;         float d = 0.f;
; #pragma unroll
;         for (int i = 0; i < 4; ++i) {
;           f32x2_t lo = __builtin_amdgcn_cvt_pk_f32_fp8((int)uq[u][i], false);
;           f32x2_t hi = __builtin_amdgcn_cvt_pk_f32_fp8((int)uq[u][i], true);
;           d += xf[4 * i] * lo.x + xf[4 * i + 1] * lo.y + xf[4 * i + 2] * hi.x + xf[4 * i + 3] * hi.y;
;         }
;         part[u] = d;
;       }
;       float q4[4], r2[2], h;
; #pragma unroll
;       for (int j = 0; j < 4; ++j) {
;         float mine = b5 ? part[j + 4] : part[j];
;         float other = b5 ? part[j] : part[j + 4];
;         q4[j] = mine + __shfl_xor(other, 32);
;       }
; #pragma unroll
;       for (int j = 0; j < 2; ++j) {
;         float mine = b4 ? q4[j + 2] : q4[j];
;         float other = b4 ? q4[j] : q4[j + 2];
;         r2[j] = mine + __shfl_xor(other, 16);
;       }
;       {
;         float mine = b3 ? r2[1] : r2[0];
;         float other = b3 ? r2[0] : r2[1];
;         h = mine + __shfl_xor(other, 8);
;       }
;       h += __shfl_xor(h, 4);
;       h += __shfl_xor(h, 2);
;       h += __shfl_xor(h, 1);
	v_cvt_pk_f32_fp8_sdwa v[220:221], v201 src0_sel:WORD_1
	v_pk_mul_f32 v[222:223], v[16:17], v[214:215]
	v_pk_mul_f32 v[224:225], v[18:19], v[216:217]
	v_cvt_pk_f32_fp8_e32 v[214:215], v202
	v_cvt_pk_f32_fp8_sdwa v[216:217], v202 src0_sel:WORD_1
	v_pk_fma_f32 v[222:223], v[20:21], v[218:219], v[222:223]
	v_pk_fma_f32 v[224:225], v[22:23], v[220:221], v[224:225]
	v_cvt_pk_f32_fp8_e32 v[218:219], v203
	v_cvt_pk_f32_fp8_sdwa v[220:221], v203 src0_sel:WORD_1
	v_pk_fma_f32 v[222:223], v[24:25], v[214:215], v[222:223]
	v_pk_fma_f32 v[224:225], v[26:27], v[216:217], v[224:225]
	v_pk_fma_f32 v[222:223], v[28:29], v[218:219], v[222:223]
	v_pk_fma_f32 v[224:225], v[30:31], v[220:221], v[224:225]
	v_pk_add_f32 v[222:223], v[222:223], v[224:225]
	s_nop 0
	v_add_f32_e32 v232, v222, v223
	v_cvt_pk_f32_fp8_e32 v[214:215], v204
	v_cvt_pk_f32_fp8_sdwa v[216:217], v204 src0_sel:WORD_1
	v_cvt_pk_f32_fp8_e32 v[218:219], v205
	v_cvt_pk_f32_fp8_sdwa v[220:221], v205 src0_sel:WORD_1
	v_pk_mul_f32 v[222:223], v[16:17], v[214:215]
	v_pk_mul_f32 v[224:225], v[18:19], v[216:217]
	v_cvt_pk_f32_fp8_e32 v[214:215], v206
	v_cvt_pk_f32_fp8_sdwa v[216:217], v206 src0_sel:WORD_1
	v_pk_fma_f32 v[222:223], v[20:21], v[218:219], v[222:223]
	v_pk_fma_f32 v[224:225], v[22:23], v[220:221], v[224:225]
	v_cvt_pk_f32_fp8_e32 v[218:219], v207
	v_cvt_pk_f32_fp8_sdwa v[220:221], v207 src0_sel:WORD_1
	v_pk_fma_f32 v[222:223], v[24:25], v[214:215], v[222:223]
	v_pk_fma_f32 v[224:225], v[26:27], v[216:217], v[224:225]
	v_pk_fma_f32 v[222:223], v[28:29], v[218:219], v[222:223]
	v_pk_fma_f32 v[224:225], v[30:31], v[220:221], v[224:225]
	v_pk_add_f32 v[222:223], v[222:223], v[224:225]
	s_nop 0
	v_add_f32_e32 v233, v222, v223
	v_permlane32_swap_b32_e32 v226, v230
	v_permlane32_swap_b32_e32 v227, v231
	v_permlane32_swap_b32_e32 v228, v232
	v_permlane32_swap_b32_e32 v229, v233
	v_add_f32_e32 v226, v226, v230
	v_add_f32_e32 v228, v228, v232
	v_add_f32_e32 v227, v227, v231
	v_add_f32_e32 v229, v229, v233
	s_nop 1
	v_permlane16_swap_b32_e32 v226, v228
	v_permlane16_swap_b32_e32 v227, v229
	v_add_f32_e32 v226, v226, v228
	v_add_f32_e32 v227, v227, v229
	s_nop 0
	v_cndmask_b32_e64 v230, v226, v227, s[24:25]
	v_cndmask_b32_e64 v231, v227, v226, s[24:25]
	s_nop 1
	v_add_f32_dpp v232, v231, v230 row_ror:8 row_mask:0xf bank_mask:0xf
	s_nop 1
	v_add_f32_dpp v233, v232, v232 quad_perm:[1,0,3,2] row_mask:0xf bank_mask:0xf
	s_nop 1
	v_add_f32_dpp v232, v233, v233 quad_perm:[2,3,0,1] row_mask:0xf bank_mask:0xf
	s_nop 1
	v_add_f32_dpp v233, v232, v232 row_half_mirror row_mask:0xf bank_mask:0xf
	ds_write_b32 v235, v233 offset:33280
	v_readlane_b32 s48, v134, s72
	v_readlane_b32 s49, v134, s73
	v_readlane_b32 s50, v134, s74
	v_readlane_b32 s51, v134, s75
	v_readlane_b32 s52, v134, s76
	v_readlane_b32 s53, v134, s77
	v_readlane_b32 s54, v134, s78
	v_readlane_b32 s55, v134, s79
	s_add_u32 s32, s0, s48
	s_addc_u32 s33, s1, 0
	s_add_u32 s34, s0, s49
	s_addc_u32 s35, s1, 0
	s_add_u32 s36, s0, s50
	s_addc_u32 s37, s1, 0
	s_add_u32 s38, s0, s51
	s_addc_u32 s39, s1, 0
	s_add_u32 s40, s0, s52
	s_addc_u32 s41, s1, 0
	s_add_u32 s42, s0, s53
	s_addc_u32 s43, s1, 0
	s_add_u32 s44, s0, s54
	s_addc_u32 s45, s1, 0
	s_add_u32 s46, s0, s55
	s_addc_u32 s47, s1, 0
	global_load_dwordx4 v[176:179], v234, s[32:33]
	global_load_dwordx4 v[180:183], v234, s[34:35]
	global_load_dwordx4 v[184:187], v234, s[36:37]
	global_load_dwordx4 v[188:191], v234, s[38:39]
	global_load_dwordx4 v[192:195], v234, s[40:41]
	global_load_dwordx4 v[196:199], v234, s[42:43]
	global_load_dwordx4 v[200:203], v234, s[44:45]
	global_load_dwordx4 v[204:207], v234, s[46:47]
	s_waitcnt vmcnt(8)
	v_cvt_pk_f32_fp8_e32 v[214:215], v144
	v_cvt_pk_f32_fp8_sdwa v[216:217], v144 src0_sel:WORD_1
	v_cvt_pk_f32_fp8_e32 v[218:219], v145
	v_cvt_pk_f32_fp8_sdwa v[220:221], v145 src0_sel:WORD_1
	v_pk_mul_f32 v[222:223], v[32:33], v[214:215]
	v_pk_mul_f32 v[224:225], v[34:35], v[216:217]
	v_cvt_pk_f32_fp8_e32 v[214:215], v146
	v_cvt_pk_f32_fp8_sdwa v[216:217], v146 src0_sel:WORD_1
	v_pk_fma_f32 v[222:223], v[36:37], v[218:219], v[222:223]
	v_pk_fma_f32 v[224:225], v[38:39], v[220:221], v[224:225]
	v_cvt_pk_f32_fp8_e32 v[218:219], v147
	v_cvt_pk_f32_fp8_sdwa v[220:221], v147 src0_sel:WORD_1
	v_pk_fma_f32 v[222:223], v[40:41], v[214:215], v[222:223]
	v_pk_fma_f32 v[224:225], v[42:43], v[216:217], v[224:225]
	v_pk_fma_f32 v[222:223], v[44:45], v[218:219], v[222:223]
	v_pk_fma_f32 v[224:225], v[46:47], v[220:221], v[224:225]
	v_pk_add_f32 v[222:223], v[222:223], v[224:225]
	s_nop 0
	v_add_f32_e32 v226, v222, v223
	v_cvt_pk_f32_fp8_e32 v[214:215], v148
	v_cvt_pk_f32_fp8_sdwa v[216:217], v148 src0_sel:WORD_1
	v_cvt_pk_f32_fp8_e32 v[218:219], v149
	v_cvt_pk_f32_fp8_sdwa v[220:221], v149 src0_sel:WORD_1
	v_pk_mul_f32 v[222:223], v[32:33], v[214:215]
	v_pk_mul_f32 v[224:225], v[34:35], v[216:217]
	v_cvt_pk_f32_fp8_e32 v[214:215], v150
	v_cvt_pk_f32_fp8_sdwa v[216:217], v150 src0_sel:WORD_1
	v_pk_fma_f32 v[222:223], v[36:37], v[218:219], v[222:223]
	v_pk_fma_f32 v[224:225], v[38:39], v[220:221], v[224:225]
	v_cvt_pk_f32_fp8_e32 v[218:219], v151
	v_cvt_pk_f32_fp8_sdwa v[220:221], v151 src0_sel:WORD_1
	v_pk_fma_f32 v[222:223], v[40:41], v[214:215], v[222:223]
	v_pk_fma_f32 v[224:225], v[42:43], v[216:217], v[224:225]
	v_pk_fma_f32 v[222:223], v[44:45], v[218:219], v[222:223]
	v_pk_fma_f32 v[224:225], v[46:47], v[220:221], v[224:225]
	v_pk_add_f32 v[222:223], v[222:223], v[224:225]
	s_nop 0
	v_add_f32_e32 v227, v222, v223
	v_cvt_pk_f32_fp8_e32 v[214:215], v152
	v_cvt_pk_f32_fp8_sdwa v[216:217], v152 src0_sel:WORD_1
	v_cvt_pk_f32_fp8_e32 v[218:219], v153
	v_cvt_pk_f32_fp8_sdwa v[220:221], v153 src0_sel:WORD_1
; template <bool STORE>
; DI void peer_item(const Params& p, int item, char* smem) {
;     ...
; #pragma unroll
;       for (int u = 0; u < 8; ++u) {
;         float d = 0.f;
; #pragma unroll
;         for (int i = 0; i < 4; ++i) {
;           f32x2_t lo = __builtin_amdgcn_cvt_pk_f32_fp8((int)uq[u][i], false);
;           f32x2_t hi = __builtin_amdgcn_cvt_pk_f32_fp8((int)uq[u][i], true);
;           d += xf[4 * i] * lo.x + xf[4 * i + 1] * lo.y + xf[4 * i + 2] * hi.x + xf[4 * i + 3] * hi.y;
;         }
;         part[u] = d;
;       }
;       float q4[4], r2[2], h;
; #pragma unroll
;       for (int j = 0; j < 4; ++j) {
;         float mine = b5 ? part[j + 4] : part[j];
;         float other = b5 ? part[j] : part[j + 4];
;         q4[j] = mine + __shfl_xor(other, 32);
;       }
; #pragma unroll
;       for (int j = 0; j < 2; ++j) {
;         float mine = b4 ? q4[j + 2] : q4[j];
;         float other = b4 ? q4[j] : q4[j + 2];
;         r2[j] = mine + __shfl_xor(other, 16);
;       }
;       {
;         float mine = b3 ? r2[1] : r2[0];
;         float other = b3 ? r2[0] : r2[1];
;         h = mine + __shfl_xor(other, 8);
;       }
;       h += __shfl_xor(h, 4);
;       h += __shfl_xor(h, 2);
;       h += __shfl_xor(h, 1);
	v_pk_mul_f32 v[222:223], v[32:33], v[214:215]
	v_pk_mul_f32 v[224:225], v[34:35], v[216:217]
	v_cvt_pk_f32_fp8_e32 v[214:215], v154
	v_cvt_pk_f32_fp8_sdwa v[216:217], v154 src0_sel:WORD_1
	v_pk_fma_f32 v[222:223], v[36:37], v[218:219], v[222:223]
	v_pk_fma_f32 v[224:225], v[38:39], v[220:221], v[224:225]
	v_cvt_pk_f32_fp8_e32 v[218:219], v155
	v_cvt_pk_f32_fp8_sdwa v[220:221], v155 src0_sel:WORD_1
	v_pk_fma_f32 v[222:223], v[40:41], v[214:215], v[222:223]
	v_pk_fma_f32 v[224:225], v[42:43], v[216:217], v[224:225]
	v_pk_fma_f32 v[222:223], v[44:45], v[218:219], v[222:223]
	v_pk_fma_f32 v[224:225], v[46:47], v[220:221], v[224:225]
	v_pk_add_f32 v[222:223], v[222:223], v[224:225]
	s_nop 0
	v_add_f32_e32 v228, v222, v223
	v_cvt_pk_f32_fp8_e32 v[214:215], v156
	v_cvt_pk_f32_fp8_sdwa v[216:217], v156 src0_sel:WORD_1
	v_cvt_pk_f32_fp8_e32 v[218:219], v157
	v_cvt_pk_f32_fp8_sdwa v[220:221], v157 src0_sel:WORD_1
	v_pk_mul_f32 v[222:223], v[32:33], v[214:215]
	v_pk_mul_f32 v[224:225], v[34:35], v[216:217]
	v_cvt_pk_f32_fp8_e32 v[214:215], v158
	v_cvt_pk_f32_fp8_sdwa v[216:217], v158 src0_sel:WORD_1
	v_pk_fma_f32 v[222:223], v[36:37], v[218:219], v[222:223]
	v_pk_fma_f32 v[224:225], v[38:39], v[220:221], v[224:225]
	v_cvt_pk_f32_fp8_e32 v[218:219], v159
	v_cvt_pk_f32_fp8_sdwa v[220:221], v159 src0_sel:WORD_1
	v_pk_fma_f32 v[222:223], v[40:41], v[214:215], v[222:223]
	v_pk_fma_f32 v[224:225], v[42:43], v[216:217], v[224:225]
	v_pk_fma_f32 v[222:223], v[44:45], v[218:219], v[222:223]
	v_pk_fma_f32 v[224:225], v[46:47], v[220:221], v[224:225]
	v_pk_add_f32 v[222:223], v[222:223], v[224:225]
	s_nop 0
	v_add_f32_e32 v229, v222, v223
	v_cvt_pk_f32_fp8_e32 v[214:215], v160
	v_cvt_pk_f32_fp8_sdwa v[216:217], v160 src0_sel:WORD_1
	v_cvt_pk_f32_fp8_e32 v[218:219], v161
	v_cvt_pk_f32_fp8_sdwa v[220:221], v161 src0_sel:WORD_1
	v_pk_mul_f32 v[222:223], v[32:33], v[214:215]
	v_pk_mul_f32 v[224:225], v[34:35], v[216:217]
	v_cvt_pk_f32_fp8_e32 v[214:215], v162
	v_cvt_pk_f32_fp8_sdwa v[216:217], v162 src0_sel:WORD_1
	v_pk_fma_f32 v[222:223], v[36:37], v[218:219], v[222:223]
	v_pk_fma_f32 v[224:225], v[38:39], v[220:221], v[224:225]
	v_cvt_pk_f32_fp8_e32 v[218:219], v163
	v_cvt_pk_f32_fp8_sdwa v[220:221], v163 src0_sel:WORD_1
	v_pk_fma_f32 v[222:223], v[40:41], v[214:215], v[222:223]
	v_pk_fma_f32 v[224:225], v[42:43], v[216:217], v[224:225]
	v_pk_fma_f32 v[222:223], v[44:45], v[218:219], v[222:223]
	v_pk_fma_f32 v[224:225], v[46:47], v[220:221], v[224:225]
	v_pk_add_f32 v[222:223], v[222:223], v[224:225]
	s_nop 0
	v_add_f32_e32 v230, v222, v223
	v_cvt_pk_f32_fp8_e32 v[214:215], v164
	v_cvt_pk_f32_fp8_sdwa v[216:217], v164 src0_sel:WORD_1
	v_cvt_pk_f32_fp8_e32 v[218:219], v165
	v_cvt_pk_f32_fp8_sdwa v[220:221], v165 src0_sel:WORD_1
	v_pk_mul_f32 v[222:223], v[32:33], v[214:215]
	v_pk_mul_f32 v[224:225], v[34:35], v[216:217]
	v_cvt_pk_f32_fp8_e32 v[214:215], v166
	v_cvt_pk_f32_fp8_sdwa v[216:217], v166 src0_sel:WORD_1
	v_pk_fma_f32 v[222:223], v[36:37], v[218:219], v[222:223]
	v_pk_fma_f32 v[224:225], v[38:39], v[220:221], v[224:225]
	v_cvt_pk_f32_fp8_e32 v[218:219], v167
	v_cvt_pk_f32_fp8_sdwa v[220:221], v167 src0_sel:WORD_1
	v_pk_fma_f32 v[222:223], v[40:41], v[214:215], v[222:223]
	v_pk_fma_f32 v[224:225], v[42:43], v[216:217], v[224:225]
	v_pk_fma_f32 v[222:223], v[44:45], v[218:219], v[222:223]
	v_pk_fma_f32 v[224:225], v[46:47], v[220:221], v[224:225]
	v_pk_add_f32 v[222:223], v[222:223], v[224:225]
	s_nop 0
	v_add_f32_e32 v231, v222, v223
	v_cvt_pk_f32_fp8_e32 v[214:215], v168
	v_cvt_pk_f32_fp8_sdwa v[216:217], v168 src0_sel:WORD_1
	v_cvt_pk_f32_fp8_e32 v[218:219], v169
	v_cvt_pk_f32_fp8_sdwa v[220:221], v169 src0_sel:WORD_1
	v_pk_mul_f32 v[222:223], v[32:33], v[214:215]
	v_pk_mul_f32 v[224:225], v[34:35], v[216:217]
	v_cvt_pk_f32_fp8_e32 v[214:215], v170
	v_cvt_pk_f32_fp8_sdwa v[216:217], v170 src0_sel:WORD_1
	v_pk_fma_f32 v[222:223], v[36:37], v[218:219], v[222:223]
	v_pk_fma_f32 v[224:225], v[38:39], v[220:221], v[224:225]
	v_cvt_pk_f32_fp8_e32 v[218:219], v171
	v_cvt_pk_f32_fp8_sdwa v[220:221], v171 src0_sel:WORD_1
	v_pk_fma_f32 v[222:223], v[40:41], v[214:215], v[222:223]
	v_pk_fma_f32 v[224:225], v[42:43], v[216:217], v[224:225]
	v_pk_fma_f32 v[222:223], v[44:45], v[218:219], v[222:223]
	v_pk_fma_f32 v[224:225], v[46:47], v[220:221], v[224:225]
	v_pk_add_f32 v[222:223], v[222:223], v[224:225]
	s_nop 0
	v_add_f32_e32 v232, v222, v223
	v_cvt_pk_f32_fp8_e32 v[214:215], v172
	v_cvt_pk_f32_fp8_sdwa v[216:217], v172 src0_sel:WORD_1
	v_cvt_pk_f32_fp8_e32 v[218:219], v173
	v_cvt_pk_f32_fp8_sdwa v[220:221], v173 src0_sel:WORD_1
	v_pk_mul_f32 v[222:223], v[32:33], v[214:215]
	v_pk_mul_f32 v[224:225], v[34:35], v[216:217]
	v_cvt_pk_f32_fp8_e32 v[214:215], v174
	v_cvt_pk_f32_fp8_sdwa v[216:217], v174 src0_sel:WORD_1
	v_pk_fma_f32 v[222:223], v[36:37], v[218:219], v[222:223]
	v_pk_fma_f32 v[224:225], v[38:39], v[220:221], v[224:225]
	v_cvt_pk_f32_fp8_e32 v[218:219], v175
	v_cvt_pk_f32_fp8_sdwa v[220:221], v175 src0_sel:WORD_1
	v_pk_fma_f32 v[222:223], v[40:41], v[214:215], v[222:223]
	v_pk_fma_f32 v[224:225], v[42:43], v[216:217], v[224:225]
	v_pk_fma_f32 v[222:223], v[44:45], v[218:219], v[222:223]
	v_pk_fma_f32 v[224:225], v[46:47], v[220:221], v[224:225]
	v_pk_add_f32 v[222:223], v[222:223], v[224:225]
	s_nop 0
	v_add_f32_e32 v233, v222, v223
	v_permlane32_swap_b32_e32 v226, v230
	v_permlane32_swap_b32_e32 v227, v231
	v_permlane32_swap_b32_e32 v228, v232
	v_permlane32_swap_b32_e32 v229, v233
	v_add_f32_e32 v226, v226, v230
	v_add_f32_e32 v228, v228, v232
	v_add_f32_e32 v227, v227, v231
	v_add_f32_e32 v229, v229, v233
	s_nop 1
	v_permlane16_swap_b32_e32 v226, v228
; template <bool STORE>
; DI void peer_item(const Params& p, int item, char* smem) {
;     ...
; #pragma unroll
;       for (int u = 0; u < 8; ++u) {
;         float d = 0.f;
; #pragma unroll
;         for (int i = 0; i < 4; ++i) {
;           f32x2_t lo = __builtin_amdgcn_cvt_pk_f32_fp8((int)uq[u][i], false);
;           f32x2_t hi = __builtin_amdgcn_cvt_pk_f32_fp8((int)uq[u][i], true);
;           d += xf[4 * i] * lo.x + xf[4 * i + 1] * lo.y + xf[4 * i + 2] * hi.x + xf[4 * i + 3] * hi.y;
;         }
;         part[u] = d;
;       }
;       float q4[4], r2[2], h;
; #pragma unroll
;       for (int j = 0; j < 4; ++j) {
;         float mine = b5 ? part[j + 4] : part[j];
;         float other = b5 ? part[j] : part[j + 4];
;         q4[j] = mine + __shfl_xor(other, 32);
;       }
; #pragma unroll
;       for (int j = 0; j < 2; ++j) {
;         float mine = b4 ? q4[j + 2] : q4[j];
;         float other = b4 ? q4[j] : q4[j + 2];
;         r2[j] = mine + __shfl_xor(other, 16);
;       }
;       {
;         float mine = b3 ? r2[1] : r2[0];
;         float other = b3 ? r2[0] : r2[1];
;         h = mine + __shfl_xor(other, 8);
;       }
;       h += __shfl_xor(h, 4);
;       h += __shfl_xor(h, 2);
;       h += __shfl_xor(h, 1);
	v_permlane16_swap_b32_e32 v227, v229
	v_add_f32_e32 v226, v226, v228
	v_add_f32_e32 v227, v227, v229
	s_nop 0
	v_cndmask_b32_e64 v230, v226, v227, s[24:25]
	v_cndmask_b32_e64 v231, v227, v226, s[24:25]
	s_nop 1
	v_add_f32_dpp v232, v231, v230 row_ror:8 row_mask:0xf bank_mask:0xf
	s_nop 1
	v_add_f32_dpp v233, v232, v232 quad_perm:[1,0,3,2] row_mask:0xf bank_mask:0xf
	s_nop 1
	v_add_f32_dpp v232, v233, v233 quad_perm:[2,3,0,1] row_mask:0xf bank_mask:0xf
	s_nop 1
	v_add_f32_dpp v233, v232, v232 row_half_mirror row_mask:0xf bank_mask:0xf
	ds_write_b32 v235, v233 offset:33792
	v_readlane_b32 s48, v136, s72
	v_readlane_b32 s49, v136, s73
	v_readlane_b32 s50, v136, s74
	v_readlane_b32 s51, v136, s75
	v_readlane_b32 s52, v136, s76
	v_readlane_b32 s53, v136, s77
	v_readlane_b32 s54, v136, s78
	v_readlane_b32 s55, v136, s79
	s_add_u32 s32, s0, s48
	s_addc_u32 s33, s1, 0
	s_add_u32 s34, s0, s49
	s_addc_u32 s35, s1, 0
	s_add_u32 s36, s0, s50
	s_addc_u32 s37, s1, 0
	s_add_u32 s38, s0, s51
	s_addc_u32 s39, s1, 0
	s_add_u32 s40, s0, s52
	s_addc_u32 s41, s1, 0
	s_add_u32 s42, s0, s53
	s_addc_u32 s43, s1, 0
	s_add_u32 s44, s0, s54
	s_addc_u32 s45, s1, 0
	s_add_u32 s46, s0, s55
	s_addc_u32 s47, s1, 0
	global_load_dwordx4 v[144:147], v234, s[32:33]
	global_load_dwordx4 v[148:151], v234, s[34:35]
	global_load_dwordx4 v[152:155], v234, s[36:37]
	global_load_dwordx4 v[156:159], v234, s[38:39]
	global_load_dwordx4 v[160:163], v234, s[40:41]
	global_load_dwordx4 v[164:167], v234, s[42:43]
	global_load_dwordx4 v[168:171], v234, s[44:45]
	global_load_dwordx4 v[172:175], v234, s[46:47]
	s_waitcnt vmcnt(8)
	v_cvt_pk_f32_fp8_e32 v[214:215], v176
	v_cvt_pk_f32_fp8_sdwa v[216:217], v176 src0_sel:WORD_1
	v_cvt_pk_f32_fp8_e32 v[218:219], v177
	v_cvt_pk_f32_fp8_sdwa v[220:221], v177 src0_sel:WORD_1
	v_pk_mul_f32 v[222:223], v[48:49], v[214:215]
	v_pk_mul_f32 v[224:225], v[50:51], v[216:217]
	v_cvt_pk_f32_fp8_e32 v[214:215], v178
	v_cvt_pk_f32_fp8_sdwa v[216:217], v178 src0_sel:WORD_1
	v_pk_fma_f32 v[222:223], v[52:53], v[218:219], v[222:223]
	v_pk_fma_f32 v[224:225], v[54:55], v[220:221], v[224:225]
	v_cvt_pk_f32_fp8_e32 v[218:219], v179
	v_cvt_pk_f32_fp8_sdwa v[220:221], v179 src0_sel:WORD_1
	v_pk_fma_f32 v[222:223], v[56:57], v[214:215], v[222:223]
	v_pk_fma_f32 v[224:225], v[58:59], v[216:217], v[224:225]
	v_pk_fma_f32 v[222:223], v[60:61], v[218:219], v[222:223]
	v_pk_fma_f32 v[224:225], v[62:63], v[220:221], v[224:225]
	v_pk_add_f32 v[222:223], v[222:223], v[224:225]
	s_nop 0
	v_add_f32_e32 v226, v222, v223
	v_cvt_pk_f32_fp8_e32 v[214:215], v180
	v_cvt_pk_f32_fp8_sdwa v[216:217], v180 src0_sel:WORD_1
	v_cvt_pk_f32_fp8_e32 v[218:219], v181
	v_cvt_pk_f32_fp8_sdwa v[220:221], v181 src0_sel:WORD_1
	v_pk_mul_f32 v[222:223], v[48:49], v[214:215]
	v_pk_mul_f32 v[224:225], v[50:51], v[216:217]
	v_cvt_pk_f32_fp8_e32 v[214:215], v182
	v_cvt_pk_f32_fp8_sdwa v[216:217], v182 src0_sel:WORD_1
	v_pk_fma_f32 v[222:223], v[52:53], v[218:219], v[222:223]
	v_pk_fma_f32 v[224:225], v[54:55], v[220:221], v[224:225]
	v_cvt_pk_f32_fp8_e32 v[218:219], v183
	v_cvt_pk_f32_fp8_sdwa v[220:221], v183 src0_sel:WORD_1
	v_pk_fma_f32 v[222:223], v[56:57], v[214:215], v[222:223]
	v_pk_fma_f32 v[224:225], v[58:59], v[216:217], v[224:225]
	v_pk_fma_f32 v[222:223], v[60:61], v[218:219], v[222:223]
	v_pk_fma_f32 v[224:225], v[62:63], v[220:221], v[224:225]
	v_pk_add_f32 v[222:223], v[222:223], v[224:225]
	s_nop 0
	v_add_f32_e32 v227, v222, v223
	v_cvt_pk_f32_fp8_e32 v[214:215], v184
	v_cvt_pk_f32_fp8_sdwa v[216:217], v184 src0_sel:WORD_1
	v_cvt_pk_f32_fp8_e32 v[218:219], v185
	v_cvt_pk_f32_fp8_sdwa v[220:221], v185 src0_sel:WORD_1
	v_pk_mul_f32 v[222:223], v[48:49], v[214:215]
	v_pk_mul_f32 v[224:225], v[50:51], v[216:217]
	v_cvt_pk_f32_fp8_e32 v[214:215], v186
	v_cvt_pk_f32_fp8_sdwa v[216:217], v186 src0_sel:WORD_1
	v_pk_fma_f32 v[222:223], v[52:53], v[218:219], v[222:223]
	v_pk_fma_f32 v[224:225], v[54:55], v[220:221], v[224:225]
	v_cvt_pk_f32_fp8_e32 v[218:219], v187
	v_cvt_pk_f32_fp8_sdwa v[220:221], v187 src0_sel:WORD_1
	v_pk_fma_f32 v[222:223], v[56:57], v[214:215], v[222:223]
	v_pk_fma_f32 v[224:225], v[58:59], v[216:217], v[224:225]
	v_pk_fma_f32 v[222:223], v[60:61], v[218:219], v[222:223]
	v_pk_fma_f32 v[224:225], v[62:63], v[220:221], v[224:225]
	v_pk_add_f32 v[222:223], v[222:223], v[224:225]
	s_nop 0
	v_add_f32_e32 v228, v222, v223
	v_cvt_pk_f32_fp8_e32 v[214:215], v188
	v_cvt_pk_f32_fp8_sdwa v[216:217], v188 src0_sel:WORD_1
	v_cvt_pk_f32_fp8_e32 v[218:219], v189
	v_cvt_pk_f32_fp8_sdwa v[220:221], v189 src0_sel:WORD_1
	v_pk_mul_f32 v[222:223], v[48:49], v[214:215]
	v_pk_mul_f32 v[224:225], v[50:51], v[216:217]
	v_cvt_pk_f32_fp8_e32 v[214:215], v190
	v_cvt_pk_f32_fp8_sdwa v[216:217], v190 src0_sel:WORD_1
	v_pk_fma_f32 v[222:223], v[52:53], v[218:219], v[222:223]
	v_pk_fma_f32 v[224:225], v[54:55], v[220:221], v[224:225]
	v_cvt_pk_f32_fp8_e32 v[218:219], v191
	v_cvt_pk_f32_fp8_sdwa v[220:221], v191 src0_sel:WORD_1
	v_pk_fma_f32 v[222:223], v[56:57], v[214:215], v[222:223]
	v_pk_fma_f32 v[224:225], v[58:59], v[216:217], v[224:225]
	v_pk_fma_f32 v[222:223], v[60:61], v[218:219], v[222:223]
	v_pk_fma_f32 v[224:225], v[62:63], v[220:221], v[224:225]
	v_pk_add_f32 v[222:223], v[222:223], v[224:225]
	s_nop 0
	v_add_f32_e32 v229, v222, v223
	v_cvt_pk_f32_fp8_e32 v[214:215], v192
	v_cvt_pk_f32_fp8_sdwa v[216:217], v192 src0_sel:WORD_1
	v_cvt_pk_f32_fp8_e32 v[218:219], v193
	v_cvt_pk_f32_fp8_sdwa v[220:221], v193 src0_sel:WORD_1
	v_pk_mul_f32 v[222:223], v[48:49], v[214:215]
	v_pk_mul_f32 v[224:225], v[50:51], v[216:217]
	v_cvt_pk_f32_fp8_e32 v[214:215], v194
	v_cvt_pk_f32_fp8_sdwa v[216:217], v194 src0_sel:WORD_1
; template <bool STORE>
; DI void peer_item(const Params& p, int item, char* smem) {
;     ...
; #pragma unroll
;       for (int u = 0; u < 8; ++u) {
;         float d = 0.f;
; #pragma unroll
;         for (int i = 0; i < 4; ++i) {
;           f32x2_t lo = __builtin_amdgcn_cvt_pk_f32_fp8((int)uq[u][i], false);
;           f32x2_t hi = __builtin_amdgcn_cvt_pk_f32_fp8((int)uq[u][i], true);
;           d += xf[4 * i] * lo.x + xf[4 * i + 1] * lo.y + xf[4 * i + 2] * hi.x + xf[4 * i + 3] * hi.y;
;         }
;         part[u] = d;
;       }
;       float q4[4], r2[2], h;
; #pragma unroll
;       for (int j = 0; j < 4; ++j) {
;         float mine = b5 ? part[j + 4] : part[j];
;         float other = b5 ? part[j] : part[j + 4];
;         q4[j] = mine + __shfl_xor(other, 32);
;       }
; #pragma unroll
;       for (int j = 0; j < 2; ++j) {
;         float mine = b4 ? q4[j + 2] : q4[j];
;         float other = b4 ? q4[j] : q4[j + 2];
;         r2[j] = mine + __shfl_xor(other, 16);
;       }
;       {
;         float mine = b3 ? r2[1] : r2[0];
;         float other = b3 ? r2[0] : r2[1];
;         h = mine + __shfl_xor(other, 8);
;       }
;       h += __shfl_xor(h, 4);
;       h += __shfl_xor(h, 2);
;       h += __shfl_xor(h, 1);
	v_pk_fma_f32 v[222:223], v[52:53], v[218:219], v[222:223]
	v_pk_fma_f32 v[224:225], v[54:55], v[220:221], v[224:225]
	v_cvt_pk_f32_fp8_e32 v[218:219], v195
	v_cvt_pk_f32_fp8_sdwa v[220:221], v195 src0_sel:WORD_1
	v_pk_fma_f32 v[222:223], v[56:57], v[214:215], v[222:223]
	v_pk_fma_f32 v[224:225], v[58:59], v[216:217], v[224:225]
	v_pk_fma_f32 v[222:223], v[60:61], v[218:219], v[222:223]
	v_pk_fma_f32 v[224:225], v[62:63], v[220:221], v[224:225]
	v_pk_add_f32 v[222:223], v[222:223], v[224:225]
	s_nop 0
	v_add_f32_e32 v230, v222, v223
	v_cvt_pk_f32_fp8_e32 v[214:215], v196
	v_cvt_pk_f32_fp8_sdwa v[216:217], v196 src0_sel:WORD_1
	v_cvt_pk_f32_fp8_e32 v[218:219], v197
	v_cvt_pk_f32_fp8_sdwa v[220:221], v197 src0_sel:WORD_1
	v_pk_mul_f32 v[222:223], v[48:49], v[214:215]
	v_pk_mul_f32 v[224:225], v[50:51], v[216:217]
	v_cvt_pk_f32_fp8_e32 v[214:215], v198
	v_cvt_pk_f32_fp8_sdwa v[216:217], v198 src0_sel:WORD_1
	v_pk_fma_f32 v[222:223], v[52:53], v[218:219], v[222:223]
	v_pk_fma_f32 v[224:225], v[54:55], v[220:221], v[224:225]
	v_cvt_pk_f32_fp8_e32 v[218:219], v199
	v_cvt_pk_f32_fp8_sdwa v[220:221], v199 src0_sel:WORD_1
	v_pk_fma_f32 v[222:223], v[56:57], v[214:215], v[222:223]
	v_pk_fma_f32 v[224:225], v[58:59], v[216:217], v[224:225]
	v_pk_fma_f32 v[222:223], v[60:61], v[218:219], v[222:223]
	v_pk_fma_f32 v[224:225], v[62:63], v[220:221], v[224:225]
	v_pk_add_f32 v[222:223], v[222:223], v[224:225]
	s_nop 0
	v_add_f32_e32 v231, v222, v223
	v_cvt_pk_f32_fp8_e32 v[214:215], v200
	v_cvt_pk_f32_fp8_sdwa v[216:217], v200 src0_sel:WORD_1
	v_cvt_pk_f32_fp8_e32 v[218:219], v201
	v_cvt_pk_f32_fp8_sdwa v[220:221], v201 src0_sel:WORD_1
	v_pk_mul_f32 v[222:223], v[48:49], v[214:215]
	v_pk_mul_f32 v[224:225], v[50:51], v[216:217]
	v_cvt_pk_f32_fp8_e32 v[214:215], v202
	v_cvt_pk_f32_fp8_sdwa v[216:217], v202 src0_sel:WORD_1
	v_pk_fma_f32 v[222:223], v[52:53], v[218:219], v[222:223]
	v_pk_fma_f32 v[224:225], v[54:55], v[220:221], v[224:225]
	v_cvt_pk_f32_fp8_e32 v[218:219], v203
	v_cvt_pk_f32_fp8_sdwa v[220:221], v203 src0_sel:WORD_1
	v_pk_fma_f32 v[222:223], v[56:57], v[214:215], v[222:223]
	v_pk_fma_f32 v[224:225], v[58:59], v[216:217], v[224:225]
	v_pk_fma_f32 v[222:223], v[60:61], v[218:219], v[222:223]
	v_pk_fma_f32 v[224:225], v[62:63], v[220:221], v[224:225]
	v_pk_add_f32 v[222:223], v[222:223], v[224:225]
	s_nop 0
	v_add_f32_e32 v232, v222, v223
	v_cvt_pk_f32_fp8_e32 v[214:215], v204
	v_cvt_pk_f32_fp8_sdwa v[216:217], v204 src0_sel:WORD_1
	v_cvt_pk_f32_fp8_e32 v[218:219], v205
	v_cvt_pk_f32_fp8_sdwa v[220:221], v205 src0_sel:WORD_1
	v_pk_mul_f32 v[222:223], v[48:49], v[214:215]
	v_pk_mul_f32 v[224:225], v[50:51], v[216:217]
	v_cvt_pk_f32_fp8_e32 v[214:215], v206
	v_cvt_pk_f32_fp8_sdwa v[216:217], v206 src0_sel:WORD_1
	v_pk_fma_f32 v[222:223], v[52:53], v[218:219], v[222:223]
	v_pk_fma_f32 v[224:225], v[54:55], v[220:221], v[224:225]
	v_cvt_pk_f32_fp8_e32 v[218:219], v207
	v_cvt_pk_f32_fp8_sdwa v[220:221], v207 src0_sel:WORD_1
	v_pk_fma_f32 v[222:223], v[56:57], v[214:215], v[222:223]
	v_pk_fma_f32 v[224:225], v[58:59], v[216:217], v[224:225]
	v_pk_fma_f32 v[222:223], v[60:61], v[218:219], v[222:223]
	v_pk_fma_f32 v[224:225], v[62:63], v[220:221], v[224:225]
	v_pk_add_f32 v[222:223], v[222:223], v[224:225]
	s_nop 0
	v_add_f32_e32 v233, v222, v223
	v_permlane32_swap_b32_e32 v226, v230
	v_permlane32_swap_b32_e32 v227, v231
	v_permlane32_swap_b32_e32 v228, v232
	v_permlane32_swap_b32_e32 v229, v233
	v_add_f32_e32 v226, v226, v230
	v_add_f32_e32 v228, v228, v232
	v_add_f32_e32 v227, v227, v231
	v_add_f32_e32 v229, v229, v233
	s_nop 1
	v_permlane16_swap_b32_e32 v226, v228
	v_permlane16_swap_b32_e32 v227, v229
	v_add_f32_e32 v226, v226, v228
	v_add_f32_e32 v227, v227, v229
	s_nop 0
	v_cndmask_b32_e64 v230, v226, v227, s[24:25]
	v_cndmask_b32_e64 v231, v227, v226, s[24:25]
	s_nop 1
	v_add_f32_dpp v232, v231, v230 row_ror:8 row_mask:0xf bank_mask:0xf
	s_nop 1
	v_add_f32_dpp v233, v232, v232 quad_perm:[1,0,3,2] row_mask:0xf bank_mask:0xf
	s_nop 1
	v_add_f32_dpp v232, v233, v233 quad_perm:[2,3,0,1] row_mask:0xf bank_mask:0xf
	s_nop 1
	v_add_f32_dpp v233, v232, v232 row_half_mirror row_mask:0xf bank_mask:0xf
	ds_write_b32 v235, v233 offset:34304
	v_readlane_b32 s48, v138, s72
	v_readlane_b32 s49, v138, s73
	v_readlane_b32 s50, v138, s74
	v_readlane_b32 s51, v138, s75
	v_readlane_b32 s52, v138, s76
	v_readlane_b32 s53, v138, s77
	v_readlane_b32 s54, v138, s78
	v_readlane_b32 s55, v138, s79
	s_add_u32 s32, s0, s48
	s_addc_u32 s33, s1, 0
	s_add_u32 s34, s0, s49
	s_addc_u32 s35, s1, 0
	s_add_u32 s36, s0, s50
	s_addc_u32 s37, s1, 0
	s_add_u32 s38, s0, s51
	s_addc_u32 s39, s1, 0
	s_add_u32 s40, s0, s52
	s_addc_u32 s41, s1, 0
	s_add_u32 s42, s0, s53
	s_addc_u32 s43, s1, 0
	s_add_u32 s44, s0, s54
	s_addc_u32 s45, s1, 0
	s_add_u32 s46, s0, s55
	s_addc_u32 s47, s1, 0
	global_load_dwordx4 v[176:179], v234, s[32:33]
	global_load_dwordx4 v[180:183], v234, s[34:35]
	global_load_dwordx4 v[184:187], v234, s[36:37]
	global_load_dwordx4 v[188:191], v234, s[38:39]
	global_load_dwordx4 v[192:195], v234, s[40:41]
	global_load_dwordx4 v[196:199], v234, s[42:43]
	global_load_dwordx4 v[200:203], v234, s[44:45]
	global_load_dwordx4 v[204:207], v234, s[46:47]
	s_waitcnt vmcnt(8)
; template <bool STORE>
; DI void peer_item(const Params& p, int item, char* smem) {
;     ...
; #pragma unroll
;       for (int u = 0; u < 8; ++u) {
;         float d = 0.f;
; #pragma unroll
;         for (int i = 0; i < 4; ++i) {
;           f32x2_t lo = __builtin_amdgcn_cvt_pk_f32_fp8((int)uq[u][i], false);
;           f32x2_t hi = __builtin_amdgcn_cvt_pk_f32_fp8((int)uq[u][i], true);
;           d += xf[4 * i] * lo.x + xf[4 * i + 1] * lo.y + xf[4 * i + 2] * hi.x + xf[4 * i + 3] * hi.y;
;         }
;         part[u] = d;
;       }
	v_cvt_pk_f32_fp8_e32 v[214:215], v144
	v_cvt_pk_f32_fp8_sdwa v[216:217], v144 src0_sel:WORD_1
	v_cvt_pk_f32_fp8_e32 v[218:219], v145
	v_cvt_pk_f32_fp8_sdwa v[220:221], v145 src0_sel:WORD_1
	v_pk_mul_f32 v[222:223], v[64:65], v[214:215]
	v_pk_mul_f32 v[224:225], v[66:67], v[216:217]
	v_cvt_pk_f32_fp8_e32 v[214:215], v146
	v_cvt_pk_f32_fp8_sdwa v[216:217], v146 src0_sel:WORD_1
	v_pk_fma_f32 v[222:223], v[68:69], v[218:219], v[222:223]
	v_pk_fma_f32 v[224:225], v[70:71], v[220:221], v[224:225]
	v_cvt_pk_f32_fp8_e32 v[218:219], v147
	v_cvt_pk_f32_fp8_sdwa v[220:221], v147 src0_sel:WORD_1
	v_pk_fma_f32 v[222:223], v[72:73], v[214:215], v[222:223]
	v_pk_fma_f32 v[224:225], v[74:75], v[216:217], v[224:225]
	v_pk_fma_f32 v[222:223], v[76:77], v[218:219], v[222:223]
	v_pk_fma_f32 v[224:225], v[78:79], v[220:221], v[224:225]
	v_pk_add_f32 v[222:223], v[222:223], v[224:225]
	s_nop 0
	v_add_f32_e32 v226, v222, v223
	v_cvt_pk_f32_fp8_e32 v[214:215], v148
	v_cvt_pk_f32_fp8_sdwa v[216:217], v148 src0_sel:WORD_1
	v_cvt_pk_f32_fp8_e32 v[218:219], v149
	v_cvt_pk_f32_fp8_sdwa v[220:221], v149 src0_sel:WORD_1
	v_pk_mul_f32 v[222:223], v[64:65], v[214:215]
	v_pk_mul_f32 v[224:225], v[66:67], v[216:217]
	v_cvt_pk_f32_fp8_e32 v[214:215], v150
	v_cvt_pk_f32_fp8_sdwa v[216:217], v150 src0_sel:WORD_1
	v_pk_fma_f32 v[222:223], v[68:69], v[218:219], v[222:223]
	v_pk_fma_f32 v[224:225], v[70:71], v[220:221], v[224:225]
	v_cvt_pk_f32_fp8_e32 v[218:219], v151
	v_cvt_pk_f32_fp8_sdwa v[220:221], v151 src0_sel:WORD_1
	v_pk_fma_f32 v[222:223], v[72:73], v[214:215], v[222:223]
	v_pk_fma_f32 v[224:225], v[74:75], v[216:217], v[224:225]
	v_pk_fma_f32 v[222:223], v[76:77], v[218:219], v[222:223]
	v_pk_fma_f32 v[224:225], v[78:79], v[220:221], v[224:225]
	v_pk_add_f32 v[222:223], v[222:223], v[224:225]
	s_nop 0
	v_add_f32_e32 v227, v222, v223
	v_cvt_pk_f32_fp8_e32 v[214:215], v152
	v_cvt_pk_f32_fp8_sdwa v[216:217], v152 src0_sel:WORD_1
	v_cvt_pk_f32_fp8_e32 v[218:219], v153
	v_cvt_pk_f32_fp8_sdwa v[220:221], v153 src0_sel:WORD_1
	v_pk_mul_f32 v[222:223], v[64:65], v[214:215]
	v_pk_mul_f32 v[224:225], v[66:67], v[216:217]
	v_cvt_pk_f32_fp8_e32 v[214:215], v154
	v_cvt_pk_f32_fp8_sdwa v[216:217], v154 src0_sel:WORD_1
	v_pk_fma_f32 v[222:223], v[68:69], v[218:219], v[222:223]
	v_pk_fma_f32 v[224:225], v[70:71], v[220:221], v[224:225]
	v_cvt_pk_f32_fp8_e32 v[218:219], v155
	v_cvt_pk_f32_fp8_sdwa v[220:221], v155 src0_sel:WORD_1
	v_pk_fma_f32 v[222:223], v[72:73], v[214:215], v[222:223]
	v_pk_fma_f32 v[224:225], v[74:75], v[216:217], v[224:225]
	v_pk_fma_f32 v[222:223], v[76:77], v[218:219], v[222:223]
	v_pk_fma_f32 v[224:225], v[78:79], v[220:221], v[224:225]
	v_pk_add_f32 v[222:223], v[222:223], v[224:225]
	s_nop 0
	v_add_f32_e32 v228, v222, v223
	v_cvt_pk_f32_fp8_e32 v[214:215], v156
	v_cvt_pk_f32_fp8_sdwa v[216:217], v156 src0_sel:WORD_1
	v_cvt_pk_f32_fp8_e32 v[218:219], v157
	v_cvt_pk_f32_fp8_sdwa v[220:221], v157 src0_sel:WORD_1
	v_pk_mul_f32 v[222:223], v[64:65], v[214:215]
	v_pk_mul_f32 v[224:225], v[66:67], v[216:217]
	v_cvt_pk_f32_fp8_e32 v[214:215], v158
	v_cvt_pk_f32_fp8_sdwa v[216:217], v158 src0_sel:WORD_1
	v_pk_fma_f32 v[222:223], v[68:69], v[218:219], v[222:223]
	v_pk_fma_f32 v[224:225], v[70:71], v[220:221], v[224:225]
	v_cvt_pk_f32_fp8_e32 v[218:219], v159
	v_cvt_pk_f32_fp8_sdwa v[220:221], v159 src0_sel:WORD_1
	v_pk_fma_f32 v[222:223], v[72:73], v[214:215], v[222:223]
	v_pk_fma_f32 v[224:225], v[74:75], v[216:217], v[224:225]
	v_pk_fma_f32 v[222:223], v[76:77], v[218:219], v[222:223]
	v_pk_fma_f32 v[224:225], v[78:79], v[220:221], v[224:225]
	v_pk_add_f32 v[222:223], v[222:223], v[224:225]
	s_nop 0
	v_add_f32_e32 v229, v222, v223
	v_cvt_pk_f32_fp8_e32 v[214:215], v160
	v_cvt_pk_f32_fp8_sdwa v[216:217], v160 src0_sel:WORD_1
	v_cvt_pk_f32_fp8_e32 v[218:219], v161
	v_cvt_pk_f32_fp8_sdwa v[220:221], v161 src0_sel:WORD_1
	v_pk_mul_f32 v[222:223], v[64:65], v[214:215]
	v_pk_mul_f32 v[224:225], v[66:67], v[216:217]
	v_cvt_pk_f32_fp8_e32 v[214:215], v162
	v_cvt_pk_f32_fp8_sdwa v[216:217], v162 src0_sel:WORD_1
	v_pk_fma_f32 v[222:223], v[68:69], v[218:219], v[222:223]
	v_pk_fma_f32 v[224:225], v[70:71], v[220:221], v[224:225]
	v_cvt_pk_f32_fp8_e32 v[218:219], v163
	v_cvt_pk_f32_fp8_sdwa v[220:221], v163 src0_sel:WORD_1
	v_pk_fma_f32 v[222:223], v[72:73], v[214:215], v[222:223]
	v_pk_fma_f32 v[224:225], v[74:75], v[216:217], v[224:225]
	v_pk_fma_f32 v[222:223], v[76:77], v[218:219], v[222:223]
	v_pk_fma_f32 v[224:225], v[78:79], v[220:221], v[224:225]
	v_pk_add_f32 v[222:223], v[222:223], v[224:225]
	s_nop 0
	v_add_f32_e32 v230, v222, v223
	v_cvt_pk_f32_fp8_e32 v[214:215], v164
	v_cvt_pk_f32_fp8_sdwa v[216:217], v164 src0_sel:WORD_1
	v_cvt_pk_f32_fp8_e32 v[218:219], v165
	v_cvt_pk_f32_fp8_sdwa v[220:221], v165 src0_sel:WORD_1
	v_pk_mul_f32 v[222:223], v[64:65], v[214:215]
	v_pk_mul_f32 v[224:225], v[66:67], v[216:217]
	v_cvt_pk_f32_fp8_e32 v[214:215], v166
	v_cvt_pk_f32_fp8_sdwa v[216:217], v166 src0_sel:WORD_1
	v_pk_fma_f32 v[222:223], v[68:69], v[218:219], v[222:223]
	v_pk_fma_f32 v[224:225], v[70:71], v[220:221], v[224:225]
	v_cvt_pk_f32_fp8_e32 v[218:219], v167
	v_cvt_pk_f32_fp8_sdwa v[220:221], v167 src0_sel:WORD_1
	v_pk_fma_f32 v[222:223], v[72:73], v[214:215], v[222:223]
	v_pk_fma_f32 v[224:225], v[74:75], v[216:217], v[224:225]
	v_pk_fma_f32 v[222:223], v[76:77], v[218:219], v[222:223]
	v_pk_fma_f32 v[224:225], v[78:79], v[220:221], v[224:225]
	v_pk_add_f32 v[222:223], v[222:223], v[224:225]
	s_nop 0
	v_add_f32_e32 v231, v222, v223
	v_cvt_pk_f32_fp8_e32 v[214:215], v168
	v_cvt_pk_f32_fp8_sdwa v[216:217], v168 src0_sel:WORD_1
	v_cvt_pk_f32_fp8_e32 v[218:219], v169
; template <bool STORE>
; DI void peer_item(const Params& p, int item, char* smem) {
;     ...
; #pragma unroll
;       for (int u = 0; u < 8; ++u) {
;         float d = 0.f;
; #pragma unroll
;         for (int i = 0; i < 4; ++i) {
;           f32x2_t lo = __builtin_amdgcn_cvt_pk_f32_fp8((int)uq[u][i], false);
;           f32x2_t hi = __builtin_amdgcn_cvt_pk_f32_fp8((int)uq[u][i], true);
;           d += xf[4 * i] * lo.x + xf[4 * i + 1] * lo.y + xf[4 * i + 2] * hi.x + xf[4 * i + 3] * hi.y;
;         }
;         part[u] = d;
;       }
;       float q4[4], r2[2], h;
; #pragma unroll
;       for (int j = 0; j < 4; ++j) {
;         float mine = b5 ? part[j + 4] : part[j];
;         float other = b5 ? part[j] : part[j + 4];
;         q4[j] = mine + __shfl_xor(other, 32);
;       }
; #pragma unroll
;       for (int j = 0; j < 2; ++j) {
;         float mine = b4 ? q4[j + 2] : q4[j];
;         float other = b4 ? q4[j] : q4[j + 2];
;         r2[j] = mine + __shfl_xor(other, 16);
;       }
;       {
;         float mine = b3 ? r2[1] : r2[0];
;         float other = b3 ? r2[0] : r2[1];
;         h = mine + __shfl_xor(other, 8);
;       }
;       h += __shfl_xor(h, 4);
;       h += __shfl_xor(h, 2);
;       h += __shfl_xor(h, 1);
	v_cvt_pk_f32_fp8_sdwa v[220:221], v169 src0_sel:WORD_1
	v_pk_mul_f32 v[222:223], v[64:65], v[214:215]
	v_pk_mul_f32 v[224:225], v[66:67], v[216:217]
	v_cvt_pk_f32_fp8_e32 v[214:215], v170
	v_cvt_pk_f32_fp8_sdwa v[216:217], v170 src0_sel:WORD_1
	v_pk_fma_f32 v[222:223], v[68:69], v[218:219], v[222:223]
	v_pk_fma_f32 v[224:225], v[70:71], v[220:221], v[224:225]
	v_cvt_pk_f32_fp8_e32 v[218:219], v171
	v_cvt_pk_f32_fp8_sdwa v[220:221], v171 src0_sel:WORD_1
	v_pk_fma_f32 v[222:223], v[72:73], v[214:215], v[222:223]
	v_pk_fma_f32 v[224:225], v[74:75], v[216:217], v[224:225]
	v_pk_fma_f32 v[222:223], v[76:77], v[218:219], v[222:223]
	v_pk_fma_f32 v[224:225], v[78:79], v[220:221], v[224:225]
	v_pk_add_f32 v[222:223], v[222:223], v[224:225]
	s_nop 0
	v_add_f32_e32 v232, v222, v223
	v_cvt_pk_f32_fp8_e32 v[214:215], v172
	v_cvt_pk_f32_fp8_sdwa v[216:217], v172 src0_sel:WORD_1
	v_cvt_pk_f32_fp8_e32 v[218:219], v173
	v_cvt_pk_f32_fp8_sdwa v[220:221], v173 src0_sel:WORD_1
	v_pk_mul_f32 v[222:223], v[64:65], v[214:215]
	v_pk_mul_f32 v[224:225], v[66:67], v[216:217]
	v_cvt_pk_f32_fp8_e32 v[214:215], v174
	v_cvt_pk_f32_fp8_sdwa v[216:217], v174 src0_sel:WORD_1
	v_pk_fma_f32 v[222:223], v[68:69], v[218:219], v[222:223]
	v_pk_fma_f32 v[224:225], v[70:71], v[220:221], v[224:225]
	v_cvt_pk_f32_fp8_e32 v[218:219], v175
	v_cvt_pk_f32_fp8_sdwa v[220:221], v175 src0_sel:WORD_1
	v_pk_fma_f32 v[222:223], v[72:73], v[214:215], v[222:223]
	v_pk_fma_f32 v[224:225], v[74:75], v[216:217], v[224:225]
	v_pk_fma_f32 v[222:223], v[76:77], v[218:219], v[222:223]
	v_pk_fma_f32 v[224:225], v[78:79], v[220:221], v[224:225]
	v_pk_add_f32 v[222:223], v[222:223], v[224:225]
	s_nop 0
	v_add_f32_e32 v233, v222, v223
	v_permlane32_swap_b32_e32 v226, v230
	v_permlane32_swap_b32_e32 v227, v231
	v_permlane32_swap_b32_e32 v228, v232
	v_permlane32_swap_b32_e32 v229, v233
	v_add_f32_e32 v226, v226, v230
	v_add_f32_e32 v228, v228, v232
	v_add_f32_e32 v227, v227, v231
	v_add_f32_e32 v229, v229, v233
	s_nop 1
	v_permlane16_swap_b32_e32 v226, v228
	v_permlane16_swap_b32_e32 v227, v229
	v_add_f32_e32 v226, v226, v228
	v_add_f32_e32 v227, v227, v229
	s_nop 0
	v_cndmask_b32_e64 v230, v226, v227, s[24:25]
	v_cndmask_b32_e64 v231, v227, v226, s[24:25]
	s_nop 1
	v_add_f32_dpp v232, v231, v230 row_ror:8 row_mask:0xf bank_mask:0xf
	s_nop 1
	v_add_f32_dpp v233, v232, v232 quad_perm:[1,0,3,2] row_mask:0xf bank_mask:0xf
	s_nop 1
	v_add_f32_dpp v232, v233, v233 quad_perm:[2,3,0,1] row_mask:0xf bank_mask:0xf
	s_nop 1
	v_add_f32_dpp v233, v232, v232 row_half_mirror row_mask:0xf bank_mask:0xf
	ds_write_b32 v235, v233 offset:34816
	v_readlane_b32 s48, v140, s72
	v_readlane_b32 s49, v140, s73
	v_readlane_b32 s50, v140, s74
	v_readlane_b32 s51, v140, s75
	v_readlane_b32 s52, v140, s76
	v_readlane_b32 s53, v140, s77
	v_readlane_b32 s54, v140, s78
	v_readlane_b32 s55, v140, s79
	s_add_u32 s32, s0, s48
	s_addc_u32 s33, s1, 0
	s_add_u32 s34, s0, s49
	s_addc_u32 s35, s1, 0
	s_add_u32 s36, s0, s50
	s_addc_u32 s37, s1, 0
	s_add_u32 s38, s0, s51
	s_addc_u32 s39, s1, 0
	s_add_u32 s40, s0, s52
	s_addc_u32 s41, s1, 0
	s_add_u32 s42, s0, s53
	s_addc_u32 s43, s1, 0
	s_add_u32 s44, s0, s54
	s_addc_u32 s45, s1, 0
	s_add_u32 s46, s0, s55
	s_addc_u32 s47, s1, 0
	global_load_dwordx4 v[144:147], v234, s[32:33]
	global_load_dwordx4 v[148:151], v234, s[34:35]
	global_load_dwordx4 v[152:155], v234, s[36:37]
	global_load_dwordx4 v[156:159], v234, s[38:39]
	global_load_dwordx4 v[160:163], v234, s[40:41]
	global_load_dwordx4 v[164:167], v234, s[42:43]
	global_load_dwordx4 v[168:171], v234, s[44:45]
	global_load_dwordx4 v[172:175], v234, s[46:47]
	s_waitcnt vmcnt(8)
	v_cvt_pk_f32_fp8_e32 v[214:215], v176
	v_cvt_pk_f32_fp8_sdwa v[216:217], v176 src0_sel:WORD_1
	v_cvt_pk_f32_fp8_e32 v[218:219], v177
	v_cvt_pk_f32_fp8_sdwa v[220:221], v177 src0_sel:WORD_1
	v_pk_mul_f32 v[222:223], v[80:81], v[214:215]
	v_pk_mul_f32 v[224:225], v[82:83], v[216:217]
	v_cvt_pk_f32_fp8_e32 v[214:215], v178
	v_cvt_pk_f32_fp8_sdwa v[216:217], v178 src0_sel:WORD_1
	v_pk_fma_f32 v[222:223], v[84:85], v[218:219], v[222:223]
	v_pk_fma_f32 v[224:225], v[86:87], v[220:221], v[224:225]
	v_cvt_pk_f32_fp8_e32 v[218:219], v179
	v_cvt_pk_f32_fp8_sdwa v[220:221], v179 src0_sel:WORD_1
	v_pk_fma_f32 v[222:223], v[88:89], v[214:215], v[222:223]
	v_pk_fma_f32 v[224:225], v[90:91], v[216:217], v[224:225]
	v_pk_fma_f32 v[222:223], v[92:93], v[218:219], v[222:223]
	v_pk_fma_f32 v[224:225], v[94:95], v[220:221], v[224:225]
	v_pk_add_f32 v[222:223], v[222:223], v[224:225]
	s_nop 0
	v_add_f32_e32 v226, v222, v223
	v_cvt_pk_f32_fp8_e32 v[214:215], v180
	v_cvt_pk_f32_fp8_sdwa v[216:217], v180 src0_sel:WORD_1
	v_cvt_pk_f32_fp8_e32 v[218:219], v181
	v_cvt_pk_f32_fp8_sdwa v[220:221], v181 src0_sel:WORD_1
	v_pk_mul_f32 v[222:223], v[80:81], v[214:215]
	v_pk_mul_f32 v[224:225], v[82:83], v[216:217]
	v_cvt_pk_f32_fp8_e32 v[214:215], v182
	v_cvt_pk_f32_fp8_sdwa v[216:217], v182 src0_sel:WORD_1
	v_pk_fma_f32 v[222:223], v[84:85], v[218:219], v[222:223]
	v_pk_fma_f32 v[224:225], v[86:87], v[220:221], v[224:225]
	v_cvt_pk_f32_fp8_e32 v[218:219], v183
	v_cvt_pk_f32_fp8_sdwa v[220:221], v183 src0_sel:WORD_1
	v_pk_fma_f32 v[222:223], v[88:89], v[214:215], v[222:223]
	v_pk_fma_f32 v[224:225], v[90:91], v[216:217], v[224:225]
	v_pk_fma_f32 v[222:223], v[92:93], v[218:219], v[222:223]
	v_pk_fma_f32 v[224:225], v[94:95], v[220:221], v[224:225]
	v_pk_add_f32 v[222:223], v[222:223], v[224:225]
	s_nop 0
	v_add_f32_e32 v227, v222, v223
	v_cvt_pk_f32_fp8_e32 v[214:215], v184
	v_cvt_pk_f32_fp8_sdwa v[216:217], v184 src0_sel:WORD_1
	v_cvt_pk_f32_fp8_e32 v[218:219], v185
	v_cvt_pk_f32_fp8_sdwa v[220:221], v185 src0_sel:WORD_1
; template <bool STORE>
; DI void peer_item(const Params& p, int item, char* smem) {
;     ...
; #pragma unroll
;       for (int u = 0; u < 8; ++u) {
;         float d = 0.f;
; #pragma unroll
;         for (int i = 0; i < 4; ++i) {
;           f32x2_t lo = __builtin_amdgcn_cvt_pk_f32_fp8((int)uq[u][i], false);
;           f32x2_t hi = __builtin_amdgcn_cvt_pk_f32_fp8((int)uq[u][i], true);
;           d += xf[4 * i] * lo.x + xf[4 * i + 1] * lo.y + xf[4 * i + 2] * hi.x + xf[4 * i + 3] * hi.y;
;         }
;         part[u] = d;
;       }
;       float q4[4], r2[2], h;
; #pragma unroll
;       for (int j = 0; j < 4; ++j) {
;         float mine = b5 ? part[j + 4] : part[j];
;         float other = b5 ? part[j] : part[j + 4];
;         q4[j] = mine + __shfl_xor(other, 32);
;       }
; #pragma unroll
;       for (int j = 0; j < 2; ++j) {
;         float mine = b4 ? q4[j + 2] : q4[j];
;         float other = b4 ? q4[j] : q4[j + 2];
;         r2[j] = mine + __shfl_xor(other, 16);
;       }
;       {
;         float mine = b3 ? r2[1] : r2[0];
;         float other = b3 ? r2[0] : r2[1];
;         h = mine + __shfl_xor(other, 8);
;       }
;       h += __shfl_xor(h, 4);
;       h += __shfl_xor(h, 2);
;       h += __shfl_xor(h, 1);
	v_pk_mul_f32 v[222:223], v[80:81], v[214:215]
	v_pk_mul_f32 v[224:225], v[82:83], v[216:217]
	v_cvt_pk_f32_fp8_e32 v[214:215], v186
	v_cvt_pk_f32_fp8_sdwa v[216:217], v186 src0_sel:WORD_1
	v_pk_fma_f32 v[222:223], v[84:85], v[218:219], v[222:223]
	v_pk_fma_f32 v[224:225], v[86:87], v[220:221], v[224:225]
	v_cvt_pk_f32_fp8_e32 v[218:219], v187
	v_cvt_pk_f32_fp8_sdwa v[220:221], v187 src0_sel:WORD_1
	v_pk_fma_f32 v[222:223], v[88:89], v[214:215], v[222:223]
	v_pk_fma_f32 v[224:225], v[90:91], v[216:217], v[224:225]
	v_pk_fma_f32 v[222:223], v[92:93], v[218:219], v[222:223]
	v_pk_fma_f32 v[224:225], v[94:95], v[220:221], v[224:225]
	v_pk_add_f32 v[222:223], v[222:223], v[224:225]
	s_nop 0
	v_add_f32_e32 v228, v222, v223
	v_cvt_pk_f32_fp8_e32 v[214:215], v188
	v_cvt_pk_f32_fp8_sdwa v[216:217], v188 src0_sel:WORD_1
	v_cvt_pk_f32_fp8_e32 v[218:219], v189
	v_cvt_pk_f32_fp8_sdwa v[220:221], v189 src0_sel:WORD_1
	v_pk_mul_f32 v[222:223], v[80:81], v[214:215]
	v_pk_mul_f32 v[224:225], v[82:83], v[216:217]
	v_cvt_pk_f32_fp8_e32 v[214:215], v190
	v_cvt_pk_f32_fp8_sdwa v[216:217], v190 src0_sel:WORD_1
	v_pk_fma_f32 v[222:223], v[84:85], v[218:219], v[222:223]
	v_pk_fma_f32 v[224:225], v[86:87], v[220:221], v[224:225]
	v_cvt_pk_f32_fp8_e32 v[218:219], v191
	v_cvt_pk_f32_fp8_sdwa v[220:221], v191 src0_sel:WORD_1
	v_pk_fma_f32 v[222:223], v[88:89], v[214:215], v[222:223]
	v_pk_fma_f32 v[224:225], v[90:91], v[216:217], v[224:225]
	v_pk_fma_f32 v[222:223], v[92:93], v[218:219], v[222:223]
	v_pk_fma_f32 v[224:225], v[94:95], v[220:221], v[224:225]
	v_pk_add_f32 v[222:223], v[222:223], v[224:225]
	s_nop 0
	v_add_f32_e32 v229, v222, v223
	v_cvt_pk_f32_fp8_e32 v[214:215], v192
	v_cvt_pk_f32_fp8_sdwa v[216:217], v192 src0_sel:WORD_1
	v_cvt_pk_f32_fp8_e32 v[218:219], v193
	v_cvt_pk_f32_fp8_sdwa v[220:221], v193 src0_sel:WORD_1
	v_pk_mul_f32 v[222:223], v[80:81], v[214:215]
	v_pk_mul_f32 v[224:225], v[82:83], v[216:217]
	v_cvt_pk_f32_fp8_e32 v[214:215], v194
	v_cvt_pk_f32_fp8_sdwa v[216:217], v194 src0_sel:WORD_1
	v_pk_fma_f32 v[222:223], v[84:85], v[218:219], v[222:223]
	v_pk_fma_f32 v[224:225], v[86:87], v[220:221], v[224:225]
	v_cvt_pk_f32_fp8_e32 v[218:219], v195
	v_cvt_pk_f32_fp8_sdwa v[220:221], v195 src0_sel:WORD_1
	v_pk_fma_f32 v[222:223], v[88:89], v[214:215], v[222:223]
	v_pk_fma_f32 v[224:225], v[90:91], v[216:217], v[224:225]
	v_pk_fma_f32 v[222:223], v[92:93], v[218:219], v[222:223]
	v_pk_fma_f32 v[224:225], v[94:95], v[220:221], v[224:225]
	v_pk_add_f32 v[222:223], v[222:223], v[224:225]
	s_nop 0
	v_add_f32_e32 v230, v222, v223
	v_cvt_pk_f32_fp8_e32 v[214:215], v196
	v_cvt_pk_f32_fp8_sdwa v[216:217], v196 src0_sel:WORD_1
	v_cvt_pk_f32_fp8_e32 v[218:219], v197
	v_cvt_pk_f32_fp8_sdwa v[220:221], v197 src0_sel:WORD_1
	v_pk_mul_f32 v[222:223], v[80:81], v[214:215]
	v_pk_mul_f32 v[224:225], v[82:83], v[216:217]
	v_cvt_pk_f32_fp8_e32 v[214:215], v198
	v_cvt_pk_f32_fp8_sdwa v[216:217], v198 src0_sel:WORD_1
	v_pk_fma_f32 v[222:223], v[84:85], v[218:219], v[222:223]
	v_pk_fma_f32 v[224:225], v[86:87], v[220:221], v[224:225]
	v_cvt_pk_f32_fp8_e32 v[218:219], v199
	v_cvt_pk_f32_fp8_sdwa v[220:221], v199 src0_sel:WORD_1
	v_pk_fma_f32 v[222:223], v[88:89], v[214:215], v[222:223]
	v_pk_fma_f32 v[224:225], v[90:91], v[216:217], v[224:225]
	v_pk_fma_f32 v[222:223], v[92:93], v[218:219], v[222:223]
	v_pk_fma_f32 v[224:225], v[94:95], v[220:221], v[224:225]
	v_pk_add_f32 v[222:223], v[222:223], v[224:225]
	s_nop 0
	v_add_f32_e32 v231, v222, v223
	v_cvt_pk_f32_fp8_e32 v[214:215], v200
	v_cvt_pk_f32_fp8_sdwa v[216:217], v200 src0_sel:WORD_1
	v_cvt_pk_f32_fp8_e32 v[218:219], v201
	v_cvt_pk_f32_fp8_sdwa v[220:221], v201 src0_sel:WORD_1
	v_pk_mul_f32 v[222:223], v[80:81], v[214:215]
	v_pk_mul_f32 v[224:225], v[82:83], v[216:217]
	v_cvt_pk_f32_fp8_e32 v[214:215], v202
	v_cvt_pk_f32_fp8_sdwa v[216:217], v202 src0_sel:WORD_1
	v_pk_fma_f32 v[222:223], v[84:85], v[218:219], v[222:223]
	v_pk_fma_f32 v[224:225], v[86:87], v[220:221], v[224:225]
	v_cvt_pk_f32_fp8_e32 v[218:219], v203
	v_cvt_pk_f32_fp8_sdwa v[220:221], v203 src0_sel:WORD_1
	v_pk_fma_f32 v[222:223], v[88:89], v[214:215], v[222:223]
	v_pk_fma_f32 v[224:225], v[90:91], v[216:217], v[224:225]
	v_pk_fma_f32 v[222:223], v[92:93], v[218:219], v[222:223]
	v_pk_fma_f32 v[224:225], v[94:95], v[220:221], v[224:225]
	v_pk_add_f32 v[222:223], v[222:223], v[224:225]
	s_nop 0
	v_add_f32_e32 v232, v222, v223
	v_cvt_pk_f32_fp8_e32 v[214:215], v204
	v_cvt_pk_f32_fp8_sdwa v[216:217], v204 src0_sel:WORD_1
	v_cvt_pk_f32_fp8_e32 v[218:219], v205
	v_cvt_pk_f32_fp8_sdwa v[220:221], v205 src0_sel:WORD_1
	v_pk_mul_f32 v[222:223], v[80:81], v[214:215]
	v_pk_mul_f32 v[224:225], v[82:83], v[216:217]
	v_cvt_pk_f32_fp8_e32 v[214:215], v206
	v_cvt_pk_f32_fp8_sdwa v[216:217], v206 src0_sel:WORD_1
	v_pk_fma_f32 v[222:223], v[84:85], v[218:219], v[222:223]
	v_pk_fma_f32 v[224:225], v[86:87], v[220:221], v[224:225]
	v_cvt_pk_f32_fp8_e32 v[218:219], v207
	v_cvt_pk_f32_fp8_sdwa v[220:221], v207 src0_sel:WORD_1
	v_pk_fma_f32 v[222:223], v[88:89], v[214:215], v[222:223]
	v_pk_fma_f32 v[224:225], v[90:91], v[216:217], v[224:225]
	v_pk_fma_f32 v[222:223], v[92:93], v[218:219], v[222:223]
	v_pk_fma_f32 v[224:225], v[94:95], v[220:221], v[224:225]
	v_pk_add_f32 v[222:223], v[222:223], v[224:225]
	s_nop 0
	v_add_f32_e32 v233, v222, v223
	v_permlane32_swap_b32_e32 v226, v230
	v_permlane32_swap_b32_e32 v227, v231
	v_permlane32_swap_b32_e32 v228, v232
	v_permlane32_swap_b32_e32 v229, v233
	v_add_f32_e32 v226, v226, v230
	v_add_f32_e32 v228, v228, v232
	v_add_f32_e32 v227, v227, v231
	v_add_f32_e32 v229, v229, v233
	s_nop 1
	v_permlane16_swap_b32_e32 v226, v228
; template <bool STORE>
; DI void peer_item(const Params& p, int item, char* smem) {
;     ...
; #pragma unroll
;       for (int u = 0; u < 8; ++u) {
;         float d = 0.f;
; #pragma unroll
;         for (int i = 0; i < 4; ++i) {
;           f32x2_t lo = __builtin_amdgcn_cvt_pk_f32_fp8((int)uq[u][i], false);
;           f32x2_t hi = __builtin_amdgcn_cvt_pk_f32_fp8((int)uq[u][i], true);
;           d += xf[4 * i] * lo.x + xf[4 * i + 1] * lo.y + xf[4 * i + 2] * hi.x + xf[4 * i + 3] * hi.y;
;         }
;         part[u] = d;
;       }
;       float q4[4], r2[2], h;
; #pragma unroll
;       for (int j = 0; j < 4; ++j) {
;         float mine = b5 ? part[j + 4] : part[j];
;         float other = b5 ? part[j] : part[j + 4];
;         q4[j] = mine + __shfl_xor(other, 32);
;       }
; #pragma unroll
;       for (int j = 0; j < 2; ++j) {
;         float mine = b4 ? q4[j + 2] : q4[j];
;         float other = b4 ? q4[j] : q4[j + 2];
;         r2[j] = mine + __shfl_xor(other, 16);
;       }
;       {
;         float mine = b3 ? r2[1] : r2[0];
;         float other = b3 ? r2[0] : r2[1];
;         h = mine + __shfl_xor(other, 8);
;       }
;       h += __shfl_xor(h, 4);
;       h += __shfl_xor(h, 2);
;       h += __shfl_xor(h, 1);
	v_permlane16_swap_b32_e32 v227, v229
	v_add_f32_e32 v226, v226, v228
	v_add_f32_e32 v227, v227, v229
	s_nop 0
	v_cndmask_b32_e64 v230, v226, v227, s[24:25]
	v_cndmask_b32_e64 v231, v227, v226, s[24:25]
	s_nop 1
	v_add_f32_dpp v232, v231, v230 row_ror:8 row_mask:0xf bank_mask:0xf
	s_nop 1
	v_add_f32_dpp v233, v232, v232 quad_perm:[1,0,3,2] row_mask:0xf bank_mask:0xf
	s_nop 1
	v_add_f32_dpp v232, v233, v233 quad_perm:[2,3,0,1] row_mask:0xf bank_mask:0xf
	s_nop 1
	v_add_f32_dpp v233, v232, v232 row_half_mirror row_mask:0xf bank_mask:0xf
	ds_write_b32 v235, v233 offset:35328
	v_readlane_b32 s48, v142, s72
	v_readlane_b32 s49, v142, s73
	v_readlane_b32 s50, v142, s74
	v_readlane_b32 s51, v142, s75
	v_readlane_b32 s52, v142, s76
	v_readlane_b32 s53, v142, s77
	v_readlane_b32 s54, v142, s78
	v_readlane_b32 s55, v142, s79
	s_add_u32 s32, s0, s48
	s_addc_u32 s33, s1, 0
	s_add_u32 s34, s0, s49
	s_addc_u32 s35, s1, 0
	s_add_u32 s36, s0, s50
	s_addc_u32 s37, s1, 0
	s_add_u32 s38, s0, s51
	s_addc_u32 s39, s1, 0
	s_add_u32 s40, s0, s52
	s_addc_u32 s41, s1, 0
	s_add_u32 s42, s0, s53
	s_addc_u32 s43, s1, 0
	s_add_u32 s44, s0, s54
	s_addc_u32 s45, s1, 0
	s_add_u32 s46, s0, s55
	s_addc_u32 s47, s1, 0
	global_load_dwordx4 v[176:179], v234, s[32:33]
	global_load_dwordx4 v[180:183], v234, s[34:35]
	global_load_dwordx4 v[184:187], v234, s[36:37]
	global_load_dwordx4 v[188:191], v234, s[38:39]
	global_load_dwordx4 v[192:195], v234, s[40:41]
	global_load_dwordx4 v[196:199], v234, s[42:43]
	global_load_dwordx4 v[200:203], v234, s[44:45]
	global_load_dwordx4 v[204:207], v234, s[46:47]
	s_waitcnt vmcnt(8)
	v_cvt_pk_f32_fp8_e32 v[214:215], v144
	v_cvt_pk_f32_fp8_sdwa v[216:217], v144 src0_sel:WORD_1
	v_cvt_pk_f32_fp8_e32 v[218:219], v145
	v_cvt_pk_f32_fp8_sdwa v[220:221], v145 src0_sel:WORD_1
	v_pk_mul_f32 v[222:223], v[96:97], v[214:215]
	v_pk_mul_f32 v[224:225], v[98:99], v[216:217]
	v_cvt_pk_f32_fp8_e32 v[214:215], v146
	v_cvt_pk_f32_fp8_sdwa v[216:217], v146 src0_sel:WORD_1
	v_pk_fma_f32 v[222:223], v[100:101], v[218:219], v[222:223]
	v_pk_fma_f32 v[224:225], v[102:103], v[220:221], v[224:225]
	v_cvt_pk_f32_fp8_e32 v[218:219], v147
	v_cvt_pk_f32_fp8_sdwa v[220:221], v147 src0_sel:WORD_1
	v_pk_fma_f32 v[222:223], v[104:105], v[214:215], v[222:223]
	v_pk_fma_f32 v[224:225], v[106:107], v[216:217], v[224:225]
	v_pk_fma_f32 v[222:223], v[108:109], v[218:219], v[222:223]
	v_pk_fma_f32 v[224:225], v[110:111], v[220:221], v[224:225]
	v_pk_add_f32 v[222:223], v[222:223], v[224:225]
	s_nop 0
	v_add_f32_e32 v226, v222, v223
	v_cvt_pk_f32_fp8_e32 v[214:215], v148
	v_cvt_pk_f32_fp8_sdwa v[216:217], v148 src0_sel:WORD_1
	v_cvt_pk_f32_fp8_e32 v[218:219], v149
	v_cvt_pk_f32_fp8_sdwa v[220:221], v149 src0_sel:WORD_1
	v_pk_mul_f32 v[222:223], v[96:97], v[214:215]
	v_pk_mul_f32 v[224:225], v[98:99], v[216:217]
	v_cvt_pk_f32_fp8_e32 v[214:215], v150
	v_cvt_pk_f32_fp8_sdwa v[216:217], v150 src0_sel:WORD_1
	v_pk_fma_f32 v[222:223], v[100:101], v[218:219], v[222:223]
	v_pk_fma_f32 v[224:225], v[102:103], v[220:221], v[224:225]
	v_cvt_pk_f32_fp8_e32 v[218:219], v151
	v_cvt_pk_f32_fp8_sdwa v[220:221], v151 src0_sel:WORD_1
	v_pk_fma_f32 v[222:223], v[104:105], v[214:215], v[222:223]
	v_pk_fma_f32 v[224:225], v[106:107], v[216:217], v[224:225]
	v_pk_fma_f32 v[222:223], v[108:109], v[218:219], v[222:223]
	v_pk_fma_f32 v[224:225], v[110:111], v[220:221], v[224:225]
	v_pk_add_f32 v[222:223], v[222:223], v[224:225]
	s_nop 0
	v_add_f32_e32 v227, v222, v223
	v_cvt_pk_f32_fp8_e32 v[214:215], v152
	v_cvt_pk_f32_fp8_sdwa v[216:217], v152 src0_sel:WORD_1
	v_cvt_pk_f32_fp8_e32 v[218:219], v153
	v_cvt_pk_f32_fp8_sdwa v[220:221], v153 src0_sel:WORD_1
	v_pk_mul_f32 v[222:223], v[96:97], v[214:215]
	v_pk_mul_f32 v[224:225], v[98:99], v[216:217]
	v_cvt_pk_f32_fp8_e32 v[214:215], v154
	v_cvt_pk_f32_fp8_sdwa v[216:217], v154 src0_sel:WORD_1
	v_pk_fma_f32 v[222:223], v[100:101], v[218:219], v[222:223]
	v_pk_fma_f32 v[224:225], v[102:103], v[220:221], v[224:225]
	v_cvt_pk_f32_fp8_e32 v[218:219], v155
	v_cvt_pk_f32_fp8_sdwa v[220:221], v155 src0_sel:WORD_1
	v_pk_fma_f32 v[222:223], v[104:105], v[214:215], v[222:223]
	v_pk_fma_f32 v[224:225], v[106:107], v[216:217], v[224:225]
	v_pk_fma_f32 v[222:223], v[108:109], v[218:219], v[222:223]
	v_pk_fma_f32 v[224:225], v[110:111], v[220:221], v[224:225]
	v_pk_add_f32 v[222:223], v[222:223], v[224:225]
	s_nop 0
	v_add_f32_e32 v228, v222, v223
	v_cvt_pk_f32_fp8_e32 v[214:215], v156
	v_cvt_pk_f32_fp8_sdwa v[216:217], v156 src0_sel:WORD_1
	v_cvt_pk_f32_fp8_e32 v[218:219], v157
	v_cvt_pk_f32_fp8_sdwa v[220:221], v157 src0_sel:WORD_1
	v_pk_mul_f32 v[222:223], v[96:97], v[214:215]
	v_pk_mul_f32 v[224:225], v[98:99], v[216:217]
	v_cvt_pk_f32_fp8_e32 v[214:215], v158
	v_cvt_pk_f32_fp8_sdwa v[216:217], v158 src0_sel:WORD_1
	v_pk_fma_f32 v[222:223], v[100:101], v[218:219], v[222:223]
	v_pk_fma_f32 v[224:225], v[102:103], v[220:221], v[224:225]
	v_cvt_pk_f32_fp8_e32 v[218:219], v159
	v_cvt_pk_f32_fp8_sdwa v[220:221], v159 src0_sel:WORD_1
	v_pk_fma_f32 v[222:223], v[104:105], v[214:215], v[222:223]
	v_pk_fma_f32 v[224:225], v[106:107], v[216:217], v[224:225]
	v_pk_fma_f32 v[222:223], v[108:109], v[218:219], v[222:223]
	v_pk_fma_f32 v[224:225], v[110:111], v[220:221], v[224:225]
	v_pk_add_f32 v[222:223], v[222:223], v[224:225]
	s_nop 0
	v_add_f32_e32 v229, v222, v223
	v_cvt_pk_f32_fp8_e32 v[214:215], v160
	v_cvt_pk_f32_fp8_sdwa v[216:217], v160 src0_sel:WORD_1
	v_cvt_pk_f32_fp8_e32 v[218:219], v161
	v_cvt_pk_f32_fp8_sdwa v[220:221], v161 src0_sel:WORD_1
	v_pk_mul_f32 v[222:223], v[96:97], v[214:215]
	v_pk_mul_f32 v[224:225], v[98:99], v[216:217]
	v_cvt_pk_f32_fp8_e32 v[214:215], v162
; template <bool STORE>
; DI void peer_item(const Params& p, int item, char* smem) {
;     ...
; #pragma unroll
;       for (int u = 0; u < 8; ++u) {
;         float d = 0.f;
; #pragma unroll
;         for (int i = 0; i < 4; ++i) {
;           f32x2_t lo = __builtin_amdgcn_cvt_pk_f32_fp8((int)uq[u][i], false);
;           f32x2_t hi = __builtin_amdgcn_cvt_pk_f32_fp8((int)uq[u][i], true);
;           d += xf[4 * i] * lo.x + xf[4 * i + 1] * lo.y + xf[4 * i + 2] * hi.x + xf[4 * i + 3] * hi.y;
;         }
;         part[u] = d;
;       }
;       float q4[4], r2[2], h;
; #pragma unroll
;       for (int j = 0; j < 4; ++j) {
;         float mine = b5 ? part[j + 4] : part[j];
;         float other = b5 ? part[j] : part[j + 4];
;         q4[j] = mine + __shfl_xor(other, 32);
;       }
; #pragma unroll
;       for (int j = 0; j < 2; ++j) {
;         float mine = b4 ? q4[j + 2] : q4[j];
;         float other = b4 ? q4[j] : q4[j + 2];
;         r2[j] = mine + __shfl_xor(other, 16);
;       }
;       {
;         float mine = b3 ? r2[1] : r2[0];
;         float other = b3 ? r2[0] : r2[1];
;         h = mine + __shfl_xor(other, 8);
;       }
;       h += __shfl_xor(h, 4);
;       h += __shfl_xor(h, 2);
;       h += __shfl_xor(h, 1);
	v_cvt_pk_f32_fp8_sdwa v[216:217], v162 src0_sel:WORD_1
	v_pk_fma_f32 v[222:223], v[100:101], v[218:219], v[222:223]
	v_pk_fma_f32 v[224:225], v[102:103], v[220:221], v[224:225]
	v_cvt_pk_f32_fp8_e32 v[218:219], v163
	v_cvt_pk_f32_fp8_sdwa v[220:221], v163 src0_sel:WORD_1
	v_pk_fma_f32 v[222:223], v[104:105], v[214:215], v[222:223]
	v_pk_fma_f32 v[224:225], v[106:107], v[216:217], v[224:225]
	v_pk_fma_f32 v[222:223], v[108:109], v[218:219], v[222:223]
	v_pk_fma_f32 v[224:225], v[110:111], v[220:221], v[224:225]
	v_pk_add_f32 v[222:223], v[222:223], v[224:225]
	s_nop 0
	v_add_f32_e32 v230, v222, v223
	v_cvt_pk_f32_fp8_e32 v[214:215], v164
	v_cvt_pk_f32_fp8_sdwa v[216:217], v164 src0_sel:WORD_1
	v_cvt_pk_f32_fp8_e32 v[218:219], v165
	v_cvt_pk_f32_fp8_sdwa v[220:221], v165 src0_sel:WORD_1
	v_pk_mul_f32 v[222:223], v[96:97], v[214:215]
	v_pk_mul_f32 v[224:225], v[98:99], v[216:217]
	v_cvt_pk_f32_fp8_e32 v[214:215], v166
	v_cvt_pk_f32_fp8_sdwa v[216:217], v166 src0_sel:WORD_1
	v_pk_fma_f32 v[222:223], v[100:101], v[218:219], v[222:223]
	v_pk_fma_f32 v[224:225], v[102:103], v[220:221], v[224:225]
	v_cvt_pk_f32_fp8_e32 v[218:219], v167
	v_cvt_pk_f32_fp8_sdwa v[220:221], v167 src0_sel:WORD_1
	v_pk_fma_f32 v[222:223], v[104:105], v[214:215], v[222:223]
	v_pk_fma_f32 v[224:225], v[106:107], v[216:217], v[224:225]
	v_pk_fma_f32 v[222:223], v[108:109], v[218:219], v[222:223]
	v_pk_fma_f32 v[224:225], v[110:111], v[220:221], v[224:225]
	v_pk_add_f32 v[222:223], v[222:223], v[224:225]
	s_nop 0
	v_add_f32_e32 v231, v222, v223
	v_cvt_pk_f32_fp8_e32 v[214:215], v168
	v_cvt_pk_f32_fp8_sdwa v[216:217], v168 src0_sel:WORD_1
	v_cvt_pk_f32_fp8_e32 v[218:219], v169
	v_cvt_pk_f32_fp8_sdwa v[220:221], v169 src0_sel:WORD_1
	v_pk_mul_f32 v[222:223], v[96:97], v[214:215]
	v_pk_mul_f32 v[224:225], v[98:99], v[216:217]
	v_cvt_pk_f32_fp8_e32 v[214:215], v170
	v_cvt_pk_f32_fp8_sdwa v[216:217], v170 src0_sel:WORD_1
	v_pk_fma_f32 v[222:223], v[100:101], v[218:219], v[222:223]
	v_pk_fma_f32 v[224:225], v[102:103], v[220:221], v[224:225]
	v_cvt_pk_f32_fp8_e32 v[218:219], v171
	v_cvt_pk_f32_fp8_sdwa v[220:221], v171 src0_sel:WORD_1
	v_pk_fma_f32 v[222:223], v[104:105], v[214:215], v[222:223]
	v_pk_fma_f32 v[224:225], v[106:107], v[216:217], v[224:225]
	v_pk_fma_f32 v[222:223], v[108:109], v[218:219], v[222:223]
	v_pk_fma_f32 v[224:225], v[110:111], v[220:221], v[224:225]
	v_pk_add_f32 v[222:223], v[222:223], v[224:225]
	s_nop 0
	v_add_f32_e32 v232, v222, v223
	v_cvt_pk_f32_fp8_e32 v[214:215], v172
	v_cvt_pk_f32_fp8_sdwa v[216:217], v172 src0_sel:WORD_1
	v_cvt_pk_f32_fp8_e32 v[218:219], v173
	v_cvt_pk_f32_fp8_sdwa v[220:221], v173 src0_sel:WORD_1
	v_pk_mul_f32 v[222:223], v[96:97], v[214:215]
	v_pk_mul_f32 v[224:225], v[98:99], v[216:217]
	v_cvt_pk_f32_fp8_e32 v[214:215], v174
	v_cvt_pk_f32_fp8_sdwa v[216:217], v174 src0_sel:WORD_1
	v_pk_fma_f32 v[222:223], v[100:101], v[218:219], v[222:223]
	v_pk_fma_f32 v[224:225], v[102:103], v[220:221], v[224:225]
	v_cvt_pk_f32_fp8_e32 v[218:219], v175
	v_cvt_pk_f32_fp8_sdwa v[220:221], v175 src0_sel:WORD_1
	v_pk_fma_f32 v[222:223], v[104:105], v[214:215], v[222:223]
	v_pk_fma_f32 v[224:225], v[106:107], v[216:217], v[224:225]
	v_pk_fma_f32 v[222:223], v[108:109], v[218:219], v[222:223]
	v_pk_fma_f32 v[224:225], v[110:111], v[220:221], v[224:225]
	v_pk_add_f32 v[222:223], v[222:223], v[224:225]
	s_nop 0
	v_add_f32_e32 v233, v222, v223
	v_permlane32_swap_b32_e32 v226, v230
	v_permlane32_swap_b32_e32 v227, v231
	v_permlane32_swap_b32_e32 v228, v232
	v_permlane32_swap_b32_e32 v229, v233
	v_add_f32_e32 v226, v226, v230
	v_add_f32_e32 v228, v228, v232
	v_add_f32_e32 v227, v227, v231
	v_add_f32_e32 v229, v229, v233
	s_nop 1
	v_permlane16_swap_b32_e32 v226, v228
	v_permlane16_swap_b32_e32 v227, v229
	v_add_f32_e32 v226, v226, v228
	v_add_f32_e32 v227, v227, v229
	s_nop 0
	v_cndmask_b32_e64 v230, v226, v227, s[24:25]
	v_cndmask_b32_e64 v231, v227, v226, s[24:25]
	s_nop 1
	v_add_f32_dpp v232, v231, v230 row_ror:8 row_mask:0xf bank_mask:0xf
	s_nop 1
	v_add_f32_dpp v233, v232, v232 quad_perm:[1,0,3,2] row_mask:0xf bank_mask:0xf
	s_nop 1
	v_add_f32_dpp v232, v233, v233 quad_perm:[2,3,0,1] row_mask:0xf bank_mask:0xf
	s_nop 1
	v_add_f32_dpp v233, v232, v232 row_half_mirror row_mask:0xf bank_mask:0xf
	ds_write_b32 v235, v233 offset:35840
	v_readlane_b32 s48, v129, s72
	v_readlane_b32 s49, v129, s73
	v_readlane_b32 s50, v129, s74
	v_readlane_b32 s51, v129, s75
	v_readlane_b32 s52, v129, s76
	v_readlane_b32 s53, v129, s77
	v_readlane_b32 s54, v129, s78
	v_readlane_b32 s55, v129, s79
	s_add_u32 s32, s0, s48
	s_addc_u32 s33, s1, 0
	s_add_u32 s34, s0, s49
	s_addc_u32 s35, s1, 0
	s_add_u32 s36, s0, s50
	s_addc_u32 s37, s1, 0
	s_add_u32 s38, s0, s51
	s_addc_u32 s39, s1, 0
	s_add_u32 s40, s0, s52
	s_addc_u32 s41, s1, 0
	s_add_u32 s42, s0, s53
	s_addc_u32 s43, s1, 0
	s_add_u32 s44, s0, s54
	s_addc_u32 s45, s1, 0
	s_add_u32 s46, s0, s55
	s_addc_u32 s47, s1, 0
	global_load_dwordx4 v[144:147], v234, s[32:33]
	global_load_dwordx4 v[148:151], v234, s[34:35]
	global_load_dwordx4 v[152:155], v234, s[36:37]
	global_load_dwordx4 v[156:159], v234, s[38:39]
	global_load_dwordx4 v[160:163], v234, s[40:41]
	global_load_dwordx4 v[164:167], v234, s[42:43]
	global_load_dwordx4 v[168:171], v234, s[44:45]
	global_load_dwordx4 v[172:175], v234, s[46:47]
	s_waitcnt vmcnt(8)
; template <bool STORE>
; DI void peer_item(const Params& p, int item, char* smem) {
;     ...
; #pragma unroll
;       for (int u = 0; u < 8; ++u) {
;         float d = 0.f;
; #pragma unroll
;         for (int i = 0; i < 4; ++i) {
;           f32x2_t lo = __builtin_amdgcn_cvt_pk_f32_fp8((int)uq[u][i], false);
;           f32x2_t hi = __builtin_amdgcn_cvt_pk_f32_fp8((int)uq[u][i], true);
;           d += xf[4 * i] * lo.x + xf[4 * i + 1] * lo.y + xf[4 * i + 2] * hi.x + xf[4 * i + 3] * hi.y;
;         }
;         part[u] = d;
;       }
	v_cvt_pk_f32_fp8_e32 v[214:215], v176
	v_cvt_pk_f32_fp8_sdwa v[216:217], v176 src0_sel:WORD_1
	v_cvt_pk_f32_fp8_e32 v[218:219], v177
	v_cvt_pk_f32_fp8_sdwa v[220:221], v177 src0_sel:WORD_1
	v_pk_mul_f32 v[222:223], v[112:113], v[214:215]
	v_pk_mul_f32 v[224:225], v[114:115], v[216:217]
	v_cvt_pk_f32_fp8_e32 v[214:215], v178
	v_cvt_pk_f32_fp8_sdwa v[216:217], v178 src0_sel:WORD_1
	v_pk_fma_f32 v[222:223], v[116:117], v[218:219], v[222:223]
	v_pk_fma_f32 v[224:225], v[118:119], v[220:221], v[224:225]
	v_cvt_pk_f32_fp8_e32 v[218:219], v179
	v_cvt_pk_f32_fp8_sdwa v[220:221], v179 src0_sel:WORD_1
	v_pk_fma_f32 v[222:223], v[120:121], v[214:215], v[222:223]
	v_pk_fma_f32 v[224:225], v[122:123], v[216:217], v[224:225]
	v_pk_fma_f32 v[222:223], v[124:125], v[218:219], v[222:223]
	v_pk_fma_f32 v[224:225], v[126:127], v[220:221], v[224:225]
	v_pk_add_f32 v[222:223], v[222:223], v[224:225]
	s_nop 0
	v_add_f32_e32 v226, v222, v223
	v_cvt_pk_f32_fp8_e32 v[214:215], v180
	v_cvt_pk_f32_fp8_sdwa v[216:217], v180 src0_sel:WORD_1
	v_cvt_pk_f32_fp8_e32 v[218:219], v181
	v_cvt_pk_f32_fp8_sdwa v[220:221], v181 src0_sel:WORD_1
	v_pk_mul_f32 v[222:223], v[112:113], v[214:215]
	v_pk_mul_f32 v[224:225], v[114:115], v[216:217]
	v_cvt_pk_f32_fp8_e32 v[214:215], v182
	v_cvt_pk_f32_fp8_sdwa v[216:217], v182 src0_sel:WORD_1
	v_pk_fma_f32 v[222:223], v[116:117], v[218:219], v[222:223]
	v_pk_fma_f32 v[224:225], v[118:119], v[220:221], v[224:225]
	v_cvt_pk_f32_fp8_e32 v[218:219], v183
	v_cvt_pk_f32_fp8_sdwa v[220:221], v183 src0_sel:WORD_1
	v_pk_fma_f32 v[222:223], v[120:121], v[214:215], v[222:223]
	v_pk_fma_f32 v[224:225], v[122:123], v[216:217], v[224:225]
	v_pk_fma_f32 v[222:223], v[124:125], v[218:219], v[222:223]
	v_pk_fma_f32 v[224:225], v[126:127], v[220:221], v[224:225]
	v_pk_add_f32 v[222:223], v[222:223], v[224:225]
	s_nop 0
	v_add_f32_e32 v227, v222, v223
	v_cvt_pk_f32_fp8_e32 v[214:215], v184
	v_cvt_pk_f32_fp8_sdwa v[216:217], v184 src0_sel:WORD_1
	v_cvt_pk_f32_fp8_e32 v[218:219], v185
	v_cvt_pk_f32_fp8_sdwa v[220:221], v185 src0_sel:WORD_1
	v_pk_mul_f32 v[222:223], v[112:113], v[214:215]
	v_pk_mul_f32 v[224:225], v[114:115], v[216:217]
	v_cvt_pk_f32_fp8_e32 v[214:215], v186
	v_cvt_pk_f32_fp8_sdwa v[216:217], v186 src0_sel:WORD_1
	v_pk_fma_f32 v[222:223], v[116:117], v[218:219], v[222:223]
	v_pk_fma_f32 v[224:225], v[118:119], v[220:221], v[224:225]
	v_cvt_pk_f32_fp8_e32 v[218:219], v187
	v_cvt_pk_f32_fp8_sdwa v[220:221], v187 src0_sel:WORD_1
	v_pk_fma_f32 v[222:223], v[120:121], v[214:215], v[222:223]
	v_pk_fma_f32 v[224:225], v[122:123], v[216:217], v[224:225]
	v_pk_fma_f32 v[222:223], v[124:125], v[218:219], v[222:223]
	v_pk_fma_f32 v[224:225], v[126:127], v[220:221], v[224:225]
	v_pk_add_f32 v[222:223], v[222:223], v[224:225]
	s_nop 0
	v_add_f32_e32 v228, v222, v223
	v_cvt_pk_f32_fp8_e32 v[214:215], v188
	v_cvt_pk_f32_fp8_sdwa v[216:217], v188 src0_sel:WORD_1
	v_cvt_pk_f32_fp8_e32 v[218:219], v189
	v_cvt_pk_f32_fp8_sdwa v[220:221], v189 src0_sel:WORD_1
	v_pk_mul_f32 v[222:223], v[112:113], v[214:215]
	v_pk_mul_f32 v[224:225], v[114:115], v[216:217]
	v_cvt_pk_f32_fp8_e32 v[214:215], v190
	v_cvt_pk_f32_fp8_sdwa v[216:217], v190 src0_sel:WORD_1
	v_pk_fma_f32 v[222:223], v[116:117], v[218:219], v[222:223]
	v_pk_fma_f32 v[224:225], v[118:119], v[220:221], v[224:225]
	v_cvt_pk_f32_fp8_e32 v[218:219], v191
	v_cvt_pk_f32_fp8_sdwa v[220:221], v191 src0_sel:WORD_1
	v_pk_fma_f32 v[222:223], v[120:121], v[214:215], v[222:223]
	v_pk_fma_f32 v[224:225], v[122:123], v[216:217], v[224:225]
	v_pk_fma_f32 v[222:223], v[124:125], v[218:219], v[222:223]
	v_pk_fma_f32 v[224:225], v[126:127], v[220:221], v[224:225]
	v_pk_add_f32 v[222:223], v[222:223], v[224:225]
	s_nop 0
	v_add_f32_e32 v229, v222, v223
	v_cvt_pk_f32_fp8_e32 v[214:215], v192
	v_cvt_pk_f32_fp8_sdwa v[216:217], v192 src0_sel:WORD_1
	v_cvt_pk_f32_fp8_e32 v[218:219], v193
	v_cvt_pk_f32_fp8_sdwa v[220:221], v193 src0_sel:WORD_1
	v_pk_mul_f32 v[222:223], v[112:113], v[214:215]
	v_pk_mul_f32 v[224:225], v[114:115], v[216:217]
	v_cvt_pk_f32_fp8_e32 v[214:215], v194
	v_cvt_pk_f32_fp8_sdwa v[216:217], v194 src0_sel:WORD_1
	v_pk_fma_f32 v[222:223], v[116:117], v[218:219], v[222:223]
	v_pk_fma_f32 v[224:225], v[118:119], v[220:221], v[224:225]
	v_cvt_pk_f32_fp8_e32 v[218:219], v195
	v_cvt_pk_f32_fp8_sdwa v[220:221], v195 src0_sel:WORD_1
	v_pk_fma_f32 v[222:223], v[120:121], v[214:215], v[222:223]
	v_pk_fma_f32 v[224:225], v[122:123], v[216:217], v[224:225]
	v_pk_fma_f32 v[222:223], v[124:125], v[218:219], v[222:223]
	v_pk_fma_f32 v[224:225], v[126:127], v[220:221], v[224:225]
	v_pk_add_f32 v[222:223], v[222:223], v[224:225]
	s_nop 0
	v_add_f32_e32 v230, v222, v223
	v_cvt_pk_f32_fp8_e32 v[214:215], v196
	v_cvt_pk_f32_fp8_sdwa v[216:217], v196 src0_sel:WORD_1
	v_cvt_pk_f32_fp8_e32 v[218:219], v197
	v_cvt_pk_f32_fp8_sdwa v[220:221], v197 src0_sel:WORD_1
	v_pk_mul_f32 v[222:223], v[112:113], v[214:215]
	v_pk_mul_f32 v[224:225], v[114:115], v[216:217]
	v_cvt_pk_f32_fp8_e32 v[214:215], v198
	v_cvt_pk_f32_fp8_sdwa v[216:217], v198 src0_sel:WORD_1
	v_pk_fma_f32 v[222:223], v[116:117], v[218:219], v[222:223]
	v_pk_fma_f32 v[224:225], v[118:119], v[220:221], v[224:225]
	v_cvt_pk_f32_fp8_e32 v[218:219], v199
	v_cvt_pk_f32_fp8_sdwa v[220:221], v199 src0_sel:WORD_1
	v_pk_fma_f32 v[222:223], v[120:121], v[214:215], v[222:223]
	v_pk_fma_f32 v[224:225], v[122:123], v[216:217], v[224:225]
	v_pk_fma_f32 v[222:223], v[124:125], v[218:219], v[222:223]
	v_pk_fma_f32 v[224:225], v[126:127], v[220:221], v[224:225]
	v_pk_add_f32 v[222:223], v[222:223], v[224:225]
	s_nop 0
	v_add_f32_e32 v231, v222, v223
	v_cvt_pk_f32_fp8_e32 v[214:215], v200
; template <bool STORE>
; DI void peer_item(const Params& p, int item, char* smem) {
;     ...
; #pragma unroll
;       for (int u = 0; u < 8; ++u) {
;         float d = 0.f;
; #pragma unroll
;         for (int i = 0; i < 4; ++i) {
;           f32x2_t lo = __builtin_amdgcn_cvt_pk_f32_fp8((int)uq[u][i], false);
;           f32x2_t hi = __builtin_amdgcn_cvt_pk_f32_fp8((int)uq[u][i], true);
;           d += xf[4 * i] * lo.x + xf[4 * i + 1] * lo.y + xf[4 * i + 2] * hi.x + xf[4 * i + 3] * hi.y;
;         }
;         part[u] = d;
;       }
;       float q4[4], r2[2], h;
; #pragma unroll
;       for (int j = 0; j < 4; ++j) {
;         float mine = b5 ? part[j + 4] : part[j];
;         float other = b5 ? part[j] : part[j + 4];
;         q4[j] = mine + __shfl_xor(other, 32);
;       }
; #pragma unroll
;       for (int j = 0; j < 2; ++j) {
;         float mine = b4 ? q4[j + 2] : q4[j];
;         float other = b4 ? q4[j] : q4[j + 2];
;         r2[j] = mine + __shfl_xor(other, 16);
;       }
;       {
;         float mine = b3 ? r2[1] : r2[0];
;         float other = b3 ? r2[0] : r2[1];
;         h = mine + __shfl_xor(other, 8);
;       }
;       h += __shfl_xor(h, 4);
;       h += __shfl_xor(h, 2);
;       h += __shfl_xor(h, 1);
	v_cvt_pk_f32_fp8_sdwa v[216:217], v200 src0_sel:WORD_1
	v_cvt_pk_f32_fp8_e32 v[218:219], v201
	v_cvt_pk_f32_fp8_sdwa v[220:221], v201 src0_sel:WORD_1
	v_pk_mul_f32 v[222:223], v[112:113], v[214:215]
	v_pk_mul_f32 v[224:225], v[114:115], v[216:217]
	v_cvt_pk_f32_fp8_e32 v[214:215], v202
	v_cvt_pk_f32_fp8_sdwa v[216:217], v202 src0_sel:WORD_1
	v_pk_fma_f32 v[222:223], v[116:117], v[218:219], v[222:223]
	v_pk_fma_f32 v[224:225], v[118:119], v[220:221], v[224:225]
	v_cvt_pk_f32_fp8_e32 v[218:219], v203
	v_cvt_pk_f32_fp8_sdwa v[220:221], v203 src0_sel:WORD_1
	v_pk_fma_f32 v[222:223], v[120:121], v[214:215], v[222:223]
	v_pk_fma_f32 v[224:225], v[122:123], v[216:217], v[224:225]
	v_pk_fma_f32 v[222:223], v[124:125], v[218:219], v[222:223]
	v_pk_fma_f32 v[224:225], v[126:127], v[220:221], v[224:225]
	v_pk_add_f32 v[222:223], v[222:223], v[224:225]
	s_nop 0
	v_add_f32_e32 v232, v222, v223
	v_cvt_pk_f32_fp8_e32 v[214:215], v204
	v_cvt_pk_f32_fp8_sdwa v[216:217], v204 src0_sel:WORD_1
	v_cvt_pk_f32_fp8_e32 v[218:219], v205
	v_cvt_pk_f32_fp8_sdwa v[220:221], v205 src0_sel:WORD_1
	v_pk_mul_f32 v[222:223], v[112:113], v[214:215]
	v_pk_mul_f32 v[224:225], v[114:115], v[216:217]
	v_cvt_pk_f32_fp8_e32 v[214:215], v206
	v_cvt_pk_f32_fp8_sdwa v[216:217], v206 src0_sel:WORD_1
	v_pk_fma_f32 v[222:223], v[116:117], v[218:219], v[222:223]
	v_pk_fma_f32 v[224:225], v[118:119], v[220:221], v[224:225]
	v_cvt_pk_f32_fp8_e32 v[218:219], v207
	v_cvt_pk_f32_fp8_sdwa v[220:221], v207 src0_sel:WORD_1
	v_pk_fma_f32 v[222:223], v[120:121], v[214:215], v[222:223]
	v_pk_fma_f32 v[224:225], v[122:123], v[216:217], v[224:225]
	v_pk_fma_f32 v[222:223], v[124:125], v[218:219], v[222:223]
	v_pk_fma_f32 v[224:225], v[126:127], v[220:221], v[224:225]
	v_pk_add_f32 v[222:223], v[222:223], v[224:225]
	s_nop 0
	v_add_f32_e32 v233, v222, v223
	v_permlane32_swap_b32_e32 v226, v230
	v_permlane32_swap_b32_e32 v227, v231
	v_permlane32_swap_b32_e32 v228, v232
	v_permlane32_swap_b32_e32 v229, v233
	v_add_f32_e32 v226, v226, v230
	v_add_f32_e32 v228, v228, v232
	v_add_f32_e32 v227, v227, v231
	v_add_f32_e32 v229, v229, v233
	s_nop 1
	v_permlane16_swap_b32_e32 v226, v228
	v_permlane16_swap_b32_e32 v227, v229
	v_add_f32_e32 v226, v226, v228
	v_add_f32_e32 v227, v227, v229
	s_nop 0
	v_cndmask_b32_e64 v230, v226, v227, s[24:25]
	v_cndmask_b32_e64 v231, v227, v226, s[24:25]
	s_nop 1
	v_add_f32_dpp v232, v231, v230 row_ror:8 row_mask:0xf bank_mask:0xf
	s_nop 1
	v_add_f32_dpp v233, v232, v232 quad_perm:[1,0,3,2] row_mask:0xf bank_mask:0xf
	s_nop 1
	v_add_f32_dpp v232, v233, v233 quad_perm:[2,3,0,1] row_mask:0xf bank_mask:0xf
	s_nop 1
	v_add_f32_dpp v233, v232, v232 row_half_mirror row_mask:0xf bank_mask:0xf
	ds_write_b32 v235, v233 offset:36352
	v_readlane_b32 s48, v131, s72
	v_readlane_b32 s49, v131, s73
	v_readlane_b32 s50, v131, s74
	v_readlane_b32 s51, v131, s75
	v_readlane_b32 s52, v131, s76
	v_readlane_b32 s53, v131, s77
	v_readlane_b32 s54, v131, s78
	v_readlane_b32 s55, v131, s79
	s_add_u32 s32, s0, s48
	s_addc_u32 s33, s1, 0
	s_add_u32 s34, s0, s49
	s_addc_u32 s35, s1, 0
	s_add_u32 s36, s0, s50
	s_addc_u32 s37, s1, 0
	s_add_u32 s38, s0, s51
	s_addc_u32 s39, s1, 0
	s_add_u32 s40, s0, s52
	s_addc_u32 s41, s1, 0
	s_add_u32 s42, s0, s53
	s_addc_u32 s43, s1, 0
	s_add_u32 s44, s0, s54
	s_addc_u32 s45, s1, 0
	s_add_u32 s46, s0, s55
	s_addc_u32 s47, s1, 0
	global_load_dwordx4 v[176:179], v234, s[32:33]
	global_load_dwordx4 v[180:183], v234, s[34:35]
	global_load_dwordx4 v[184:187], v234, s[36:37]
	global_load_dwordx4 v[188:191], v234, s[38:39]
	global_load_dwordx4 v[192:195], v234, s[40:41]
	global_load_dwordx4 v[196:199], v234, s[42:43]
	global_load_dwordx4 v[200:203], v234, s[44:45]
	global_load_dwordx4 v[204:207], v234, s[46:47]
	s_waitcnt vmcnt(8)
	v_cvt_pk_f32_fp8_e32 v[214:215], v144
	v_cvt_pk_f32_fp8_sdwa v[216:217], v144 src0_sel:WORD_1
	v_cvt_pk_f32_fp8_e32 v[218:219], v145
	v_cvt_pk_f32_fp8_sdwa v[220:221], v145 src0_sel:WORD_1
	v_pk_mul_f32 v[222:223], v[0:1], v[214:215]
	v_pk_mul_f32 v[224:225], v[2:3], v[216:217]
	v_cvt_pk_f32_fp8_e32 v[214:215], v146
	v_cvt_pk_f32_fp8_sdwa v[216:217], v146 src0_sel:WORD_1
	v_pk_fma_f32 v[222:223], v[4:5], v[218:219], v[222:223]
	v_pk_fma_f32 v[224:225], v[6:7], v[220:221], v[224:225]
	v_cvt_pk_f32_fp8_e32 v[218:219], v147
	v_cvt_pk_f32_fp8_sdwa v[220:221], v147 src0_sel:WORD_1
	v_pk_fma_f32 v[222:223], v[8:9], v[214:215], v[222:223]
	v_pk_fma_f32 v[224:225], v[10:11], v[216:217], v[224:225]
	v_pk_fma_f32 v[222:223], v[12:13], v[218:219], v[222:223]
	v_pk_fma_f32 v[224:225], v[14:15], v[220:221], v[224:225]
	v_pk_add_f32 v[222:223], v[222:223], v[224:225]
	s_nop 0
	v_add_f32_e32 v226, v222, v223
	v_cvt_pk_f32_fp8_e32 v[214:215], v148
	v_cvt_pk_f32_fp8_sdwa v[216:217], v148 src0_sel:WORD_1
	v_cvt_pk_f32_fp8_e32 v[218:219], v149
	v_cvt_pk_f32_fp8_sdwa v[220:221], v149 src0_sel:WORD_1
	v_pk_mul_f32 v[222:223], v[0:1], v[214:215]
	v_pk_mul_f32 v[224:225], v[2:3], v[216:217]
	v_cvt_pk_f32_fp8_e32 v[214:215], v150
	v_cvt_pk_f32_fp8_sdwa v[216:217], v150 src0_sel:WORD_1
	v_pk_fma_f32 v[222:223], v[4:5], v[218:219], v[222:223]
	v_pk_fma_f32 v[224:225], v[6:7], v[220:221], v[224:225]
	v_cvt_pk_f32_fp8_e32 v[218:219], v151
	v_cvt_pk_f32_fp8_sdwa v[220:221], v151 src0_sel:WORD_1
	v_pk_fma_f32 v[222:223], v[8:9], v[214:215], v[222:223]
	v_pk_fma_f32 v[224:225], v[10:11], v[216:217], v[224:225]
	v_pk_fma_f32 v[222:223], v[12:13], v[218:219], v[222:223]
	v_pk_fma_f32 v[224:225], v[14:15], v[220:221], v[224:225]
	v_pk_add_f32 v[222:223], v[222:223], v[224:225]
	s_nop 0
	v_add_f32_e32 v227, v222, v223
	v_cvt_pk_f32_fp8_e32 v[214:215], v152
; template <bool STORE>
; DI void peer_item(const Params& p, int item, char* smem) {
;     ...
; #pragma unroll
;       for (int u = 0; u < 8; ++u) {
;         float d = 0.f;
; #pragma unroll
;         for (int i = 0; i < 4; ++i) {
;           f32x2_t lo = __builtin_amdgcn_cvt_pk_f32_fp8((int)uq[u][i], false);
;           f32x2_t hi = __builtin_amdgcn_cvt_pk_f32_fp8((int)uq[u][i], true);
;           d += xf[4 * i] * lo.x + xf[4 * i + 1] * lo.y + xf[4 * i + 2] * hi.x + xf[4 * i + 3] * hi.y;
;         }
;         part[u] = d;
;       }
;       float q4[4], r2[2], h;
; #pragma unroll
;       for (int j = 0; j < 4; ++j) {
;         float mine = b5 ? part[j + 4] : part[j];
;         float other = b5 ? part[j] : part[j + 4];
;         q4[j] = mine + __shfl_xor(other, 32);
;       }
; #pragma unroll
;       for (int j = 0; j < 2; ++j) {
;         float mine = b4 ? q4[j + 2] : q4[j];
;         float other = b4 ? q4[j] : q4[j + 2];
;         r2[j] = mine + __shfl_xor(other, 16);
;       }
;       {
;         float mine = b3 ? r2[1] : r2[0];
;         float other = b3 ? r2[0] : r2[1];
;         h = mine + __shfl_xor(other, 8);
;       }
;       h += __shfl_xor(h, 4);
;       h += __shfl_xor(h, 2);
;       h += __shfl_xor(h, 1);
	v_cvt_pk_f32_fp8_sdwa v[216:217], v152 src0_sel:WORD_1
	v_cvt_pk_f32_fp8_e32 v[218:219], v153
	v_cvt_pk_f32_fp8_sdwa v[220:221], v153 src0_sel:WORD_1
	v_pk_mul_f32 v[222:223], v[0:1], v[214:215]
	v_pk_mul_f32 v[224:225], v[2:3], v[216:217]
	v_cvt_pk_f32_fp8_e32 v[214:215], v154
	v_cvt_pk_f32_fp8_sdwa v[216:217], v154 src0_sel:WORD_1
	v_pk_fma_f32 v[222:223], v[4:5], v[218:219], v[222:223]
	v_pk_fma_f32 v[224:225], v[6:7], v[220:221], v[224:225]
	v_cvt_pk_f32_fp8_e32 v[218:219], v155
	v_cvt_pk_f32_fp8_sdwa v[220:221], v155 src0_sel:WORD_1
	v_pk_fma_f32 v[222:223], v[8:9], v[214:215], v[222:223]
	v_pk_fma_f32 v[224:225], v[10:11], v[216:217], v[224:225]
	v_pk_fma_f32 v[222:223], v[12:13], v[218:219], v[222:223]
	v_pk_fma_f32 v[224:225], v[14:15], v[220:221], v[224:225]
	v_pk_add_f32 v[222:223], v[222:223], v[224:225]
	s_nop 0
	v_add_f32_e32 v228, v222, v223
	v_cvt_pk_f32_fp8_e32 v[214:215], v156
	v_cvt_pk_f32_fp8_sdwa v[216:217], v156 src0_sel:WORD_1
	v_cvt_pk_f32_fp8_e32 v[218:219], v157
	v_cvt_pk_f32_fp8_sdwa v[220:221], v157 src0_sel:WORD_1
	v_pk_mul_f32 v[222:223], v[0:1], v[214:215]
	v_pk_mul_f32 v[224:225], v[2:3], v[216:217]
	v_cvt_pk_f32_fp8_e32 v[214:215], v158
	v_cvt_pk_f32_fp8_sdwa v[216:217], v158 src0_sel:WORD_1
	v_pk_fma_f32 v[222:223], v[4:5], v[218:219], v[222:223]
	v_pk_fma_f32 v[224:225], v[6:7], v[220:221], v[224:225]
	v_cvt_pk_f32_fp8_e32 v[218:219], v159
	v_cvt_pk_f32_fp8_sdwa v[220:221], v159 src0_sel:WORD_1
	v_pk_fma_f32 v[222:223], v[8:9], v[214:215], v[222:223]
	v_pk_fma_f32 v[224:225], v[10:11], v[216:217], v[224:225]
	v_pk_fma_f32 v[222:223], v[12:13], v[218:219], v[222:223]
	v_pk_fma_f32 v[224:225], v[14:15], v[220:221], v[224:225]
	v_pk_add_f32 v[222:223], v[222:223], v[224:225]
	s_nop 0
	v_add_f32_e32 v229, v222, v223
	v_cvt_pk_f32_fp8_e32 v[214:215], v160
	v_cvt_pk_f32_fp8_sdwa v[216:217], v160 src0_sel:WORD_1
	v_cvt_pk_f32_fp8_e32 v[218:219], v161
	v_cvt_pk_f32_fp8_sdwa v[220:221], v161 src0_sel:WORD_1
	v_pk_mul_f32 v[222:223], v[0:1], v[214:215]
	v_pk_mul_f32 v[224:225], v[2:3], v[216:217]
	v_cvt_pk_f32_fp8_e32 v[214:215], v162
	v_cvt_pk_f32_fp8_sdwa v[216:217], v162 src0_sel:WORD_1
	v_pk_fma_f32 v[222:223], v[4:5], v[218:219], v[222:223]
	v_pk_fma_f32 v[224:225], v[6:7], v[220:221], v[224:225]
	v_cvt_pk_f32_fp8_e32 v[218:219], v163
	v_cvt_pk_f32_fp8_sdwa v[220:221], v163 src0_sel:WORD_1
	v_pk_fma_f32 v[222:223], v[8:9], v[214:215], v[222:223]
	v_pk_fma_f32 v[224:225], v[10:11], v[216:217], v[224:225]
	v_pk_fma_f32 v[222:223], v[12:13], v[218:219], v[222:223]
	v_pk_fma_f32 v[224:225], v[14:15], v[220:221], v[224:225]
	v_pk_add_f32 v[222:223], v[222:223], v[224:225]
	s_nop 0
	v_add_f32_e32 v230, v222, v223
	v_cvt_pk_f32_fp8_e32 v[214:215], v164
	v_cvt_pk_f32_fp8_sdwa v[216:217], v164 src0_sel:WORD_1
	v_cvt_pk_f32_fp8_e32 v[218:219], v165
	v_cvt_pk_f32_fp8_sdwa v[220:221], v165 src0_sel:WORD_1
	v_pk_mul_f32 v[222:223], v[0:1], v[214:215]
	v_pk_mul_f32 v[224:225], v[2:3], v[216:217]
	v_cvt_pk_f32_fp8_e32 v[214:215], v166
	v_cvt_pk_f32_fp8_sdwa v[216:217], v166 src0_sel:WORD_1
	v_pk_fma_f32 v[222:223], v[4:5], v[218:219], v[222:223]
	v_pk_fma_f32 v[224:225], v[6:7], v[220:221], v[224:225]
	v_cvt_pk_f32_fp8_e32 v[218:219], v167
	v_cvt_pk_f32_fp8_sdwa v[220:221], v167 src0_sel:WORD_1
	v_pk_fma_f32 v[222:223], v[8:9], v[214:215], v[222:223]
	v_pk_fma_f32 v[224:225], v[10:11], v[216:217], v[224:225]
	v_pk_fma_f32 v[222:223], v[12:13], v[218:219], v[222:223]
	v_pk_fma_f32 v[224:225], v[14:15], v[220:221], v[224:225]
	v_pk_add_f32 v[222:223], v[222:223], v[224:225]
	s_nop 0
	v_add_f32_e32 v231, v222, v223
	v_cvt_pk_f32_fp8_e32 v[214:215], v168
	v_cvt_pk_f32_fp8_sdwa v[216:217], v168 src0_sel:WORD_1
	v_cvt_pk_f32_fp8_e32 v[218:219], v169
	v_cvt_pk_f32_fp8_sdwa v[220:221], v169 src0_sel:WORD_1
	v_pk_mul_f32 v[222:223], v[0:1], v[214:215]
	v_pk_mul_f32 v[224:225], v[2:3], v[216:217]
	v_cvt_pk_f32_fp8_e32 v[214:215], v170
	v_cvt_pk_f32_fp8_sdwa v[216:217], v170 src0_sel:WORD_1
	v_pk_fma_f32 v[222:223], v[4:5], v[218:219], v[222:223]
	v_pk_fma_f32 v[224:225], v[6:7], v[220:221], v[224:225]
	v_cvt_pk_f32_fp8_e32 v[218:219], v171
	v_cvt_pk_f32_fp8_sdwa v[220:221], v171 src0_sel:WORD_1
	v_pk_fma_f32 v[222:223], v[8:9], v[214:215], v[222:223]
	v_pk_fma_f32 v[224:225], v[10:11], v[216:217], v[224:225]
	v_pk_fma_f32 v[222:223], v[12:13], v[218:219], v[222:223]
	v_pk_fma_f32 v[224:225], v[14:15], v[220:221], v[224:225]
	v_pk_add_f32 v[222:223], v[222:223], v[224:225]
	s_nop 0
	v_add_f32_e32 v232, v222, v223
	v_cvt_pk_f32_fp8_e32 v[214:215], v172
	v_cvt_pk_f32_fp8_sdwa v[216:217], v172 src0_sel:WORD_1
	v_cvt_pk_f32_fp8_e32 v[218:219], v173
	v_cvt_pk_f32_fp8_sdwa v[220:221], v173 src0_sel:WORD_1
	v_pk_mul_f32 v[222:223], v[0:1], v[214:215]
	v_pk_mul_f32 v[224:225], v[2:3], v[216:217]
	v_cvt_pk_f32_fp8_e32 v[214:215], v174
	v_cvt_pk_f32_fp8_sdwa v[216:217], v174 src0_sel:WORD_1
	v_pk_fma_f32 v[222:223], v[4:5], v[218:219], v[222:223]
	v_pk_fma_f32 v[224:225], v[6:7], v[220:221], v[224:225]
	v_cvt_pk_f32_fp8_e32 v[218:219], v175
	v_cvt_pk_f32_fp8_sdwa v[220:221], v175 src0_sel:WORD_1
	v_pk_fma_f32 v[222:223], v[8:9], v[214:215], v[222:223]
	v_pk_fma_f32 v[224:225], v[10:11], v[216:217], v[224:225]
	v_pk_fma_f32 v[222:223], v[12:13], v[218:219], v[222:223]
	v_pk_fma_f32 v[224:225], v[14:15], v[220:221], v[224:225]
	v_pk_add_f32 v[222:223], v[222:223], v[224:225]
	s_nop 0
	v_add_f32_e32 v233, v222, v223
	v_permlane32_swap_b32_e32 v226, v230
	v_permlane32_swap_b32_e32 v227, v231
	v_permlane32_swap_b32_e32 v228, v232
	v_permlane32_swap_b32_e32 v229, v233
	v_add_f32_e32 v226, v226, v230
	v_add_f32_e32 v228, v228, v232
; template <bool STORE>
; DI void peer_item(const Params& p, int item, char* smem) {
;     ...
; #pragma unroll
;       for (int u = 0; u < 8; ++u) {
;         int e = e_s[tl * 128 + k + u];
;         uq[u] = *(const u32x4*)(U8 + (size_t)e * 1024 + lane * 16);
;       }
;       float part[8];
; #pragma unroll
;       for (int u = 0; u < 8; ++u) {
;         float d = 0.f;
; #pragma unroll
;         for (int i = 0; i < 4; ++i) {
;           f32x2_t lo = __builtin_amdgcn_cvt_pk_f32_fp8((int)uq[u][i], false);
;           f32x2_t hi = __builtin_amdgcn_cvt_pk_f32_fp8((int)uq[u][i], true);
;           d += xf[4 * i] * lo.x + xf[4 * i + 1] * lo.y + xf[4 * i + 2] * hi.x + xf[4 * i + 3] * hi.y;
;         }
;         part[u] = d;
;       }
;       float q4[4], r2[2], h;
; #pragma unroll
;       for (int j = 0; j < 4; ++j) {
;         float mine = b5 ? part[j + 4] : part[j];
;         float other = b5 ? part[j] : part[j + 4];
;         q4[j] = mine + __shfl_xor(other, 32);
;       }
; #pragma unroll
;       for (int j = 0; j < 2; ++j) {
;         float mine = b4 ? q4[j + 2] : q4[j];
;         float other = b4 ? q4[j] : q4[j + 2];
;         r2[j] = mine + __shfl_xor(other, 16);
;       }
;       {
;         float mine = b3 ? r2[1] : r2[0];
;         float other = b3 ? r2[0] : r2[1];
;         h = mine + __shfl_xor(other, 8);
;       }
;       h += __shfl_xor(h, 4);
;       h += __shfl_xor(h, 2);
;       h += __shfl_xor(h, 1);
	v_add_f32_e32 v227, v227, v231
	v_add_f32_e32 v229, v229, v233
	s_nop 1
	v_permlane16_swap_b32_e32 v226, v228
	v_permlane16_swap_b32_e32 v227, v229
	v_add_f32_e32 v226, v226, v228
	v_add_f32_e32 v227, v227, v229
	s_nop 0
	v_cndmask_b32_e64 v230, v226, v227, s[24:25]
	v_cndmask_b32_e64 v231, v227, v226, s[24:25]
	s_nop 1
	v_add_f32_dpp v232, v231, v230 row_ror:8 row_mask:0xf bank_mask:0xf
	s_nop 1
	v_add_f32_dpp v233, v232, v232 quad_perm:[1,0,3,2] row_mask:0xf bank_mask:0xf
	s_nop 1
	v_add_f32_dpp v232, v233, v233 quad_perm:[2,3,0,1] row_mask:0xf bank_mask:0xf
	s_nop 1
	v_add_f32_dpp v233, v232, v232 row_half_mirror row_mask:0xf bank_mask:0xf
	ds_write_b32 v235, v233 offset:32800
	v_readlane_b32 s48, v133, s72
	v_readlane_b32 s49, v133, s73
	v_readlane_b32 s50, v133, s74
	v_readlane_b32 s51, v133, s75
	v_readlane_b32 s52, v133, s76
	v_readlane_b32 s53, v133, s77
	v_readlane_b32 s54, v133, s78
	v_readlane_b32 s55, v133, s79
	s_add_u32 s32, s0, s48
	s_addc_u32 s33, s1, 0
	s_add_u32 s34, s0, s49
	s_addc_u32 s35, s1, 0
	s_add_u32 s36, s0, s50
	s_addc_u32 s37, s1, 0
	s_add_u32 s38, s0, s51
	s_addc_u32 s39, s1, 0
	s_add_u32 s40, s0, s52
	s_addc_u32 s41, s1, 0
	s_add_u32 s42, s0, s53
	s_addc_u32 s43, s1, 0
	s_add_u32 s44, s0, s54
	s_addc_u32 s45, s1, 0
	s_add_u32 s46, s0, s55
	s_addc_u32 s47, s1, 0
	global_load_dwordx4 v[144:147], v234, s[32:33]
	global_load_dwordx4 v[148:151], v234, s[34:35]
	global_load_dwordx4 v[152:155], v234, s[36:37]
	global_load_dwordx4 v[156:159], v234, s[38:39]
	global_load_dwordx4 v[160:163], v234, s[40:41]
	global_load_dwordx4 v[164:167], v234, s[42:43]
	global_load_dwordx4 v[168:171], v234, s[44:45]
	global_load_dwordx4 v[172:175], v234, s[46:47]
	s_waitcnt vmcnt(8)
	v_cvt_pk_f32_fp8_e32 v[214:215], v176
	v_cvt_pk_f32_fp8_sdwa v[216:217], v176 src0_sel:WORD_1
	v_cvt_pk_f32_fp8_e32 v[218:219], v177
	v_cvt_pk_f32_fp8_sdwa v[220:221], v177 src0_sel:WORD_1
	v_pk_mul_f32 v[222:223], v[16:17], v[214:215]
	v_pk_mul_f32 v[224:225], v[18:19], v[216:217]
	v_cvt_pk_f32_fp8_e32 v[214:215], v178
	v_cvt_pk_f32_fp8_sdwa v[216:217], v178 src0_sel:WORD_1
	v_pk_fma_f32 v[222:223], v[20:21], v[218:219], v[222:223]
	v_pk_fma_f32 v[224:225], v[22:23], v[220:221], v[224:225]
	v_cvt_pk_f32_fp8_e32 v[218:219], v179
	v_cvt_pk_f32_fp8_sdwa v[220:221], v179 src0_sel:WORD_1
	v_pk_fma_f32 v[222:223], v[24:25], v[214:215], v[222:223]
	v_pk_fma_f32 v[224:225], v[26:27], v[216:217], v[224:225]
	v_pk_fma_f32 v[222:223], v[28:29], v[218:219], v[222:223]
	v_pk_fma_f32 v[224:225], v[30:31], v[220:221], v[224:225]
	v_pk_add_f32 v[222:223], v[222:223], v[224:225]
	s_nop 0
	v_add_f32_e32 v226, v222, v223
	v_cvt_pk_f32_fp8_e32 v[214:215], v180
	v_cvt_pk_f32_fp8_sdwa v[216:217], v180 src0_sel:WORD_1
	v_cvt_pk_f32_fp8_e32 v[218:219], v181
	v_cvt_pk_f32_fp8_sdwa v[220:221], v181 src0_sel:WORD_1
	v_pk_mul_f32 v[222:223], v[16:17], v[214:215]
	v_pk_mul_f32 v[224:225], v[18:19], v[216:217]
	v_cvt_pk_f32_fp8_e32 v[214:215], v182
	v_cvt_pk_f32_fp8_sdwa v[216:217], v182 src0_sel:WORD_1
	v_pk_fma_f32 v[222:223], v[20:21], v[218:219], v[222:223]
	v_pk_fma_f32 v[224:225], v[22:23], v[220:221], v[224:225]
	v_cvt_pk_f32_fp8_e32 v[218:219], v183
	v_cvt_pk_f32_fp8_sdwa v[220:221], v183 src0_sel:WORD_1
	v_pk_fma_f32 v[222:223], v[24:25], v[214:215], v[222:223]
	v_pk_fma_f32 v[224:225], v[26:27], v[216:217], v[224:225]
	v_pk_fma_f32 v[222:223], v[28:29], v[218:219], v[222:223]
	v_pk_fma_f32 v[224:225], v[30:31], v[220:221], v[224:225]
	v_pk_add_f32 v[222:223], v[222:223], v[224:225]
	s_nop 0
	v_add_f32_e32 v227, v222, v223
	v_cvt_pk_f32_fp8_e32 v[214:215], v184
	v_cvt_pk_f32_fp8_sdwa v[216:217], v184 src0_sel:WORD_1
	v_cvt_pk_f32_fp8_e32 v[218:219], v185
	v_cvt_pk_f32_fp8_sdwa v[220:221], v185 src0_sel:WORD_1
	v_pk_mul_f32 v[222:223], v[16:17], v[214:215]
	v_pk_mul_f32 v[224:225], v[18:19], v[216:217]
	v_cvt_pk_f32_fp8_e32 v[214:215], v186
	v_cvt_pk_f32_fp8_sdwa v[216:217], v186 src0_sel:WORD_1
	v_pk_fma_f32 v[222:223], v[20:21], v[218:219], v[222:223]
	v_pk_fma_f32 v[224:225], v[22:23], v[220:221], v[224:225]
	v_cvt_pk_f32_fp8_e32 v[218:219], v187
	v_cvt_pk_f32_fp8_sdwa v[220:221], v187 src0_sel:WORD_1
	v_pk_fma_f32 v[222:223], v[24:25], v[214:215], v[222:223]
	v_pk_fma_f32 v[224:225], v[26:27], v[216:217], v[224:225]
	v_pk_fma_f32 v[222:223], v[28:29], v[218:219], v[222:223]
	v_pk_fma_f32 v[224:225], v[30:31], v[220:221], v[224:225]
	v_pk_add_f32 v[222:223], v[222:223], v[224:225]
	s_nop 0
	v_add_f32_e32 v228, v222, v223
	v_cvt_pk_f32_fp8_e32 v[214:215], v188
	v_cvt_pk_f32_fp8_sdwa v[216:217], v188 src0_sel:WORD_1
	v_cvt_pk_f32_fp8_e32 v[218:219], v189
	v_cvt_pk_f32_fp8_sdwa v[220:221], v189 src0_sel:WORD_1
	v_pk_mul_f32 v[222:223], v[16:17], v[214:215]
	v_pk_mul_f32 v[224:225], v[18:19], v[216:217]
	v_cvt_pk_f32_fp8_e32 v[214:215], v190
	v_cvt_pk_f32_fp8_sdwa v[216:217], v190 src0_sel:WORD_1
	v_pk_fma_f32 v[222:223], v[20:21], v[218:219], v[222:223]
	v_pk_fma_f32 v[224:225], v[22:23], v[220:221], v[224:225]
	v_cvt_pk_f32_fp8_e32 v[218:219], v191
	v_cvt_pk_f32_fp8_sdwa v[220:221], v191 src0_sel:WORD_1
	v_pk_fma_f32 v[222:223], v[24:25], v[214:215], v[222:223]
	v_pk_fma_f32 v[224:225], v[26:27], v[216:217], v[224:225]
	v_pk_fma_f32 v[222:223], v[28:29], v[218:219], v[222:223]
	v_pk_fma_f32 v[224:225], v[30:31], v[220:221], v[224:225]
	v_pk_add_f32 v[222:223], v[222:223], v[224:225]
	s_nop 0
	v_add_f32_e32 v229, v222, v223
	v_cvt_pk_f32_fp8_e32 v[214:215], v192
	v_cvt_pk_f32_fp8_sdwa v[216:217], v192 src0_sel:WORD_1
	v_cvt_pk_f32_fp8_e32 v[218:219], v193
	v_cvt_pk_f32_fp8_sdwa v[220:221], v193 src0_sel:WORD_1
	v_pk_mul_f32 v[222:223], v[16:17], v[214:215]
; template <bool STORE>
; DI void peer_item(const Params& p, int item, char* smem) {
;     ...
; #pragma unroll
;       for (int u = 0; u < 8; ++u) {
;         int e = e_s[tl * 128 + k + u];
;         uq[u] = *(const u32x4*)(U8 + (size_t)e * 1024 + lane * 16);
;       }
;       float part[8];
; #pragma unroll
;       for (int u = 0; u < 8; ++u) {
;         float d = 0.f;
; #pragma unroll
;         for (int i = 0; i < 4; ++i) {
;           f32x2_t lo = __builtin_amdgcn_cvt_pk_f32_fp8((int)uq[u][i], false);
;           f32x2_t hi = __builtin_amdgcn_cvt_pk_f32_fp8((int)uq[u][i], true);
;           d += xf[4 * i] * lo.x + xf[4 * i + 1] * lo.y + xf[4 * i + 2] * hi.x + xf[4 * i + 3] * hi.y;
;         }
;         part[u] = d;
;       }
;       float q4[4], r2[2], h;
; #pragma unroll
;       for (int j = 0; j < 4; ++j) {
;         float mine = b5 ? part[j + 4] : part[j];
;         float other = b5 ? part[j] : part[j + 4];
;         q4[j] = mine + __shfl_xor(other, 32);
;       }
; #pragma unroll
;       for (int j = 0; j < 2; ++j) {
;         float mine = b4 ? q4[j + 2] : q4[j];
;         float other = b4 ? q4[j] : q4[j + 2];
;         r2[j] = mine + __shfl_xor(other, 16);
;       }
;       {
;         float mine = b3 ? r2[1] : r2[0];
;         float other = b3 ? r2[0] : r2[1];
;         h = mine + __shfl_xor(other, 8);
;       }
;       h += __shfl_xor(h, 4);
;       h += __shfl_xor(h, 2);
;       h += __shfl_xor(h, 1);
	v_pk_mul_f32 v[224:225], v[18:19], v[216:217]
	v_cvt_pk_f32_fp8_e32 v[214:215], v194
	v_cvt_pk_f32_fp8_sdwa v[216:217], v194 src0_sel:WORD_1
	v_pk_fma_f32 v[222:223], v[20:21], v[218:219], v[222:223]
	v_pk_fma_f32 v[224:225], v[22:23], v[220:221], v[224:225]
	v_cvt_pk_f32_fp8_e32 v[218:219], v195
	v_cvt_pk_f32_fp8_sdwa v[220:221], v195 src0_sel:WORD_1
	v_pk_fma_f32 v[222:223], v[24:25], v[214:215], v[222:223]
	v_pk_fma_f32 v[224:225], v[26:27], v[216:217], v[224:225]
	v_pk_fma_f32 v[222:223], v[28:29], v[218:219], v[222:223]
	v_pk_fma_f32 v[224:225], v[30:31], v[220:221], v[224:225]
	v_pk_add_f32 v[222:223], v[222:223], v[224:225]
	s_nop 0
	v_add_f32_e32 v230, v222, v223
	v_cvt_pk_f32_fp8_e32 v[214:215], v196
	v_cvt_pk_f32_fp8_sdwa v[216:217], v196 src0_sel:WORD_1
	v_cvt_pk_f32_fp8_e32 v[218:219], v197
	v_cvt_pk_f32_fp8_sdwa v[220:221], v197 src0_sel:WORD_1
	v_pk_mul_f32 v[222:223], v[16:17], v[214:215]
	v_pk_mul_f32 v[224:225], v[18:19], v[216:217]
	v_cvt_pk_f32_fp8_e32 v[214:215], v198
	v_cvt_pk_f32_fp8_sdwa v[216:217], v198 src0_sel:WORD_1
	v_pk_fma_f32 v[222:223], v[20:21], v[218:219], v[222:223]
	v_pk_fma_f32 v[224:225], v[22:23], v[220:221], v[224:225]
	v_cvt_pk_f32_fp8_e32 v[218:219], v199
	v_cvt_pk_f32_fp8_sdwa v[220:221], v199 src0_sel:WORD_1
	v_pk_fma_f32 v[222:223], v[24:25], v[214:215], v[222:223]
	v_pk_fma_f32 v[224:225], v[26:27], v[216:217], v[224:225]
	v_pk_fma_f32 v[222:223], v[28:29], v[218:219], v[222:223]
	v_pk_fma_f32 v[224:225], v[30:31], v[220:221], v[224:225]
	v_pk_add_f32 v[222:223], v[222:223], v[224:225]
	s_nop 0
	v_add_f32_e32 v231, v222, v223
	v_cvt_pk_f32_fp8_e32 v[214:215], v200
	v_cvt_pk_f32_fp8_sdwa v[216:217], v200 src0_sel:WORD_1
	v_cvt_pk_f32_fp8_e32 v[218:219], v201
	v_cvt_pk_f32_fp8_sdwa v[220:221], v201 src0_sel:WORD_1
	v_pk_mul_f32 v[222:223], v[16:17], v[214:215]
	v_pk_mul_f32 v[224:225], v[18:19], v[216:217]
	v_cvt_pk_f32_fp8_e32 v[214:215], v202
	v_cvt_pk_f32_fp8_sdwa v[216:217], v202 src0_sel:WORD_1
	v_pk_fma_f32 v[222:223], v[20:21], v[218:219], v[222:223]
	v_pk_fma_f32 v[224:225], v[22:23], v[220:221], v[224:225]
	v_cvt_pk_f32_fp8_e32 v[218:219], v203
	v_cvt_pk_f32_fp8_sdwa v[220:221], v203 src0_sel:WORD_1
	v_pk_fma_f32 v[222:223], v[24:25], v[214:215], v[222:223]
	v_pk_fma_f32 v[224:225], v[26:27], v[216:217], v[224:225]
	v_pk_fma_f32 v[222:223], v[28:29], v[218:219], v[222:223]
	v_pk_fma_f32 v[224:225], v[30:31], v[220:221], v[224:225]
	v_pk_add_f32 v[222:223], v[222:223], v[224:225]
	s_nop 0
	v_add_f32_e32 v232, v222, v223
	v_cvt_pk_f32_fp8_e32 v[214:215], v204
	v_cvt_pk_f32_fp8_sdwa v[216:217], v204 src0_sel:WORD_1
	v_cvt_pk_f32_fp8_e32 v[218:219], v205
	v_cvt_pk_f32_fp8_sdwa v[220:221], v205 src0_sel:WORD_1
	v_pk_mul_f32 v[222:223], v[16:17], v[214:215]
	v_pk_mul_f32 v[224:225], v[18:19], v[216:217]
	v_cvt_pk_f32_fp8_e32 v[214:215], v206
	v_cvt_pk_f32_fp8_sdwa v[216:217], v206 src0_sel:WORD_1
	v_pk_fma_f32 v[222:223], v[20:21], v[218:219], v[222:223]
	v_pk_fma_f32 v[224:225], v[22:23], v[220:221], v[224:225]
	v_cvt_pk_f32_fp8_e32 v[218:219], v207
	v_cvt_pk_f32_fp8_sdwa v[220:221], v207 src0_sel:WORD_1
	v_pk_fma_f32 v[222:223], v[24:25], v[214:215], v[222:223]
	v_pk_fma_f32 v[224:225], v[26:27], v[216:217], v[224:225]
	v_pk_fma_f32 v[222:223], v[28:29], v[218:219], v[222:223]
	v_pk_fma_f32 v[224:225], v[30:31], v[220:221], v[224:225]
	v_pk_add_f32 v[222:223], v[222:223], v[224:225]
	s_nop 0
	v_add_f32_e32 v233, v222, v223
	v_permlane32_swap_b32_e32 v226, v230
	v_permlane32_swap_b32_e32 v227, v231
	v_permlane32_swap_b32_e32 v228, v232
	v_permlane32_swap_b32_e32 v229, v233
	v_add_f32_e32 v226, v226, v230
	v_add_f32_e32 v228, v228, v232
	v_add_f32_e32 v227, v227, v231
	v_add_f32_e32 v229, v229, v233
	s_nop 1
	v_permlane16_swap_b32_e32 v226, v228
	v_permlane16_swap_b32_e32 v227, v229
	v_add_f32_e32 v226, v226, v228
	v_add_f32_e32 v227, v227, v229
	s_nop 0
	v_cndmask_b32_e64 v230, v226, v227, s[24:25]
	v_cndmask_b32_e64 v231, v227, v226, s[24:25]
	s_nop 1
	v_add_f32_dpp v232, v231, v230 row_ror:8 row_mask:0xf bank_mask:0xf
	s_nop 1
	v_add_f32_dpp v233, v232, v232 quad_perm:[1,0,3,2] row_mask:0xf bank_mask:0xf
	s_nop 1
	v_add_f32_dpp v232, v233, v233 quad_perm:[2,3,0,1] row_mask:0xf bank_mask:0xf
	s_nop 1
	v_add_f32_dpp v233, v232, v232 row_half_mirror row_mask:0xf bank_mask:0xf
	ds_write_b32 v235, v233 offset:33312
	v_readlane_b32 s48, v135, s72
	v_readlane_b32 s49, v135, s73
	v_readlane_b32 s50, v135, s74
	v_readlane_b32 s51, v135, s75
	v_readlane_b32 s52, v135, s76
	v_readlane_b32 s53, v135, s77
	v_readlane_b32 s54, v135, s78
	v_readlane_b32 s55, v135, s79
	s_add_u32 s32, s0, s48
	s_addc_u32 s33, s1, 0
	s_add_u32 s34, s0, s49
	s_addc_u32 s35, s1, 0
	s_add_u32 s36, s0, s50
	s_addc_u32 s37, s1, 0
	s_add_u32 s38, s0, s51
	s_addc_u32 s39, s1, 0
	s_add_u32 s40, s0, s52
	s_addc_u32 s41, s1, 0
	s_add_u32 s42, s0, s53
	s_addc_u32 s43, s1, 0
	s_add_u32 s44, s0, s54
	s_addc_u32 s45, s1, 0
	s_add_u32 s46, s0, s55
	s_addc_u32 s47, s1, 0
	global_load_dwordx4 v[176:179], v234, s[32:33]
	global_load_dwordx4 v[180:183], v234, s[34:35]
	global_load_dwordx4 v[184:187], v234, s[36:37]
	global_load_dwordx4 v[188:191], v234, s[38:39]
	global_load_dwordx4 v[192:195], v234, s[40:41]
	global_load_dwordx4 v[196:199], v234, s[42:43]
	global_load_dwordx4 v[200:203], v234, s[44:45]
	global_load_dwordx4 v[204:207], v234, s[46:47]
	s_waitcnt vmcnt(8)
; template <bool STORE>
; DI void peer_item(const Params& p, int item, char* smem) {
;     ...
;       for (int u = 0; u < 8; ++u) {
;         int e = e_s[tl * 128 + k + u];
;         uq[u] = *(const u32x4*)(U8 + (size_t)e * 1024 + lane * 16);
;       }
;       float part[8];
; #pragma unroll
;       for (int u = 0; u < 8; ++u) {
;         float d = 0.f;
; #pragma unroll
;         for (int i = 0; i < 4; ++i) {
;           f32x2_t lo = __builtin_amdgcn_cvt_pk_f32_fp8((int)uq[u][i], false);
;           f32x2_t hi = __builtin_amdgcn_cvt_pk_f32_fp8((int)uq[u][i], true);
;           d += xf[4 * i] * lo.x + xf[4 * i + 1] * lo.y + xf[4 * i + 2] * hi.x + xf[4 * i + 3] * hi.y;
;         }
;         part[u] = d;
;       }
	v_cvt_pk_f32_fp8_e32 v[214:215], v144
	v_cvt_pk_f32_fp8_sdwa v[216:217], v144 src0_sel:WORD_1
	v_cvt_pk_f32_fp8_e32 v[218:219], v145
	v_cvt_pk_f32_fp8_sdwa v[220:221], v145 src0_sel:WORD_1
	v_pk_mul_f32 v[222:223], v[32:33], v[214:215]
	v_pk_mul_f32 v[224:225], v[34:35], v[216:217]
	v_cvt_pk_f32_fp8_e32 v[214:215], v146
	v_cvt_pk_f32_fp8_sdwa v[216:217], v146 src0_sel:WORD_1
	v_pk_fma_f32 v[222:223], v[36:37], v[218:219], v[222:223]
	v_pk_fma_f32 v[224:225], v[38:39], v[220:221], v[224:225]
	v_cvt_pk_f32_fp8_e32 v[218:219], v147
	v_cvt_pk_f32_fp8_sdwa v[220:221], v147 src0_sel:WORD_1
	v_pk_fma_f32 v[222:223], v[40:41], v[214:215], v[222:223]
	v_pk_fma_f32 v[224:225], v[42:43], v[216:217], v[224:225]
	v_pk_fma_f32 v[222:223], v[44:45], v[218:219], v[222:223]
	v_pk_fma_f32 v[224:225], v[46:47], v[220:221], v[224:225]
	v_pk_add_f32 v[222:223], v[222:223], v[224:225]
	s_nop 0
	v_add_f32_e32 v226, v222, v223
	v_cvt_pk_f32_fp8_e32 v[214:215], v148
	v_cvt_pk_f32_fp8_sdwa v[216:217], v148 src0_sel:WORD_1
	v_cvt_pk_f32_fp8_e32 v[218:219], v149
	v_cvt_pk_f32_fp8_sdwa v[220:221], v149 src0_sel:WORD_1
	v_pk_mul_f32 v[222:223], v[32:33], v[214:215]
	v_pk_mul_f32 v[224:225], v[34:35], v[216:217]
	v_cvt_pk_f32_fp8_e32 v[214:215], v150
	v_cvt_pk_f32_fp8_sdwa v[216:217], v150 src0_sel:WORD_1
	v_pk_fma_f32 v[222:223], v[36:37], v[218:219], v[222:223]
	v_pk_fma_f32 v[224:225], v[38:39], v[220:221], v[224:225]
	v_cvt_pk_f32_fp8_e32 v[218:219], v151
	v_cvt_pk_f32_fp8_sdwa v[220:221], v151 src0_sel:WORD_1
	v_pk_fma_f32 v[222:223], v[40:41], v[214:215], v[222:223]
	v_pk_fma_f32 v[224:225], v[42:43], v[216:217], v[224:225]
	v_pk_fma_f32 v[222:223], v[44:45], v[218:219], v[222:223]
	v_pk_fma_f32 v[224:225], v[46:47], v[220:221], v[224:225]
	v_pk_add_f32 v[222:223], v[222:223], v[224:225]
	s_nop 0
	v_add_f32_e32 v227, v222, v223
	v_cvt_pk_f32_fp8_e32 v[214:215], v152
	v_cvt_pk_f32_fp8_sdwa v[216:217], v152 src0_sel:WORD_1
	v_cvt_pk_f32_fp8_e32 v[218:219], v153
	v_cvt_pk_f32_fp8_sdwa v[220:221], v153 src0_sel:WORD_1
	v_pk_mul_f32 v[222:223], v[32:33], v[214:215]
	v_pk_mul_f32 v[224:225], v[34:35], v[216:217]
	v_cvt_pk_f32_fp8_e32 v[214:215], v154
	v_cvt_pk_f32_fp8_sdwa v[216:217], v154 src0_sel:WORD_1
	v_pk_fma_f32 v[222:223], v[36:37], v[218:219], v[222:223]
	v_pk_fma_f32 v[224:225], v[38:39], v[220:221], v[224:225]
	v_cvt_pk_f32_fp8_e32 v[218:219], v155
	v_cvt_pk_f32_fp8_sdwa v[220:221], v155 src0_sel:WORD_1
	v_pk_fma_f32 v[222:223], v[40:41], v[214:215], v[222:223]
	v_pk_fma_f32 v[224:225], v[42:43], v[216:217], v[224:225]
	v_pk_fma_f32 v[222:223], v[44:45], v[218:219], v[222:223]
	v_pk_fma_f32 v[224:225], v[46:47], v[220:221], v[224:225]
	v_pk_add_f32 v[222:223], v[222:223], v[224:225]
	s_nop 0
	v_add_f32_e32 v228, v222, v223
	v_cvt_pk_f32_fp8_e32 v[214:215], v156
	v_cvt_pk_f32_fp8_sdwa v[216:217], v156 src0_sel:WORD_1
	v_cvt_pk_f32_fp8_e32 v[218:219], v157
	v_cvt_pk_f32_fp8_sdwa v[220:221], v157 src0_sel:WORD_1
	v_pk_mul_f32 v[222:223], v[32:33], v[214:215]
	v_pk_mul_f32 v[224:225], v[34:35], v[216:217]
	v_cvt_pk_f32_fp8_e32 v[214:215], v158
	v_cvt_pk_f32_fp8_sdwa v[216:217], v158 src0_sel:WORD_1
	v_pk_fma_f32 v[222:223], v[36:37], v[218:219], v[222:223]
	v_pk_fma_f32 v[224:225], v[38:39], v[220:221], v[224:225]
	v_cvt_pk_f32_fp8_e32 v[218:219], v159
	v_cvt_pk_f32_fp8_sdwa v[220:221], v159 src0_sel:WORD_1
	v_pk_fma_f32 v[222:223], v[40:41], v[214:215], v[222:223]
	v_pk_fma_f32 v[224:225], v[42:43], v[216:217], v[224:225]
	v_pk_fma_f32 v[222:223], v[44:45], v[218:219], v[222:223]
	v_pk_fma_f32 v[224:225], v[46:47], v[220:221], v[224:225]
	v_pk_add_f32 v[222:223], v[222:223], v[224:225]
	s_nop 0
	v_add_f32_e32 v229, v222, v223
	v_cvt_pk_f32_fp8_e32 v[214:215], v160
	v_cvt_pk_f32_fp8_sdwa v[216:217], v160 src0_sel:WORD_1
	v_cvt_pk_f32_fp8_e32 v[218:219], v161
	v_cvt_pk_f32_fp8_sdwa v[220:221], v161 src0_sel:WORD_1
	v_pk_mul_f32 v[222:223], v[32:33], v[214:215]
	v_pk_mul_f32 v[224:225], v[34:35], v[216:217]
	v_cvt_pk_f32_fp8_e32 v[214:215], v162
	v_cvt_pk_f32_fp8_sdwa v[216:217], v162 src0_sel:WORD_1
	v_pk_fma_f32 v[222:223], v[36:37], v[218:219], v[222:223]
	v_pk_fma_f32 v[224:225], v[38:39], v[220:221], v[224:225]
	v_cvt_pk_f32_fp8_e32 v[218:219], v163
	v_cvt_pk_f32_fp8_sdwa v[220:221], v163 src0_sel:WORD_1
	v_pk_fma_f32 v[222:223], v[40:41], v[214:215], v[222:223]
	v_pk_fma_f32 v[224:225], v[42:43], v[216:217], v[224:225]
	v_pk_fma_f32 v[222:223], v[44:45], v[218:219], v[222:223]
	v_pk_fma_f32 v[224:225], v[46:47], v[220:221], v[224:225]
	v_pk_add_f32 v[222:223], v[222:223], v[224:225]
	s_nop 0
	v_add_f32_e32 v230, v222, v223
	v_cvt_pk_f32_fp8_e32 v[214:215], v164
	v_cvt_pk_f32_fp8_sdwa v[216:217], v164 src0_sel:WORD_1
	v_cvt_pk_f32_fp8_e32 v[218:219], v165
	v_cvt_pk_f32_fp8_sdwa v[220:221], v165 src0_sel:WORD_1
	v_pk_mul_f32 v[222:223], v[32:33], v[214:215]
	v_pk_mul_f32 v[224:225], v[34:35], v[216:217]
	v_cvt_pk_f32_fp8_e32 v[214:215], v166
	v_cvt_pk_f32_fp8_sdwa v[216:217], v166 src0_sel:WORD_1
	v_pk_fma_f32 v[222:223], v[36:37], v[218:219], v[222:223]
	v_pk_fma_f32 v[224:225], v[38:39], v[220:221], v[224:225]
	v_cvt_pk_f32_fp8_e32 v[218:219], v167
	v_cvt_pk_f32_fp8_sdwa v[220:221], v167 src0_sel:WORD_1
	v_pk_fma_f32 v[222:223], v[40:41], v[214:215], v[222:223]
	v_pk_fma_f32 v[224:225], v[42:43], v[216:217], v[224:225]
	v_pk_fma_f32 v[222:223], v[44:45], v[218:219], v[222:223]
	v_pk_fma_f32 v[224:225], v[46:47], v[220:221], v[224:225]
	v_pk_add_f32 v[222:223], v[222:223], v[224:225]
	s_nop 0
	v_add_f32_e32 v231, v222, v223
	v_cvt_pk_f32_fp8_e32 v[214:215], v168
	v_cvt_pk_f32_fp8_sdwa v[216:217], v168 src0_sel:WORD_1
	v_cvt_pk_f32_fp8_e32 v[218:219], v169
; template <bool STORE>
; DI void peer_item(const Params& p, int item, char* smem) {
;     ...
; #pragma unroll
;       for (int u = 0; u < 8; ++u) {
;         int e = e_s[tl * 128 + k + u];
;         uq[u] = *(const u32x4*)(U8 + (size_t)e * 1024 + lane * 16);
;       }
;       float part[8];
; #pragma unroll
;       for (int u = 0; u < 8; ++u) {
;         float d = 0.f;
; #pragma unroll
;         for (int i = 0; i < 4; ++i) {
;           f32x2_t lo = __builtin_amdgcn_cvt_pk_f32_fp8((int)uq[u][i], false);
;           f32x2_t hi = __builtin_amdgcn_cvt_pk_f32_fp8((int)uq[u][i], true);
;           d += xf[4 * i] * lo.x + xf[4 * i + 1] * lo.y + xf[4 * i + 2] * hi.x + xf[4 * i + 3] * hi.y;
;         }
;         part[u] = d;
;       }
;       float q4[4], r2[2], h;
; #pragma unroll
;       for (int j = 0; j < 4; ++j) {
;         float mine = b5 ? part[j + 4] : part[j];
;         float other = b5 ? part[j] : part[j + 4];
;         q4[j] = mine + __shfl_xor(other, 32);
;       }
; #pragma unroll
;       for (int j = 0; j < 2; ++j) {
;         float mine = b4 ? q4[j + 2] : q4[j];
;         float other = b4 ? q4[j] : q4[j + 2];
;         r2[j] = mine + __shfl_xor(other, 16);
;       }
;       {
;         float mine = b3 ? r2[1] : r2[0];
;         float other = b3 ? r2[0] : r2[1];
;         h = mine + __shfl_xor(other, 8);
;       }
;       h += __shfl_xor(h, 4);
;       h += __shfl_xor(h, 2);
;       h += __shfl_xor(h, 1);
	v_cvt_pk_f32_fp8_sdwa v[220:221], v169 src0_sel:WORD_1
	v_pk_mul_f32 v[222:223], v[32:33], v[214:215]
	v_pk_mul_f32 v[224:225], v[34:35], v[216:217]
	v_cvt_pk_f32_fp8_e32 v[214:215], v170
	v_cvt_pk_f32_fp8_sdwa v[216:217], v170 src0_sel:WORD_1
	v_pk_fma_f32 v[222:223], v[36:37], v[218:219], v[222:223]
	v_pk_fma_f32 v[224:225], v[38:39], v[220:221], v[224:225]
	v_cvt_pk_f32_fp8_e32 v[218:219], v171
	v_cvt_pk_f32_fp8_sdwa v[220:221], v171 src0_sel:WORD_1
	v_pk_fma_f32 v[222:223], v[40:41], v[214:215], v[222:223]
	v_pk_fma_f32 v[224:225], v[42:43], v[216:217], v[224:225]
	v_pk_fma_f32 v[222:223], v[44:45], v[218:219], v[222:223]
	v_pk_fma_f32 v[224:225], v[46:47], v[220:221], v[224:225]
	v_pk_add_f32 v[222:223], v[222:223], v[224:225]
	s_nop 0
	v_add_f32_e32 v232, v222, v223
	v_cvt_pk_f32_fp8_e32 v[214:215], v172
	v_cvt_pk_f32_fp8_sdwa v[216:217], v172 src0_sel:WORD_1
	v_cvt_pk_f32_fp8_e32 v[218:219], v173
	v_cvt_pk_f32_fp8_sdwa v[220:221], v173 src0_sel:WORD_1
	v_pk_mul_f32 v[222:223], v[32:33], v[214:215]
	v_pk_mul_f32 v[224:225], v[34:35], v[216:217]
	v_cvt_pk_f32_fp8_e32 v[214:215], v174
	v_cvt_pk_f32_fp8_sdwa v[216:217], v174 src0_sel:WORD_1
	v_pk_fma_f32 v[222:223], v[36:37], v[218:219], v[222:223]
	v_pk_fma_f32 v[224:225], v[38:39], v[220:221], v[224:225]
	v_cvt_pk_f32_fp8_e32 v[218:219], v175
	v_cvt_pk_f32_fp8_sdwa v[220:221], v175 src0_sel:WORD_1
	v_pk_fma_f32 v[222:223], v[40:41], v[214:215], v[222:223]
	v_pk_fma_f32 v[224:225], v[42:43], v[216:217], v[224:225]
	v_pk_fma_f32 v[222:223], v[44:45], v[218:219], v[222:223]
	v_pk_fma_f32 v[224:225], v[46:47], v[220:221], v[224:225]
	v_pk_add_f32 v[222:223], v[222:223], v[224:225]
	s_nop 0
	v_add_f32_e32 v233, v222, v223
	v_permlane32_swap_b32_e32 v226, v230
	v_permlane32_swap_b32_e32 v227, v231
	v_permlane32_swap_b32_e32 v228, v232
	v_permlane32_swap_b32_e32 v229, v233
	v_add_f32_e32 v226, v226, v230
	v_add_f32_e32 v228, v228, v232
	v_add_f32_e32 v227, v227, v231
	v_add_f32_e32 v229, v229, v233
	s_nop 1
	v_permlane16_swap_b32_e32 v226, v228
	v_permlane16_swap_b32_e32 v227, v229
	v_add_f32_e32 v226, v226, v228
	v_add_f32_e32 v227, v227, v229
	s_nop 0
	v_cndmask_b32_e64 v230, v226, v227, s[24:25]
	v_cndmask_b32_e64 v231, v227, v226, s[24:25]
	s_nop 1
	v_add_f32_dpp v232, v231, v230 row_ror:8 row_mask:0xf bank_mask:0xf
	s_nop 1
	v_add_f32_dpp v233, v232, v232 quad_perm:[1,0,3,2] row_mask:0xf bank_mask:0xf
	s_nop 1
	v_add_f32_dpp v232, v233, v233 quad_perm:[2,3,0,1] row_mask:0xf bank_mask:0xf
	s_nop 1
	v_add_f32_dpp v233, v232, v232 row_half_mirror row_mask:0xf bank_mask:0xf
	ds_write_b32 v235, v233 offset:33824
	v_readlane_b32 s48, v137, s72
	v_readlane_b32 s49, v137, s73
	v_readlane_b32 s50, v137, s74
	v_readlane_b32 s51, v137, s75
	v_readlane_b32 s52, v137, s76
	v_readlane_b32 s53, v137, s77
	v_readlane_b32 s54, v137, s78
	v_readlane_b32 s55, v137, s79
	s_add_u32 s32, s0, s48
	s_addc_u32 s33, s1, 0
	s_add_u32 s34, s0, s49
	s_addc_u32 s35, s1, 0
	s_add_u32 s36, s0, s50
	s_addc_u32 s37, s1, 0
	s_add_u32 s38, s0, s51
	s_addc_u32 s39, s1, 0
	s_add_u32 s40, s0, s52
	s_addc_u32 s41, s1, 0
	s_add_u32 s42, s0, s53
	s_addc_u32 s43, s1, 0
	s_add_u32 s44, s0, s54
	s_addc_u32 s45, s1, 0
	s_add_u32 s46, s0, s55
	s_addc_u32 s47, s1, 0
	global_load_dwordx4 v[144:147], v234, s[32:33]
	global_load_dwordx4 v[148:151], v234, s[34:35]
	global_load_dwordx4 v[152:155], v234, s[36:37]
	global_load_dwordx4 v[156:159], v234, s[38:39]
	global_load_dwordx4 v[160:163], v234, s[40:41]
	global_load_dwordx4 v[164:167], v234, s[42:43]
	global_load_dwordx4 v[168:171], v234, s[44:45]
	global_load_dwordx4 v[172:175], v234, s[46:47]
	s_waitcnt vmcnt(8)
	v_cvt_pk_f32_fp8_e32 v[214:215], v176
	v_cvt_pk_f32_fp8_sdwa v[216:217], v176 src0_sel:WORD_1
	v_cvt_pk_f32_fp8_e32 v[218:219], v177
	v_cvt_pk_f32_fp8_sdwa v[220:221], v177 src0_sel:WORD_1
	v_pk_mul_f32 v[222:223], v[48:49], v[214:215]
	v_pk_mul_f32 v[224:225], v[50:51], v[216:217]
	v_cvt_pk_f32_fp8_e32 v[214:215], v178
	v_cvt_pk_f32_fp8_sdwa v[216:217], v178 src0_sel:WORD_1
	v_pk_fma_f32 v[222:223], v[52:53], v[218:219], v[222:223]
	v_pk_fma_f32 v[224:225], v[54:55], v[220:221], v[224:225]
	v_cvt_pk_f32_fp8_e32 v[218:219], v179
	v_cvt_pk_f32_fp8_sdwa v[220:221], v179 src0_sel:WORD_1
	v_pk_fma_f32 v[222:223], v[56:57], v[214:215], v[222:223]
	v_pk_fma_f32 v[224:225], v[58:59], v[216:217], v[224:225]
	v_pk_fma_f32 v[222:223], v[60:61], v[218:219], v[222:223]
	v_pk_fma_f32 v[224:225], v[62:63], v[220:221], v[224:225]
	v_pk_add_f32 v[222:223], v[222:223], v[224:225]
	s_nop 0
	v_add_f32_e32 v226, v222, v223
	v_cvt_pk_f32_fp8_e32 v[214:215], v180
	v_cvt_pk_f32_fp8_sdwa v[216:217], v180 src0_sel:WORD_1
	v_cvt_pk_f32_fp8_e32 v[218:219], v181
	v_cvt_pk_f32_fp8_sdwa v[220:221], v181 src0_sel:WORD_1
	v_pk_mul_f32 v[222:223], v[48:49], v[214:215]
	v_pk_mul_f32 v[224:225], v[50:51], v[216:217]
	v_cvt_pk_f32_fp8_e32 v[214:215], v182
	v_cvt_pk_f32_fp8_sdwa v[216:217], v182 src0_sel:WORD_1
	v_pk_fma_f32 v[222:223], v[52:53], v[218:219], v[222:223]
	v_pk_fma_f32 v[224:225], v[54:55], v[220:221], v[224:225]
	v_cvt_pk_f32_fp8_e32 v[218:219], v183
	v_cvt_pk_f32_fp8_sdwa v[220:221], v183 src0_sel:WORD_1
	v_pk_fma_f32 v[222:223], v[56:57], v[214:215], v[222:223]
	v_pk_fma_f32 v[224:225], v[58:59], v[216:217], v[224:225]
	v_pk_fma_f32 v[222:223], v[60:61], v[218:219], v[222:223]
	v_pk_fma_f32 v[224:225], v[62:63], v[220:221], v[224:225]
	v_pk_add_f32 v[222:223], v[222:223], v[224:225]
	s_nop 0
	v_add_f32_e32 v227, v222, v223
	v_cvt_pk_f32_fp8_e32 v[214:215], v184
	v_cvt_pk_f32_fp8_sdwa v[216:217], v184 src0_sel:WORD_1
	v_cvt_pk_f32_fp8_e32 v[218:219], v185
	v_cvt_pk_f32_fp8_sdwa v[220:221], v185 src0_sel:WORD_1
; template <bool STORE>
; DI void peer_item(const Params& p, int item, char* smem) {
;     ...
;       for (int u = 0; u < 8; ++u) {
;         int e = e_s[tl * 128 + k + u];
;         uq[u] = *(const u32x4*)(U8 + (size_t)e * 1024 + lane * 16);
;       }
;       float part[8];
; #pragma unroll
;       for (int u = 0; u < 8; ++u) {
;         float d = 0.f;
; #pragma unroll
;         for (int i = 0; i < 4; ++i) {
;           f32x2_t lo = __builtin_amdgcn_cvt_pk_f32_fp8((int)uq[u][i], false);
;           f32x2_t hi = __builtin_amdgcn_cvt_pk_f32_fp8((int)uq[u][i], true);
;           d += xf[4 * i] * lo.x + xf[4 * i + 1] * lo.y + xf[4 * i + 2] * hi.x + xf[4 * i + 3] * hi.y;
;         }
;         part[u] = d;
;       }
;       float q4[4], r2[2], h;
; #pragma unroll
;       for (int j = 0; j < 4; ++j) {
;         float mine = b5 ? part[j + 4] : part[j];
;         float other = b5 ? part[j] : part[j + 4];
;         q4[j] = mine + __shfl_xor(other, 32);
;       }
; #pragma unroll
;       for (int j = 0; j < 2; ++j) {
;         float mine = b4 ? q4[j + 2] : q4[j];
;         float other = b4 ? q4[j] : q4[j + 2];
;         r2[j] = mine + __shfl_xor(other, 16);
;       }
;       {
;         float mine = b3 ? r2[1] : r2[0];
;         float other = b3 ? r2[0] : r2[1];
;         h = mine + __shfl_xor(other, 8);
;       }
;       h += __shfl_xor(h, 4);
;       h += __shfl_xor(h, 2);
;       h += __shfl_xor(h, 1);
	v_pk_mul_f32 v[222:223], v[48:49], v[214:215]
	v_pk_mul_f32 v[224:225], v[50:51], v[216:217]
	v_cvt_pk_f32_fp8_e32 v[214:215], v186
	v_cvt_pk_f32_fp8_sdwa v[216:217], v186 src0_sel:WORD_1
	v_pk_fma_f32 v[222:223], v[52:53], v[218:219], v[222:223]
	v_pk_fma_f32 v[224:225], v[54:55], v[220:221], v[224:225]
	v_cvt_pk_f32_fp8_e32 v[218:219], v187
	v_cvt_pk_f32_fp8_sdwa v[220:221], v187 src0_sel:WORD_1
	v_pk_fma_f32 v[222:223], v[56:57], v[214:215], v[222:223]
	v_pk_fma_f32 v[224:225], v[58:59], v[216:217], v[224:225]
	v_pk_fma_f32 v[222:223], v[60:61], v[218:219], v[222:223]
	v_pk_fma_f32 v[224:225], v[62:63], v[220:221], v[224:225]
	v_pk_add_f32 v[222:223], v[222:223], v[224:225]
	s_nop 0
	v_add_f32_e32 v228, v222, v223
	v_cvt_pk_f32_fp8_e32 v[214:215], v188
	v_cvt_pk_f32_fp8_sdwa v[216:217], v188 src0_sel:WORD_1
	v_cvt_pk_f32_fp8_e32 v[218:219], v189
	v_cvt_pk_f32_fp8_sdwa v[220:221], v189 src0_sel:WORD_1
	v_pk_mul_f32 v[222:223], v[48:49], v[214:215]
	v_pk_mul_f32 v[224:225], v[50:51], v[216:217]
	v_cvt_pk_f32_fp8_e32 v[214:215], v190
	v_cvt_pk_f32_fp8_sdwa v[216:217], v190 src0_sel:WORD_1
	v_pk_fma_f32 v[222:223], v[52:53], v[218:219], v[222:223]
	v_pk_fma_f32 v[224:225], v[54:55], v[220:221], v[224:225]
	v_cvt_pk_f32_fp8_e32 v[218:219], v191
	v_cvt_pk_f32_fp8_sdwa v[220:221], v191 src0_sel:WORD_1
	v_pk_fma_f32 v[222:223], v[56:57], v[214:215], v[222:223]
	v_pk_fma_f32 v[224:225], v[58:59], v[216:217], v[224:225]
	v_pk_fma_f32 v[222:223], v[60:61], v[218:219], v[222:223]
	v_pk_fma_f32 v[224:225], v[62:63], v[220:221], v[224:225]
	v_pk_add_f32 v[222:223], v[222:223], v[224:225]
	s_nop 0
	v_add_f32_e32 v229, v222, v223
	v_cvt_pk_f32_fp8_e32 v[214:215], v192
	v_cvt_pk_f32_fp8_sdwa v[216:217], v192 src0_sel:WORD_1
	v_cvt_pk_f32_fp8_e32 v[218:219], v193
	v_cvt_pk_f32_fp8_sdwa v[220:221], v193 src0_sel:WORD_1
	v_pk_mul_f32 v[222:223], v[48:49], v[214:215]
	v_pk_mul_f32 v[224:225], v[50:51], v[216:217]
	v_cvt_pk_f32_fp8_e32 v[214:215], v194
	v_cvt_pk_f32_fp8_sdwa v[216:217], v194 src0_sel:WORD_1
	v_pk_fma_f32 v[222:223], v[52:53], v[218:219], v[222:223]
	v_pk_fma_f32 v[224:225], v[54:55], v[220:221], v[224:225]
	v_cvt_pk_f32_fp8_e32 v[218:219], v195
	v_cvt_pk_f32_fp8_sdwa v[220:221], v195 src0_sel:WORD_1
	v_pk_fma_f32 v[222:223], v[56:57], v[214:215], v[222:223]
	v_pk_fma_f32 v[224:225], v[58:59], v[216:217], v[224:225]
	v_pk_fma_f32 v[222:223], v[60:61], v[218:219], v[222:223]
	v_pk_fma_f32 v[224:225], v[62:63], v[220:221], v[224:225]
	v_pk_add_f32 v[222:223], v[222:223], v[224:225]
	s_nop 0
	v_add_f32_e32 v230, v222, v223
	v_cvt_pk_f32_fp8_e32 v[214:215], v196
	v_cvt_pk_f32_fp8_sdwa v[216:217], v196 src0_sel:WORD_1
	v_cvt_pk_f32_fp8_e32 v[218:219], v197
	v_cvt_pk_f32_fp8_sdwa v[220:221], v197 src0_sel:WORD_1
	v_pk_mul_f32 v[222:223], v[48:49], v[214:215]
	v_pk_mul_f32 v[224:225], v[50:51], v[216:217]
	v_cvt_pk_f32_fp8_e32 v[214:215], v198
	v_cvt_pk_f32_fp8_sdwa v[216:217], v198 src0_sel:WORD_1
	v_pk_fma_f32 v[222:223], v[52:53], v[218:219], v[222:223]
	v_pk_fma_f32 v[224:225], v[54:55], v[220:221], v[224:225]
	v_cvt_pk_f32_fp8_e32 v[218:219], v199
	v_cvt_pk_f32_fp8_sdwa v[220:221], v199 src0_sel:WORD_1
	v_pk_fma_f32 v[222:223], v[56:57], v[214:215], v[222:223]
	v_pk_fma_f32 v[224:225], v[58:59], v[216:217], v[224:225]
	v_pk_fma_f32 v[222:223], v[60:61], v[218:219], v[222:223]
	v_pk_fma_f32 v[224:225], v[62:63], v[220:221], v[224:225]
	v_pk_add_f32 v[222:223], v[222:223], v[224:225]
	s_nop 0
	v_add_f32_e32 v231, v222, v223
	v_cvt_pk_f32_fp8_e32 v[214:215], v200
	v_cvt_pk_f32_fp8_sdwa v[216:217], v200 src0_sel:WORD_1
	v_cvt_pk_f32_fp8_e32 v[218:219], v201
	v_cvt_pk_f32_fp8_sdwa v[220:221], v201 src0_sel:WORD_1
	v_pk_mul_f32 v[222:223], v[48:49], v[214:215]
	v_pk_mul_f32 v[224:225], v[50:51], v[216:217]
	v_cvt_pk_f32_fp8_e32 v[214:215], v202
	v_cvt_pk_f32_fp8_sdwa v[216:217], v202 src0_sel:WORD_1
	v_pk_fma_f32 v[222:223], v[52:53], v[218:219], v[222:223]
	v_pk_fma_f32 v[224:225], v[54:55], v[220:221], v[224:225]
	v_cvt_pk_f32_fp8_e32 v[218:219], v203
	v_cvt_pk_f32_fp8_sdwa v[220:221], v203 src0_sel:WORD_1
	v_pk_fma_f32 v[222:223], v[56:57], v[214:215], v[222:223]
	v_pk_fma_f32 v[224:225], v[58:59], v[216:217], v[224:225]
	v_pk_fma_f32 v[222:223], v[60:61], v[218:219], v[222:223]
	v_pk_fma_f32 v[224:225], v[62:63], v[220:221], v[224:225]
	v_pk_add_f32 v[222:223], v[222:223], v[224:225]
	s_nop 0
	v_add_f32_e32 v232, v222, v223
	v_cvt_pk_f32_fp8_e32 v[214:215], v204
	v_cvt_pk_f32_fp8_sdwa v[216:217], v204 src0_sel:WORD_1
	v_cvt_pk_f32_fp8_e32 v[218:219], v205
	v_cvt_pk_f32_fp8_sdwa v[220:221], v205 src0_sel:WORD_1
	v_pk_mul_f32 v[222:223], v[48:49], v[214:215]
	v_pk_mul_f32 v[224:225], v[50:51], v[216:217]
	v_cvt_pk_f32_fp8_e32 v[214:215], v206
	v_cvt_pk_f32_fp8_sdwa v[216:217], v206 src0_sel:WORD_1
	v_pk_fma_f32 v[222:223], v[52:53], v[218:219], v[222:223]
	v_pk_fma_f32 v[224:225], v[54:55], v[220:221], v[224:225]
	v_cvt_pk_f32_fp8_e32 v[218:219], v207
	v_cvt_pk_f32_fp8_sdwa v[220:221], v207 src0_sel:WORD_1
	v_pk_fma_f32 v[222:223], v[56:57], v[214:215], v[222:223]
	v_pk_fma_f32 v[224:225], v[58:59], v[216:217], v[224:225]
	v_pk_fma_f32 v[222:223], v[60:61], v[218:219], v[222:223]
	v_pk_fma_f32 v[224:225], v[62:63], v[220:221], v[224:225]
	v_pk_add_f32 v[222:223], v[222:223], v[224:225]
	s_nop 0
	v_add_f32_e32 v233, v222, v223
	v_permlane32_swap_b32_e32 v226, v230
	v_permlane32_swap_b32_e32 v227, v231
	v_permlane32_swap_b32_e32 v228, v232
	v_permlane32_swap_b32_e32 v229, v233
	v_add_f32_e32 v226, v226, v230
	v_add_f32_e32 v228, v228, v232
	v_add_f32_e32 v227, v227, v231
	v_add_f32_e32 v229, v229, v233
	s_nop 1
	v_permlane16_swap_b32_e32 v226, v228
; template <bool STORE>
; DI void peer_item(const Params& p, int item, char* smem) {
;     ...
; #pragma unroll
;       for (int u = 0; u < 8; ++u) {
;         int e = e_s[tl * 128 + k + u];
;         uq[u] = *(const u32x4*)(U8 + (size_t)e * 1024 + lane * 16);
;       }
;       float part[8];
; #pragma unroll
;       for (int u = 0; u < 8; ++u) {
;         float d = 0.f;
; #pragma unroll
;         for (int i = 0; i < 4; ++i) {
;           f32x2_t lo = __builtin_amdgcn_cvt_pk_f32_fp8((int)uq[u][i], false);
;           f32x2_t hi = __builtin_amdgcn_cvt_pk_f32_fp8((int)uq[u][i], true);
;           d += xf[4 * i] * lo.x + xf[4 * i + 1] * lo.y + xf[4 * i + 2] * hi.x + xf[4 * i + 3] * hi.y;
;         }
;         part[u] = d;
;       }
;       float q4[4], r2[2], h;
; #pragma unroll
;       for (int j = 0; j < 4; ++j) {
;         float mine = b5 ? part[j + 4] : part[j];
;         float other = b5 ? part[j] : part[j + 4];
;         q4[j] = mine + __shfl_xor(other, 32);
;       }
; #pragma unroll
;       for (int j = 0; j < 2; ++j) {
;         float mine = b4 ? q4[j + 2] : q4[j];
;         float other = b4 ? q4[j] : q4[j + 2];
;         r2[j] = mine + __shfl_xor(other, 16);
;       }
;       {
;         float mine = b3 ? r2[1] : r2[0];
;         float other = b3 ? r2[0] : r2[1];
;         h = mine + __shfl_xor(other, 8);
;       }
;       h += __shfl_xor(h, 4);
;       h += __shfl_xor(h, 2);
;       h += __shfl_xor(h, 1);
	v_permlane16_swap_b32_e32 v227, v229
	v_add_f32_e32 v226, v226, v228
	v_add_f32_e32 v227, v227, v229
	s_nop 0
	v_cndmask_b32_e64 v230, v226, v227, s[24:25]
	v_cndmask_b32_e64 v231, v227, v226, s[24:25]
	s_nop 1
	v_add_f32_dpp v232, v231, v230 row_ror:8 row_mask:0xf bank_mask:0xf
	s_nop 1
	v_add_f32_dpp v233, v232, v232 quad_perm:[1,0,3,2] row_mask:0xf bank_mask:0xf
	s_nop 1
	v_add_f32_dpp v232, v233, v233 quad_perm:[2,3,0,1] row_mask:0xf bank_mask:0xf
	s_nop 1
	v_add_f32_dpp v233, v232, v232 row_half_mirror row_mask:0xf bank_mask:0xf
	ds_write_b32 v235, v233 offset:34336
	v_readlane_b32 s48, v139, s72
	v_readlane_b32 s49, v139, s73
	v_readlane_b32 s50, v139, s74
	v_readlane_b32 s51, v139, s75
	v_readlane_b32 s52, v139, s76
	v_readlane_b32 s53, v139, s77
	v_readlane_b32 s54, v139, s78
	v_readlane_b32 s55, v139, s79
	s_add_u32 s32, s0, s48
	s_addc_u32 s33, s1, 0
	s_add_u32 s34, s0, s49
	s_addc_u32 s35, s1, 0
	s_add_u32 s36, s0, s50
	s_addc_u32 s37, s1, 0
	s_add_u32 s38, s0, s51
	s_addc_u32 s39, s1, 0
	s_add_u32 s40, s0, s52
	s_addc_u32 s41, s1, 0
	s_add_u32 s42, s0, s53
	s_addc_u32 s43, s1, 0
	s_add_u32 s44, s0, s54
	s_addc_u32 s45, s1, 0
	s_add_u32 s46, s0, s55
	s_addc_u32 s47, s1, 0
	global_load_dwordx4 v[176:179], v234, s[32:33]
	global_load_dwordx4 v[180:183], v234, s[34:35]
	global_load_dwordx4 v[184:187], v234, s[36:37]
	global_load_dwordx4 v[188:191], v234, s[38:39]
	global_load_dwordx4 v[192:195], v234, s[40:41]
	global_load_dwordx4 v[196:199], v234, s[42:43]
	global_load_dwordx4 v[200:203], v234, s[44:45]
	global_load_dwordx4 v[204:207], v234, s[46:47]
	s_waitcnt vmcnt(8)
	v_cvt_pk_f32_fp8_e32 v[214:215], v144
	v_cvt_pk_f32_fp8_sdwa v[216:217], v144 src0_sel:WORD_1
	v_cvt_pk_f32_fp8_e32 v[218:219], v145
	v_cvt_pk_f32_fp8_sdwa v[220:221], v145 src0_sel:WORD_1
	v_pk_mul_f32 v[222:223], v[64:65], v[214:215]
	v_pk_mul_f32 v[224:225], v[66:67], v[216:217]
	v_cvt_pk_f32_fp8_e32 v[214:215], v146
	v_cvt_pk_f32_fp8_sdwa v[216:217], v146 src0_sel:WORD_1
	v_pk_fma_f32 v[222:223], v[68:69], v[218:219], v[222:223]
	v_pk_fma_f32 v[224:225], v[70:71], v[220:221], v[224:225]
	v_cvt_pk_f32_fp8_e32 v[218:219], v147
	v_cvt_pk_f32_fp8_sdwa v[220:221], v147 src0_sel:WORD_1
	v_pk_fma_f32 v[222:223], v[72:73], v[214:215], v[222:223]
	v_pk_fma_f32 v[224:225], v[74:75], v[216:217], v[224:225]
	v_pk_fma_f32 v[222:223], v[76:77], v[218:219], v[222:223]
	v_pk_fma_f32 v[224:225], v[78:79], v[220:221], v[224:225]
	v_pk_add_f32 v[222:223], v[222:223], v[224:225]
	s_nop 0
	v_add_f32_e32 v226, v222, v223
	v_cvt_pk_f32_fp8_e32 v[214:215], v148
	v_cvt_pk_f32_fp8_sdwa v[216:217], v148 src0_sel:WORD_1
	v_cvt_pk_f32_fp8_e32 v[218:219], v149
	v_cvt_pk_f32_fp8_sdwa v[220:221], v149 src0_sel:WORD_1
	v_pk_mul_f32 v[222:223], v[64:65], v[214:215]
	v_pk_mul_f32 v[224:225], v[66:67], v[216:217]
	v_cvt_pk_f32_fp8_e32 v[214:215], v150
	v_cvt_pk_f32_fp8_sdwa v[216:217], v150 src0_sel:WORD_1
	v_pk_fma_f32 v[222:223], v[68:69], v[218:219], v[222:223]
	v_pk_fma_f32 v[224:225], v[70:71], v[220:221], v[224:225]
	v_cvt_pk_f32_fp8_e32 v[218:219], v151
	v_cvt_pk_f32_fp8_sdwa v[220:221], v151 src0_sel:WORD_1
	v_pk_fma_f32 v[222:223], v[72:73], v[214:215], v[222:223]
	v_pk_fma_f32 v[224:225], v[74:75], v[216:217], v[224:225]
	v_pk_fma_f32 v[222:223], v[76:77], v[218:219], v[222:223]
	v_pk_fma_f32 v[224:225], v[78:79], v[220:221], v[224:225]
	v_pk_add_f32 v[222:223], v[222:223], v[224:225]
	s_nop 0
	v_add_f32_e32 v227, v222, v223
	v_cvt_pk_f32_fp8_e32 v[214:215], v152
	v_cvt_pk_f32_fp8_sdwa v[216:217], v152 src0_sel:WORD_1
	v_cvt_pk_f32_fp8_e32 v[218:219], v153
	v_cvt_pk_f32_fp8_sdwa v[220:221], v153 src0_sel:WORD_1
	v_pk_mul_f32 v[222:223], v[64:65], v[214:215]
	v_pk_mul_f32 v[224:225], v[66:67], v[216:217]
	v_cvt_pk_f32_fp8_e32 v[214:215], v154
	v_cvt_pk_f32_fp8_sdwa v[216:217], v154 src0_sel:WORD_1
	v_pk_fma_f32 v[222:223], v[68:69], v[218:219], v[222:223]
	v_pk_fma_f32 v[224:225], v[70:71], v[220:221], v[224:225]
	v_cvt_pk_f32_fp8_e32 v[218:219], v155
	v_cvt_pk_f32_fp8_sdwa v[220:221], v155 src0_sel:WORD_1
	v_pk_fma_f32 v[222:223], v[72:73], v[214:215], v[222:223]
	v_pk_fma_f32 v[224:225], v[74:75], v[216:217], v[224:225]
	v_pk_fma_f32 v[222:223], v[76:77], v[218:219], v[222:223]
	v_pk_fma_f32 v[224:225], v[78:79], v[220:221], v[224:225]
	v_pk_add_f32 v[222:223], v[222:223], v[224:225]
	s_nop 0
	v_add_f32_e32 v228, v222, v223
	v_cvt_pk_f32_fp8_e32 v[214:215], v156
	v_cvt_pk_f32_fp8_sdwa v[216:217], v156 src0_sel:WORD_1
	v_cvt_pk_f32_fp8_e32 v[218:219], v157
	v_cvt_pk_f32_fp8_sdwa v[220:221], v157 src0_sel:WORD_1
	v_pk_mul_f32 v[222:223], v[64:65], v[214:215]
	v_pk_mul_f32 v[224:225], v[66:67], v[216:217]
	v_cvt_pk_f32_fp8_e32 v[214:215], v158
	v_cvt_pk_f32_fp8_sdwa v[216:217], v158 src0_sel:WORD_1
	v_pk_fma_f32 v[222:223], v[68:69], v[218:219], v[222:223]
	v_pk_fma_f32 v[224:225], v[70:71], v[220:221], v[224:225]
	v_cvt_pk_f32_fp8_e32 v[218:219], v159
	v_cvt_pk_f32_fp8_sdwa v[220:221], v159 src0_sel:WORD_1
	v_pk_fma_f32 v[222:223], v[72:73], v[214:215], v[222:223]
	v_pk_fma_f32 v[224:225], v[74:75], v[216:217], v[224:225]
	v_pk_fma_f32 v[222:223], v[76:77], v[218:219], v[222:223]
	v_pk_fma_f32 v[224:225], v[78:79], v[220:221], v[224:225]
	v_pk_add_f32 v[222:223], v[222:223], v[224:225]
	s_nop 0
	v_add_f32_e32 v229, v222, v223
	v_cvt_pk_f32_fp8_e32 v[214:215], v160
	v_cvt_pk_f32_fp8_sdwa v[216:217], v160 src0_sel:WORD_1
	v_cvt_pk_f32_fp8_e32 v[218:219], v161
	v_cvt_pk_f32_fp8_sdwa v[220:221], v161 src0_sel:WORD_1
	v_pk_mul_f32 v[222:223], v[64:65], v[214:215]
	v_pk_mul_f32 v[224:225], v[66:67], v[216:217]
	v_cvt_pk_f32_fp8_e32 v[214:215], v162
	v_cvt_pk_f32_fp8_sdwa v[216:217], v162 src0_sel:WORD_1
; template <bool STORE>
; DI void peer_item(const Params& p, int item, char* smem) {
;     ...
; #pragma unroll
;       for (int u = 0; u < 8; ++u) {
;         int e = e_s[tl * 128 + k + u];
;         uq[u] = *(const u32x4*)(U8 + (size_t)e * 1024 + lane * 16);
;       }
;       float part[8];
; #pragma unroll
;       for (int u = 0; u < 8; ++u) {
;         float d = 0.f;
; #pragma unroll
;         for (int i = 0; i < 4; ++i) {
;           f32x2_t lo = __builtin_amdgcn_cvt_pk_f32_fp8((int)uq[u][i], false);
;           f32x2_t hi = __builtin_amdgcn_cvt_pk_f32_fp8((int)uq[u][i], true);
;           d += xf[4 * i] * lo.x + xf[4 * i + 1] * lo.y + xf[4 * i + 2] * hi.x + xf[4 * i + 3] * hi.y;
;         }
;         part[u] = d;
;       }
;       float q4[4], r2[2], h;
; #pragma unroll
;       for (int j = 0; j < 4; ++j) {
;         float mine = b5 ? part[j + 4] : part[j];
;         float other = b5 ? part[j] : part[j + 4];
;         q4[j] = mine + __shfl_xor(other, 32);
;       }
; #pragma unroll
;       for (int j = 0; j < 2; ++j) {
;         float mine = b4 ? q4[j + 2] : q4[j];
;         float other = b4 ? q4[j] : q4[j + 2];
;         r2[j] = mine + __shfl_xor(other, 16);
;       }
;       {
;         float mine = b3 ? r2[1] : r2[0];
;         float other = b3 ? r2[0] : r2[1];
;         h = mine + __shfl_xor(other, 8);
;       }
;       h += __shfl_xor(h, 4);
;       h += __shfl_xor(h, 2);
;       h += __shfl_xor(h, 1);
	v_pk_fma_f32 v[222:223], v[68:69], v[218:219], v[222:223]
	v_pk_fma_f32 v[224:225], v[70:71], v[220:221], v[224:225]
	v_cvt_pk_f32_fp8_e32 v[218:219], v163
	v_cvt_pk_f32_fp8_sdwa v[220:221], v163 src0_sel:WORD_1
	v_pk_fma_f32 v[222:223], v[72:73], v[214:215], v[222:223]
	v_pk_fma_f32 v[224:225], v[74:75], v[216:217], v[224:225]
	v_pk_fma_f32 v[222:223], v[76:77], v[218:219], v[222:223]
	v_pk_fma_f32 v[224:225], v[78:79], v[220:221], v[224:225]
	v_pk_add_f32 v[222:223], v[222:223], v[224:225]
	s_nop 0
	v_add_f32_e32 v230, v222, v223
	v_cvt_pk_f32_fp8_e32 v[214:215], v164
	v_cvt_pk_f32_fp8_sdwa v[216:217], v164 src0_sel:WORD_1
	v_cvt_pk_f32_fp8_e32 v[218:219], v165
	v_cvt_pk_f32_fp8_sdwa v[220:221], v165 src0_sel:WORD_1
	v_pk_mul_f32 v[222:223], v[64:65], v[214:215]
	v_pk_mul_f32 v[224:225], v[66:67], v[216:217]
	v_cvt_pk_f32_fp8_e32 v[214:215], v166
	v_cvt_pk_f32_fp8_sdwa v[216:217], v166 src0_sel:WORD_1
	v_pk_fma_f32 v[222:223], v[68:69], v[218:219], v[222:223]
	v_pk_fma_f32 v[224:225], v[70:71], v[220:221], v[224:225]
	v_cvt_pk_f32_fp8_e32 v[218:219], v167
	v_cvt_pk_f32_fp8_sdwa v[220:221], v167 src0_sel:WORD_1
	v_pk_fma_f32 v[222:223], v[72:73], v[214:215], v[222:223]
	v_pk_fma_f32 v[224:225], v[74:75], v[216:217], v[224:225]
	v_pk_fma_f32 v[222:223], v[76:77], v[218:219], v[222:223]
	v_pk_fma_f32 v[224:225], v[78:79], v[220:221], v[224:225]
	v_pk_add_f32 v[222:223], v[222:223], v[224:225]
	s_nop 0
	v_add_f32_e32 v231, v222, v223
	v_cvt_pk_f32_fp8_e32 v[214:215], v168
	v_cvt_pk_f32_fp8_sdwa v[216:217], v168 src0_sel:WORD_1
	v_cvt_pk_f32_fp8_e32 v[218:219], v169
	v_cvt_pk_f32_fp8_sdwa v[220:221], v169 src0_sel:WORD_1
	v_pk_mul_f32 v[222:223], v[64:65], v[214:215]
	v_pk_mul_f32 v[224:225], v[66:67], v[216:217]
	v_cvt_pk_f32_fp8_e32 v[214:215], v170
	v_cvt_pk_f32_fp8_sdwa v[216:217], v170 src0_sel:WORD_1
	v_pk_fma_f32 v[222:223], v[68:69], v[218:219], v[222:223]
	v_pk_fma_f32 v[224:225], v[70:71], v[220:221], v[224:225]
	v_cvt_pk_f32_fp8_e32 v[218:219], v171
	v_cvt_pk_f32_fp8_sdwa v[220:221], v171 src0_sel:WORD_1
	v_pk_fma_f32 v[222:223], v[72:73], v[214:215], v[222:223]
	v_pk_fma_f32 v[224:225], v[74:75], v[216:217], v[224:225]
	v_pk_fma_f32 v[222:223], v[76:77], v[218:219], v[222:223]
	v_pk_fma_f32 v[224:225], v[78:79], v[220:221], v[224:225]
	v_pk_add_f32 v[222:223], v[222:223], v[224:225]
	s_nop 0
	v_add_f32_e32 v232, v222, v223
	v_cvt_pk_f32_fp8_e32 v[214:215], v172
	v_cvt_pk_f32_fp8_sdwa v[216:217], v172 src0_sel:WORD_1
	v_cvt_pk_f32_fp8_e32 v[218:219], v173
	v_cvt_pk_f32_fp8_sdwa v[220:221], v173 src0_sel:WORD_1
	v_pk_mul_f32 v[222:223], v[64:65], v[214:215]
	v_pk_mul_f32 v[224:225], v[66:67], v[216:217]
	v_cvt_pk_f32_fp8_e32 v[214:215], v174
	v_cvt_pk_f32_fp8_sdwa v[216:217], v174 src0_sel:WORD_1
	v_pk_fma_f32 v[222:223], v[68:69], v[218:219], v[222:223]
	v_pk_fma_f32 v[224:225], v[70:71], v[220:221], v[224:225]
	v_cvt_pk_f32_fp8_e32 v[218:219], v175
	v_cvt_pk_f32_fp8_sdwa v[220:221], v175 src0_sel:WORD_1
	v_pk_fma_f32 v[222:223], v[72:73], v[214:215], v[222:223]
	v_pk_fma_f32 v[224:225], v[74:75], v[216:217], v[224:225]
	v_pk_fma_f32 v[222:223], v[76:77], v[218:219], v[222:223]
	v_pk_fma_f32 v[224:225], v[78:79], v[220:221], v[224:225]
	v_pk_add_f32 v[222:223], v[222:223], v[224:225]
	s_nop 0
	v_add_f32_e32 v233, v222, v223
	v_permlane32_swap_b32_e32 v226, v230
	v_permlane32_swap_b32_e32 v227, v231
	v_permlane32_swap_b32_e32 v228, v232
	v_permlane32_swap_b32_e32 v229, v233
	v_add_f32_e32 v226, v226, v230
	v_add_f32_e32 v228, v228, v232
	v_add_f32_e32 v227, v227, v231
	v_add_f32_e32 v229, v229, v233
	s_nop 1
	v_permlane16_swap_b32_e32 v226, v228
	v_permlane16_swap_b32_e32 v227, v229
	v_add_f32_e32 v226, v226, v228
	v_add_f32_e32 v227, v227, v229
	s_nop 0
	v_cndmask_b32_e64 v230, v226, v227, s[24:25]
	v_cndmask_b32_e64 v231, v227, v226, s[24:25]
	s_nop 1
	v_add_f32_dpp v232, v231, v230 row_ror:8 row_mask:0xf bank_mask:0xf
	s_nop 1
	v_add_f32_dpp v233, v232, v232 quad_perm:[1,0,3,2] row_mask:0xf bank_mask:0xf
	s_nop 1
	v_add_f32_dpp v232, v233, v233 quad_perm:[2,3,0,1] row_mask:0xf bank_mask:0xf
	s_nop 1
	v_add_f32_dpp v233, v232, v232 row_half_mirror row_mask:0xf bank_mask:0xf
	ds_write_b32 v235, v233 offset:34848
	v_readlane_b32 s48, v141, s72
	v_readlane_b32 s49, v141, s73
	v_readlane_b32 s50, v141, s74
	v_readlane_b32 s51, v141, s75
	v_readlane_b32 s52, v141, s76
	v_readlane_b32 s53, v141, s77
	v_readlane_b32 s54, v141, s78
	v_readlane_b32 s55, v141, s79
	s_add_u32 s32, s0, s48
	s_addc_u32 s33, s1, 0
	s_add_u32 s34, s0, s49
	s_addc_u32 s35, s1, 0
	s_add_u32 s36, s0, s50
	s_addc_u32 s37, s1, 0
	s_add_u32 s38, s0, s51
	s_addc_u32 s39, s1, 0
	s_add_u32 s40, s0, s52
	s_addc_u32 s41, s1, 0
	s_add_u32 s42, s0, s53
	s_addc_u32 s43, s1, 0
	s_add_u32 s44, s0, s54
	s_addc_u32 s45, s1, 0
	s_add_u32 s46, s0, s55
	s_addc_u32 s47, s1, 0
	global_load_dwordx4 v[144:147], v234, s[32:33]
	global_load_dwordx4 v[148:151], v234, s[34:35]
	global_load_dwordx4 v[152:155], v234, s[36:37]
	global_load_dwordx4 v[156:159], v234, s[38:39]
	global_load_dwordx4 v[160:163], v234, s[40:41]
	global_load_dwordx4 v[164:167], v234, s[42:43]
	global_load_dwordx4 v[168:171], v234, s[44:45]
	global_load_dwordx4 v[172:175], v234, s[46:47]
	s_waitcnt vmcnt(8)
; template <bool STORE>
; DI void peer_item(const Params& p, int item, char* smem) {
;     ...
;       for (int u = 0; u < 8; ++u) {
;         int e = e_s[tl * 128 + k + u];
;         uq[u] = *(const u32x4*)(U8 + (size_t)e * 1024 + lane * 16);
;       }
;       float part[8];
; #pragma unroll
;       for (int u = 0; u < 8; ++u) {
;         float d = 0.f;
; #pragma unroll
;         for (int i = 0; i < 4; ++i) {
;           f32x2_t lo = __builtin_amdgcn_cvt_pk_f32_fp8((int)uq[u][i], false);
;           f32x2_t hi = __builtin_amdgcn_cvt_pk_f32_fp8((int)uq[u][i], true);
;           d += xf[4 * i] * lo.x + xf[4 * i + 1] * lo.y + xf[4 * i + 2] * hi.x + xf[4 * i + 3] * hi.y;
;         }
;         part[u] = d;
;       }
	v_cvt_pk_f32_fp8_e32 v[214:215], v176
	v_cvt_pk_f32_fp8_sdwa v[216:217], v176 src0_sel:WORD_1
	v_cvt_pk_f32_fp8_e32 v[218:219], v177
	v_cvt_pk_f32_fp8_sdwa v[220:221], v177 src0_sel:WORD_1
	v_pk_mul_f32 v[222:223], v[80:81], v[214:215]
	v_pk_mul_f32 v[224:225], v[82:83], v[216:217]
	v_cvt_pk_f32_fp8_e32 v[214:215], v178
	v_cvt_pk_f32_fp8_sdwa v[216:217], v178 src0_sel:WORD_1
	v_pk_fma_f32 v[222:223], v[84:85], v[218:219], v[222:223]
	v_pk_fma_f32 v[224:225], v[86:87], v[220:221], v[224:225]
	v_cvt_pk_f32_fp8_e32 v[218:219], v179
	v_cvt_pk_f32_fp8_sdwa v[220:221], v179 src0_sel:WORD_1
	v_pk_fma_f32 v[222:223], v[88:89], v[214:215], v[222:223]
	v_pk_fma_f32 v[224:225], v[90:91], v[216:217], v[224:225]
	v_pk_fma_f32 v[222:223], v[92:93], v[218:219], v[222:223]
	v_pk_fma_f32 v[224:225], v[94:95], v[220:221], v[224:225]
	v_pk_add_f32 v[222:223], v[222:223], v[224:225]
	s_nop 0
	v_add_f32_e32 v226, v222, v223
	v_cvt_pk_f32_fp8_e32 v[214:215], v180
	v_cvt_pk_f32_fp8_sdwa v[216:217], v180 src0_sel:WORD_1
	v_cvt_pk_f32_fp8_e32 v[218:219], v181
	v_cvt_pk_f32_fp8_sdwa v[220:221], v181 src0_sel:WORD_1
	v_pk_mul_f32 v[222:223], v[80:81], v[214:215]
	v_pk_mul_f32 v[224:225], v[82:83], v[216:217]
	v_cvt_pk_f32_fp8_e32 v[214:215], v182
	v_cvt_pk_f32_fp8_sdwa v[216:217], v182 src0_sel:WORD_1
	v_pk_fma_f32 v[222:223], v[84:85], v[218:219], v[222:223]
	v_pk_fma_f32 v[224:225], v[86:87], v[220:221], v[224:225]
	v_cvt_pk_f32_fp8_e32 v[218:219], v183
	v_cvt_pk_f32_fp8_sdwa v[220:221], v183 src0_sel:WORD_1
	v_pk_fma_f32 v[222:223], v[88:89], v[214:215], v[222:223]
	v_pk_fma_f32 v[224:225], v[90:91], v[216:217], v[224:225]
	v_pk_fma_f32 v[222:223], v[92:93], v[218:219], v[222:223]
	v_pk_fma_f32 v[224:225], v[94:95], v[220:221], v[224:225]
	v_pk_add_f32 v[222:223], v[222:223], v[224:225]
	s_nop 0
	v_add_f32_e32 v227, v222, v223
	v_cvt_pk_f32_fp8_e32 v[214:215], v184
	v_cvt_pk_f32_fp8_sdwa v[216:217], v184 src0_sel:WORD_1
	v_cvt_pk_f32_fp8_e32 v[218:219], v185
	v_cvt_pk_f32_fp8_sdwa v[220:221], v185 src0_sel:WORD_1
	v_pk_mul_f32 v[222:223], v[80:81], v[214:215]
	v_pk_mul_f32 v[224:225], v[82:83], v[216:217]
	v_cvt_pk_f32_fp8_e32 v[214:215], v186
	v_cvt_pk_f32_fp8_sdwa v[216:217], v186 src0_sel:WORD_1
	v_pk_fma_f32 v[222:223], v[84:85], v[218:219], v[222:223]
	v_pk_fma_f32 v[224:225], v[86:87], v[220:221], v[224:225]
	v_cvt_pk_f32_fp8_e32 v[218:219], v187
	v_cvt_pk_f32_fp8_sdwa v[220:221], v187 src0_sel:WORD_1
	v_pk_fma_f32 v[222:223], v[88:89], v[214:215], v[222:223]
	v_pk_fma_f32 v[224:225], v[90:91], v[216:217], v[224:225]
	v_pk_fma_f32 v[222:223], v[92:93], v[218:219], v[222:223]
	v_pk_fma_f32 v[224:225], v[94:95], v[220:221], v[224:225]
	v_pk_add_f32 v[222:223], v[222:223], v[224:225]
	s_nop 0
	v_add_f32_e32 v228, v222, v223
	v_cvt_pk_f32_fp8_e32 v[214:215], v188
	v_cvt_pk_f32_fp8_sdwa v[216:217], v188 src0_sel:WORD_1
	v_cvt_pk_f32_fp8_e32 v[218:219], v189
	v_cvt_pk_f32_fp8_sdwa v[220:221], v189 src0_sel:WORD_1
	v_pk_mul_f32 v[222:223], v[80:81], v[214:215]
	v_pk_mul_f32 v[224:225], v[82:83], v[216:217]
	v_cvt_pk_f32_fp8_e32 v[214:215], v190
	v_cvt_pk_f32_fp8_sdwa v[216:217], v190 src0_sel:WORD_1
	v_pk_fma_f32 v[222:223], v[84:85], v[218:219], v[222:223]
	v_pk_fma_f32 v[224:225], v[86:87], v[220:221], v[224:225]
	v_cvt_pk_f32_fp8_e32 v[218:219], v191
	v_cvt_pk_f32_fp8_sdwa v[220:221], v191 src0_sel:WORD_1
	v_pk_fma_f32 v[222:223], v[88:89], v[214:215], v[222:223]
	v_pk_fma_f32 v[224:225], v[90:91], v[216:217], v[224:225]
	v_pk_fma_f32 v[222:223], v[92:93], v[218:219], v[222:223]
	v_pk_fma_f32 v[224:225], v[94:95], v[220:221], v[224:225]
	v_pk_add_f32 v[222:223], v[222:223], v[224:225]
	s_nop 0
	v_add_f32_e32 v229, v222, v223
	v_cvt_pk_f32_fp8_e32 v[214:215], v192
	v_cvt_pk_f32_fp8_sdwa v[216:217], v192 src0_sel:WORD_1
	v_cvt_pk_f32_fp8_e32 v[218:219], v193
	v_cvt_pk_f32_fp8_sdwa v[220:221], v193 src0_sel:WORD_1
	v_pk_mul_f32 v[222:223], v[80:81], v[214:215]
	v_pk_mul_f32 v[224:225], v[82:83], v[216:217]
	v_cvt_pk_f32_fp8_e32 v[214:215], v194
	v_cvt_pk_f32_fp8_sdwa v[216:217], v194 src0_sel:WORD_1
	v_pk_fma_f32 v[222:223], v[84:85], v[218:219], v[222:223]
	v_pk_fma_f32 v[224:225], v[86:87], v[220:221], v[224:225]
	v_cvt_pk_f32_fp8_e32 v[218:219], v195
	v_cvt_pk_f32_fp8_sdwa v[220:221], v195 src0_sel:WORD_1
	v_pk_fma_f32 v[222:223], v[88:89], v[214:215], v[222:223]
	v_pk_fma_f32 v[224:225], v[90:91], v[216:217], v[224:225]
	v_pk_fma_f32 v[222:223], v[92:93], v[218:219], v[222:223]
	v_pk_fma_f32 v[224:225], v[94:95], v[220:221], v[224:225]
	v_pk_add_f32 v[222:223], v[222:223], v[224:225]
	s_nop 0
	v_add_f32_e32 v230, v222, v223
	v_cvt_pk_f32_fp8_e32 v[214:215], v196
	v_cvt_pk_f32_fp8_sdwa v[216:217], v196 src0_sel:WORD_1
	v_cvt_pk_f32_fp8_e32 v[218:219], v197
	v_cvt_pk_f32_fp8_sdwa v[220:221], v197 src0_sel:WORD_1
	v_pk_mul_f32 v[222:223], v[80:81], v[214:215]
	v_pk_mul_f32 v[224:225], v[82:83], v[216:217]
	v_cvt_pk_f32_fp8_e32 v[214:215], v198
	v_cvt_pk_f32_fp8_sdwa v[216:217], v198 src0_sel:WORD_1
	v_pk_fma_f32 v[222:223], v[84:85], v[218:219], v[222:223]
	v_pk_fma_f32 v[224:225], v[86:87], v[220:221], v[224:225]
	v_cvt_pk_f32_fp8_e32 v[218:219], v199
	v_cvt_pk_f32_fp8_sdwa v[220:221], v199 src0_sel:WORD_1
	v_pk_fma_f32 v[222:223], v[88:89], v[214:215], v[222:223]
	v_pk_fma_f32 v[224:225], v[90:91], v[216:217], v[224:225]
	v_pk_fma_f32 v[222:223], v[92:93], v[218:219], v[222:223]
	v_pk_fma_f32 v[224:225], v[94:95], v[220:221], v[224:225]
	v_pk_add_f32 v[222:223], v[222:223], v[224:225]
	s_nop 0
	v_add_f32_e32 v231, v222, v223
	v_cvt_pk_f32_fp8_e32 v[214:215], v200
	v_cvt_pk_f32_fp8_sdwa v[216:217], v200 src0_sel:WORD_1
	v_cvt_pk_f32_fp8_e32 v[218:219], v201
; template <bool STORE>
; DI void peer_item(const Params& p, int item, char* smem) {
;     ...
; #pragma unroll
;       for (int u = 0; u < 8; ++u) {
;         int e = e_s[tl * 128 + k + u];
;         uq[u] = *(const u32x4*)(U8 + (size_t)e * 1024 + lane * 16);
;       }
;       float part[8];
; #pragma unroll
;       for (int u = 0; u < 8; ++u) {
;         float d = 0.f;
; #pragma unroll
;         for (int i = 0; i < 4; ++i) {
;           f32x2_t lo = __builtin_amdgcn_cvt_pk_f32_fp8((int)uq[u][i], false);
;           f32x2_t hi = __builtin_amdgcn_cvt_pk_f32_fp8((int)uq[u][i], true);
;           d += xf[4 * i] * lo.x + xf[4 * i + 1] * lo.y + xf[4 * i + 2] * hi.x + xf[4 * i + 3] * hi.y;
;         }
;         part[u] = d;
;       }
;       float q4[4], r2[2], h;
; #pragma unroll
;       for (int j = 0; j < 4; ++j) {
;         float mine = b5 ? part[j + 4] : part[j];
;         float other = b5 ? part[j] : part[j + 4];
;         q4[j] = mine + __shfl_xor(other, 32);
;       }
; #pragma unroll
;       for (int j = 0; j < 2; ++j) {
;         float mine = b4 ? q4[j + 2] : q4[j];
;         float other = b4 ? q4[j] : q4[j + 2];
;         r2[j] = mine + __shfl_xor(other, 16);
;       }
;       {
;         float mine = b3 ? r2[1] : r2[0];
;         float other = b3 ? r2[0] : r2[1];
;         h = mine + __shfl_xor(other, 8);
;       }
;       h += __shfl_xor(h, 4);
;       h += __shfl_xor(h, 2);
;       h += __shfl_xor(h, 1);
	v_cvt_pk_f32_fp8_sdwa v[220:221], v201 src0_sel:WORD_1
	v_pk_mul_f32 v[222:223], v[80:81], v[214:215]
	v_pk_mul_f32 v[224:225], v[82:83], v[216:217]
	v_cvt_pk_f32_fp8_e32 v[214:215], v202
	v_cvt_pk_f32_fp8_sdwa v[216:217], v202 src0_sel:WORD_1
	v_pk_fma_f32 v[222:223], v[84:85], v[218:219], v[222:223]
	v_pk_fma_f32 v[224:225], v[86:87], v[220:221], v[224:225]
	v_cvt_pk_f32_fp8_e32 v[218:219], v203
	v_cvt_pk_f32_fp8_sdwa v[220:221], v203 src0_sel:WORD_1
	v_pk_fma_f32 v[222:223], v[88:89], v[214:215], v[222:223]
	v_pk_fma_f32 v[224:225], v[90:91], v[216:217], v[224:225]
	v_pk_fma_f32 v[222:223], v[92:93], v[218:219], v[222:223]
	v_pk_fma_f32 v[224:225], v[94:95], v[220:221], v[224:225]
	v_pk_add_f32 v[222:223], v[222:223], v[224:225]
	s_nop 0
	v_add_f32_e32 v232, v222, v223
	v_cvt_pk_f32_fp8_e32 v[214:215], v204
	v_cvt_pk_f32_fp8_sdwa v[216:217], v204 src0_sel:WORD_1
	v_cvt_pk_f32_fp8_e32 v[218:219], v205
	v_cvt_pk_f32_fp8_sdwa v[220:221], v205 src0_sel:WORD_1
	v_pk_mul_f32 v[222:223], v[80:81], v[214:215]
	v_pk_mul_f32 v[224:225], v[82:83], v[216:217]
	v_cvt_pk_f32_fp8_e32 v[214:215], v206
	v_cvt_pk_f32_fp8_sdwa v[216:217], v206 src0_sel:WORD_1
	v_pk_fma_f32 v[222:223], v[84:85], v[218:219], v[222:223]
	v_pk_fma_f32 v[224:225], v[86:87], v[220:221], v[224:225]
	v_cvt_pk_f32_fp8_e32 v[218:219], v207
	v_cvt_pk_f32_fp8_sdwa v[220:221], v207 src0_sel:WORD_1
	v_pk_fma_f32 v[222:223], v[88:89], v[214:215], v[222:223]
	v_pk_fma_f32 v[224:225], v[90:91], v[216:217], v[224:225]
	v_pk_fma_f32 v[222:223], v[92:93], v[218:219], v[222:223]
	v_pk_fma_f32 v[224:225], v[94:95], v[220:221], v[224:225]
	v_pk_add_f32 v[222:223], v[222:223], v[224:225]
	s_nop 0
	v_add_f32_e32 v233, v222, v223
	v_permlane32_swap_b32_e32 v226, v230
	v_permlane32_swap_b32_e32 v227, v231
	v_permlane32_swap_b32_e32 v228, v232
	v_permlane32_swap_b32_e32 v229, v233
	v_add_f32_e32 v226, v226, v230
	v_add_f32_e32 v228, v228, v232
	v_add_f32_e32 v227, v227, v231
	v_add_f32_e32 v229, v229, v233
	s_nop 1
	v_permlane16_swap_b32_e32 v226, v228
	v_permlane16_swap_b32_e32 v227, v229
	v_add_f32_e32 v226, v226, v228
	v_add_f32_e32 v227, v227, v229
	s_nop 0
	v_cndmask_b32_e64 v230, v226, v227, s[24:25]
	v_cndmask_b32_e64 v231, v227, v226, s[24:25]
	s_nop 1
	v_add_f32_dpp v232, v231, v230 row_ror:8 row_mask:0xf bank_mask:0xf
	s_nop 1
	v_add_f32_dpp v233, v232, v232 quad_perm:[1,0,3,2] row_mask:0xf bank_mask:0xf
	s_nop 1
	v_add_f32_dpp v232, v233, v233 quad_perm:[2,3,0,1] row_mask:0xf bank_mask:0xf
	s_nop 1
	v_add_f32_dpp v233, v232, v232 row_half_mirror row_mask:0xf bank_mask:0xf
	ds_write_b32 v235, v233 offset:35360
	v_readlane_b32 s48, v143, s72
	v_readlane_b32 s49, v143, s73
	v_readlane_b32 s50, v143, s74
	v_readlane_b32 s51, v143, s75
	v_readlane_b32 s52, v143, s76
	v_readlane_b32 s53, v143, s77
	v_readlane_b32 s54, v143, s78
	v_readlane_b32 s55, v143, s79
	s_add_u32 s32, s0, s48
	s_addc_u32 s33, s1, 0
	s_add_u32 s34, s0, s49
	s_addc_u32 s35, s1, 0
	s_add_u32 s36, s0, s50
	s_addc_u32 s37, s1, 0
	s_add_u32 s38, s0, s51
	s_addc_u32 s39, s1, 0
	s_add_u32 s40, s0, s52
	s_addc_u32 s41, s1, 0
	s_add_u32 s42, s0, s53
	s_addc_u32 s43, s1, 0
	s_add_u32 s44, s0, s54
	s_addc_u32 s45, s1, 0
	s_add_u32 s46, s0, s55
	s_addc_u32 s47, s1, 0
	global_load_dwordx4 v[176:179], v234, s[32:33]
	global_load_dwordx4 v[180:183], v234, s[34:35]
	global_load_dwordx4 v[184:187], v234, s[36:37]
	global_load_dwordx4 v[188:191], v234, s[38:39]
	global_load_dwordx4 v[192:195], v234, s[40:41]
	global_load_dwordx4 v[196:199], v234, s[42:43]
	global_load_dwordx4 v[200:203], v234, s[44:45]
	global_load_dwordx4 v[204:207], v234, s[46:47]
	s_waitcnt vmcnt(8)
	v_cvt_pk_f32_fp8_e32 v[214:215], v144
	v_cvt_pk_f32_fp8_sdwa v[216:217], v144 src0_sel:WORD_1
	v_cvt_pk_f32_fp8_e32 v[218:219], v145
	v_cvt_pk_f32_fp8_sdwa v[220:221], v145 src0_sel:WORD_1
	v_pk_mul_f32 v[222:223], v[96:97], v[214:215]
	v_pk_mul_f32 v[224:225], v[98:99], v[216:217]
	v_cvt_pk_f32_fp8_e32 v[214:215], v146
	v_cvt_pk_f32_fp8_sdwa v[216:217], v146 src0_sel:WORD_1
	v_pk_fma_f32 v[222:223], v[100:101], v[218:219], v[222:223]
	v_pk_fma_f32 v[224:225], v[102:103], v[220:221], v[224:225]
	v_cvt_pk_f32_fp8_e32 v[218:219], v147
	v_cvt_pk_f32_fp8_sdwa v[220:221], v147 src0_sel:WORD_1
	v_pk_fma_f32 v[222:223], v[104:105], v[214:215], v[222:223]
	v_pk_fma_f32 v[224:225], v[106:107], v[216:217], v[224:225]
	v_pk_fma_f32 v[222:223], v[108:109], v[218:219], v[222:223]
	v_pk_fma_f32 v[224:225], v[110:111], v[220:221], v[224:225]
	v_pk_add_f32 v[222:223], v[222:223], v[224:225]
	s_nop 0
	v_add_f32_e32 v226, v222, v223
	v_cvt_pk_f32_fp8_e32 v[214:215], v148
	v_cvt_pk_f32_fp8_sdwa v[216:217], v148 src0_sel:WORD_1
	v_cvt_pk_f32_fp8_e32 v[218:219], v149
	v_cvt_pk_f32_fp8_sdwa v[220:221], v149 src0_sel:WORD_1
	v_pk_mul_f32 v[222:223], v[96:97], v[214:215]
	v_pk_mul_f32 v[224:225], v[98:99], v[216:217]
	v_cvt_pk_f32_fp8_e32 v[214:215], v150
	v_cvt_pk_f32_fp8_sdwa v[216:217], v150 src0_sel:WORD_1
	v_pk_fma_f32 v[222:223], v[100:101], v[218:219], v[222:223]
	v_pk_fma_f32 v[224:225], v[102:103], v[220:221], v[224:225]
	v_cvt_pk_f32_fp8_e32 v[218:219], v151
	v_cvt_pk_f32_fp8_sdwa v[220:221], v151 src0_sel:WORD_1
	v_pk_fma_f32 v[222:223], v[104:105], v[214:215], v[222:223]
	v_pk_fma_f32 v[224:225], v[106:107], v[216:217], v[224:225]
	v_pk_fma_f32 v[222:223], v[108:109], v[218:219], v[222:223]
	v_pk_fma_f32 v[224:225], v[110:111], v[220:221], v[224:225]
	v_pk_add_f32 v[222:223], v[222:223], v[224:225]
	s_nop 0
	v_add_f32_e32 v227, v222, v223
	v_cvt_pk_f32_fp8_e32 v[214:215], v152
	v_cvt_pk_f32_fp8_sdwa v[216:217], v152 src0_sel:WORD_1
	v_cvt_pk_f32_fp8_e32 v[218:219], v153
; template <bool STORE>
; DI void peer_item(const Params& p, int item, char* smem) {
;     ...
;       for (int u = 0; u < 8; ++u) {
;         int e = e_s[tl * 128 + k + u];
;         uq[u] = *(const u32x4*)(U8 + (size_t)e * 1024 + lane * 16);
;       }
;       float part[8];
; #pragma unroll
;       for (int u = 0; u < 8; ++u) {
;         float d = 0.f;
; #pragma unroll
;         for (int i = 0; i < 4; ++i) {
;           f32x2_t lo = __builtin_amdgcn_cvt_pk_f32_fp8((int)uq[u][i], false);
;           f32x2_t hi = __builtin_amdgcn_cvt_pk_f32_fp8((int)uq[u][i], true);
;           d += xf[4 * i] * lo.x + xf[4 * i + 1] * lo.y + xf[4 * i + 2] * hi.x + xf[4 * i + 3] * hi.y;
;         }
;         part[u] = d;
;       }
;       float q4[4], r2[2], h;
; #pragma unroll
;       for (int j = 0; j < 4; ++j) {
;         float mine = b5 ? part[j + 4] : part[j];
;         float other = b5 ? part[j] : part[j + 4];
;         q4[j] = mine + __shfl_xor(other, 32);
;       }
; #pragma unroll
;       for (int j = 0; j < 2; ++j) {
;         float mine = b4 ? q4[j + 2] : q4[j];
;         float other = b4 ? q4[j] : q4[j + 2];
;         r2[j] = mine + __shfl_xor(other, 16);
;       }
;       {
;         float mine = b3 ? r2[1] : r2[0];
;         float other = b3 ? r2[0] : r2[1];
;         h = mine + __shfl_xor(other, 8);
;       }
;       h += __shfl_xor(h, 4);
;       h += __shfl_xor(h, 2);
;       h += __shfl_xor(h, 1);
	v_cvt_pk_f32_fp8_sdwa v[220:221], v153 src0_sel:WORD_1
	v_pk_mul_f32 v[222:223], v[96:97], v[214:215]
	v_pk_mul_f32 v[224:225], v[98:99], v[216:217]
	v_cvt_pk_f32_fp8_e32 v[214:215], v154
	v_cvt_pk_f32_fp8_sdwa v[216:217], v154 src0_sel:WORD_1
	v_pk_fma_f32 v[222:223], v[100:101], v[218:219], v[222:223]
	v_pk_fma_f32 v[224:225], v[102:103], v[220:221], v[224:225]
	v_cvt_pk_f32_fp8_e32 v[218:219], v155
	v_cvt_pk_f32_fp8_sdwa v[220:221], v155 src0_sel:WORD_1
	v_pk_fma_f32 v[222:223], v[104:105], v[214:215], v[222:223]
	v_pk_fma_f32 v[224:225], v[106:107], v[216:217], v[224:225]
	v_pk_fma_f32 v[222:223], v[108:109], v[218:219], v[222:223]
	v_pk_fma_f32 v[224:225], v[110:111], v[220:221], v[224:225]
	v_pk_add_f32 v[222:223], v[222:223], v[224:225]
	s_nop 0
	v_add_f32_e32 v228, v222, v223
	v_cvt_pk_f32_fp8_e32 v[214:215], v156
	v_cvt_pk_f32_fp8_sdwa v[216:217], v156 src0_sel:WORD_1
	v_cvt_pk_f32_fp8_e32 v[218:219], v157
	v_cvt_pk_f32_fp8_sdwa v[220:221], v157 src0_sel:WORD_1
	v_pk_mul_f32 v[222:223], v[96:97], v[214:215]
	v_pk_mul_f32 v[224:225], v[98:99], v[216:217]
	v_cvt_pk_f32_fp8_e32 v[214:215], v158
	v_cvt_pk_f32_fp8_sdwa v[216:217], v158 src0_sel:WORD_1
	v_pk_fma_f32 v[222:223], v[100:101], v[218:219], v[222:223]
	v_pk_fma_f32 v[224:225], v[102:103], v[220:221], v[224:225]
	v_cvt_pk_f32_fp8_e32 v[218:219], v159
	v_cvt_pk_f32_fp8_sdwa v[220:221], v159 src0_sel:WORD_1
	v_pk_fma_f32 v[222:223], v[104:105], v[214:215], v[222:223]
	v_pk_fma_f32 v[224:225], v[106:107], v[216:217], v[224:225]
	v_pk_fma_f32 v[222:223], v[108:109], v[218:219], v[222:223]
	v_pk_fma_f32 v[224:225], v[110:111], v[220:221], v[224:225]
	v_pk_add_f32 v[222:223], v[222:223], v[224:225]
	s_nop 0
	v_add_f32_e32 v229, v222, v223
	v_cvt_pk_f32_fp8_e32 v[214:215], v160
	v_cvt_pk_f32_fp8_sdwa v[216:217], v160 src0_sel:WORD_1
	v_cvt_pk_f32_fp8_e32 v[218:219], v161
	v_cvt_pk_f32_fp8_sdwa v[220:221], v161 src0_sel:WORD_1
	v_pk_mul_f32 v[222:223], v[96:97], v[214:215]
	v_pk_mul_f32 v[224:225], v[98:99], v[216:217]
	v_cvt_pk_f32_fp8_e32 v[214:215], v162
	v_cvt_pk_f32_fp8_sdwa v[216:217], v162 src0_sel:WORD_1
	v_pk_fma_f32 v[222:223], v[100:101], v[218:219], v[222:223]
	v_pk_fma_f32 v[224:225], v[102:103], v[220:221], v[224:225]
	v_cvt_pk_f32_fp8_e32 v[218:219], v163
	v_cvt_pk_f32_fp8_sdwa v[220:221], v163 src0_sel:WORD_1
	v_pk_fma_f32 v[222:223], v[104:105], v[214:215], v[222:223]
	v_pk_fma_f32 v[224:225], v[106:107], v[216:217], v[224:225]
	v_pk_fma_f32 v[222:223], v[108:109], v[218:219], v[222:223]
	v_pk_fma_f32 v[224:225], v[110:111], v[220:221], v[224:225]
	v_pk_add_f32 v[222:223], v[222:223], v[224:225]
	s_nop 0
	v_add_f32_e32 v230, v222, v223
	v_cvt_pk_f32_fp8_e32 v[214:215], v164
	v_cvt_pk_f32_fp8_sdwa v[216:217], v164 src0_sel:WORD_1
	v_cvt_pk_f32_fp8_e32 v[218:219], v165
	v_cvt_pk_f32_fp8_sdwa v[220:221], v165 src0_sel:WORD_1
	v_pk_mul_f32 v[222:223], v[96:97], v[214:215]
	v_pk_mul_f32 v[224:225], v[98:99], v[216:217]
	v_cvt_pk_f32_fp8_e32 v[214:215], v166
	v_cvt_pk_f32_fp8_sdwa v[216:217], v166 src0_sel:WORD_1
	v_pk_fma_f32 v[222:223], v[100:101], v[218:219], v[222:223]
	v_pk_fma_f32 v[224:225], v[102:103], v[220:221], v[224:225]
	v_cvt_pk_f32_fp8_e32 v[218:219], v167
	v_cvt_pk_f32_fp8_sdwa v[220:221], v167 src0_sel:WORD_1
	v_pk_fma_f32 v[222:223], v[104:105], v[214:215], v[222:223]
	v_pk_fma_f32 v[224:225], v[106:107], v[216:217], v[224:225]
	v_pk_fma_f32 v[222:223], v[108:109], v[218:219], v[222:223]
	v_pk_fma_f32 v[224:225], v[110:111], v[220:221], v[224:225]
	v_pk_add_f32 v[222:223], v[222:223], v[224:225]
	s_nop 0
	v_add_f32_e32 v231, v222, v223
	v_cvt_pk_f32_fp8_e32 v[214:215], v168
	v_cvt_pk_f32_fp8_sdwa v[216:217], v168 src0_sel:WORD_1
	v_cvt_pk_f32_fp8_e32 v[218:219], v169
	v_cvt_pk_f32_fp8_sdwa v[220:221], v169 src0_sel:WORD_1
	v_pk_mul_f32 v[222:223], v[96:97], v[214:215]
	v_pk_mul_f32 v[224:225], v[98:99], v[216:217]
	v_cvt_pk_f32_fp8_e32 v[214:215], v170
	v_cvt_pk_f32_fp8_sdwa v[216:217], v170 src0_sel:WORD_1
	v_pk_fma_f32 v[222:223], v[100:101], v[218:219], v[222:223]
	v_pk_fma_f32 v[224:225], v[102:103], v[220:221], v[224:225]
	v_cvt_pk_f32_fp8_e32 v[218:219], v171
	v_cvt_pk_f32_fp8_sdwa v[220:221], v171 src0_sel:WORD_1
	v_pk_fma_f32 v[222:223], v[104:105], v[214:215], v[222:223]
	v_pk_fma_f32 v[224:225], v[106:107], v[216:217], v[224:225]
	v_pk_fma_f32 v[222:223], v[108:109], v[218:219], v[222:223]
	v_pk_fma_f32 v[224:225], v[110:111], v[220:221], v[224:225]
	v_pk_add_f32 v[222:223], v[222:223], v[224:225]
	s_nop 0
	v_add_f32_e32 v232, v222, v223
	v_cvt_pk_f32_fp8_e32 v[214:215], v172
	v_cvt_pk_f32_fp8_sdwa v[216:217], v172 src0_sel:WORD_1
	v_cvt_pk_f32_fp8_e32 v[218:219], v173
	v_cvt_pk_f32_fp8_sdwa v[220:221], v173 src0_sel:WORD_1
	v_pk_mul_f32 v[222:223], v[96:97], v[214:215]
	v_pk_mul_f32 v[224:225], v[98:99], v[216:217]
	v_cvt_pk_f32_fp8_e32 v[214:215], v174
	v_cvt_pk_f32_fp8_sdwa v[216:217], v174 src0_sel:WORD_1
	v_pk_fma_f32 v[222:223], v[100:101], v[218:219], v[222:223]
	v_pk_fma_f32 v[224:225], v[102:103], v[220:221], v[224:225]
	v_cvt_pk_f32_fp8_e32 v[218:219], v175
	v_cvt_pk_f32_fp8_sdwa v[220:221], v175 src0_sel:WORD_1
	v_pk_fma_f32 v[222:223], v[104:105], v[214:215], v[222:223]
	v_pk_fma_f32 v[224:225], v[106:107], v[216:217], v[224:225]
	v_pk_fma_f32 v[222:223], v[108:109], v[218:219], v[222:223]
	v_pk_fma_f32 v[224:225], v[110:111], v[220:221], v[224:225]
	v_pk_add_f32 v[222:223], v[222:223], v[224:225]
	s_nop 0
	v_add_f32_e32 v233, v222, v223
	v_permlane32_swap_b32_e32 v226, v230
	v_permlane32_swap_b32_e32 v227, v231
	v_permlane32_swap_b32_e32 v228, v232
	v_permlane32_swap_b32_e32 v229, v233
	v_add_f32_e32 v226, v226, v230
; template <bool STORE>
; DI void peer_item(const Params& p, int item, char* smem) {
;     ...
; #pragma unroll
;       for (int u = 0; u < 8; ++u) {
;         int e = e_s[tl * 128 + k + u];
;         uq[u] = *(const u32x4*)(U8 + (size_t)e * 1024 + lane * 16);
;       }
;       float part[8];
; #pragma unroll
;       for (int u = 0; u < 8; ++u) {
;         float d = 0.f;
; #pragma unroll
;         for (int i = 0; i < 4; ++i) {
;           f32x2_t lo = __builtin_amdgcn_cvt_pk_f32_fp8((int)uq[u][i], false);
;           f32x2_t hi = __builtin_amdgcn_cvt_pk_f32_fp8((int)uq[u][i], true);
;           d += xf[4 * i] * lo.x + xf[4 * i + 1] * lo.y + xf[4 * i + 2] * hi.x + xf[4 * i + 3] * hi.y;
;         }
;         part[u] = d;
;       }
;       float q4[4], r2[2], h;
; #pragma unroll
;       for (int j = 0; j < 4; ++j) {
;         float mine = b5 ? part[j + 4] : part[j];
;         float other = b5 ? part[j] : part[j + 4];
;         q4[j] = mine + __shfl_xor(other, 32);
;       }
; #pragma unroll
;       for (int j = 0; j < 2; ++j) {
;         float mine = b4 ? q4[j + 2] : q4[j];
;         float other = b4 ? q4[j] : q4[j + 2];
;         r2[j] = mine + __shfl_xor(other, 16);
;       }
;       {
;         float mine = b3 ? r2[1] : r2[0];
;         float other = b3 ? r2[0] : r2[1];
;         h = mine + __shfl_xor(other, 8);
;       }
;       h += __shfl_xor(h, 4);
;       h += __shfl_xor(h, 2);
;       h += __shfl_xor(h, 1);
	v_add_f32_e32 v228, v228, v232
	v_add_f32_e32 v227, v227, v231
	v_add_f32_e32 v229, v229, v233
	s_nop 1
	v_permlane16_swap_b32_e32 v226, v228
	v_permlane16_swap_b32_e32 v227, v229
	v_add_f32_e32 v226, v226, v228
	v_add_f32_e32 v227, v227, v229
	s_nop 0
	v_cndmask_b32_e64 v230, v226, v227, s[24:25]
	v_cndmask_b32_e64 v231, v227, v226, s[24:25]
	s_nop 1
	v_add_f32_dpp v232, v231, v230 row_ror:8 row_mask:0xf bank_mask:0xf
	s_nop 1
	v_add_f32_dpp v233, v232, v232 quad_perm:[1,0,3,2] row_mask:0xf bank_mask:0xf
	s_nop 1
	v_add_f32_dpp v232, v233, v233 quad_perm:[2,3,0,1] row_mask:0xf bank_mask:0xf
	s_nop 1
	v_add_f32_dpp v233, v232, v232 row_half_mirror row_mask:0xf bank_mask:0xf
	ds_write_b32 v235, v233 offset:35872
	s_add_u32 s72, s72, 8
	s_add_u32 s73, s73, 8
	s_add_u32 s74, s74, 8
	s_add_u32 s75, s75, 8
	s_add_u32 s76, s76, 8
	s_add_u32 s77, s77, 8
	s_add_u32 s78, s78, 8
	s_add_u32 s79, s79, 8
	s_and_b32 s72, s72, 63
	s_and_b32 s73, s73, 63
	s_and_b32 s74, s74, 63
	s_and_b32 s75, s75, 63
	s_and_b32 s76, s76, 63
	s_and_b32 s77, s77, 63
	s_and_b32 s78, s78, 63
	s_and_b32 s79, s79, 63
	v_readlane_b32 s48, v128, s72
	v_readlane_b32 s49, v128, s73
	v_readlane_b32 s50, v128, s74
	v_readlane_b32 s51, v128, s75
	v_readlane_b32 s52, v128, s76
	v_readlane_b32 s53, v128, s77
	v_readlane_b32 s54, v128, s78
	v_readlane_b32 s55, v128, s79
	s_add_u32 s32, s0, s48
	s_addc_u32 s33, s1, 0
	s_add_u32 s34, s0, s49
	s_addc_u32 s35, s1, 0
	s_add_u32 s36, s0, s50
	s_addc_u32 s37, s1, 0
	s_add_u32 s38, s0, s51
	s_addc_u32 s39, s1, 0
	s_add_u32 s40, s0, s52
	s_addc_u32 s41, s1, 0
	s_add_u32 s42, s0, s53
	s_addc_u32 s43, s1, 0
	s_add_u32 s44, s0, s54
	s_addc_u32 s45, s1, 0
	s_add_u32 s46, s0, s55
	s_addc_u32 s47, s1, 0
	global_load_dwordx4 v[144:147], v234, s[32:33]
	global_load_dwordx4 v[148:151], v234, s[34:35]
	global_load_dwordx4 v[152:155], v234, s[36:37]
	global_load_dwordx4 v[156:159], v234, s[38:39]
	global_load_dwordx4 v[160:163], v234, s[40:41]
	global_load_dwordx4 v[164:167], v234, s[42:43]
	global_load_dwordx4 v[168:171], v234, s[44:45]
	global_load_dwordx4 v[172:175], v234, s[46:47]
	s_waitcnt vmcnt(8)
	v_cvt_pk_f32_fp8_e32 v[214:215], v176
	v_cvt_pk_f32_fp8_sdwa v[216:217], v176 src0_sel:WORD_1
	v_cvt_pk_f32_fp8_e32 v[218:219], v177
	v_cvt_pk_f32_fp8_sdwa v[220:221], v177 src0_sel:WORD_1
	v_pk_mul_f32 v[222:223], v[112:113], v[214:215]
	v_pk_mul_f32 v[224:225], v[114:115], v[216:217]
	v_cvt_pk_f32_fp8_e32 v[214:215], v178
	v_cvt_pk_f32_fp8_sdwa v[216:217], v178 src0_sel:WORD_1
	v_pk_fma_f32 v[222:223], v[116:117], v[218:219], v[222:223]
	v_pk_fma_f32 v[224:225], v[118:119], v[220:221], v[224:225]
	v_cvt_pk_f32_fp8_e32 v[218:219], v179
	v_cvt_pk_f32_fp8_sdwa v[220:221], v179 src0_sel:WORD_1
	v_pk_fma_f32 v[222:223], v[120:121], v[214:215], v[222:223]
	v_pk_fma_f32 v[224:225], v[122:123], v[216:217], v[224:225]
	v_pk_fma_f32 v[222:223], v[124:125], v[218:219], v[222:223]
	v_pk_fma_f32 v[224:225], v[126:127], v[220:221], v[224:225]
	v_pk_add_f32 v[222:223], v[222:223], v[224:225]
	s_nop 0
	v_add_f32_e32 v226, v222, v223
	v_cvt_pk_f32_fp8_e32 v[214:215], v180
	v_cvt_pk_f32_fp8_sdwa v[216:217], v180 src0_sel:WORD_1
	v_cvt_pk_f32_fp8_e32 v[218:219], v181
	v_cvt_pk_f32_fp8_sdwa v[220:221], v181 src0_sel:WORD_1
	v_pk_mul_f32 v[222:223], v[112:113], v[214:215]
	v_pk_mul_f32 v[224:225], v[114:115], v[216:217]
	v_cvt_pk_f32_fp8_e32 v[214:215], v182
	v_cvt_pk_f32_fp8_sdwa v[216:217], v182 src0_sel:WORD_1
	v_pk_fma_f32 v[222:223], v[116:117], v[218:219], v[222:223]
	v_pk_fma_f32 v[224:225], v[118:119], v[220:221], v[224:225]
	v_cvt_pk_f32_fp8_e32 v[218:219], v183
	v_cvt_pk_f32_fp8_sdwa v[220:221], v183 src0_sel:WORD_1
	v_pk_fma_f32 v[222:223], v[120:121], v[214:215], v[222:223]
	v_pk_fma_f32 v[224:225], v[122:123], v[216:217], v[224:225]
	v_pk_fma_f32 v[222:223], v[124:125], v[218:219], v[222:223]
	v_pk_fma_f32 v[224:225], v[126:127], v[220:221], v[224:225]
	v_pk_add_f32 v[222:223], v[222:223], v[224:225]
	s_nop 0
	v_add_f32_e32 v227, v222, v223
	v_cvt_pk_f32_fp8_e32 v[214:215], v184
	v_cvt_pk_f32_fp8_sdwa v[216:217], v184 src0_sel:WORD_1
	v_cvt_pk_f32_fp8_e32 v[218:219], v185
	v_cvt_pk_f32_fp8_sdwa v[220:221], v185 src0_sel:WORD_1
	v_pk_mul_f32 v[222:223], v[112:113], v[214:215]
	v_pk_mul_f32 v[224:225], v[114:115], v[216:217]
	v_cvt_pk_f32_fp8_e32 v[214:215], v186
	v_cvt_pk_f32_fp8_sdwa v[216:217], v186 src0_sel:WORD_1
	v_pk_fma_f32 v[222:223], v[116:117], v[218:219], v[222:223]
	v_pk_fma_f32 v[224:225], v[118:119], v[220:221], v[224:225]
	v_cvt_pk_f32_fp8_e32 v[218:219], v187
	v_cvt_pk_f32_fp8_sdwa v[220:221], v187 src0_sel:WORD_1
	v_pk_fma_f32 v[222:223], v[120:121], v[214:215], v[222:223]
	v_pk_fma_f32 v[224:225], v[122:123], v[216:217], v[224:225]
	v_pk_fma_f32 v[222:223], v[124:125], v[218:219], v[222:223]
	v_pk_fma_f32 v[224:225], v[126:127], v[220:221], v[224:225]
	v_pk_add_f32 v[222:223], v[222:223], v[224:225]
	s_nop 0
	v_add_f32_e32 v228, v222, v223
	v_cvt_pk_f32_fp8_e32 v[214:215], v188
	v_cvt_pk_f32_fp8_sdwa v[216:217], v188 src0_sel:WORD_1
	v_cvt_pk_f32_fp8_e32 v[218:219], v189
	v_cvt_pk_f32_fp8_sdwa v[220:221], v189 src0_sel:WORD_1
	v_pk_mul_f32 v[222:223], v[112:113], v[214:215]
	v_pk_mul_f32 v[224:225], v[114:115], v[216:217]
	v_cvt_pk_f32_fp8_e32 v[214:215], v190
	v_cvt_pk_f32_fp8_sdwa v[216:217], v190 src0_sel:WORD_1
	v_pk_fma_f32 v[222:223], v[116:117], v[218:219], v[222:223]
	v_pk_fma_f32 v[224:225], v[118:119], v[220:221], v[224:225]
	v_cvt_pk_f32_fp8_e32 v[218:219], v191
	v_cvt_pk_f32_fp8_sdwa v[220:221], v191 src0_sel:WORD_1
	v_pk_fma_f32 v[222:223], v[120:121], v[214:215], v[222:223]
	v_pk_fma_f32 v[224:225], v[122:123], v[216:217], v[224:225]
; DI float gelu_exact(float x) { return 0.5f * x * (1.f + erff(x * 0.7071067811865476f)); }
; template <bool STORE>
; DI void peer_item(const Params& p, int item, char* smem) {
;     ...
; #pragma unroll 2
;     for (int k = 0; k < 128; k += 8) {
;       u32x4 uq[8];
;       const int emine = e_s[tl * 128 + k + (lane >> 3)];
;       const float gmine = g_s[tl * 128 + k + (lane >> 3)];
;       const float su = SU[emine], sv = SV[emine];
; #pragma unroll
;       for (int u = 0; u < 8; ++u) {
;         int e = e_s[tl * 128 + k + u];
;         uq[u] = *(const u32x4*)(U8 + (size_t)e * 1024 + lane * 16);
;       }
;       float part[8];
; #pragma unroll
;       for (int u = 0; u < 8; ++u) {
;         float d = 0.f;
; #pragma unroll
;         for (int i = 0; i < 4; ++i) {
;           f32x2_t lo = __builtin_amdgcn_cvt_pk_f32_fp8((int)uq[u][i], false);
;           f32x2_t hi = __builtin_amdgcn_cvt_pk_f32_fp8((int)uq[u][i], true);
;           d += xf[4 * i] * lo.x + xf[4 * i + 1] * lo.y + xf[4 * i + 2] * hi.x + xf[4 * i + 3] * hi.y;
;         }
;         part[u] = d;
;       }
;       float q4[4], r2[2], h;
; #pragma unroll
;       for (int j = 0; j < 4; ++j) {
;         float mine = b5 ? part[j + 4] : part[j];
;         float other = b5 ? part[j] : part[j + 4];
;         q4[j] = mine + __shfl_xor(other, 32);
;       }
; #pragma unroll
;       for (int j = 0; j < 2; ++j) {
;         float mine = b4 ? q4[j + 2] : q4[j];
;         float other = b4 ? q4[j] : q4[j + 2];
;         r2[j] = mine + __shfl_xor(other, 16);
;       }
;       {
;         float mine = b3 ? r2[1] : r2[0];
;         float other = b3 ? r2[0] : r2[1];
;         h = mine + __shfl_xor(other, 8);
;       }
;       h += __shfl_xor(h, 4);
;       h += __shfl_xor(h, 2);
;       h += __shfl_xor(h, 1);
;       const float amine = gelu_exact(h * su) * gmine * sv;
;       if ((lane & 7) == 0) {
;         EG[tok * 128 + k + (lane >> 3)] = emine;
;         AG[tok * 128 + k + (lane >> 3)] = amine;
;       }
;     }
	v_pk_fma_f32 v[222:223], v[124:125], v[218:219], v[222:223]
	v_pk_fma_f32 v[224:225], v[126:127], v[220:221], v[224:225]
	v_pk_add_f32 v[222:223], v[222:223], v[224:225]
	s_nop 0
	v_add_f32_e32 v229, v222, v223
	v_cvt_pk_f32_fp8_e32 v[214:215], v192
	v_cvt_pk_f32_fp8_sdwa v[216:217], v192 src0_sel:WORD_1
	v_cvt_pk_f32_fp8_e32 v[218:219], v193
	v_cvt_pk_f32_fp8_sdwa v[220:221], v193 src0_sel:WORD_1
	v_pk_mul_f32 v[222:223], v[112:113], v[214:215]
	v_pk_mul_f32 v[224:225], v[114:115], v[216:217]
	v_cvt_pk_f32_fp8_e32 v[214:215], v194
	v_cvt_pk_f32_fp8_sdwa v[216:217], v194 src0_sel:WORD_1
	v_pk_fma_f32 v[222:223], v[116:117], v[218:219], v[222:223]
	v_pk_fma_f32 v[224:225], v[118:119], v[220:221], v[224:225]
	v_cvt_pk_f32_fp8_e32 v[218:219], v195
	v_cvt_pk_f32_fp8_sdwa v[220:221], v195 src0_sel:WORD_1
	v_pk_fma_f32 v[222:223], v[120:121], v[214:215], v[222:223]
	v_pk_fma_f32 v[224:225], v[122:123], v[216:217], v[224:225]
	v_pk_fma_f32 v[222:223], v[124:125], v[218:219], v[222:223]
	v_pk_fma_f32 v[224:225], v[126:127], v[220:221], v[224:225]
	v_pk_add_f32 v[222:223], v[222:223], v[224:225]
	s_nop 0
	v_add_f32_e32 v230, v222, v223
	v_cvt_pk_f32_fp8_e32 v[214:215], v196
	v_cvt_pk_f32_fp8_sdwa v[216:217], v196 src0_sel:WORD_1
	v_cvt_pk_f32_fp8_e32 v[218:219], v197
	v_cvt_pk_f32_fp8_sdwa v[220:221], v197 src0_sel:WORD_1
	v_pk_mul_f32 v[222:223], v[112:113], v[214:215]
	v_pk_mul_f32 v[224:225], v[114:115], v[216:217]
	v_cvt_pk_f32_fp8_e32 v[214:215], v198
	v_cvt_pk_f32_fp8_sdwa v[216:217], v198 src0_sel:WORD_1
	v_pk_fma_f32 v[222:223], v[116:117], v[218:219], v[222:223]
	v_pk_fma_f32 v[224:225], v[118:119], v[220:221], v[224:225]
	v_cvt_pk_f32_fp8_e32 v[218:219], v199
	v_cvt_pk_f32_fp8_sdwa v[220:221], v199 src0_sel:WORD_1
	v_pk_fma_f32 v[222:223], v[120:121], v[214:215], v[222:223]
	v_pk_fma_f32 v[224:225], v[122:123], v[216:217], v[224:225]
	v_pk_fma_f32 v[222:223], v[124:125], v[218:219], v[222:223]
	v_pk_fma_f32 v[224:225], v[126:127], v[220:221], v[224:225]
	v_pk_add_f32 v[222:223], v[222:223], v[224:225]
	s_nop 0
	v_add_f32_e32 v231, v222, v223
	v_cvt_pk_f32_fp8_e32 v[214:215], v200
	v_cvt_pk_f32_fp8_sdwa v[216:217], v200 src0_sel:WORD_1
	v_cvt_pk_f32_fp8_e32 v[218:219], v201
	v_cvt_pk_f32_fp8_sdwa v[220:221], v201 src0_sel:WORD_1
	v_pk_mul_f32 v[222:223], v[112:113], v[214:215]
	v_pk_mul_f32 v[224:225], v[114:115], v[216:217]
	v_cvt_pk_f32_fp8_e32 v[214:215], v202
	v_cvt_pk_f32_fp8_sdwa v[216:217], v202 src0_sel:WORD_1
	v_pk_fma_f32 v[222:223], v[116:117], v[218:219], v[222:223]
	v_pk_fma_f32 v[224:225], v[118:119], v[220:221], v[224:225]
	v_cvt_pk_f32_fp8_e32 v[218:219], v203
	v_cvt_pk_f32_fp8_sdwa v[220:221], v203 src0_sel:WORD_1
	v_pk_fma_f32 v[222:223], v[120:121], v[214:215], v[222:223]
	v_pk_fma_f32 v[224:225], v[122:123], v[216:217], v[224:225]
	v_pk_fma_f32 v[222:223], v[124:125], v[218:219], v[222:223]
	v_pk_fma_f32 v[224:225], v[126:127], v[220:221], v[224:225]
	v_pk_add_f32 v[222:223], v[222:223], v[224:225]
	s_nop 0
	v_add_f32_e32 v232, v222, v223
	v_cvt_pk_f32_fp8_e32 v[214:215], v204
	v_cvt_pk_f32_fp8_sdwa v[216:217], v204 src0_sel:WORD_1
	v_cvt_pk_f32_fp8_e32 v[218:219], v205
	v_cvt_pk_f32_fp8_sdwa v[220:221], v205 src0_sel:WORD_1
	v_pk_mul_f32 v[222:223], v[112:113], v[214:215]
	v_pk_mul_f32 v[224:225], v[114:115], v[216:217]
	v_cvt_pk_f32_fp8_e32 v[214:215], v206
	v_cvt_pk_f32_fp8_sdwa v[216:217], v206 src0_sel:WORD_1
	v_pk_fma_f32 v[222:223], v[116:117], v[218:219], v[222:223]
	v_pk_fma_f32 v[224:225], v[118:119], v[220:221], v[224:225]
	v_cvt_pk_f32_fp8_e32 v[218:219], v207
	v_cvt_pk_f32_fp8_sdwa v[220:221], v207 src0_sel:WORD_1
	v_pk_fma_f32 v[222:223], v[120:121], v[214:215], v[222:223]
	v_pk_fma_f32 v[224:225], v[122:123], v[216:217], v[224:225]
	v_pk_fma_f32 v[222:223], v[124:125], v[218:219], v[222:223]
	v_pk_fma_f32 v[224:225], v[126:127], v[220:221], v[224:225]
	v_pk_add_f32 v[222:223], v[222:223], v[224:225]
	s_nop 0
	v_add_f32_e32 v233, v222, v223
	v_permlane32_swap_b32_e32 v226, v230
	v_permlane32_swap_b32_e32 v227, v231
	v_permlane32_swap_b32_e32 v228, v232
	v_permlane32_swap_b32_e32 v229, v233
	v_add_f32_e32 v226, v226, v230
	v_add_f32_e32 v228, v228, v232
	v_add_f32_e32 v227, v227, v231
	v_add_f32_e32 v229, v229, v233
	s_nop 1
	v_permlane16_swap_b32_e32 v226, v228
	v_permlane16_swap_b32_e32 v227, v229
	v_add_f32_e32 v226, v226, v228
	v_add_f32_e32 v227, v227, v229
	s_nop 0
	v_cndmask_b32_e64 v230, v226, v227, s[24:25]
	v_cndmask_b32_e64 v231, v227, v226, s[24:25]
	s_nop 1
	v_add_f32_dpp v232, v231, v230 row_ror:8 row_mask:0xf bank_mask:0xf
	s_nop 1
	v_add_f32_dpp v233, v232, v232 quad_perm:[1,0,3,2] row_mask:0xf bank_mask:0xf
	s_nop 1
	v_add_f32_dpp v232, v233, v233 quad_perm:[2,3,0,1] row_mask:0xf bank_mask:0xf
	s_nop 1
	v_add_f32_dpp v233, v232, v232 row_half_mirror row_mask:0xf bank_mask:0xf
	ds_write_b32 v235, v233 offset:36384
	v_add_u32_e32 v235, 64, v235
	s_add_u32 s12, s12, 1
	s_cmp_lt_u32 s12, 8
	s_cbranch_scc1 .Lup_k
; DI float gelu_exact(float x) { return 0.5f * x * (1.f + erff(x * 0.7071067811865476f)); }
; template <bool STORE>
; DI void peer_item(const Params& p, int item, char* smem) {
;     ...
;       const int emine = e_s[tl * 128 + k + (lane >> 3)];
;       const float gmine = g_s[tl * 128 + k + (lane >> 3)];
;       const float su = SU[emine], sv = SV[emine];
; #pragma unroll
;       for (int u = 0; u < 8; ++u) {
;         int e = e_s[tl * 128 + k + u];
;         uq[u] = *(const u32x4*)(U8 + (size_t)e * 1024 + lane * 16);
;       }
;       float part[8];
; #pragma unroll
;       for (int u = 0; u < 8; ++u) {
;         float d = 0.f;
; #pragma unroll
;         for (int i = 0; i < 4; ++i) {
;           f32x2_t lo = __builtin_amdgcn_cvt_pk_f32_fp8((int)uq[u][i], false);
;           f32x2_t hi = __builtin_amdgcn_cvt_pk_f32_fp8((int)uq[u][i], true);
;           d += xf[4 * i] * lo.x + xf[4 * i + 1] * lo.y + xf[4 * i + 2] * hi.x + xf[4 * i + 3] * hi.y;
;         }
;         part[u] = d;
;       }
;       float q4[4], r2[2], h;
; #pragma unroll
;       for (int j = 0; j < 4; ++j) {
;         float mine = b5 ? part[j + 4] : part[j];
;         float other = b5 ? part[j] : part[j + 4];
;         q4[j] = mine + __shfl_xor(other, 32);
;       }
; #pragma unroll
;       for (int j = 0; j < 2; ++j) {
;         float mine = b4 ? q4[j + 2] : q4[j];
;         float other = b4 ? q4[j] : q4[j + 2];
;         r2[j] = mine + __shfl_xor(other, 16);
;       }
;       {
;         float mine = b3 ? r2[1] : r2[0];
;         float other = b3 ? r2[0] : r2[1];
;         h = mine + __shfl_xor(other, 8);
;       }
;       h += __shfl_xor(h, 4);
;       h += __shfl_xor(h, 2);
;       h += __shfl_xor(h, 1);
;       const float amine = gelu_exact(h * su) * gmine * sv;
;       if ((lane & 7) == 0) {
;         EG[tok * 128 + k + (lane >> 3)] = emine;
;         AG[tok * 128 + k + (lane >> 3)] = amine;
;       }
	s_waitcnt vmcnt(0) lgkmcnt(0)
	s_lshl_b32 s13, s14, 9
	s_add_u32 s26, s4, s13
	s_addc_u32 s27, s5, 0
	s_add_u32 s28, s6, s13
	s_addc_u32 s29, s7, 0
	ds_read_b32 v0, v237 offset:32768
	ds_read_b32 v1, v237 offset:33024
	ds_read_b32 v2, v237 offset:0
	ds_read_b32 v3, v237 offset:256
	ds_read_b32 v4, v237 offset:16384
	ds_read_b32 v5, v237 offset:16640
	ds_read_b32 v16, v237 offset:33280
	ds_read_b32 v17, v237 offset:33536
	ds_read_b32 v18, v237 offset:512
	ds_read_b32 v19, v237 offset:768
	ds_read_b32 v20, v237 offset:16896
	ds_read_b32 v21, v237 offset:17152
	ds_read_b32 v32, v237 offset:33792
	ds_read_b32 v33, v237 offset:34048
	ds_read_b32 v34, v237 offset:1024
	ds_read_b32 v35, v237 offset:1280
	ds_read_b32 v36, v237 offset:17408
	ds_read_b32 v37, v237 offset:17664
	ds_read_b32 v48, v237 offset:34304
	ds_read_b32 v49, v237 offset:34560
	ds_read_b32 v50, v237 offset:1536
	ds_read_b32 v51, v237 offset:1792
	ds_read_b32 v52, v237 offset:17920
	ds_read_b32 v53, v237 offset:18176
	ds_read_b32 v64, v237 offset:34816
	ds_read_b32 v65, v237 offset:35072
	ds_read_b32 v66, v237 offset:2048
	ds_read_b32 v67, v237 offset:2304
	ds_read_b32 v68, v237 offset:18432
	ds_read_b32 v69, v237 offset:18688
	ds_read_b32 v80, v237 offset:35328
	ds_read_b32 v81, v237 offset:35584
	ds_read_b32 v82, v237 offset:2560
	ds_read_b32 v83, v237 offset:2816
	ds_read_b32 v84, v237 offset:18944
	ds_read_b32 v85, v237 offset:19200
	ds_read_b32 v96, v237 offset:35840
	ds_read_b32 v97, v237 offset:36096
	ds_read_b32 v98, v237 offset:3072
	ds_read_b32 v99, v237 offset:3328
	ds_read_b32 v100, v237 offset:19456
	ds_read_b32 v101, v237 offset:19712
	ds_read_b32 v112, v237 offset:36352
	ds_read_b32 v113, v237 offset:36608
	ds_read_b32 v114, v237 offset:3584
	ds_read_b32 v115, v237 offset:3840
	ds_read_b32 v116, v237 offset:19968
	ds_read_b32 v117, v237 offset:20224
	s_waitcnt lgkmcnt(15)
	v_lshlrev_b32_e32 v10, 2, v2
	v_lshlrev_b32_e32 v11, 2, v3
	global_load_dword v6, v10, s[8:9]
	global_load_dword v7, v11, s[8:9]
	global_load_dword v8, v10, s[10:11]
	global_load_dword v9, v11, s[10:11]
	s_waitcnt lgkmcnt(15)
	v_lshlrev_b32_e32 v26, 2, v18
	v_lshlrev_b32_e32 v27, 2, v19
	global_load_dword v22, v26, s[8:9]
	global_load_dword v23, v27, s[8:9]
	global_load_dword v24, v26, s[10:11]
	global_load_dword v25, v27, s[10:11]
	s_waitcnt lgkmcnt(15)
	v_lshlrev_b32_e32 v42, 2, v34
	v_lshlrev_b32_e32 v43, 2, v35
	global_load_dword v38, v42, s[8:9]
	global_load_dword v39, v43, s[8:9]
	global_load_dword v40, v42, s[10:11]
	global_load_dword v41, v43, s[10:11]
	s_waitcnt lgkmcnt(15)
	v_lshlrev_b32_e32 v58, 2, v50
	v_lshlrev_b32_e32 v59, 2, v51
	global_load_dword v54, v58, s[8:9]
	global_load_dword v55, v59, s[8:9]
	global_load_dword v56, v58, s[10:11]
	global_load_dword v57, v59, s[10:11]
	s_waitcnt lgkmcnt(15)
	v_lshlrev_b32_e32 v74, 2, v66
	v_lshlrev_b32_e32 v75, 2, v67
	global_load_dword v70, v74, s[8:9]
	global_load_dword v71, v75, s[8:9]
	global_load_dword v72, v74, s[10:11]
	global_load_dword v73, v75, s[10:11]
	s_waitcnt lgkmcnt(12)
	v_lshlrev_b32_e32 v90, 2, v82
	v_lshlrev_b32_e32 v91, 2, v83
	global_load_dword v86, v90, s[8:9]
	global_load_dword v87, v91, s[8:9]
	global_load_dword v88, v90, s[10:11]
	global_load_dword v89, v91, s[10:11]
	s_waitcnt lgkmcnt(6)
	v_lshlrev_b32_e32 v106, 2, v98
	v_lshlrev_b32_e32 v107, 2, v99
	global_load_dword v102, v106, s[8:9]
	global_load_dword v103, v107, s[8:9]
	global_load_dword v104, v106, s[10:11]
	global_load_dword v105, v107, s[10:11]
	s_waitcnt lgkmcnt(0)
	v_lshlrev_b32_e32 v122, 2, v114
	v_lshlrev_b32_e32 v123, 2, v115
	global_load_dword v118, v122, s[8:9]
	global_load_dword v119, v123, s[8:9]
	global_load_dword v120, v122, s[10:11]
	global_load_dword v121, v123, s[10:11]
	s_waitcnt vmcnt(28)
	v_mul_f32_e32 v144, v6, v0
	v_mul_f32_e32 v145, 0x3f3504f3, v144
	v_mov_b32_e32 v146, 0xb9c68948
	v_fma_f32 v146, |v145|, s80, v146
	v_fma_f32 v146, |v145|, v146, s81
	v_fma_f32 v146, |v145|, v146, s82
	v_fma_f32 v146, |v145|, v146, s83
	v_fma_f32 v146, |v145|, v146, s84
	v_fma_f32 v146, |v145|, v146, s85
	v_fma_f32 v146, |v145|, v146, |v145|
	v_mul_f32_e32 v147, 0xbfb8aa3b, v146
	v_fma_f32 v148, v146, s86, -v147
	v_rndne_f32_e32 v149, v147
	v_fmac_f32_e32 v148, 0xb2a5705f, v146
	v_sub_f32_e32 v147, v147, v149
	v_add_f32_e32 v147, v147, v148
	v_cvt_i32_f32_e32 v148, v149
	v_exp_f32_e32 v147, v147
	v_cmp_nlt_f32_e32 vcc, s87, v146
	v_ldexp_f32 v147, v147, v148
	s_nop 0
	v_cndmask_b32_e32 v147, 0, v147, vcc
	v_cmp_ngt_f32_e32 vcc, s88, v146
	v_mov_b32_e32 v148, 0x7f800000
	s_nop 0
	v_cndmask_b32_e32 v147, v148, v147, vcc
	v_sub_f32_e32 v147, 1.0, v147
	v_mul_f32_e32 v148, v145, v145
	v_mov_b32_e32 v149, 0x3ba10414
	v_fmamk_f32 v149, v148, 0xba1345e1, v149
	v_fmaak_f32 v149, v148, v149, 0xbcdac9b8
	v_fmaak_f32 v149, v148, v149, 0x3de703be
	v_fmaak_f32 v149, v148, v149, 0xbec09330
	v_fmaak_f32 v149, v148, v149, 0x3e0375d0
	v_fma_f32 v149, |v145|, v149, |v145|
	v_cmp_nlt_f32_e64 vcc, |v145|, 1.0
	s_nop 1
	v_cndmask_b32_e32 v147, v149, v147, vcc
	v_bfi_b32 v147, s89, v147, v145
	v_mul_f32_e32 v144, 0.5, v144
	v_add_f32_e32 v147, 1.0, v147
	v_mul_f32_e32 v144, v144, v147
	v_mul_f32_e32 v144, v4, v144
	v_mul_f32_e32 v0, v8, v144
	v_mul_f32_e32 v144, v7, v1
	v_mul_f32_e32 v145, 0x3f3504f3, v144
	v_mov_b32_e32 v146, 0xb9c68948
	v_fma_f32 v146, |v145|, s80, v146
	v_fma_f32 v146, |v145|, v146, s81
	v_fma_f32 v146, |v145|, v146, s82
	v_fma_f32 v146, |v145|, v146, s83
	v_fma_f32 v146, |v145|, v146, s84
	v_fma_f32 v146, |v145|, v146, s85
	v_fma_f32 v146, |v145|, v146, |v145|
	v_mul_f32_e32 v147, 0xbfb8aa3b, v146
	v_fma_f32 v148, v146, s86, -v147
	v_rndne_f32_e32 v149, v147
	v_fmac_f32_e32 v148, 0xb2a5705f, v146
	v_sub_f32_e32 v147, v147, v149
	v_add_f32_e32 v147, v147, v148
	v_cvt_i32_f32_e32 v148, v149
	v_exp_f32_e32 v147, v147
	v_cmp_nlt_f32_e32 vcc, s87, v146
	v_ldexp_f32 v147, v147, v148
	s_nop 0
	v_cndmask_b32_e32 v147, 0, v147, vcc
	v_cmp_ngt_f32_e32 vcc, s88, v146
	v_mov_b32_e32 v148, 0x7f800000
	s_nop 0
	v_cndmask_b32_e32 v147, v148, v147, vcc
	v_sub_f32_e32 v147, 1.0, v147
	v_mul_f32_e32 v148, v145, v145
	v_mov_b32_e32 v149, 0x3ba10414
	v_fmamk_f32 v149, v148, 0xba1345e1, v149
	v_fmaak_f32 v149, v148, v149, 0xbcdac9b8
	v_fmaak_f32 v149, v148, v149, 0x3de703be
	v_fmaak_f32 v149, v148, v149, 0xbec09330
	v_fmaak_f32 v149, v148, v149, 0x3e0375d0
	v_fma_f32 v149, |v145|, v149, |v145|
	v_cmp_nlt_f32_e64 vcc, |v145|, 1.0
	s_nop 1
	v_cndmask_b32_e32 v147, v149, v147, vcc
	v_bfi_b32 v147, s89, v147, v145
	v_mul_f32_e32 v144, 0.5, v144
	v_add_f32_e32 v147, 1.0, v147
	v_mul_f32_e32 v144, v144, v147
	v_mul_f32_e32 v144, v5, v144
	v_mul_f32_e32 v1, v9, v144
	global_store_dword v238, v2, s[26:27] offset:0
	global_store_dword v238, v3, s[26:27] offset:256
	global_store_dword v238, v0, s[28:29] offset:0
	global_store_dword v238, v1, s[28:29] offset:256
	s_waitcnt vmcnt(28)
; DI float gelu_exact(float x) { return 0.5f * x * (1.f + erff(x * 0.7071067811865476f)); }
; template <bool STORE>
; DI void peer_item(const Params& p, int item, char* smem) {
;     ...
;       const float amine = gelu_exact(h * su) * gmine * sv;
;       if ((lane & 7) == 0) {
;         EG[tok * 128 + k + (lane >> 3)] = emine;
;         AG[tok * 128 + k + (lane >> 3)] = amine;
;       }
	v_mul_f32_e32 v144, v22, v16
	v_mul_f32_e32 v145, 0x3f3504f3, v144
	v_mov_b32_e32 v146, 0xb9c68948
	v_fma_f32 v146, |v145|, s80, v146
	v_fma_f32 v146, |v145|, v146, s81
	v_fma_f32 v146, |v145|, v146, s82
	v_fma_f32 v146, |v145|, v146, s83
	v_fma_f32 v146, |v145|, v146, s84
	v_fma_f32 v146, |v145|, v146, s85
	v_fma_f32 v146, |v145|, v146, |v145|
	v_mul_f32_e32 v147, 0xbfb8aa3b, v146
	v_fma_f32 v148, v146, s86, -v147
	v_rndne_f32_e32 v149, v147
	v_fmac_f32_e32 v148, 0xb2a5705f, v146
	v_sub_f32_e32 v147, v147, v149
	v_add_f32_e32 v147, v147, v148
	v_cvt_i32_f32_e32 v148, v149
	v_exp_f32_e32 v147, v147
	v_cmp_nlt_f32_e32 vcc, s87, v146
	v_ldexp_f32 v147, v147, v148
	s_nop 0
	v_cndmask_b32_e32 v147, 0, v147, vcc
	v_cmp_ngt_f32_e32 vcc, s88, v146
	v_mov_b32_e32 v148, 0x7f800000
	s_nop 0
	v_cndmask_b32_e32 v147, v148, v147, vcc
	v_sub_f32_e32 v147, 1.0, v147
	v_mul_f32_e32 v148, v145, v145
	v_mov_b32_e32 v149, 0x3ba10414
	v_fmamk_f32 v149, v148, 0xba1345e1, v149
	v_fmaak_f32 v149, v148, v149, 0xbcdac9b8
	v_fmaak_f32 v149, v148, v149, 0x3de703be
	v_fmaak_f32 v149, v148, v149, 0xbec09330
	v_fmaak_f32 v149, v148, v149, 0x3e0375d0
	v_fma_f32 v149, |v145|, v149, |v145|
	v_cmp_nlt_f32_e64 vcc, |v145|, 1.0
	s_nop 1
	v_cndmask_b32_e32 v147, v149, v147, vcc
	v_bfi_b32 v147, s89, v147, v145
	v_mul_f32_e32 v144, 0.5, v144
	v_add_f32_e32 v147, 1.0, v147
	v_mul_f32_e32 v144, v144, v147
	v_mul_f32_e32 v144, v20, v144
	v_mul_f32_e32 v16, v24, v144
	v_mul_f32_e32 v144, v23, v17
	v_mul_f32_e32 v145, 0x3f3504f3, v144
	v_mov_b32_e32 v146, 0xb9c68948
	v_fma_f32 v146, |v145|, s80, v146
	v_fma_f32 v146, |v145|, v146, s81
	v_fma_f32 v146, |v145|, v146, s82
	v_fma_f32 v146, |v145|, v146, s83
	v_fma_f32 v146, |v145|, v146, s84
	v_fma_f32 v146, |v145|, v146, s85
	v_fma_f32 v146, |v145|, v146, |v145|
	v_mul_f32_e32 v147, 0xbfb8aa3b, v146
	v_fma_f32 v148, v146, s86, -v147
	v_rndne_f32_e32 v149, v147
	v_fmac_f32_e32 v148, 0xb2a5705f, v146
	v_sub_f32_e32 v147, v147, v149
	v_add_f32_e32 v147, v147, v148
	v_cvt_i32_f32_e32 v148, v149
	v_exp_f32_e32 v147, v147
	v_cmp_nlt_f32_e32 vcc, s87, v146
	v_ldexp_f32 v147, v147, v148
	s_nop 0
	v_cndmask_b32_e32 v147, 0, v147, vcc
	v_cmp_ngt_f32_e32 vcc, s88, v146
	v_mov_b32_e32 v148, 0x7f800000
	s_nop 0
	v_cndmask_b32_e32 v147, v148, v147, vcc
	v_sub_f32_e32 v147, 1.0, v147
	v_mul_f32_e32 v148, v145, v145
	v_mov_b32_e32 v149, 0x3ba10414
	v_fmamk_f32 v149, v148, 0xba1345e1, v149
	v_fmaak_f32 v149, v148, v149, 0xbcdac9b8
	v_fmaak_f32 v149, v148, v149, 0x3de703be
	v_fmaak_f32 v149, v148, v149, 0xbec09330
	v_fmaak_f32 v149, v148, v149, 0x3e0375d0
	v_fma_f32 v149, |v145|, v149, |v145|
	v_cmp_nlt_f32_e64 vcc, |v145|, 1.0
	s_nop 1
	v_cndmask_b32_e32 v147, v149, v147, vcc
	v_bfi_b32 v147, s89, v147, v145
	v_mul_f32_e32 v144, 0.5, v144
	v_add_f32_e32 v147, 1.0, v147
	v_mul_f32_e32 v144, v144, v147
	v_mul_f32_e32 v144, v21, v144
	v_mul_f32_e32 v17, v25, v144
	global_store_dword v238, v18, s[26:27] offset:512
	global_store_dword v238, v19, s[26:27] offset:768
	global_store_dword v238, v16, s[28:29] offset:512
	global_store_dword v238, v17, s[28:29] offset:768
	s_waitcnt vmcnt(28)
	v_mul_f32_e32 v144, v38, v32
	v_mul_f32_e32 v145, 0x3f3504f3, v144
	v_mov_b32_e32 v146, 0xb9c68948
	v_fma_f32 v146, |v145|, s80, v146
	v_fma_f32 v146, |v145|, v146, s81
	v_fma_f32 v146, |v145|, v146, s82
	v_fma_f32 v146, |v145|, v146, s83
	v_fma_f32 v146, |v145|, v146, s84
	v_fma_f32 v146, |v145|, v146, s85
	v_fma_f32 v146, |v145|, v146, |v145|
	v_mul_f32_e32 v147, 0xbfb8aa3b, v146
	v_fma_f32 v148, v146, s86, -v147
	v_rndne_f32_e32 v149, v147
	v_fmac_f32_e32 v148, 0xb2a5705f, v146
	v_sub_f32_e32 v147, v147, v149
	v_add_f32_e32 v147, v147, v148
	v_cvt_i32_f32_e32 v148, v149
	v_exp_f32_e32 v147, v147
	v_cmp_nlt_f32_e32 vcc, s87, v146
	v_ldexp_f32 v147, v147, v148
	s_nop 0
	v_cndmask_b32_e32 v147, 0, v147, vcc
	v_cmp_ngt_f32_e32 vcc, s88, v146
	v_mov_b32_e32 v148, 0x7f800000
	s_nop 0
	v_cndmask_b32_e32 v147, v148, v147, vcc
	v_sub_f32_e32 v147, 1.0, v147
	v_mul_f32_e32 v148, v145, v145
	v_mov_b32_e32 v149, 0x3ba10414
	v_fmamk_f32 v149, v148, 0xba1345e1, v149
	v_fmaak_f32 v149, v148, v149, 0xbcdac9b8
	v_fmaak_f32 v149, v148, v149, 0x3de703be
	v_fmaak_f32 v149, v148, v149, 0xbec09330
	v_fmaak_f32 v149, v148, v149, 0x3e0375d0
	v_fma_f32 v149, |v145|, v149, |v145|
	v_cmp_nlt_f32_e64 vcc, |v145|, 1.0
	s_nop 1
	v_cndmask_b32_e32 v147, v149, v147, vcc
	v_bfi_b32 v147, s89, v147, v145
	v_mul_f32_e32 v144, 0.5, v144
	v_add_f32_e32 v147, 1.0, v147
	v_mul_f32_e32 v144, v144, v147
	v_mul_f32_e32 v144, v36, v144
	v_mul_f32_e32 v32, v40, v144
	v_mul_f32_e32 v144, v39, v33
	v_mul_f32_e32 v145, 0x3f3504f3, v144
	v_mov_b32_e32 v146, 0xb9c68948
	v_fma_f32 v146, |v145|, s80, v146
	v_fma_f32 v146, |v145|, v146, s81
	v_fma_f32 v146, |v145|, v146, s82
	v_fma_f32 v146, |v145|, v146, s83
	v_fma_f32 v146, |v145|, v146, s84
	v_fma_f32 v146, |v145|, v146, s85
	v_fma_f32 v146, |v145|, v146, |v145|
	v_mul_f32_e32 v147, 0xbfb8aa3b, v146
	v_fma_f32 v148, v146, s86, -v147
	v_rndne_f32_e32 v149, v147
	v_fmac_f32_e32 v148, 0xb2a5705f, v146
	v_sub_f32_e32 v147, v147, v149
	v_add_f32_e32 v147, v147, v148
	v_cvt_i32_f32_e32 v148, v149
	v_exp_f32_e32 v147, v147
	v_cmp_nlt_f32_e32 vcc, s87, v146
	v_ldexp_f32 v147, v147, v148
	s_nop 0
	v_cndmask_b32_e32 v147, 0, v147, vcc
	v_cmp_ngt_f32_e32 vcc, s88, v146
	v_mov_b32_e32 v148, 0x7f800000
	s_nop 0
	v_cndmask_b32_e32 v147, v148, v147, vcc
	v_sub_f32_e32 v147, 1.0, v147
	v_mul_f32_e32 v148, v145, v145
	v_mov_b32_e32 v149, 0x3ba10414
	v_fmamk_f32 v149, v148, 0xba1345e1, v149
	v_fmaak_f32 v149, v148, v149, 0xbcdac9b8
	v_fmaak_f32 v149, v148, v149, 0x3de703be
	v_fmaak_f32 v149, v148, v149, 0xbec09330
	v_fmaak_f32 v149, v148, v149, 0x3e0375d0
	v_fma_f32 v149, |v145|, v149, |v145|
	v_cmp_nlt_f32_e64 vcc, |v145|, 1.0
	s_nop 1
	v_cndmask_b32_e32 v147, v149, v147, vcc
	v_bfi_b32 v147, s89, v147, v145
	v_mul_f32_e32 v144, 0.5, v144
	v_add_f32_e32 v147, 1.0, v147
	v_mul_f32_e32 v144, v144, v147
	v_mul_f32_e32 v144, v37, v144
	v_mul_f32_e32 v33, v41, v144
	global_store_dword v238, v34, s[26:27] offset:1024
	global_store_dword v238, v35, s[26:27] offset:1280
	global_store_dword v238, v32, s[28:29] offset:1024
	global_store_dword v238, v33, s[28:29] offset:1280
	s_waitcnt vmcnt(28)
; DI float gelu_exact(float x) { return 0.5f * x * (1.f + erff(x * 0.7071067811865476f)); }
; template <bool STORE>
; DI void peer_item(const Params& p, int item, char* smem) {
;     ...
;       const float amine = gelu_exact(h * su) * gmine * sv;
;       if ((lane & 7) == 0) {
;         EG[tok * 128 + k + (lane >> 3)] = emine;
;         AG[tok * 128 + k + (lane >> 3)] = amine;
;       }
	v_mul_f32_e32 v144, v54, v48
	v_mul_f32_e32 v145, 0x3f3504f3, v144
	v_mov_b32_e32 v146, 0xb9c68948
	v_fma_f32 v146, |v145|, s80, v146
	v_fma_f32 v146, |v145|, v146, s81
	v_fma_f32 v146, |v145|, v146, s82
	v_fma_f32 v146, |v145|, v146, s83
	v_fma_f32 v146, |v145|, v146, s84
	v_fma_f32 v146, |v145|, v146, s85
	v_fma_f32 v146, |v145|, v146, |v145|
	v_mul_f32_e32 v147, 0xbfb8aa3b, v146
	v_fma_f32 v148, v146, s86, -v147
	v_rndne_f32_e32 v149, v147
	v_fmac_f32_e32 v148, 0xb2a5705f, v146
	v_sub_f32_e32 v147, v147, v149
	v_add_f32_e32 v147, v147, v148
	v_cvt_i32_f32_e32 v148, v149
	v_exp_f32_e32 v147, v147
	v_cmp_nlt_f32_e32 vcc, s87, v146
	v_ldexp_f32 v147, v147, v148
	s_nop 0
	v_cndmask_b32_e32 v147, 0, v147, vcc
	v_cmp_ngt_f32_e32 vcc, s88, v146
	v_mov_b32_e32 v148, 0x7f800000
	s_nop 0
	v_cndmask_b32_e32 v147, v148, v147, vcc
	v_sub_f32_e32 v147, 1.0, v147
	v_mul_f32_e32 v148, v145, v145
	v_mov_b32_e32 v149, 0x3ba10414
	v_fmamk_f32 v149, v148, 0xba1345e1, v149
	v_fmaak_f32 v149, v148, v149, 0xbcdac9b8
	v_fmaak_f32 v149, v148, v149, 0x3de703be
	v_fmaak_f32 v149, v148, v149, 0xbec09330
	v_fmaak_f32 v149, v148, v149, 0x3e0375d0
	v_fma_f32 v149, |v145|, v149, |v145|
	v_cmp_nlt_f32_e64 vcc, |v145|, 1.0
	s_nop 1
	v_cndmask_b32_e32 v147, v149, v147, vcc
	v_bfi_b32 v147, s89, v147, v145
	v_mul_f32_e32 v144, 0.5, v144
	v_add_f32_e32 v147, 1.0, v147
	v_mul_f32_e32 v144, v144, v147
	v_mul_f32_e32 v144, v52, v144
	v_mul_f32_e32 v48, v56, v144
	v_mul_f32_e32 v144, v55, v49
	v_mul_f32_e32 v145, 0x3f3504f3, v144
	v_mov_b32_e32 v146, 0xb9c68948
	v_fma_f32 v146, |v145|, s80, v146
	v_fma_f32 v146, |v145|, v146, s81
	v_fma_f32 v146, |v145|, v146, s82
	v_fma_f32 v146, |v145|, v146, s83
	v_fma_f32 v146, |v145|, v146, s84
	v_fma_f32 v146, |v145|, v146, s85
	v_fma_f32 v146, |v145|, v146, |v145|
	v_mul_f32_e32 v147, 0xbfb8aa3b, v146
	v_fma_f32 v148, v146, s86, -v147
	v_rndne_f32_e32 v149, v147
	v_fmac_f32_e32 v148, 0xb2a5705f, v146
	v_sub_f32_e32 v147, v147, v149
	v_add_f32_e32 v147, v147, v148
	v_cvt_i32_f32_e32 v148, v149
	v_exp_f32_e32 v147, v147
	v_cmp_nlt_f32_e32 vcc, s87, v146
	v_ldexp_f32 v147, v147, v148
	s_nop 0
	v_cndmask_b32_e32 v147, 0, v147, vcc
	v_cmp_ngt_f32_e32 vcc, s88, v146
	v_mov_b32_e32 v148, 0x7f800000
	s_nop 0
	v_cndmask_b32_e32 v147, v148, v147, vcc
	v_sub_f32_e32 v147, 1.0, v147
	v_mul_f32_e32 v148, v145, v145
	v_mov_b32_e32 v149, 0x3ba10414
	v_fmamk_f32 v149, v148, 0xba1345e1, v149
	v_fmaak_f32 v149, v148, v149, 0xbcdac9b8
	v_fmaak_f32 v149, v148, v149, 0x3de703be
	v_fmaak_f32 v149, v148, v149, 0xbec09330
	v_fmaak_f32 v149, v148, v149, 0x3e0375d0
	v_fma_f32 v149, |v145|, v149, |v145|
	v_cmp_nlt_f32_e64 vcc, |v145|, 1.0
	s_nop 1
	v_cndmask_b32_e32 v147, v149, v147, vcc
	v_bfi_b32 v147, s89, v147, v145
	v_mul_f32_e32 v144, 0.5, v144
	v_add_f32_e32 v147, 1.0, v147
	v_mul_f32_e32 v144, v144, v147
	v_mul_f32_e32 v144, v53, v144
	v_mul_f32_e32 v49, v57, v144
	global_store_dword v238, v50, s[26:27] offset:1536
	global_store_dword v238, v51, s[26:27] offset:1792
	global_store_dword v238, v48, s[28:29] offset:1536
	global_store_dword v238, v49, s[28:29] offset:1792
	s_waitcnt vmcnt(28)
	v_mul_f32_e32 v144, v70, v64
	v_mul_f32_e32 v145, 0x3f3504f3, v144
	v_mov_b32_e32 v146, 0xb9c68948
	v_fma_f32 v146, |v145|, s80, v146
	v_fma_f32 v146, |v145|, v146, s81
	v_fma_f32 v146, |v145|, v146, s82
	v_fma_f32 v146, |v145|, v146, s83
	v_fma_f32 v146, |v145|, v146, s84
	v_fma_f32 v146, |v145|, v146, s85
	v_fma_f32 v146, |v145|, v146, |v145|
	v_mul_f32_e32 v147, 0xbfb8aa3b, v146
	v_fma_f32 v148, v146, s86, -v147
	v_rndne_f32_e32 v149, v147
	v_fmac_f32_e32 v148, 0xb2a5705f, v146
	v_sub_f32_e32 v147, v147, v149
	v_add_f32_e32 v147, v147, v148
	v_cvt_i32_f32_e32 v148, v149
	v_exp_f32_e32 v147, v147
	v_cmp_nlt_f32_e32 vcc, s87, v146
	v_ldexp_f32 v147, v147, v148
	s_nop 0
	v_cndmask_b32_e32 v147, 0, v147, vcc
	v_cmp_ngt_f32_e32 vcc, s88, v146
	v_mov_b32_e32 v148, 0x7f800000
	s_nop 0
	v_cndmask_b32_e32 v147, v148, v147, vcc
	v_sub_f32_e32 v147, 1.0, v147
	v_mul_f32_e32 v148, v145, v145
	v_mov_b32_e32 v149, 0x3ba10414
	v_fmamk_f32 v149, v148, 0xba1345e1, v149
	v_fmaak_f32 v149, v148, v149, 0xbcdac9b8
	v_fmaak_f32 v149, v148, v149, 0x3de703be
	v_fmaak_f32 v149, v148, v149, 0xbec09330
	v_fmaak_f32 v149, v148, v149, 0x3e0375d0
	v_fma_f32 v149, |v145|, v149, |v145|
	v_cmp_nlt_f32_e64 vcc, |v145|, 1.0
	s_nop 1
	v_cndmask_b32_e32 v147, v149, v147, vcc
	v_bfi_b32 v147, s89, v147, v145
	v_mul_f32_e32 v144, 0.5, v144
	v_add_f32_e32 v147, 1.0, v147
	v_mul_f32_e32 v144, v144, v147
	v_mul_f32_e32 v144, v68, v144
	v_mul_f32_e32 v64, v72, v144
	v_mul_f32_e32 v144, v71, v65
	v_mul_f32_e32 v145, 0x3f3504f3, v144
	v_mov_b32_e32 v146, 0xb9c68948
	v_fma_f32 v146, |v145|, s80, v146
	v_fma_f32 v146, |v145|, v146, s81
	v_fma_f32 v146, |v145|, v146, s82
	v_fma_f32 v146, |v145|, v146, s83
	v_fma_f32 v146, |v145|, v146, s84
	v_fma_f32 v146, |v145|, v146, s85
	v_fma_f32 v146, |v145|, v146, |v145|
	v_mul_f32_e32 v147, 0xbfb8aa3b, v146
	v_fma_f32 v148, v146, s86, -v147
	v_rndne_f32_e32 v149, v147
	v_fmac_f32_e32 v148, 0xb2a5705f, v146
	v_sub_f32_e32 v147, v147, v149
	v_add_f32_e32 v147, v147, v148
	v_cvt_i32_f32_e32 v148, v149
	v_exp_f32_e32 v147, v147
	v_cmp_nlt_f32_e32 vcc, s87, v146
	v_ldexp_f32 v147, v147, v148
	s_nop 0
	v_cndmask_b32_e32 v147, 0, v147, vcc
	v_cmp_ngt_f32_e32 vcc, s88, v146
	v_mov_b32_e32 v148, 0x7f800000
	s_nop 0
	v_cndmask_b32_e32 v147, v148, v147, vcc
	v_sub_f32_e32 v147, 1.0, v147
	v_mul_f32_e32 v148, v145, v145
	v_mov_b32_e32 v149, 0x3ba10414
	v_fmamk_f32 v149, v148, 0xba1345e1, v149
	v_fmaak_f32 v149, v148, v149, 0xbcdac9b8
	v_fmaak_f32 v149, v148, v149, 0x3de703be
	v_fmaak_f32 v149, v148, v149, 0xbec09330
	v_fmaak_f32 v149, v148, v149, 0x3e0375d0
	v_fma_f32 v149, |v145|, v149, |v145|
	v_cmp_nlt_f32_e64 vcc, |v145|, 1.0
	s_nop 1
	v_cndmask_b32_e32 v147, v149, v147, vcc
	v_bfi_b32 v147, s89, v147, v145
	v_mul_f32_e32 v144, 0.5, v144
	v_add_f32_e32 v147, 1.0, v147
	v_mul_f32_e32 v144, v144, v147
	v_mul_f32_e32 v144, v69, v144
	v_mul_f32_e32 v65, v73, v144
	global_store_dword v238, v66, s[26:27] offset:2048
	global_store_dword v238, v67, s[26:27] offset:2304
	global_store_dword v238, v64, s[28:29] offset:2048
	global_store_dword v238, v65, s[28:29] offset:2304
	s_waitcnt vmcnt(28)
; DI float gelu_exact(float x) { return 0.5f * x * (1.f + erff(x * 0.7071067811865476f)); }
; template <bool STORE>
; DI void peer_item(const Params& p, int item, char* smem) {
;     ...
;       const float amine = gelu_exact(h * su) * gmine * sv;
;       if ((lane & 7) == 0) {
;         EG[tok * 128 + k + (lane >> 3)] = emine;
;         AG[tok * 128 + k + (lane >> 3)] = amine;
;       }
	v_mul_f32_e32 v144, v86, v80
	v_mul_f32_e32 v145, 0x3f3504f3, v144
	v_mov_b32_e32 v146, 0xb9c68948
	v_fma_f32 v146, |v145|, s80, v146
	v_fma_f32 v146, |v145|, v146, s81
	v_fma_f32 v146, |v145|, v146, s82
	v_fma_f32 v146, |v145|, v146, s83
	v_fma_f32 v146, |v145|, v146, s84
	v_fma_f32 v146, |v145|, v146, s85
	v_fma_f32 v146, |v145|, v146, |v145|
	v_mul_f32_e32 v147, 0xbfb8aa3b, v146
	v_fma_f32 v148, v146, s86, -v147
	v_rndne_f32_e32 v149, v147
	v_fmac_f32_e32 v148, 0xb2a5705f, v146
	v_sub_f32_e32 v147, v147, v149
	v_add_f32_e32 v147, v147, v148
	v_cvt_i32_f32_e32 v148, v149
	v_exp_f32_e32 v147, v147
	v_cmp_nlt_f32_e32 vcc, s87, v146
	v_ldexp_f32 v147, v147, v148
	s_nop 0
	v_cndmask_b32_e32 v147, 0, v147, vcc
	v_cmp_ngt_f32_e32 vcc, s88, v146
	v_mov_b32_e32 v148, 0x7f800000
	s_nop 0
	v_cndmask_b32_e32 v147, v148, v147, vcc
	v_sub_f32_e32 v147, 1.0, v147
	v_mul_f32_e32 v148, v145, v145
	v_mov_b32_e32 v149, 0x3ba10414
	v_fmamk_f32 v149, v148, 0xba1345e1, v149
	v_fmaak_f32 v149, v148, v149, 0xbcdac9b8
	v_fmaak_f32 v149, v148, v149, 0x3de703be
	v_fmaak_f32 v149, v148, v149, 0xbec09330
	v_fmaak_f32 v149, v148, v149, 0x3e0375d0
	v_fma_f32 v149, |v145|, v149, |v145|
	v_cmp_nlt_f32_e64 vcc, |v145|, 1.0
	s_nop 1
	v_cndmask_b32_e32 v147, v149, v147, vcc
	v_bfi_b32 v147, s89, v147, v145
	v_mul_f32_e32 v144, 0.5, v144
	v_add_f32_e32 v147, 1.0, v147
	v_mul_f32_e32 v144, v144, v147
	v_mul_f32_e32 v144, v84, v144
	v_mul_f32_e32 v80, v88, v144
	v_mul_f32_e32 v144, v87, v81
	v_mul_f32_e32 v145, 0x3f3504f3, v144
	v_mov_b32_e32 v146, 0xb9c68948
	v_fma_f32 v146, |v145|, s80, v146
	v_fma_f32 v146, |v145|, v146, s81
	v_fma_f32 v146, |v145|, v146, s82
	v_fma_f32 v146, |v145|, v146, s83
	v_fma_f32 v146, |v145|, v146, s84
	v_fma_f32 v146, |v145|, v146, s85
	v_fma_f32 v146, |v145|, v146, |v145|
	v_mul_f32_e32 v147, 0xbfb8aa3b, v146
	v_fma_f32 v148, v146, s86, -v147
	v_rndne_f32_e32 v149, v147
	v_fmac_f32_e32 v148, 0xb2a5705f, v146
	v_sub_f32_e32 v147, v147, v149
	v_add_f32_e32 v147, v147, v148
	v_cvt_i32_f32_e32 v148, v149
	v_exp_f32_e32 v147, v147
	v_cmp_nlt_f32_e32 vcc, s87, v146
	v_ldexp_f32 v147, v147, v148
	s_nop 0
	v_cndmask_b32_e32 v147, 0, v147, vcc
	v_cmp_ngt_f32_e32 vcc, s88, v146
	v_mov_b32_e32 v148, 0x7f800000
	s_nop 0
	v_cndmask_b32_e32 v147, v148, v147, vcc
	v_sub_f32_e32 v147, 1.0, v147
	v_mul_f32_e32 v148, v145, v145
	v_mov_b32_e32 v149, 0x3ba10414
	v_fmamk_f32 v149, v148, 0xba1345e1, v149
	v_fmaak_f32 v149, v148, v149, 0xbcdac9b8
	v_fmaak_f32 v149, v148, v149, 0x3de703be
	v_fmaak_f32 v149, v148, v149, 0xbec09330
	v_fmaak_f32 v149, v148, v149, 0x3e0375d0
	v_fma_f32 v149, |v145|, v149, |v145|
	v_cmp_nlt_f32_e64 vcc, |v145|, 1.0
	s_nop 1
	v_cndmask_b32_e32 v147, v149, v147, vcc
	v_bfi_b32 v147, s89, v147, v145
	v_mul_f32_e32 v144, 0.5, v144
	v_add_f32_e32 v147, 1.0, v147
	v_mul_f32_e32 v144, v144, v147
	v_mul_f32_e32 v144, v85, v144
	v_mul_f32_e32 v81, v89, v144
	global_store_dword v238, v82, s[26:27] offset:2560
	global_store_dword v238, v83, s[26:27] offset:2816
	global_store_dword v238, v80, s[28:29] offset:2560
	global_store_dword v238, v81, s[28:29] offset:2816
	s_waitcnt vmcnt(28)
	v_mul_f32_e32 v144, v102, v96
	v_mul_f32_e32 v145, 0x3f3504f3, v144
	v_mov_b32_e32 v146, 0xb9c68948
	v_fma_f32 v146, |v145|, s80, v146
	v_fma_f32 v146, |v145|, v146, s81
	v_fma_f32 v146, |v145|, v146, s82
	v_fma_f32 v146, |v145|, v146, s83
	v_fma_f32 v146, |v145|, v146, s84
	v_fma_f32 v146, |v145|, v146, s85
	v_fma_f32 v146, |v145|, v146, |v145|
	v_mul_f32_e32 v147, 0xbfb8aa3b, v146
	v_fma_f32 v148, v146, s86, -v147
	v_rndne_f32_e32 v149, v147
	v_fmac_f32_e32 v148, 0xb2a5705f, v146
	v_sub_f32_e32 v147, v147, v149
	v_add_f32_e32 v147, v147, v148
	v_cvt_i32_f32_e32 v148, v149
	v_exp_f32_e32 v147, v147
	v_cmp_nlt_f32_e32 vcc, s87, v146
	v_ldexp_f32 v147, v147, v148
	s_nop 0
	v_cndmask_b32_e32 v147, 0, v147, vcc
	v_cmp_ngt_f32_e32 vcc, s88, v146
	v_mov_b32_e32 v148, 0x7f800000
	s_nop 0
	v_cndmask_b32_e32 v147, v148, v147, vcc
	v_sub_f32_e32 v147, 1.0, v147
	v_mul_f32_e32 v148, v145, v145
	v_mov_b32_e32 v149, 0x3ba10414
	v_fmamk_f32 v149, v148, 0xba1345e1, v149
	v_fmaak_f32 v149, v148, v149, 0xbcdac9b8
	v_fmaak_f32 v149, v148, v149, 0x3de703be
	v_fmaak_f32 v149, v148, v149, 0xbec09330
	v_fmaak_f32 v149, v148, v149, 0x3e0375d0
	v_fma_f32 v149, |v145|, v149, |v145|
	v_cmp_nlt_f32_e64 vcc, |v145|, 1.0
	s_nop 1
	v_cndmask_b32_e32 v147, v149, v147, vcc
	v_bfi_b32 v147, s89, v147, v145
	v_mul_f32_e32 v144, 0.5, v144
	v_add_f32_e32 v147, 1.0, v147
	v_mul_f32_e32 v144, v144, v147
	v_mul_f32_e32 v144, v100, v144
	v_mul_f32_e32 v96, v104, v144
	v_mul_f32_e32 v144, v103, v97
	v_mul_f32_e32 v145, 0x3f3504f3, v144
	v_mov_b32_e32 v146, 0xb9c68948
	v_fma_f32 v146, |v145|, s80, v146
	v_fma_f32 v146, |v145|, v146, s81
	v_fma_f32 v146, |v145|, v146, s82
	v_fma_f32 v146, |v145|, v146, s83
	v_fma_f32 v146, |v145|, v146, s84
	v_fma_f32 v146, |v145|, v146, s85
	v_fma_f32 v146, |v145|, v146, |v145|
	v_mul_f32_e32 v147, 0xbfb8aa3b, v146
	v_fma_f32 v148, v146, s86, -v147
	v_rndne_f32_e32 v149, v147
	v_fmac_f32_e32 v148, 0xb2a5705f, v146
	v_sub_f32_e32 v147, v147, v149
	v_add_f32_e32 v147, v147, v148
	v_cvt_i32_f32_e32 v148, v149
	v_exp_f32_e32 v147, v147
	v_cmp_nlt_f32_e32 vcc, s87, v146
	v_ldexp_f32 v147, v147, v148
	s_nop 0
	v_cndmask_b32_e32 v147, 0, v147, vcc
	v_cmp_ngt_f32_e32 vcc, s88, v146
	v_mov_b32_e32 v148, 0x7f800000
	s_nop 0
	v_cndmask_b32_e32 v147, v148, v147, vcc
	v_sub_f32_e32 v147, 1.0, v147
	v_mul_f32_e32 v148, v145, v145
	v_mov_b32_e32 v149, 0x3ba10414
	v_fmamk_f32 v149, v148, 0xba1345e1, v149
	v_fmaak_f32 v149, v148, v149, 0xbcdac9b8
	v_fmaak_f32 v149, v148, v149, 0x3de703be
	v_fmaak_f32 v149, v148, v149, 0xbec09330
	v_fmaak_f32 v149, v148, v149, 0x3e0375d0
	v_fma_f32 v149, |v145|, v149, |v145|
	v_cmp_nlt_f32_e64 vcc, |v145|, 1.0
	s_nop 1
	v_cndmask_b32_e32 v147, v149, v147, vcc
	v_bfi_b32 v147, s89, v147, v145
	v_mul_f32_e32 v144, 0.5, v144
	v_add_f32_e32 v147, 1.0, v147
	v_mul_f32_e32 v144, v144, v147
	v_mul_f32_e32 v144, v101, v144
	v_mul_f32_e32 v97, v105, v144
	global_store_dword v238, v98, s[26:27] offset:3072
	global_store_dword v238, v99, s[26:27] offset:3328
	global_store_dword v238, v96, s[28:29] offset:3072
	global_store_dword v238, v97, s[28:29] offset:3328
	s_waitcnt vmcnt(28)
; DI void hsync() { hsync_impl(false); }
; DI float gelu_exact(float x) { return 0.5f * x * (1.f + erff(x * 0.7071067811865476f)); }
; template <bool STORE>
; DI void peer_item(const Params& p, int item, char* smem) {
;     ...
;       const float amine = gelu_exact(h * su) * gmine * sv;
;       if ((lane & 7) == 0) {
;         EG[tok * 128 + k + (lane >> 3)] = emine;
;         AG[tok * 128 + k + (lane >> 3)] = amine;
;       }
;     }
;   }
;   hsync();
	v_mul_f32_e32 v144, v118, v112
	v_mul_f32_e32 v145, 0x3f3504f3, v144
	v_mov_b32_e32 v146, 0xb9c68948
	v_fma_f32 v146, |v145|, s80, v146
	v_fma_f32 v146, |v145|, v146, s81
	v_fma_f32 v146, |v145|, v146, s82
	v_fma_f32 v146, |v145|, v146, s83
	v_fma_f32 v146, |v145|, v146, s84
	v_fma_f32 v146, |v145|, v146, s85
	v_fma_f32 v146, |v145|, v146, |v145|
	v_mul_f32_e32 v147, 0xbfb8aa3b, v146
	v_fma_f32 v148, v146, s86, -v147
	v_rndne_f32_e32 v149, v147
	v_fmac_f32_e32 v148, 0xb2a5705f, v146
	v_sub_f32_e32 v147, v147, v149
	v_add_f32_e32 v147, v147, v148
	v_cvt_i32_f32_e32 v148, v149
	v_exp_f32_e32 v147, v147
	v_cmp_nlt_f32_e32 vcc, s87, v146
	v_ldexp_f32 v147, v147, v148
	s_nop 0
	v_cndmask_b32_e32 v147, 0, v147, vcc
	v_cmp_ngt_f32_e32 vcc, s88, v146
	v_mov_b32_e32 v148, 0x7f800000
	s_nop 0
	v_cndmask_b32_e32 v147, v148, v147, vcc
	v_sub_f32_e32 v147, 1.0, v147
	v_mul_f32_e32 v148, v145, v145
	v_mov_b32_e32 v149, 0x3ba10414
	v_fmamk_f32 v149, v148, 0xba1345e1, v149
	v_fmaak_f32 v149, v148, v149, 0xbcdac9b8
	v_fmaak_f32 v149, v148, v149, 0x3de703be
	v_fmaak_f32 v149, v148, v149, 0xbec09330
	v_fmaak_f32 v149, v148, v149, 0x3e0375d0
	v_fma_f32 v149, |v145|, v149, |v145|
	v_cmp_nlt_f32_e64 vcc, |v145|, 1.0
	s_nop 1
	v_cndmask_b32_e32 v147, v149, v147, vcc
	v_bfi_b32 v147, s89, v147, v145
	v_mul_f32_e32 v144, 0.5, v144
	v_add_f32_e32 v147, 1.0, v147
	v_mul_f32_e32 v144, v144, v147
	v_mul_f32_e32 v144, v116, v144
	v_mul_f32_e32 v112, v120, v144
	v_mul_f32_e32 v144, v119, v113
	v_mul_f32_e32 v145, 0x3f3504f3, v144
	v_mov_b32_e32 v146, 0xb9c68948
	v_fma_f32 v146, |v145|, s80, v146
	v_fma_f32 v146, |v145|, v146, s81
	v_fma_f32 v146, |v145|, v146, s82
	v_fma_f32 v146, |v145|, v146, s83
	v_fma_f32 v146, |v145|, v146, s84
	v_fma_f32 v146, |v145|, v146, s85
	v_fma_f32 v146, |v145|, v146, |v145|
	v_mul_f32_e32 v147, 0xbfb8aa3b, v146
	v_fma_f32 v148, v146, s86, -v147
	v_rndne_f32_e32 v149, v147
	v_fmac_f32_e32 v148, 0xb2a5705f, v146
	v_sub_f32_e32 v147, v147, v149
	v_add_f32_e32 v147, v147, v148
	v_cvt_i32_f32_e32 v148, v149
	v_exp_f32_e32 v147, v147
	v_cmp_nlt_f32_e32 vcc, s87, v146
	v_ldexp_f32 v147, v147, v148
	s_nop 0
	v_cndmask_b32_e32 v147, 0, v147, vcc
	v_cmp_ngt_f32_e32 vcc, s88, v146
	v_mov_b32_e32 v148, 0x7f800000
	s_nop 0
	v_cndmask_b32_e32 v147, v148, v147, vcc
	v_sub_f32_e32 v147, 1.0, v147
	v_mul_f32_e32 v148, v145, v145
	v_mov_b32_e32 v149, 0x3ba10414
	v_fmamk_f32 v149, v148, 0xba1345e1, v149
	v_fmaak_f32 v149, v148, v149, 0xbcdac9b8
	v_fmaak_f32 v149, v148, v149, 0x3de703be
	v_fmaak_f32 v149, v148, v149, 0xbec09330
	v_fmaak_f32 v149, v148, v149, 0x3e0375d0
	v_fma_f32 v149, |v145|, v149, |v145|
	v_cmp_nlt_f32_e64 vcc, |v145|, 1.0
	s_nop 1
	v_cndmask_b32_e32 v147, v149, v147, vcc
	v_bfi_b32 v147, s89, v147, v145
	v_mul_f32_e32 v144, 0.5, v144
	v_add_f32_e32 v147, 1.0, v147
	v_mul_f32_e32 v144, v144, v147
	v_mul_f32_e32 v144, v117, v144
	v_mul_f32_e32 v113, v121, v144
	global_store_dword v238, v114, s[26:27] offset:3584
	global_store_dword v238, v115, s[26:27] offset:3840
	global_store_dword v238, v112, s[28:29] offset:3584
	global_store_dword v238, v113, s[28:29] offset:3840
	ds_read_b32 v3, v236 offset:512
	ds_read_b32 v53, v236 offset:768
	ds_read_b32 v64, v236 offset:1024
	ds_read_b32 v65, v236 offset:1280
	ds_read_b32 v66, v236 offset:1536
	ds_read_b32 v67, v236 offset:1792
	ds_read_b32 v68, v236 offset:2048
	ds_read_b32 v69, v236 offset:2304
	ds_read_b32 v70, v236 offset:2560
	ds_read_b32 v71, v236 offset:2816
	ds_read_b32 v72, v236 offset:3072
	ds_read_b32 v73, v236 offset:3328
	ds_read_b32 v74, v236 offset:3584
	ds_read_b32 v75, v236 offset:3840
	ds_read_b32 v76, v236 offset:4096
	ds_read_b32 v77, v236 offset:4352
	ds_read_b32 v78, v236 offset:4608
	ds_read_b32 v79, v236 offset:4864
	ds_read_b32 v80, v236 offset:5120
	ds_read_b32 v81, v236 offset:5376
	ds_read_b32 v82, v236 offset:5632
	ds_read_b32 v83, v236 offset:5888
	ds_read_b32 v96, v236 offset:6144
	v_readlane_b32 s6, v254, 0
	v_readlane_b32 s7, v254, 1
	v_readlane_b32 s12, v254, 2
	v_readlane_b32 s13, v254, 3
	v_readlane_b32 s14, v254, 4
	v_readlane_b32 s15, v254, 5
	v_readlane_b32 s16, v254, 6
	v_readlane_b32 s17, v254, 7
	v_readlane_b32 s18, v254, 8
	v_readlane_b32 s19, v254, 9
	v_readlane_b32 s20, v254, 10
	v_readlane_b32 s21, v254, 11
	v_readlane_b32 s22, v254, 12
	v_readlane_b32 s23, v254, 13
	v_readlane_b32 s24, v254, 14
	v_readlane_b32 s25, v254, 15
	v_readlane_b32 s26, v254, 16
	v_readlane_b32 s27, v254, 17
	v_readlane_b32 s28, v254, 18
	v_readlane_b32 s29, v254, 19
	v_readlane_b32 s30, v254, 20
	v_readlane_b32 s31, v254, 21
	v_readlane_b32 s33, v254, 22
	v_readlane_b32 s34, v254, 23
	v_readlane_b32 s35, v254, 24
	v_readlane_b32 s36, v254, 25
	v_readlane_b32 s37, v254, 26
	v_readlane_b32 s38, v254, 27
	v_readlane_b32 s39, v254, 28
	v_readlane_b32 s40, v254, 29
	v_readlane_b32 s41, v254, 30
	v_readlane_b32 s42, v254, 31
	v_readlane_b32 s44, v254, 32
	v_readlane_b32 s45, v254, 33
	v_readlane_b32 s48, v254, 34
	v_readlane_b32 s49, v254, 35
	v_readlane_b32 s50, v254, 36
	v_readlane_b32 s51, v254, 37
	v_readlane_b32 s52, v254, 38
	v_readlane_b32 s53, v254, 39
	v_readlane_b32 s55, v254, 40
	v_readlane_b32 s60, v254, 41
	v_readlane_b32 s61, v254, 42
	v_readlane_b32 s62, v254, 43
	v_readlane_b32 s63, v254, 44
	v_readlane_b32 s66, v254, 45
	v_readlane_b32 s67, v254, 46
	v_readlane_b32 s68, v254, 47
	v_readlane_b32 s69, v254, 48
	v_readlane_b32 s74, v254, 49
	v_readlane_b32 s75, v254, 50
	v_readlane_b32 s76, v254, 51
	v_readlane_b32 s77, v254, 52
	v_readlane_b32 s78, v254, 53
	v_readlane_b32 s79, v254, 54
	v_readlane_b32 s88, v254, 55
	s_waitcnt lgkmcnt(0)
	s_nop 3

; DI void peer_item_v(const Params& p, int item) {
;     ...
;   for (int ti = 0; ti < 8; ++ti) {
;     const size_t tok = (size_t)item * 32 + wave * 8 + ti;
;     const int e_lo = EG[tok * 128 + lane], e_hi = EG[tok * 128 + 64 + lane];
;     const int a_lo = __float_as_int(AG[tok * 128 + lane]), a_hi = __float_as_int(AG[tok * 128 + 64 + lane]);
;     float out[16];
; #pragma unroll
;     for (int i = 0; i < 16; ++i) out[i] = 0.f;
;     u32x4 vqa[8], vqb[8];
.Lvq_item:
	s_lshl_b32 s14, s10, 5
	s_add_u32 s14, s14, s56
	s_lshl_b32 s13, s14, 9
	s_add_u32 s58, s2, s13
	s_addc_u32 s59, s3, 0
	s_add_u32 s60, s4, s13
	s_addc_u32 s61, s5, 0
	v_lshrrev_b32_e32 v250, 3, v249
	v_and_b32_e32 v251, 7, v249
	v_lshlrev_b32_e32 v250, 6, v250
	v_lshl_add_u32 v250, v251, 2, v250
	global_load_dword v128, v250, s[58:59] offset:0
	global_load_dword v129, v250, s[58:59] offset:32
	global_load_dword v130, v250, s[60:61] offset:0
	global_load_dword v131, v250, s[60:61] offset:32
	global_load_dword v132, v250, s[58:59] offset:512
	global_load_dword v133, v250, s[58:59] offset:544
	global_load_dword v134, v250, s[60:61] offset:512
	global_load_dword v135, v250, s[60:61] offset:544
	global_load_dword v136, v250, s[58:59] offset:1024
	global_load_dword v137, v250, s[58:59] offset:1056
	global_load_dword v138, v250, s[60:61] offset:1024
	global_load_dword v139, v250, s[60:61] offset:1056
	global_load_dword v140, v250, s[58:59] offset:1536
	global_load_dword v141, v250, s[58:59] offset:1568
	global_load_dword v142, v250, s[60:61] offset:1536
	global_load_dword v143, v250, s[60:61] offset:1568
	global_load_dword v144, v250, s[58:59] offset:2048
	global_load_dword v145, v250, s[58:59] offset:2080
	global_load_dword v146, v250, s[60:61] offset:2048
	global_load_dword v147, v250, s[60:61] offset:2080
	global_load_dword v148, v250, s[58:59] offset:2560
	global_load_dword v149, v250, s[58:59] offset:2592
	global_load_dword v150, v250, s[60:61] offset:2560
	global_load_dword v151, v250, s[60:61] offset:2592
	global_load_dword v152, v250, s[58:59] offset:3072
	global_load_dword v153, v250, s[58:59] offset:3104
	global_load_dword v154, v250, s[60:61] offset:3072
	global_load_dword v155, v250, s[60:61] offset:3104
	global_load_dword v156, v250, s[58:59] offset:3584
	global_load_dword v157, v250, s[58:59] offset:3616
	global_load_dword v158, v250, s[60:61] offset:3584
	global_load_dword v159, v250, s[60:61] offset:3616
	v_add_u32_e32 v160, s57, v241
	v_mov_b32_e32 v161, 0
	v_mov_b32_e32 v162, 1
	v_lshrrev_b32_e32 v163, 3, v249
	v_and_b32_e32 v164, 7, v249
	v_lshlrev_b32_e32 v163, 6, v163
	v_lshl_add_u32 v163, v164, 2, v163
	v_add_u32_e32 v163, s57, v163
	v_add_u32_e32 v164, 32, v163
	v_subrev_u32_e32 v165, 1, v249
	v_subrev_u32_e32 v166, 2, v249
	v_subrev_u32_e32 v167, 4, v249
	v_subrev_u32_e32 v168, 8, v249
	v_subrev_u32_e32 v169, 16, v249
	v_subrev_u32_e32 v170, 32, v249
	v_lshlrev_b32_e32 v165, 2, v165
	v_lshlrev_b32_e32 v166, 2, v166
	v_lshlrev_b32_e32 v167, 2, v167
	v_lshlrev_b32_e32 v168, 2, v168
	v_lshlrev_b32_e32 v169, 2, v169
	v_lshlrev_b32_e32 v170, 2, v170
	v_mov_b32_e32 v0, 0
	v_mov_b32_e32 v1, 0
	v_mov_b32_e32 v2, 0
	v_mov_b32_e32 v3, 0
	v_mov_b32_e32 v4, 0
	v_mov_b32_e32 v5, 0
	v_mov_b32_e32 v6, 0
	v_mov_b32_e32 v7, 0
	v_mov_b32_e32 v8, 0
	v_mov_b32_e32 v9, 0
	v_mov_b32_e32 v10, 0
	v_mov_b32_e32 v11, 0
	v_mov_b32_e32 v12, 0
	v_mov_b32_e32 v13, 0
	v_mov_b32_e32 v14, 0
	v_mov_b32_e32 v15, 0
	v_mov_b32_e32 v16, 0
	v_mov_b32_e32 v17, 0
	v_mov_b32_e32 v18, 0
	v_mov_b32_e32 v19, 0
	v_mov_b32_e32 v20, 0
	v_mov_b32_e32 v21, 0
	v_mov_b32_e32 v22, 0
	v_mov_b32_e32 v23, 0
	v_mov_b32_e32 v24, 0
	v_mov_b32_e32 v25, 0
	v_mov_b32_e32 v26, 0
	v_mov_b32_e32 v27, 0
	v_mov_b32_e32 v28, 0
	v_mov_b32_e32 v29, 0
	v_mov_b32_e32 v30, 0
	v_mov_b32_e32 v31, 0
	v_mov_b32_e32 v32, 0
	v_mov_b32_e32 v33, 0
	v_mov_b32_e32 v34, 0
	v_mov_b32_e32 v35, 0
	v_mov_b32_e32 v36, 0
	v_mov_b32_e32 v37, 0
	v_mov_b32_e32 v38, 0
	v_mov_b32_e32 v39, 0
	v_mov_b32_e32 v40, 0
	v_mov_b32_e32 v41, 0
	v_mov_b32_e32 v42, 0
	v_mov_b32_e32 v43, 0
	v_mov_b32_e32 v44, 0
	v_mov_b32_e32 v45, 0
	v_mov_b32_e32 v46, 0
	v_mov_b32_e32 v47, 0
	v_mov_b32_e32 v48, 0
	v_mov_b32_e32 v49, 0
	v_mov_b32_e32 v50, 0
	v_mov_b32_e32 v51, 0
	v_mov_b32_e32 v52, 0
	v_mov_b32_e32 v53, 0
	v_mov_b32_e32 v54, 0
	v_mov_b32_e32 v55, 0
	v_mov_b32_e32 v56, 0
	v_mov_b32_e32 v57, 0
	v_mov_b32_e32 v58, 0
	v_mov_b32_e32 v59, 0
	v_mov_b32_e32 v60, 0
	v_mov_b32_e32 v61, 0
	v_mov_b32_e32 v62, 0
	v_mov_b32_e32 v63, 0
	v_mov_b32_e32 v64, 0
	v_mov_b32_e32 v65, 0
	v_mov_b32_e32 v66, 0
	v_mov_b32_e32 v67, 0
	v_mov_b32_e32 v68, 0
	v_mov_b32_e32 v69, 0
	v_mov_b32_e32 v70, 0
	v_mov_b32_e32 v71, 0
	v_mov_b32_e32 v72, 0
	v_mov_b32_e32 v73, 0
	v_mov_b32_e32 v74, 0
	v_mov_b32_e32 v75, 0
	v_mov_b32_e32 v76, 0
	v_mov_b32_e32 v77, 0
	v_mov_b32_e32 v78, 0
	v_mov_b32_e32 v79, 0
	v_mov_b32_e32 v80, 0
	v_mov_b32_e32 v81, 0
	v_mov_b32_e32 v82, 0
	v_mov_b32_e32 v83, 0
	v_mov_b32_e32 v84, 0
	v_mov_b32_e32 v85, 0
	v_mov_b32_e32 v86, 0
	v_mov_b32_e32 v87, 0
	v_mov_b32_e32 v88, 0
	v_mov_b32_e32 v89, 0
	v_mov_b32_e32 v90, 0
	v_mov_b32_e32 v91, 0
	v_mov_b32_e32 v92, 0
	v_mov_b32_e32 v93, 0
	v_mov_b32_e32 v94, 0
	v_mov_b32_e32 v95, 0
	v_mov_b32_e32 v96, 0
	v_mov_b32_e32 v97, 0
	v_mov_b32_e32 v98, 0
	v_mov_b32_e32 v99, 0
	v_mov_b32_e32 v100, 0
	v_mov_b32_e32 v101, 0
	v_mov_b32_e32 v102, 0
	v_mov_b32_e32 v103, 0
	v_mov_b32_e32 v104, 0
	v_mov_b32_e32 v105, 0
	v_mov_b32_e32 v106, 0
	v_mov_b32_e32 v107, 0
	v_mov_b32_e32 v108, 0
	v_mov_b32_e32 v109, 0
	v_mov_b32_e32 v110, 0
	v_mov_b32_e32 v111, 0
	v_mov_b32_e32 v112, 0
	v_mov_b32_e32 v113, 0
	v_mov_b32_e32 v114, 0
	v_mov_b32_e32 v115, 0
	v_mov_b32_e32 v116, 0
	v_mov_b32_e32 v117, 0
	v_mov_b32_e32 v118, 0
	v_mov_b32_e32 v119, 0
	v_mov_b32_e32 v120, 0
	v_mov_b32_e32 v121, 0
	v_mov_b32_e32 v122, 0
	v_mov_b32_e32 v123, 0
	v_mov_b32_e32 v124, 0
	v_mov_b32_e32 v125, 0
	v_mov_b32_e32 v126, 0
	v_mov_b32_e32 v127, 0
	s_waitcnt vmcnt(0)
; DI void peer_item_v(const Params& p, int item) {
;     ...
;     V_ISSUE(vqa, 0)
	v_lshlrev_b32_e32 v128, 10, v128
	v_lshlrev_b32_e32 v129, 10, v129
	v_lshlrev_b32_e32 v132, 10, v132
	v_lshlrev_b32_e32 v133, 10, v133
	v_lshlrev_b32_e32 v136, 10, v136
	v_lshlrev_b32_e32 v137, 10, v137
	v_lshlrev_b32_e32 v140, 10, v140
	v_lshlrev_b32_e32 v141, 10, v141
	v_lshlrev_b32_e32 v144, 10, v144
	v_lshlrev_b32_e32 v145, 10, v145
	v_lshlrev_b32_e32 v148, 10, v148
	v_lshlrev_b32_e32 v149, 10, v149
	v_lshlrev_b32_e32 v152, 10, v152
	v_lshlrev_b32_e32 v153, 10, v153
	v_lshlrev_b32_e32 v156, 10, v156
	v_lshlrev_b32_e32 v157, 10, v157
	s_mov_b32 s72, 0
	s_mov_b32 s73, 1
	s_mov_b32 s74, 2
	s_mov_b32 s75, 3
	s_mov_b32 s76, 4
	s_mov_b32 s77, 5
	s_mov_b32 s78, 6
	s_mov_b32 s79, 7
	s_nop 0
	v_readlane_b32 s48, v128, s72
	v_readlane_b32 s49, v128, s73
	v_readlane_b32 s50, v128, s74
	v_readlane_b32 s51, v128, s75
	v_readlane_b32 s52, v128, s76
	v_readlane_b32 s53, v128, s77
	v_readlane_b32 s54, v128, s78
	v_readlane_b32 s55, v128, s79
	s_add_u32 s32, s0, s48
	s_addc_u32 s33, s1, 0
	s_add_u32 s34, s0, s49
	s_addc_u32 s35, s1, 0
	s_add_u32 s36, s0, s50
	s_addc_u32 s37, s1, 0
	s_add_u32 s38, s0, s51
	s_addc_u32 s39, s1, 0
	s_add_u32 s40, s0, s52
	s_addc_u32 s41, s1, 0
	s_add_u32 s42, s0, s53
	s_addc_u32 s43, s1, 0
	s_add_u32 s44, s0, s54
	s_addc_u32 s45, s1, 0
	s_add_u32 s46, s0, s55
	s_addc_u32 s47, s1, 0
	global_load_dwordx4 v[160:163], v240, s[32:33]
	global_load_dwordx4 v[164:167], v240, s[34:35]
	global_load_dwordx4 v[168:171], v240, s[36:37]
	global_load_dwordx4 v[172:175], v240, s[38:39]
	global_load_dwordx4 v[176:179], v240, s[40:41]
	global_load_dwordx4 v[180:183], v240, s[42:43]
	global_load_dwordx4 v[184:187], v240, s[44:45]
	global_load_dwordx4 v[188:191], v240, s[46:47]
	s_mov_b32 s12, 0

; __global__ void __launch_bounds__(512) fwd_megakernel(Params p) {
;   extern __shared__ __attribute__((aligned(16))) char smem[];
	.amdhsa_kernel _Z14fwd_megakernel6Params
		.amdhsa_group_segment_fixed_size 32
		.amdhsa_private_segment_fixed_size 0
		.amdhsa_kernarg_size 448
		.amdhsa_user_sgpr_count 2
		.amdhsa_user_sgpr_dispatch_ptr 0
		.amdhsa_user_sgpr_queue_ptr 0
		.amdhsa_user_sgpr_kernarg_segment_ptr 1
		.amdhsa_user_sgpr_dispatch_id 0
		.amdhsa_user_sgpr_kernarg_preload_length 0
		.amdhsa_user_sgpr_kernarg_preload_offset 0
		.amdhsa_user_sgpr_private_segment_size 0
		.amdhsa_uses_dynamic_stack 0
		.amdhsa_enable_private_segment 0
		.amdhsa_system_sgpr_workgroup_id_x 1
		.amdhsa_system_sgpr_workgroup_id_y 0
		.amdhsa_system_sgpr_workgroup_id_z 0
		.amdhsa_system_sgpr_workgroup_info 0
		.amdhsa_system_vgpr_workitem_id 2
		.amdhsa_next_free_vgpr 255
		.amdhsa_next_free_sgpr 98
		.amdhsa_accum_offset 256
		.amdhsa_reserve_vcc 1
		.amdhsa_float_round_mode_32 0
		.amdhsa_float_round_mode_16_64 0
		.amdhsa_float_denorm_mode_32 3
		.amdhsa_float_denorm_mode_16_64 3
		.amdhsa_dx10_clamp 1
		.amdhsa_ieee_mode 1
		.amdhsa_fp16_overflow 0
		.amdhsa_tg_split 0
		.amdhsa_exception_fp_ieee_invalid_op 0
		.amdhsa_exception_fp_denorm_src 0
		.amdhsa_exception_fp_ieee_div_zero 0
		.amdhsa_exception_fp_ieee_overflow 0
		.amdhsa_exception_fp_ieee_underflow 0
		.amdhsa_exception_fp_ieee_inexact 0
		.amdhsa_exception_int_div_zero 0
	.end_amdhsa_kernel

; __global__ void __launch_bounds__(512) fwd_megakernel(Params p) {
;   extern __shared__ __attribute__((aligned(16))) char smem[];
.Lfunc_end0:
	.size	_Z14fwd_megakernel6Params, .Lfunc_end0-_Z14fwd_megakernel6Params
	.set _Z14fwd_megakernel6Params.num_vgpr, 255
	.set _Z14fwd_megakernel6Params.num_agpr, 0
	.set _Z14fwd_megakernel6Params.numbered_sgpr, 98
	.set _Z14fwd_megakernel6Params.num_named_barrier, 0
	.set _Z14fwd_megakernel6Params.private_seg_size, 0
	.set _Z14fwd_megakernel6Params.uses_vcc, 1
	.set _Z14fwd_megakernel6Params.uses_flat_scratch, 0
	.set _Z14fwd_megakernel6Params.has_dyn_sized_stack, 0
	.set _Z14fwd_megakernel6Params.has_recursion, 0
	.set _Z14fwd_megakernel6Params.has_indirect_call, 0

; __global__ void __launch_bounds__(512) fwd_megakernel(Params p) {
;   extern __shared__ __attribute__((aligned(16))) char smem[];
amdhsa.kernels:
  - .agpr_count:     0
    .args:
      - .offset:         0
        .size:           192
        .value_kind:     by_value
      - .offset:         192
        .size:           4
        .value_kind:     hidden_block_count_x
      - .offset:         196
        .size:           4
        .value_kind:     hidden_block_count_y
      - .offset:         200
        .size:           4
        .value_kind:     hidden_block_count_z
      - .offset:         204
        .size:           2
        .value_kind:     hidden_group_size_x
      - .offset:         206
        .size:           2
        .value_kind:     hidden_group_size_y
      - .offset:         208
        .size:           2
        .value_kind:     hidden_group_size_z
      - .offset:         210
        .size:           2
        .value_kind:     hidden_remainder_x
      - .offset:         212
        .size:           2
        .value_kind:     hidden_remainder_y
      - .offset:         214
        .size:           2
        .value_kind:     hidden_remainder_z
      - .offset:         232
        .size:           8
        .value_kind:     hidden_global_offset_x
      - .offset:         240
        .size:           8
        .value_kind:     hidden_global_offset_y
      - .offset:         248
        .size:           8
        .value_kind:     hidden_global_offset_z
      - .offset:         256
        .size:           2
        .value_kind:     hidden_grid_dims
      - .offset:         280
        .size:           8
        .value_kind:     hidden_multigrid_sync_arg
      - .offset:         312
        .size:           4
        .value_kind:     hidden_dynamic_lds_size
    .group_segment_fixed_size: 32
    .kernarg_segment_align: 8
    .kernarg_segment_size: 448
    .language:       OpenCL C
    .language_version:
      - 2
      - 0
    .max_flat_workgroup_size: 512
    .name:           _Z14fwd_megakernel6Params
    .private_segment_fixed_size: 0
    .sgpr_count:     104
    .sgpr_spill_count: 75
    .symbol:         _Z14fwd_megakernel6Params.kd
    .uniform_work_group_size: 1
    .uses_dynamic_stack: false
    .vgpr_count:     255
    .vgpr_spill_count: 0
    .wavefront_size: 64
